# chained MFMA pairs with the weight fragment stationary across pairs (instead of the activation fragment) + SP2 load-seg interleave
# baseline (speedup 1.0000x reference)
.LBB0_303:
	s_lshl_b32 s18, s91, 20
	s_and_b64 s[8:9], s[34:35], exec
	s_cselect_b32 s8, s18, s94
	s_lshl_b32 s19, s90, 20
	s_and_b64 s[42:43], s[34:35], exec
	s_cselect_b32 s9, s19, s95
	s_add_i32 s94, s94, 0x80080
	s_addk_i32 s95, 0x100
	s_mov_b32 vcc_lo, -2
	ds_read_b128 v[142:145], v136
	ds_read_b128 v[170:173], v136 offset:1024
	ds_read_b128 v[174:177], v136 offset:2048
	ds_read_b128 v[178:181], v136 offset:3072
	ds_read_b128 v[182:185], v137
	ds_read_b128 v[186:189], v137 offset:1024
	ds_read_b128 v[190:193], v137 offset:2048
	ds_read_b128 v[194:197], v137 offset:3072
	s_add_i32 s42, s94, 0xfff80080
	s_cmp_eq_u32 vcc_lo, 28
	s_cselect_b32 s97, s8, s42
	s_cselect_b32 s52, s9, s95
	s_or_b32 vcc_hi, s97, 0x80
	s_mov_b32 m0, s72
	ds_read_b128 v[198:201], v138
	ds_read_b128 v[202:205], v138 offset:1024
	ds_read_b128 v[228:231], v138 offset:2048
	ds_read_b128 v[232:235], v138 offset:3072
	ds_read_b128 v[236:239], v138 offset:4096
	ds_read_b128 v[240:243], v138 offset:5120
	ds_read_b128 v[244:247], v138 offset:6144
	ds_read_b128 v[248:251], v138 offset:7168
	buffer_load_dwordx4 v132, s[60:63], s94 offen lds
	s_mov_b32 m0, s47
	s_nop 0
	buffer_load_dwordx4 v134, s[60:63], s94 offen lds
	s_waitcnt vmcnt(8)
	s_waitcnt lgkmcnt(0)
	s_setprio 1
	s_barrier
	v_mfma_f32_16x16x32_bf16 v[114:117], v[142:145], v[198:201], 0
	v_mfma_f32_16x16x32_bf16 v[114:117], v[170:173], v[202:205], v[114:117]
	v_mfma_f32_16x16x32_bf16 v[106:109], v[142:145], v[228:231], 0
	v_mfma_f32_16x16x32_bf16 v[106:109], v[170:173], v[232:235], v[106:109]
	v_mfma_f32_16x16x32_bf16 v[94:97], v[142:145], v[236:239], 0
	v_mfma_f32_16x16x32_bf16 v[94:97], v[170:173], v[240:243], v[94:97]
	v_mfma_f32_16x16x32_bf16 v[78:81], v[142:145], v[244:247], 0
	v_mfma_f32_16x16x32_bf16 v[78:81], v[170:173], v[248:251], v[78:81]
	v_mfma_f32_16x16x32_bf16 v[70:73], v[174:177], v[244:247], 0
	v_mfma_f32_16x16x32_bf16 v[70:73], v[178:181], v[248:251], v[70:73]
	v_mfma_f32_16x16x32_bf16 v[86:89], v[174:177], v[236:239], 0
	v_mfma_f32_16x16x32_bf16 v[86:89], v[178:181], v[240:243], v[86:89]
	v_mfma_f32_16x16x32_bf16 v[102:105], v[174:177], v[228:231], 0
	v_mfma_f32_16x16x32_bf16 v[102:105], v[178:181], v[232:235], v[102:105]
	v_mfma_f32_16x16x32_bf16 v[110:113], v[174:177], v[198:201], 0
	v_mfma_f32_16x16x32_bf16 v[110:113], v[178:181], v[202:205], v[110:113]
	v_mfma_f32_16x16x32_bf16 v[122:125], v[190:193], v[198:201], 0
	v_mfma_f32_16x16x32_bf16 v[122:125], v[194:197], v[202:205], v[122:125]
	v_mfma_f32_16x16x32_bf16 v[98:101], v[190:193], v[228:231], 0
	v_mfma_f32_16x16x32_bf16 v[98:101], v[194:197], v[232:235], v[98:101]
	v_mfma_f32_16x16x32_bf16 v[82:85], v[190:193], v[236:239], 0
	v_mfma_f32_16x16x32_bf16 v[82:85], v[194:197], v[240:243], v[82:85]
	v_mfma_f32_16x16x32_bf16 v[66:69], v[190:193], v[244:247], 0
	v_mfma_f32_16x16x32_bf16 v[66:69], v[194:197], v[248:251], v[66:69]
	v_mfma_f32_16x16x32_bf16 v[74:77], v[182:185], v[244:247], 0
	v_mfma_f32_16x16x32_bf16 v[74:77], v[186:189], v[248:251], v[74:77]
	v_mfma_f32_16x16x32_bf16 v[90:93], v[182:185], v[236:239], 0
	v_mfma_f32_16x16x32_bf16 v[90:93], v[186:189], v[240:243], v[90:93]
	v_mfma_f32_16x16x32_bf16 v[118:121], v[182:185], v[228:231], 0
	v_mfma_f32_16x16x32_bf16 v[118:121], v[186:189], v[232:235], v[118:121]
	v_mfma_f32_16x16x32_bf16 v[126:129], v[182:185], v[198:201], 0
	v_mfma_f32_16x16x32_bf16 v[126:129], v[186:189], v[202:205], v[126:129]
	s_barrier
	s_setprio 0
	s_mov_b32 s42, s62
	s_mov_b32 s43, s63
	s_mov_b32 m0, s13
	ds_read_b128 v[198:201], v138 offset:16384
	buffer_load_dwordx4 v133, s[40:43], s52 offen lds
	s_add_i32 s96, s52, 0x80000
	s_mov_b32 m0, s14
	ds_read_b128 v[202:205], v138 offset:17408
	buffer_load_dwordx4 v135, s[40:43], s52 offen lds
	s_mov_b32 m0, s15
	ds_read_b128 v[228:231], v138 offset:18432
	buffer_load_dwordx4 v133, s[40:43], s96 offen lds
	s_mov_b32 m0, s16
	ds_read_b128 v[232:235], v138 offset:19456
	buffer_load_dwordx4 v135, s[40:43], s96 offen lds
	s_mov_b32 m0, s2
	ds_read_b128 v[236:239], v138 offset:20480
	buffer_load_dwordx4 v132, s[60:63], s97 offen lds
	s_mov_b32 m0, s21
	ds_read_b128 v[240:243], v138 offset:21504
	buffer_load_dwordx4 v134, s[60:63], s97 offen lds
	ds_read_b128 v[244:247], v138 offset:22528
	ds_read_b128 v[248:251], v138 offset:23552
	s_waitcnt vmcnt(8)
	s_waitcnt lgkmcnt(0)
	s_setprio 1
	s_barrier
	v_mfma_f32_16x16x32_bf16 v[62:65], v[142:145], v[198:201], 0
	v_mfma_f32_16x16x32_bf16 v[62:65], v[170:173], v[202:205], v[62:65]
	v_mfma_f32_16x16x32_bf16 v[46:49], v[142:145], v[228:231], 0
	v_mfma_f32_16x16x32_bf16 v[46:49], v[170:173], v[232:235], v[46:49]
	v_mfma_f32_16x16x32_bf16 v[30:33], v[142:145], v[236:239], 0
	v_mfma_f32_16x16x32_bf16 v[30:33], v[170:173], v[240:243], v[30:33]
	v_mfma_f32_16x16x32_bf16 v[14:17], v[142:145], v[244:247], 0
	v_mfma_f32_16x16x32_bf16 v[14:17], v[170:173], v[248:251], v[14:17]
	v_mfma_f32_16x16x32_bf16 v[6:9], v[174:177], v[244:247], 0
	v_mfma_f32_16x16x32_bf16 v[6:9], v[178:181], v[248:251], v[6:9]
	v_mfma_f32_16x16x32_bf16 v[22:25], v[174:177], v[236:239], 0
	v_mfma_f32_16x16x32_bf16 v[22:25], v[178:181], v[240:243], v[22:25]
	v_mfma_f32_16x16x32_bf16 v[38:41], v[174:177], v[228:231], 0
	v_mfma_f32_16x16x32_bf16 v[38:41], v[178:181], v[232:235], v[38:41]
	v_mfma_f32_16x16x32_bf16 v[54:57], v[174:177], v[198:201], 0
	v_mfma_f32_16x16x32_bf16 v[54:57], v[178:181], v[202:205], v[54:57]
	v_mfma_f32_16x16x32_bf16 v[50:53], v[190:193], v[198:201], 0
	v_mfma_f32_16x16x32_bf16 v[50:53], v[194:197], v[202:205], v[50:53]
	v_mfma_f32_16x16x32_bf16 v[34:37], v[190:193], v[228:231], 0
	v_mfma_f32_16x16x32_bf16 v[34:37], v[194:197], v[232:235], v[34:37]
	v_mfma_f32_16x16x32_bf16 v[18:21], v[190:193], v[236:239], 0
	v_mfma_f32_16x16x32_bf16 v[18:21], v[194:197], v[240:243], v[18:21]
	v_mfma_f32_16x16x32_bf16 v[2:5], v[190:193], v[244:247], 0
	v_mfma_f32_16x16x32_bf16 v[2:5], v[194:197], v[248:251], v[2:5]
	v_mfma_f32_16x16x32_bf16 v[10:13], v[182:185], v[244:247], 0
	v_mfma_f32_16x16x32_bf16 v[10:13], v[186:189], v[248:251], v[10:13]
	v_mfma_f32_16x16x32_bf16 v[26:29], v[182:185], v[236:239], 0
	v_mfma_f32_16x16x32_bf16 v[26:29], v[186:189], v[240:243], v[26:29]
	v_mfma_f32_16x16x32_bf16 v[42:45], v[182:185], v[228:231], 0
	v_mfma_f32_16x16x32_bf16 v[42:45], v[186:189], v[232:235], v[42:45]
	v_mfma_f32_16x16x32_bf16 v[58:61], v[182:185], v[198:201], 0
	v_mfma_f32_16x16x32_bf16 v[58:61], v[186:189], v[202:205], v[58:61]
	s_barrier
	s_setprio 0
	ds_read_b128 v[142:145], v139
	ds_read_b128 v[170:173], v139 offset:1024
	ds_read_b128 v[174:177], v139 offset:2048
	ds_read_b128 v[178:181], v139 offset:3072
	ds_read_b128 v[182:185], v140
	ds_read_b128 v[186:189], v140 offset:1024
	ds_read_b128 v[190:193], v140 offset:2048
	ds_read_b128 v[194:197], v140 offset:3072
	s_add_i32 s97, s97, 0x80000
	s_mov_b32 m0, s23
	ds_read_b128 v[198:201], v138 offset:32768
	ds_read_b128 v[202:205], v138 offset:33792
	ds_read_b128 v[228:231], v138 offset:34816
	ds_read_b128 v[232:235], v138 offset:35840
	ds_read_b128 v[236:239], v138 offset:36864
	ds_read_b128 v[240:243], v138 offset:37888
	ds_read_b128 v[244:247], v138 offset:38912
	ds_read_b128 v[248:251], v138 offset:39936
	buffer_load_dwordx4 v132, s[60:63], s97 offen lds
	s_mov_b32 m0, s24
	s_nop 0
	buffer_load_dwordx4 v134, s[60:63], s97 offen lds
	s_waitcnt vmcnt(8)
	s_waitcnt lgkmcnt(0)
	s_setprio 1
	s_barrier
	v_mfma_f32_16x16x32_bf16 v[114:117], v[142:145], v[198:201], v[114:117]
	v_mfma_f32_16x16x32_bf16 v[114:117], v[170:173], v[202:205], v[114:117]
	v_mfma_f32_16x16x32_bf16 v[106:109], v[142:145], v[228:231], v[106:109]
	v_mfma_f32_16x16x32_bf16 v[106:109], v[170:173], v[232:235], v[106:109]
	v_mfma_f32_16x16x32_bf16 v[94:97], v[142:145], v[236:239], v[94:97]
	v_mfma_f32_16x16x32_bf16 v[94:97], v[170:173], v[240:243], v[94:97]
	v_mfma_f32_16x16x32_bf16 v[78:81], v[142:145], v[244:247], v[78:81]
	v_mfma_f32_16x16x32_bf16 v[78:81], v[170:173], v[248:251], v[78:81]
	v_mfma_f32_16x16x32_bf16 v[70:73], v[174:177], v[244:247], v[70:73]
	v_mfma_f32_16x16x32_bf16 v[70:73], v[178:181], v[248:251], v[70:73]
	v_mfma_f32_16x16x32_bf16 v[86:89], v[174:177], v[236:239], v[86:89]
	v_mfma_f32_16x16x32_bf16 v[86:89], v[178:181], v[240:243], v[86:89]
	v_mfma_f32_16x16x32_bf16 v[102:105], v[174:177], v[228:231], v[102:105]
	v_mfma_f32_16x16x32_bf16 v[102:105], v[178:181], v[232:235], v[102:105]
	v_mfma_f32_16x16x32_bf16 v[110:113], v[174:177], v[198:201], v[110:113]
	v_mfma_f32_16x16x32_bf16 v[110:113], v[178:181], v[202:205], v[110:113]
	v_mfma_f32_16x16x32_bf16 v[122:125], v[190:193], v[198:201], v[122:125]
	v_mfma_f32_16x16x32_bf16 v[122:125], v[194:197], v[202:205], v[122:125]
	v_mfma_f32_16x16x32_bf16 v[98:101], v[190:193], v[228:231], v[98:101]
	v_mfma_f32_16x16x32_bf16 v[98:101], v[194:197], v[232:235], v[98:101]
	v_mfma_f32_16x16x32_bf16 v[82:85], v[190:193], v[236:239], v[82:85]
	v_mfma_f32_16x16x32_bf16 v[82:85], v[194:197], v[240:243], v[82:85]
	v_mfma_f32_16x16x32_bf16 v[66:69], v[190:193], v[244:247], v[66:69]
	v_mfma_f32_16x16x32_bf16 v[66:69], v[194:197], v[248:251], v[66:69]
	v_mfma_f32_16x16x32_bf16 v[74:77], v[182:185], v[244:247], v[74:77]
	v_mfma_f32_16x16x32_bf16 v[74:77], v[186:189], v[248:251], v[74:77]
	v_mfma_f32_16x16x32_bf16 v[90:93], v[182:185], v[236:239], v[90:93]
	v_mfma_f32_16x16x32_bf16 v[90:93], v[186:189], v[240:243], v[90:93]
	v_mfma_f32_16x16x32_bf16 v[118:121], v[182:185], v[228:231], v[118:121]
	v_mfma_f32_16x16x32_bf16 v[118:121], v[186:189], v[232:235], v[118:121]
	v_mfma_f32_16x16x32_bf16 v[126:129], v[182:185], v[198:201], v[126:129]
	v_mfma_f32_16x16x32_bf16 v[126:129], v[186:189], v[202:205], v[126:129]
	s_barrier
	s_setprio 0
	s_or_b32 s53, s52, 0x80
	s_mov_b32 m0, s31
	ds_read_b128 v[198:201], v138 offset:49152
	buffer_load_dwordx4 v133, s[40:43], s53 offen lds
	s_add_i32 s52, s52, 0x80080
	s_mov_b32 m0, s33
	ds_read_b128 v[202:205], v138 offset:50176
	buffer_load_dwordx4 v135, s[40:43], s53 offen lds
	s_mov_b32 m0, s68
	ds_read_b128 v[228:231], v138 offset:51200
	buffer_load_dwordx4 v133, s[40:43], s52 offen lds
	s_mov_b32 m0, s69
	ds_read_b128 v[232:235], v138 offset:52224
	buffer_load_dwordx4 v135, s[40:43], s52 offen lds
	s_mov_b32 m0, s36
	ds_read_b128 v[236:239], v138 offset:53248
	buffer_load_dwordx4 v132, s[60:63], vcc_hi offen lds
	s_mov_b32 m0, s37
	ds_read_b128 v[240:243], v138 offset:54272
	buffer_load_dwordx4 v134, s[60:63], vcc_hi offen lds
	ds_read_b128 v[244:247], v138 offset:55296
	ds_read_b128 v[248:251], v138 offset:56320
	s_waitcnt vmcnt(8)
	s_waitcnt lgkmcnt(0)
	s_setprio 1
	s_barrier
	v_mfma_f32_16x16x32_bf16 v[62:65], v[142:145], v[198:201], v[62:65]
	v_mfma_f32_16x16x32_bf16 v[62:65], v[170:173], v[202:205], v[62:65]
	v_mfma_f32_16x16x32_bf16 v[46:49], v[142:145], v[228:231], v[46:49]
	v_mfma_f32_16x16x32_bf16 v[46:49], v[170:173], v[232:235], v[46:49]
	v_mfma_f32_16x16x32_bf16 v[30:33], v[142:145], v[236:239], v[30:33]
	v_mfma_f32_16x16x32_bf16 v[30:33], v[170:173], v[240:243], v[30:33]
	v_mfma_f32_16x16x32_bf16 v[14:17], v[142:145], v[244:247], v[14:17]
	v_mfma_f32_16x16x32_bf16 v[14:17], v[170:173], v[248:251], v[14:17]
	v_mfma_f32_16x16x32_bf16 v[6:9], v[174:177], v[244:247], v[6:9]
	v_mfma_f32_16x16x32_bf16 v[6:9], v[178:181], v[248:251], v[6:9]
	v_mfma_f32_16x16x32_bf16 v[22:25], v[174:177], v[236:239], v[22:25]
	v_mfma_f32_16x16x32_bf16 v[22:25], v[178:181], v[240:243], v[22:25]
	v_mfma_f32_16x16x32_bf16 v[38:41], v[174:177], v[228:231], v[38:41]
	v_mfma_f32_16x16x32_bf16 v[38:41], v[178:181], v[232:235], v[38:41]
	v_mfma_f32_16x16x32_bf16 v[54:57], v[174:177], v[198:201], v[54:57]
	v_mfma_f32_16x16x32_bf16 v[54:57], v[178:181], v[202:205], v[54:57]
	v_mfma_f32_16x16x32_bf16 v[50:53], v[190:193], v[198:201], v[50:53]
	v_mfma_f32_16x16x32_bf16 v[50:53], v[194:197], v[202:205], v[50:53]
	v_mfma_f32_16x16x32_bf16 v[34:37], v[190:193], v[228:231], v[34:37]
	v_mfma_f32_16x16x32_bf16 v[34:37], v[194:197], v[232:235], v[34:37]
	v_mfma_f32_16x16x32_bf16 v[18:21], v[190:193], v[236:239], v[18:21]
	v_mfma_f32_16x16x32_bf16 v[18:21], v[194:197], v[240:243], v[18:21]
	v_mfma_f32_16x16x32_bf16 v[2:5], v[190:193], v[244:247], v[2:5]
	v_mfma_f32_16x16x32_bf16 v[2:5], v[194:197], v[248:251], v[2:5]
	v_mfma_f32_16x16x32_bf16 v[10:13], v[182:185], v[244:247], v[10:13]
	v_mfma_f32_16x16x32_bf16 v[10:13], v[186:189], v[248:251], v[10:13]
	v_mfma_f32_16x16x32_bf16 v[26:29], v[182:185], v[236:239], v[26:29]
	v_mfma_f32_16x16x32_bf16 v[26:29], v[186:189], v[240:243], v[26:29]
	v_mfma_f32_16x16x32_bf16 v[42:45], v[182:185], v[228:231], v[42:45]
	v_mfma_f32_16x16x32_bf16 v[42:45], v[186:189], v[232:235], v[42:45]
	v_mfma_f32_16x16x32_bf16 v[58:61], v[182:185], v[198:201], v[58:61]
	v_mfma_f32_16x16x32_bf16 v[58:61], v[186:189], v[202:205], v[58:61]
	s_barrier
	s_setprio 0
	s_add_i32 vcc_lo, vcc_lo, 2
	s_addk_i32 s94, 0x100
	s_addk_i32 s95, 0x100
	s_cmp_gt_u32 vcc_lo, 29
.LBB0_304:
	ds_read_b128 v[142:145], v136
	ds_read_b128 v[170:173], v136 offset:1024
	ds_read_b128 v[174:177], v136 offset:2048
	ds_read_b128 v[178:181], v136 offset:3072
	ds_read_b128 v[182:185], v137
	ds_read_b128 v[186:189], v137 offset:1024
	ds_read_b128 v[190:193], v137 offset:2048
	ds_read_b128 v[194:197], v137 offset:3072
	s_add_i32 s42, s94, 0xfff80080
	s_cmp_eq_u32 vcc_lo, 28
	s_cselect_b32 s97, s8, s42
	s_cselect_b32 s52, s9, s95
	s_or_b32 vcc_hi, s97, 0x80
	s_mov_b32 m0, s72
	ds_read_b128 v[198:201], v138
	ds_read_b128 v[202:205], v138 offset:1024
	ds_read_b128 v[228:231], v138 offset:2048
	ds_read_b128 v[232:235], v138 offset:3072
	ds_read_b128 v[236:239], v138 offset:4096
	ds_read_b128 v[240:243], v138 offset:5120
	ds_read_b128 v[244:247], v138 offset:6144
	ds_read_b128 v[248:251], v138 offset:7168
	buffer_load_dwordx4 v132, s[60:63], s94 offen lds
	s_mov_b32 m0, s47
	s_nop 0
	buffer_load_dwordx4 v134, s[60:63], s94 offen lds
	s_waitcnt vmcnt(8)
	s_waitcnt lgkmcnt(0)
	s_setprio 1
	s_barrier
	v_mfma_f32_16x16x32_bf16 v[114:117], v[142:145], v[198:201], v[114:117]
	v_mfma_f32_16x16x32_bf16 v[114:117], v[170:173], v[202:205], v[114:117]
	v_mfma_f32_16x16x32_bf16 v[106:109], v[142:145], v[228:231], v[106:109]
	v_mfma_f32_16x16x32_bf16 v[106:109], v[170:173], v[232:235], v[106:109]
	v_mfma_f32_16x16x32_bf16 v[94:97], v[142:145], v[236:239], v[94:97]
	v_mfma_f32_16x16x32_bf16 v[94:97], v[170:173], v[240:243], v[94:97]
	v_mfma_f32_16x16x32_bf16 v[78:81], v[142:145], v[244:247], v[78:81]
	v_mfma_f32_16x16x32_bf16 v[78:81], v[170:173], v[248:251], v[78:81]
	v_mfma_f32_16x16x32_bf16 v[70:73], v[174:177], v[244:247], v[70:73]
	v_mfma_f32_16x16x32_bf16 v[70:73], v[178:181], v[248:251], v[70:73]
	v_mfma_f32_16x16x32_bf16 v[86:89], v[174:177], v[236:239], v[86:89]
	v_mfma_f32_16x16x32_bf16 v[86:89], v[178:181], v[240:243], v[86:89]
	v_mfma_f32_16x16x32_bf16 v[102:105], v[174:177], v[228:231], v[102:105]
	v_mfma_f32_16x16x32_bf16 v[102:105], v[178:181], v[232:235], v[102:105]
	v_mfma_f32_16x16x32_bf16 v[110:113], v[174:177], v[198:201], v[110:113]
	v_mfma_f32_16x16x32_bf16 v[110:113], v[178:181], v[202:205], v[110:113]
	v_mfma_f32_16x16x32_bf16 v[122:125], v[190:193], v[198:201], v[122:125]
	v_mfma_f32_16x16x32_bf16 v[122:125], v[194:197], v[202:205], v[122:125]
	v_mfma_f32_16x16x32_bf16 v[98:101], v[190:193], v[228:231], v[98:101]
	v_mfma_f32_16x16x32_bf16 v[98:101], v[194:197], v[232:235], v[98:101]
	v_mfma_f32_16x16x32_bf16 v[82:85], v[190:193], v[236:239], v[82:85]
	v_mfma_f32_16x16x32_bf16 v[82:85], v[194:197], v[240:243], v[82:85]
	v_mfma_f32_16x16x32_bf16 v[66:69], v[190:193], v[244:247], v[66:69]
	v_mfma_f32_16x16x32_bf16 v[66:69], v[194:197], v[248:251], v[66:69]
	v_mfma_f32_16x16x32_bf16 v[74:77], v[182:185], v[244:247], v[74:77]
	v_mfma_f32_16x16x32_bf16 v[74:77], v[186:189], v[248:251], v[74:77]
	v_mfma_f32_16x16x32_bf16 v[90:93], v[182:185], v[236:239], v[90:93]
	v_mfma_f32_16x16x32_bf16 v[90:93], v[186:189], v[240:243], v[90:93]
	v_mfma_f32_16x16x32_bf16 v[118:121], v[182:185], v[228:231], v[118:121]
	v_mfma_f32_16x16x32_bf16 v[118:121], v[186:189], v[232:235], v[118:121]
	v_mfma_f32_16x16x32_bf16 v[126:129], v[182:185], v[198:201], v[126:129]
	v_mfma_f32_16x16x32_bf16 v[126:129], v[186:189], v[202:205], v[126:129]
	s_barrier
	s_setprio 0
	s_mov_b32 s42, s62
	s_mov_b32 s43, s63
	s_mov_b32 m0, s13
	ds_read_b128 v[198:201], v138 offset:16384
	buffer_load_dwordx4 v133, s[40:43], s52 offen lds
	s_add_i32 s96, s52, 0x80000
	s_mov_b32 m0, s14
	ds_read_b128 v[202:205], v138 offset:17408
	buffer_load_dwordx4 v135, s[40:43], s52 offen lds
	s_mov_b32 m0, s15
	ds_read_b128 v[228:231], v138 offset:18432
	buffer_load_dwordx4 v133, s[40:43], s96 offen lds
	s_mov_b32 m0, s16
	ds_read_b128 v[232:235], v138 offset:19456
	buffer_load_dwordx4 v135, s[40:43], s96 offen lds
	s_mov_b32 m0, s2
	ds_read_b128 v[236:239], v138 offset:20480
	buffer_load_dwordx4 v132, s[60:63], s97 offen lds
	s_mov_b32 m0, s21
	ds_read_b128 v[240:243], v138 offset:21504
	buffer_load_dwordx4 v134, s[60:63], s97 offen lds
	ds_read_b128 v[244:247], v138 offset:22528
	ds_read_b128 v[248:251], v138 offset:23552
	s_waitcnt vmcnt(8)
	s_waitcnt lgkmcnt(0)
	s_setprio 1
	s_barrier
	v_mfma_f32_16x16x32_bf16 v[62:65], v[142:145], v[198:201], v[62:65]
	v_mfma_f32_16x16x32_bf16 v[62:65], v[170:173], v[202:205], v[62:65]
	v_mfma_f32_16x16x32_bf16 v[46:49], v[142:145], v[228:231], v[46:49]
	v_mfma_f32_16x16x32_bf16 v[46:49], v[170:173], v[232:235], v[46:49]
	v_mfma_f32_16x16x32_bf16 v[30:33], v[142:145], v[236:239], v[30:33]
	v_mfma_f32_16x16x32_bf16 v[30:33], v[170:173], v[240:243], v[30:33]
	v_mfma_f32_16x16x32_bf16 v[14:17], v[142:145], v[244:247], v[14:17]
	v_mfma_f32_16x16x32_bf16 v[14:17], v[170:173], v[248:251], v[14:17]
	v_mfma_f32_16x16x32_bf16 v[6:9], v[174:177], v[244:247], v[6:9]
	v_mfma_f32_16x16x32_bf16 v[6:9], v[178:181], v[248:251], v[6:9]
	v_mfma_f32_16x16x32_bf16 v[22:25], v[174:177], v[236:239], v[22:25]
	v_mfma_f32_16x16x32_bf16 v[22:25], v[178:181], v[240:243], v[22:25]
	v_mfma_f32_16x16x32_bf16 v[38:41], v[174:177], v[228:231], v[38:41]
	v_mfma_f32_16x16x32_bf16 v[38:41], v[178:181], v[232:235], v[38:41]
	v_mfma_f32_16x16x32_bf16 v[54:57], v[174:177], v[198:201], v[54:57]
	v_mfma_f32_16x16x32_bf16 v[54:57], v[178:181], v[202:205], v[54:57]
	v_mfma_f32_16x16x32_bf16 v[50:53], v[190:193], v[198:201], v[50:53]
	v_mfma_f32_16x16x32_bf16 v[50:53], v[194:197], v[202:205], v[50:53]
	v_mfma_f32_16x16x32_bf16 v[34:37], v[190:193], v[228:231], v[34:37]
	v_mfma_f32_16x16x32_bf16 v[34:37], v[194:197], v[232:235], v[34:37]
	v_mfma_f32_16x16x32_bf16 v[18:21], v[190:193], v[236:239], v[18:21]
	v_mfma_f32_16x16x32_bf16 v[18:21], v[194:197], v[240:243], v[18:21]
	v_mfma_f32_16x16x32_bf16 v[2:5], v[190:193], v[244:247], v[2:5]
	v_mfma_f32_16x16x32_bf16 v[2:5], v[194:197], v[248:251], v[2:5]
	v_mfma_f32_16x16x32_bf16 v[10:13], v[182:185], v[244:247], v[10:13]
	v_mfma_f32_16x16x32_bf16 v[10:13], v[186:189], v[248:251], v[10:13]
	v_mfma_f32_16x16x32_bf16 v[26:29], v[182:185], v[236:239], v[26:29]
	v_mfma_f32_16x16x32_bf16 v[26:29], v[186:189], v[240:243], v[26:29]
	v_mfma_f32_16x16x32_bf16 v[42:45], v[182:185], v[228:231], v[42:45]
	v_mfma_f32_16x16x32_bf16 v[42:45], v[186:189], v[232:235], v[42:45]
	v_mfma_f32_16x16x32_bf16 v[58:61], v[182:185], v[198:201], v[58:61]
	v_mfma_f32_16x16x32_bf16 v[58:61], v[186:189], v[202:205], v[58:61]
	s_barrier
	s_setprio 0
	ds_read_b128 v[142:145], v139
	ds_read_b128 v[170:173], v139 offset:1024
	ds_read_b128 v[174:177], v139 offset:2048
	ds_read_b128 v[178:181], v139 offset:3072
	ds_read_b128 v[182:185], v140
	ds_read_b128 v[186:189], v140 offset:1024
	ds_read_b128 v[190:193], v140 offset:2048
	ds_read_b128 v[194:197], v140 offset:3072
	s_add_i32 s97, s97, 0x80000
	s_mov_b32 m0, s23
	ds_read_b128 v[198:201], v138 offset:32768
	ds_read_b128 v[202:205], v138 offset:33792
	ds_read_b128 v[228:231], v138 offset:34816
	ds_read_b128 v[232:235], v138 offset:35840
	ds_read_b128 v[236:239], v138 offset:36864
	ds_read_b128 v[240:243], v138 offset:37888
	ds_read_b128 v[244:247], v138 offset:38912
	ds_read_b128 v[248:251], v138 offset:39936
	buffer_load_dwordx4 v132, s[60:63], s97 offen lds
	s_mov_b32 m0, s24
	s_nop 0
	buffer_load_dwordx4 v134, s[60:63], s97 offen lds
	s_waitcnt vmcnt(8)
	s_waitcnt lgkmcnt(0)
	s_setprio 1
	s_barrier
	v_mfma_f32_16x16x32_bf16 v[114:117], v[142:145], v[198:201], v[114:117]
	v_mfma_f32_16x16x32_bf16 v[114:117], v[170:173], v[202:205], v[114:117]
	v_mfma_f32_16x16x32_bf16 v[106:109], v[142:145], v[228:231], v[106:109]
	v_mfma_f32_16x16x32_bf16 v[106:109], v[170:173], v[232:235], v[106:109]
	v_mfma_f32_16x16x32_bf16 v[94:97], v[142:145], v[236:239], v[94:97]
	v_mfma_f32_16x16x32_bf16 v[94:97], v[170:173], v[240:243], v[94:97]
	v_mfma_f32_16x16x32_bf16 v[78:81], v[142:145], v[244:247], v[78:81]
	v_mfma_f32_16x16x32_bf16 v[78:81], v[170:173], v[248:251], v[78:81]
	v_mfma_f32_16x16x32_bf16 v[70:73], v[174:177], v[244:247], v[70:73]
	v_mfma_f32_16x16x32_bf16 v[70:73], v[178:181], v[248:251], v[70:73]
	v_mfma_f32_16x16x32_bf16 v[86:89], v[174:177], v[236:239], v[86:89]
	v_mfma_f32_16x16x32_bf16 v[86:89], v[178:181], v[240:243], v[86:89]
	v_mfma_f32_16x16x32_bf16 v[102:105], v[174:177], v[228:231], v[102:105]
	v_mfma_f32_16x16x32_bf16 v[102:105], v[178:181], v[232:235], v[102:105]
	v_mfma_f32_16x16x32_bf16 v[110:113], v[174:177], v[198:201], v[110:113]
	v_mfma_f32_16x16x32_bf16 v[110:113], v[178:181], v[202:205], v[110:113]
	v_mfma_f32_16x16x32_bf16 v[122:125], v[190:193], v[198:201], v[122:125]
	v_mfma_f32_16x16x32_bf16 v[122:125], v[194:197], v[202:205], v[122:125]
	v_mfma_f32_16x16x32_bf16 v[98:101], v[190:193], v[228:231], v[98:101]
	v_mfma_f32_16x16x32_bf16 v[98:101], v[194:197], v[232:235], v[98:101]
	v_mfma_f32_16x16x32_bf16 v[82:85], v[190:193], v[236:239], v[82:85]
	v_mfma_f32_16x16x32_bf16 v[82:85], v[194:197], v[240:243], v[82:85]
	v_mfma_f32_16x16x32_bf16 v[66:69], v[190:193], v[244:247], v[66:69]
	v_mfma_f32_16x16x32_bf16 v[66:69], v[194:197], v[248:251], v[66:69]
	v_mfma_f32_16x16x32_bf16 v[74:77], v[182:185], v[244:247], v[74:77]
	v_mfma_f32_16x16x32_bf16 v[74:77], v[186:189], v[248:251], v[74:77]
	v_mfma_f32_16x16x32_bf16 v[90:93], v[182:185], v[236:239], v[90:93]
	v_mfma_f32_16x16x32_bf16 v[90:93], v[186:189], v[240:243], v[90:93]
	v_mfma_f32_16x16x32_bf16 v[118:121], v[182:185], v[228:231], v[118:121]
	v_mfma_f32_16x16x32_bf16 v[118:121], v[186:189], v[232:235], v[118:121]
	v_mfma_f32_16x16x32_bf16 v[126:129], v[182:185], v[198:201], v[126:129]
	v_mfma_f32_16x16x32_bf16 v[126:129], v[186:189], v[202:205], v[126:129]
	s_barrier
	s_setprio 0
	s_or_b32 s53, s52, 0x80
	s_mov_b32 m0, s31
	ds_read_b128 v[198:201], v138 offset:49152
	buffer_load_dwordx4 v133, s[40:43], s53 offen lds
	s_add_i32 s52, s52, 0x80080
	s_mov_b32 m0, s33
	ds_read_b128 v[202:205], v138 offset:50176
	buffer_load_dwordx4 v135, s[40:43], s53 offen lds
	s_mov_b32 m0, s68
	ds_read_b128 v[228:231], v138 offset:51200
	buffer_load_dwordx4 v133, s[40:43], s52 offen lds
	s_mov_b32 m0, s69
	ds_read_b128 v[232:235], v138 offset:52224
	buffer_load_dwordx4 v135, s[40:43], s52 offen lds
	s_mov_b32 m0, s36
	ds_read_b128 v[236:239], v138 offset:53248
	buffer_load_dwordx4 v132, s[60:63], vcc_hi offen lds
	s_mov_b32 m0, s37
	ds_read_b128 v[240:243], v138 offset:54272
	buffer_load_dwordx4 v134, s[60:63], vcc_hi offen lds
	ds_read_b128 v[244:247], v138 offset:55296
	ds_read_b128 v[248:251], v138 offset:56320
	s_waitcnt vmcnt(8)
	s_waitcnt lgkmcnt(0)
	s_setprio 1
	s_barrier
	v_mfma_f32_16x16x32_bf16 v[62:65], v[142:145], v[198:201], v[62:65]
	v_mfma_f32_16x16x32_bf16 v[62:65], v[170:173], v[202:205], v[62:65]
	v_mfma_f32_16x16x32_bf16 v[46:49], v[142:145], v[228:231], v[46:49]
	v_mfma_f32_16x16x32_bf16 v[46:49], v[170:173], v[232:235], v[46:49]
	v_mfma_f32_16x16x32_bf16 v[30:33], v[142:145], v[236:239], v[30:33]
	v_mfma_f32_16x16x32_bf16 v[30:33], v[170:173], v[240:243], v[30:33]
	v_mfma_f32_16x16x32_bf16 v[14:17], v[142:145], v[244:247], v[14:17]
	v_mfma_f32_16x16x32_bf16 v[14:17], v[170:173], v[248:251], v[14:17]
	v_mfma_f32_16x16x32_bf16 v[6:9], v[174:177], v[244:247], v[6:9]
	v_mfma_f32_16x16x32_bf16 v[6:9], v[178:181], v[248:251], v[6:9]
	v_mfma_f32_16x16x32_bf16 v[22:25], v[174:177], v[236:239], v[22:25]
	v_mfma_f32_16x16x32_bf16 v[22:25], v[178:181], v[240:243], v[22:25]
	v_mfma_f32_16x16x32_bf16 v[38:41], v[174:177], v[228:231], v[38:41]
	v_mfma_f32_16x16x32_bf16 v[38:41], v[178:181], v[232:235], v[38:41]
	v_mfma_f32_16x16x32_bf16 v[54:57], v[174:177], v[198:201], v[54:57]
	v_mfma_f32_16x16x32_bf16 v[54:57], v[178:181], v[202:205], v[54:57]
	v_mfma_f32_16x16x32_bf16 v[50:53], v[190:193], v[198:201], v[50:53]
	v_mfma_f32_16x16x32_bf16 v[50:53], v[194:197], v[202:205], v[50:53]
	v_mfma_f32_16x16x32_bf16 v[34:37], v[190:193], v[228:231], v[34:37]
	v_mfma_f32_16x16x32_bf16 v[34:37], v[194:197], v[232:235], v[34:37]
	v_mfma_f32_16x16x32_bf16 v[18:21], v[190:193], v[236:239], v[18:21]
	v_mfma_f32_16x16x32_bf16 v[18:21], v[194:197], v[240:243], v[18:21]
	v_mfma_f32_16x16x32_bf16 v[2:5], v[190:193], v[244:247], v[2:5]
	v_mfma_f32_16x16x32_bf16 v[2:5], v[194:197], v[248:251], v[2:5]
	v_mfma_f32_16x16x32_bf16 v[10:13], v[182:185], v[244:247], v[10:13]
	v_mfma_f32_16x16x32_bf16 v[10:13], v[186:189], v[248:251], v[10:13]
	v_mfma_f32_16x16x32_bf16 v[26:29], v[182:185], v[236:239], v[26:29]
	v_mfma_f32_16x16x32_bf16 v[26:29], v[186:189], v[240:243], v[26:29]
	v_mfma_f32_16x16x32_bf16 v[42:45], v[182:185], v[228:231], v[42:45]
	v_mfma_f32_16x16x32_bf16 v[42:45], v[186:189], v[232:235], v[42:45]
	v_mfma_f32_16x16x32_bf16 v[58:61], v[182:185], v[198:201], v[58:61]
	v_mfma_f32_16x16x32_bf16 v[58:61], v[186:189], v[202:205], v[58:61]
	s_barrier
	s_setprio 0
	s_add_i32 vcc_lo, vcc_lo, 2
	s_addk_i32 s94, 0x100
	s_addk_i32 s95, 0x100
	s_cmp_gt_u32 vcc_lo, 29
	s_cbranch_scc0 .LBB0_304
	s_and_b64 vcc, exec, s[48:49]
	s_cbranch_vccz .LBB0_307
	s_barrier

.LBB0_579:
	s_mul_i32 s73, s72, 0x2c0000
	s_and_b64 s[8:9], s[42:43], exec
	s_mul_i32 s84, s71, 0x2c0000
	s_cselect_b32 s8, s73, s21
	s_cselect_b32 s9, s84, s13
	s_addk_i32 s13, 0x100
	s_add_i32 s21, s21, 0xc000
	s_mov_b32 s22, -2
	s_waitcnt lgkmcnt(0)
	v_add_u32_e32 v154, 0x10000, v140
	ds_read_b128 v[132:135], v154
	ds_read_b128 v[142:145], v154 offset:1024
	ds_read_b128 v[170:173], v154 offset:2048
	ds_read_b128 v[174:177], v154 offset:3072
	v_add_u32_e32 v154, 0x14000, v140
	ds_read_b128 v[178:181], v154
	ds_read_b128 v[182:185], v154 offset:1024
	ds_read_b128 v[186:189], v154 offset:2048
	ds_read_b128 v[190:193], v154 offset:3072
	s_add_i32 s23, s21, 0x4000
	s_cmpk_eq_i32 s22, 0x54
	s_cselect_b32 s27, s8, s23
	s_cselect_b32 s26, s9, s13
	s_or_b32 s23, s27, 0x8000
	s_mov_b32 m0, s68
	ds_read_b128 v[194:197], v141
	ds_read_b128 v[198:201], v141 offset:1024
	ds_read_b128 v[202:205], v141 offset:2048
	ds_read_b128 v[228:231], v141 offset:3072
	ds_read_b128 v[232:235], v141 offset:4096
	ds_read_b128 v[236:239], v141 offset:5120
	ds_read_b128 v[240:243], v141 offset:6144
	ds_read_b128 v[244:247], v141 offset:7168
	buffer_load_dwordx4 v136, s[60:63], s21 offen lds
	s_mov_b32 m0, s70
	s_nop 0
	buffer_load_dwordx4 v138, s[60:63], s21 offen lds
	s_waitcnt vmcnt(8)
	s_waitcnt lgkmcnt(0)
	s_setprio 1
	s_barrier
	v_mfma_f32_16x16x32_bf16 v[126:129], v[132:135], v[194:197], 0
	v_mfma_f32_16x16x32_bf16 v[126:129], v[142:145], v[198:201], v[126:129]
	v_mfma_f32_16x16x32_bf16 v[118:121], v[132:135], v[202:205], 0
	v_mfma_f32_16x16x32_bf16 v[118:121], v[142:145], v[228:231], v[118:121]
	v_mfma_f32_16x16x32_bf16 v[94:97], v[132:135], v[232:235], 0
	v_mfma_f32_16x16x32_bf16 v[94:97], v[142:145], v[236:239], v[94:97]
	v_mfma_f32_16x16x32_bf16 v[78:81], v[132:135], v[240:243], 0
	v_mfma_f32_16x16x32_bf16 v[78:81], v[142:145], v[244:247], v[78:81]
	v_mfma_f32_16x16x32_bf16 v[74:77], v[170:173], v[240:243], 0
	v_mfma_f32_16x16x32_bf16 v[74:77], v[174:177], v[244:247], v[74:77]
	v_mfma_f32_16x16x32_bf16 v[90:93], v[170:173], v[232:235], 0
	v_mfma_f32_16x16x32_bf16 v[90:93], v[174:177], v[236:239], v[90:93]
	v_mfma_f32_16x16x32_bf16 v[114:117], v[170:173], v[202:205], 0
	v_mfma_f32_16x16x32_bf16 v[114:117], v[174:177], v[228:231], v[114:117]
	v_mfma_f32_16x16x32_bf16 v[106:109], v[170:173], v[194:197], 0
	v_mfma_f32_16x16x32_bf16 v[106:109], v[174:177], v[198:201], v[106:109]
	v_mfma_f32_16x16x32_bf16 v[110:113], v[186:189], v[194:197], 0
	v_mfma_f32_16x16x32_bf16 v[110:113], v[190:193], v[198:201], v[110:113]
	v_mfma_f32_16x16x32_bf16 v[98:101], v[186:189], v[202:205], 0
	v_mfma_f32_16x16x32_bf16 v[98:101], v[190:193], v[228:231], v[98:101]
	v_mfma_f32_16x16x32_bf16 v[82:85], v[186:189], v[232:235], 0
	v_mfma_f32_16x16x32_bf16 v[82:85], v[190:193], v[236:239], v[82:85]
	v_mfma_f32_16x16x32_bf16 v[66:69], v[186:189], v[240:243], 0
	v_mfma_f32_16x16x32_bf16 v[66:69], v[190:193], v[244:247], v[66:69]
	v_mfma_f32_16x16x32_bf16 v[70:73], v[178:181], v[240:243], 0
	v_mfma_f32_16x16x32_bf16 v[70:73], v[182:185], v[244:247], v[70:73]
	v_mfma_f32_16x16x32_bf16 v[86:89], v[178:181], v[232:235], 0
	v_mfma_f32_16x16x32_bf16 v[86:89], v[182:185], v[236:239], v[86:89]
	v_mfma_f32_16x16x32_bf16 v[102:105], v[178:181], v[202:205], 0
	v_mfma_f32_16x16x32_bf16 v[102:105], v[182:185], v[228:231], v[102:105]
	v_mfma_f32_16x16x32_bf16 v[122:125], v[178:181], v[194:197], 0
	v_mfma_f32_16x16x32_bf16 v[122:125], v[182:185], v[198:201], v[122:125]
	s_barrier
	s_setprio 0
	s_mov_b32 s46, s62
	s_mov_b32 s47, s63
	s_mov_b32 m0, s15
	ds_read_b128 v[194:197], v141 offset:16384
	buffer_load_dwordx4 v137, s[44:47], s26 offen lds
	s_add_i32 s52, s26, 0x160000
	s_mov_b32 m0, s16
	ds_read_b128 v[198:201], v141 offset:17408
	buffer_load_dwordx4 v139, s[44:47], s26 offen lds
	s_mov_b32 m0, s18
	ds_read_b128 v[202:205], v141 offset:18432
	buffer_load_dwordx4 v137, s[44:47], s52 offen lds
	s_mov_b32 m0, s19
	ds_read_b128 v[228:231], v141 offset:19456
	buffer_load_dwordx4 v139, s[44:47], s52 offen lds
	s_mov_b32 m0, s14
	ds_read_b128 v[232:235], v141 offset:20480
	buffer_load_dwordx4 v136, s[60:63], s27 offen lds
	s_mov_b32 m0, s24
	ds_read_b128 v[236:239], v141 offset:21504
	buffer_load_dwordx4 v138, s[60:63], s27 offen lds
	ds_read_b128 v[240:243], v141 offset:22528
	ds_read_b128 v[244:247], v141 offset:23552
	s_waitcnt vmcnt(8)
	s_waitcnt lgkmcnt(0)
	s_setprio 1
	s_barrier
	v_mfma_f32_16x16x32_bf16 v[62:65], v[132:135], v[194:197], 0
	v_mfma_f32_16x16x32_bf16 v[62:65], v[142:145], v[198:201], v[62:65]
	v_mfma_f32_16x16x32_bf16 v[46:49], v[132:135], v[202:205], 0
	v_mfma_f32_16x16x32_bf16 v[46:49], v[142:145], v[228:231], v[46:49]
	v_mfma_f32_16x16x32_bf16 v[30:33], v[132:135], v[232:235], 0
	v_mfma_f32_16x16x32_bf16 v[30:33], v[142:145], v[236:239], v[30:33]
	v_mfma_f32_16x16x32_bf16 v[14:17], v[132:135], v[240:243], 0
	v_mfma_f32_16x16x32_bf16 v[14:17], v[142:145], v[244:247], v[14:17]
	v_mfma_f32_16x16x32_bf16 v[10:13], v[170:173], v[240:243], 0
	v_mfma_f32_16x16x32_bf16 v[10:13], v[174:177], v[244:247], v[10:13]
	v_mfma_f32_16x16x32_bf16 v[26:29], v[170:173], v[232:235], 0
	v_mfma_f32_16x16x32_bf16 v[26:29], v[174:177], v[236:239], v[26:29]
	v_mfma_f32_16x16x32_bf16 v[42:45], v[170:173], v[202:205], 0
	v_mfma_f32_16x16x32_bf16 v[42:45], v[174:177], v[228:231], v[42:45]
	v_mfma_f32_16x16x32_bf16 v[58:61], v[170:173], v[194:197], 0
	v_mfma_f32_16x16x32_bf16 v[58:61], v[174:177], v[198:201], v[58:61]
	v_mfma_f32_16x16x32_bf16 v[50:53], v[186:189], v[194:197], 0
	v_mfma_f32_16x16x32_bf16 v[50:53], v[190:193], v[198:201], v[50:53]
	v_mfma_f32_16x16x32_bf16 v[34:37], v[186:189], v[202:205], 0
	v_mfma_f32_16x16x32_bf16 v[34:37], v[190:193], v[228:231], v[34:37]
	v_mfma_f32_16x16x32_bf16 v[18:21], v[186:189], v[232:235], 0
	v_mfma_f32_16x16x32_bf16 v[18:21], v[190:193], v[236:239], v[18:21]
	v_mfma_f32_16x16x32_bf16 v[2:5], v[186:189], v[240:243], 0
	v_mfma_f32_16x16x32_bf16 v[2:5], v[190:193], v[244:247], v[2:5]
	v_mfma_f32_16x16x32_bf16 v[6:9], v[178:181], v[240:243], 0
	v_mfma_f32_16x16x32_bf16 v[6:9], v[182:185], v[244:247], v[6:9]
	v_mfma_f32_16x16x32_bf16 v[22:25], v[178:181], v[232:235], 0
	v_mfma_f32_16x16x32_bf16 v[22:25], v[182:185], v[236:239], v[22:25]
	v_mfma_f32_16x16x32_bf16 v[38:41], v[178:181], v[202:205], 0
	v_mfma_f32_16x16x32_bf16 v[38:41], v[182:185], v[228:231], v[38:41]
	v_mfma_f32_16x16x32_bf16 v[54:57], v[178:181], v[194:197], 0
	v_mfma_f32_16x16x32_bf16 v[54:57], v[182:185], v[198:201], v[54:57]
	s_barrier
	s_setprio 0
	v_add_u32_e32 v154, 0x18000, v140
	ds_read_b128 v[132:135], v154
	ds_read_b128 v[142:145], v154 offset:1024
	ds_read_b128 v[170:173], v154 offset:2048
	ds_read_b128 v[174:177], v154 offset:3072
	v_add_u32_e32 v154, 0x1c000, v140
	ds_read_b128 v[178:181], v154
	ds_read_b128 v[182:185], v154 offset:1024
	ds_read_b128 v[186:189], v154 offset:2048
	ds_read_b128 v[190:193], v154 offset:3072
	s_bitset1_b32 s27, 14
	s_mov_b32 m0, s25
	ds_read_b128 v[194:197], v141 offset:32768
	ds_read_b128 v[198:201], v141 offset:33792
	ds_read_b128 v[202:205], v141 offset:34816
	ds_read_b128 v[228:231], v141 offset:35840
	ds_read_b128 v[232:235], v141 offset:36864
	ds_read_b128 v[236:239], v141 offset:37888
	ds_read_b128 v[240:243], v141 offset:38912
	ds_read_b128 v[244:247], v141 offset:39936
	buffer_load_dwordx4 v136, s[60:63], s27 offen lds
	s_mov_b32 m0, s30
	s_nop 0
	buffer_load_dwordx4 v138, s[60:63], s27 offen lds
	s_waitcnt vmcnt(8)
	s_waitcnt lgkmcnt(0)
	s_setprio 1
	s_barrier
	v_mfma_f32_16x16x32_bf16 v[126:129], v[132:135], v[194:197], v[126:129]
	v_mfma_f32_16x16x32_bf16 v[126:129], v[142:145], v[198:201], v[126:129]
	v_mfma_f32_16x16x32_bf16 v[118:121], v[132:135], v[202:205], v[118:121]
	v_mfma_f32_16x16x32_bf16 v[118:121], v[142:145], v[228:231], v[118:121]
	v_mfma_f32_16x16x32_bf16 v[94:97], v[132:135], v[232:235], v[94:97]
	v_mfma_f32_16x16x32_bf16 v[94:97], v[142:145], v[236:239], v[94:97]
	v_mfma_f32_16x16x32_bf16 v[78:81], v[132:135], v[240:243], v[78:81]
	v_mfma_f32_16x16x32_bf16 v[78:81], v[142:145], v[244:247], v[78:81]
	v_mfma_f32_16x16x32_bf16 v[74:77], v[170:173], v[240:243], v[74:77]
	v_mfma_f32_16x16x32_bf16 v[74:77], v[174:177], v[244:247], v[74:77]
	v_mfma_f32_16x16x32_bf16 v[90:93], v[170:173], v[232:235], v[90:93]
	v_mfma_f32_16x16x32_bf16 v[90:93], v[174:177], v[236:239], v[90:93]
	v_mfma_f32_16x16x32_bf16 v[114:117], v[170:173], v[202:205], v[114:117]
	v_mfma_f32_16x16x32_bf16 v[114:117], v[174:177], v[228:231], v[114:117]
	v_mfma_f32_16x16x32_bf16 v[106:109], v[170:173], v[194:197], v[106:109]
	v_mfma_f32_16x16x32_bf16 v[106:109], v[174:177], v[198:201], v[106:109]
	v_mfma_f32_16x16x32_bf16 v[110:113], v[186:189], v[194:197], v[110:113]
	v_mfma_f32_16x16x32_bf16 v[110:113], v[190:193], v[198:201], v[110:113]
	v_mfma_f32_16x16x32_bf16 v[98:101], v[186:189], v[202:205], v[98:101]
	v_mfma_f32_16x16x32_bf16 v[98:101], v[190:193], v[228:231], v[98:101]
	v_mfma_f32_16x16x32_bf16 v[82:85], v[186:189], v[232:235], v[82:85]
	v_mfma_f32_16x16x32_bf16 v[82:85], v[190:193], v[236:239], v[82:85]
	v_mfma_f32_16x16x32_bf16 v[66:69], v[186:189], v[240:243], v[66:69]
	v_mfma_f32_16x16x32_bf16 v[66:69], v[190:193], v[244:247], v[66:69]
	v_mfma_f32_16x16x32_bf16 v[70:73], v[178:181], v[240:243], v[70:73]
	v_mfma_f32_16x16x32_bf16 v[70:73], v[182:185], v[244:247], v[70:73]
	v_mfma_f32_16x16x32_bf16 v[86:89], v[178:181], v[232:235], v[86:89]
	v_mfma_f32_16x16x32_bf16 v[86:89], v[182:185], v[236:239], v[86:89]
	v_mfma_f32_16x16x32_bf16 v[102:105], v[178:181], v[202:205], v[102:105]
	v_mfma_f32_16x16x32_bf16 v[102:105], v[182:185], v[228:231], v[102:105]
	v_mfma_f32_16x16x32_bf16 v[122:125], v[178:181], v[194:197], v[122:125]
	v_mfma_f32_16x16x32_bf16 v[122:125], v[182:185], v[198:201], v[122:125]
	s_barrier
	s_setprio 0
	s_or_b32 s27, s26, 0x80
	s_mov_b32 m0, s36
	ds_read_b128 v[194:197], v141 offset:49152
	buffer_load_dwordx4 v137, s[44:47], s27 offen lds
	s_add_i32 s26, s26, 0x160080
	s_mov_b32 m0, s37
	ds_read_b128 v[198:201], v141 offset:50176
	buffer_load_dwordx4 v139, s[44:47], s27 offen lds
	s_mov_b32 m0, s66
	ds_read_b128 v[202:205], v141 offset:51200
	buffer_load_dwordx4 v137, s[44:47], s26 offen lds
	s_mov_b32 m0, s67
	ds_read_b128 v[228:231], v141 offset:52224
	buffer_load_dwordx4 v139, s[44:47], s26 offen lds
	s_mov_b32 m0, s48
	ds_read_b128 v[232:235], v141 offset:53248
	buffer_load_dwordx4 v136, s[60:63], s23 offen lds
	s_mov_b32 m0, s49
	ds_read_b128 v[236:239], v141 offset:54272
	buffer_load_dwordx4 v138, s[60:63], s23 offen lds
	ds_read_b128 v[240:243], v141 offset:55296
	ds_read_b128 v[244:247], v141 offset:56320
	s_waitcnt vmcnt(8)
	s_waitcnt lgkmcnt(0)
	s_setprio 1
	s_barrier
	v_mfma_f32_16x16x32_bf16 v[62:65], v[132:135], v[194:197], v[62:65]
	v_mfma_f32_16x16x32_bf16 v[62:65], v[142:145], v[198:201], v[62:65]
	v_mfma_f32_16x16x32_bf16 v[46:49], v[132:135], v[202:205], v[46:49]
	v_mfma_f32_16x16x32_bf16 v[46:49], v[142:145], v[228:231], v[46:49]
	v_mfma_f32_16x16x32_bf16 v[30:33], v[132:135], v[232:235], v[30:33]
	v_mfma_f32_16x16x32_bf16 v[30:33], v[142:145], v[236:239], v[30:33]
	v_mfma_f32_16x16x32_bf16 v[14:17], v[132:135], v[240:243], v[14:17]
	v_mfma_f32_16x16x32_bf16 v[14:17], v[142:145], v[244:247], v[14:17]
	v_mfma_f32_16x16x32_bf16 v[10:13], v[170:173], v[240:243], v[10:13]
	v_mfma_f32_16x16x32_bf16 v[10:13], v[174:177], v[244:247], v[10:13]
	v_mfma_f32_16x16x32_bf16 v[26:29], v[170:173], v[232:235], v[26:29]
	v_mfma_f32_16x16x32_bf16 v[26:29], v[174:177], v[236:239], v[26:29]
	v_mfma_f32_16x16x32_bf16 v[42:45], v[170:173], v[202:205], v[42:45]
	v_mfma_f32_16x16x32_bf16 v[42:45], v[174:177], v[228:231], v[42:45]
	v_mfma_f32_16x16x32_bf16 v[58:61], v[170:173], v[194:197], v[58:61]
	v_mfma_f32_16x16x32_bf16 v[58:61], v[174:177], v[198:201], v[58:61]
	v_mfma_f32_16x16x32_bf16 v[50:53], v[186:189], v[194:197], v[50:53]
	v_mfma_f32_16x16x32_bf16 v[50:53], v[190:193], v[198:201], v[50:53]
	v_mfma_f32_16x16x32_bf16 v[34:37], v[186:189], v[202:205], v[34:37]
	v_mfma_f32_16x16x32_bf16 v[34:37], v[190:193], v[228:231], v[34:37]
	v_mfma_f32_16x16x32_bf16 v[18:21], v[186:189], v[232:235], v[18:21]
	v_mfma_f32_16x16x32_bf16 v[18:21], v[190:193], v[236:239], v[18:21]
	v_mfma_f32_16x16x32_bf16 v[2:5], v[186:189], v[240:243], v[2:5]
	v_mfma_f32_16x16x32_bf16 v[2:5], v[190:193], v[244:247], v[2:5]
	v_mfma_f32_16x16x32_bf16 v[6:9], v[178:181], v[240:243], v[6:9]
	v_mfma_f32_16x16x32_bf16 v[6:9], v[182:185], v[244:247], v[6:9]
	v_mfma_f32_16x16x32_bf16 v[22:25], v[178:181], v[232:235], v[22:25]
	v_mfma_f32_16x16x32_bf16 v[22:25], v[182:185], v[236:239], v[22:25]
	v_mfma_f32_16x16x32_bf16 v[38:41], v[178:181], v[202:205], v[38:41]
	v_mfma_f32_16x16x32_bf16 v[38:41], v[182:185], v[228:231], v[38:41]
	v_mfma_f32_16x16x32_bf16 v[54:57], v[178:181], v[194:197], v[54:57]
	v_mfma_f32_16x16x32_bf16 v[54:57], v[182:185], v[198:201], v[54:57]
	s_barrier
	s_setprio 0
	s_addk_i32 s13, 0x100
	s_add_i32 s22, s22, 2
	s_add_i32 s21, s21, 0x10000
	s_cmpk_gt_u32 s22, 0x55
.LBB0_580:
	v_add_u32_e32 v154, 0x10000, v140
	ds_read_b128 v[132:135], v154
	ds_read_b128 v[142:145], v154 offset:1024
	ds_read_b128 v[170:173], v154 offset:2048
	ds_read_b128 v[174:177], v154 offset:3072
	v_add_u32_e32 v154, 0x14000, v140
	ds_read_b128 v[178:181], v154
	ds_read_b128 v[182:185], v154 offset:1024
	ds_read_b128 v[186:189], v154 offset:2048
	ds_read_b128 v[190:193], v154 offset:3072
	s_add_i32 s23, s21, 0x4000
	s_cmpk_eq_i32 s22, 0x54
	s_cselect_b32 s27, s8, s23
	s_cselect_b32 s26, s9, s13
	s_or_b32 s23, s27, 0x8000
	s_mov_b32 m0, s68
	ds_read_b128 v[194:197], v141
	ds_read_b128 v[198:201], v141 offset:1024
	ds_read_b128 v[202:205], v141 offset:2048
	ds_read_b128 v[228:231], v141 offset:3072
	ds_read_b128 v[232:235], v141 offset:4096
	ds_read_b128 v[236:239], v141 offset:5120
	ds_read_b128 v[240:243], v141 offset:6144
	ds_read_b128 v[244:247], v141 offset:7168
	buffer_load_dwordx4 v136, s[60:63], s21 offen lds
	s_mov_b32 m0, s70
	s_nop 0
	buffer_load_dwordx4 v138, s[60:63], s21 offen lds
	s_waitcnt vmcnt(8)
	s_waitcnt lgkmcnt(0)
	s_setprio 1
	s_barrier
	v_mfma_f32_16x16x32_bf16 v[126:129], v[132:135], v[194:197], v[126:129]
	v_mfma_f32_16x16x32_bf16 v[126:129], v[142:145], v[198:201], v[126:129]
	v_mfma_f32_16x16x32_bf16 v[118:121], v[132:135], v[202:205], v[118:121]
	v_mfma_f32_16x16x32_bf16 v[118:121], v[142:145], v[228:231], v[118:121]
	v_mfma_f32_16x16x32_bf16 v[94:97], v[132:135], v[232:235], v[94:97]
	v_mfma_f32_16x16x32_bf16 v[94:97], v[142:145], v[236:239], v[94:97]
	v_mfma_f32_16x16x32_bf16 v[78:81], v[132:135], v[240:243], v[78:81]
	v_mfma_f32_16x16x32_bf16 v[78:81], v[142:145], v[244:247], v[78:81]
	v_mfma_f32_16x16x32_bf16 v[74:77], v[170:173], v[240:243], v[74:77]
	v_mfma_f32_16x16x32_bf16 v[74:77], v[174:177], v[244:247], v[74:77]
	v_mfma_f32_16x16x32_bf16 v[90:93], v[170:173], v[232:235], v[90:93]
	v_mfma_f32_16x16x32_bf16 v[90:93], v[174:177], v[236:239], v[90:93]
	v_mfma_f32_16x16x32_bf16 v[114:117], v[170:173], v[202:205], v[114:117]
	v_mfma_f32_16x16x32_bf16 v[114:117], v[174:177], v[228:231], v[114:117]
	v_mfma_f32_16x16x32_bf16 v[106:109], v[170:173], v[194:197], v[106:109]
	v_mfma_f32_16x16x32_bf16 v[106:109], v[174:177], v[198:201], v[106:109]
	v_mfma_f32_16x16x32_bf16 v[110:113], v[186:189], v[194:197], v[110:113]
	v_mfma_f32_16x16x32_bf16 v[110:113], v[190:193], v[198:201], v[110:113]
	v_mfma_f32_16x16x32_bf16 v[98:101], v[186:189], v[202:205], v[98:101]
	v_mfma_f32_16x16x32_bf16 v[98:101], v[190:193], v[228:231], v[98:101]
	v_mfma_f32_16x16x32_bf16 v[82:85], v[186:189], v[232:235], v[82:85]
	v_mfma_f32_16x16x32_bf16 v[82:85], v[190:193], v[236:239], v[82:85]
	v_mfma_f32_16x16x32_bf16 v[66:69], v[186:189], v[240:243], v[66:69]
	v_mfma_f32_16x16x32_bf16 v[66:69], v[190:193], v[244:247], v[66:69]
	v_mfma_f32_16x16x32_bf16 v[70:73], v[178:181], v[240:243], v[70:73]
	v_mfma_f32_16x16x32_bf16 v[70:73], v[182:185], v[244:247], v[70:73]
	v_mfma_f32_16x16x32_bf16 v[86:89], v[178:181], v[232:235], v[86:89]
	v_mfma_f32_16x16x32_bf16 v[86:89], v[182:185], v[236:239], v[86:89]
	v_mfma_f32_16x16x32_bf16 v[102:105], v[178:181], v[202:205], v[102:105]
	v_mfma_f32_16x16x32_bf16 v[102:105], v[182:185], v[228:231], v[102:105]
	v_mfma_f32_16x16x32_bf16 v[122:125], v[178:181], v[194:197], v[122:125]
	v_mfma_f32_16x16x32_bf16 v[122:125], v[182:185], v[198:201], v[122:125]
	s_barrier
	s_setprio 0
	s_mov_b32 s46, s62
	s_mov_b32 s47, s63
	s_mov_b32 m0, s15
	ds_read_b128 v[194:197], v141 offset:16384
	buffer_load_dwordx4 v137, s[44:47], s26 offen lds
	s_add_i32 s52, s26, 0x160000
	s_mov_b32 m0, s16
	ds_read_b128 v[198:201], v141 offset:17408
	buffer_load_dwordx4 v139, s[44:47], s26 offen lds
	s_mov_b32 m0, s18
	ds_read_b128 v[202:205], v141 offset:18432
	buffer_load_dwordx4 v137, s[44:47], s52 offen lds
	s_mov_b32 m0, s19
	ds_read_b128 v[228:231], v141 offset:19456
	buffer_load_dwordx4 v139, s[44:47], s52 offen lds
	s_mov_b32 m0, s14
	ds_read_b128 v[232:235], v141 offset:20480
	buffer_load_dwordx4 v136, s[60:63], s27 offen lds
	s_mov_b32 m0, s24
	ds_read_b128 v[236:239], v141 offset:21504
	buffer_load_dwordx4 v138, s[60:63], s27 offen lds
	ds_read_b128 v[240:243], v141 offset:22528
	ds_read_b128 v[244:247], v141 offset:23552
	s_waitcnt vmcnt(8)
	s_waitcnt lgkmcnt(0)
	s_setprio 1
	s_barrier
	v_mfma_f32_16x16x32_bf16 v[62:65], v[132:135], v[194:197], v[62:65]
	v_mfma_f32_16x16x32_bf16 v[62:65], v[142:145], v[198:201], v[62:65]
	v_mfma_f32_16x16x32_bf16 v[46:49], v[132:135], v[202:205], v[46:49]
	v_mfma_f32_16x16x32_bf16 v[46:49], v[142:145], v[228:231], v[46:49]
	v_mfma_f32_16x16x32_bf16 v[30:33], v[132:135], v[232:235], v[30:33]
	v_mfma_f32_16x16x32_bf16 v[30:33], v[142:145], v[236:239], v[30:33]
	v_mfma_f32_16x16x32_bf16 v[14:17], v[132:135], v[240:243], v[14:17]
	v_mfma_f32_16x16x32_bf16 v[14:17], v[142:145], v[244:247], v[14:17]
	v_mfma_f32_16x16x32_bf16 v[10:13], v[170:173], v[240:243], v[10:13]
	v_mfma_f32_16x16x32_bf16 v[10:13], v[174:177], v[244:247], v[10:13]
	v_mfma_f32_16x16x32_bf16 v[26:29], v[170:173], v[232:235], v[26:29]
	v_mfma_f32_16x16x32_bf16 v[26:29], v[174:177], v[236:239], v[26:29]
	v_mfma_f32_16x16x32_bf16 v[42:45], v[170:173], v[202:205], v[42:45]
	v_mfma_f32_16x16x32_bf16 v[42:45], v[174:177], v[228:231], v[42:45]
	v_mfma_f32_16x16x32_bf16 v[58:61], v[170:173], v[194:197], v[58:61]
	v_mfma_f32_16x16x32_bf16 v[58:61], v[174:177], v[198:201], v[58:61]
	v_mfma_f32_16x16x32_bf16 v[50:53], v[186:189], v[194:197], v[50:53]
	v_mfma_f32_16x16x32_bf16 v[50:53], v[190:193], v[198:201], v[50:53]
	v_mfma_f32_16x16x32_bf16 v[34:37], v[186:189], v[202:205], v[34:37]
	v_mfma_f32_16x16x32_bf16 v[34:37], v[190:193], v[228:231], v[34:37]
	v_mfma_f32_16x16x32_bf16 v[18:21], v[186:189], v[232:235], v[18:21]
	v_mfma_f32_16x16x32_bf16 v[18:21], v[190:193], v[236:239], v[18:21]
	v_mfma_f32_16x16x32_bf16 v[2:5], v[186:189], v[240:243], v[2:5]
	v_mfma_f32_16x16x32_bf16 v[2:5], v[190:193], v[244:247], v[2:5]
	v_mfma_f32_16x16x32_bf16 v[6:9], v[178:181], v[240:243], v[6:9]
	v_mfma_f32_16x16x32_bf16 v[6:9], v[182:185], v[244:247], v[6:9]
	v_mfma_f32_16x16x32_bf16 v[22:25], v[178:181], v[232:235], v[22:25]
	v_mfma_f32_16x16x32_bf16 v[22:25], v[182:185], v[236:239], v[22:25]
	v_mfma_f32_16x16x32_bf16 v[38:41], v[178:181], v[202:205], v[38:41]
	v_mfma_f32_16x16x32_bf16 v[38:41], v[182:185], v[228:231], v[38:41]
	v_mfma_f32_16x16x32_bf16 v[54:57], v[178:181], v[194:197], v[54:57]
	v_mfma_f32_16x16x32_bf16 v[54:57], v[182:185], v[198:201], v[54:57]
	s_barrier
	s_setprio 0
	v_add_u32_e32 v154, 0x18000, v140
	ds_read_b128 v[132:135], v154
	ds_read_b128 v[142:145], v154 offset:1024
	ds_read_b128 v[170:173], v154 offset:2048
	ds_read_b128 v[174:177], v154 offset:3072
	v_add_u32_e32 v154, 0x1c000, v140
	ds_read_b128 v[178:181], v154
	ds_read_b128 v[182:185], v154 offset:1024
	ds_read_b128 v[186:189], v154 offset:2048
	ds_read_b128 v[190:193], v154 offset:3072
	s_bitset1_b32 s27, 14
	s_mov_b32 m0, s25
	ds_read_b128 v[194:197], v141 offset:32768
	ds_read_b128 v[198:201], v141 offset:33792
	ds_read_b128 v[202:205], v141 offset:34816
	ds_read_b128 v[228:231], v141 offset:35840
	ds_read_b128 v[232:235], v141 offset:36864
	ds_read_b128 v[236:239], v141 offset:37888
	ds_read_b128 v[240:243], v141 offset:38912
	ds_read_b128 v[244:247], v141 offset:39936
	buffer_load_dwordx4 v136, s[60:63], s27 offen lds
	s_mov_b32 m0, s30
	s_nop 0
	buffer_load_dwordx4 v138, s[60:63], s27 offen lds
	s_waitcnt vmcnt(8)
	s_waitcnt lgkmcnt(0)
	s_setprio 1
	s_barrier
	v_mfma_f32_16x16x32_bf16 v[126:129], v[132:135], v[194:197], v[126:129]
	v_mfma_f32_16x16x32_bf16 v[126:129], v[142:145], v[198:201], v[126:129]
	v_mfma_f32_16x16x32_bf16 v[118:121], v[132:135], v[202:205], v[118:121]
	v_mfma_f32_16x16x32_bf16 v[118:121], v[142:145], v[228:231], v[118:121]
	v_mfma_f32_16x16x32_bf16 v[94:97], v[132:135], v[232:235], v[94:97]
	v_mfma_f32_16x16x32_bf16 v[94:97], v[142:145], v[236:239], v[94:97]
	v_mfma_f32_16x16x32_bf16 v[78:81], v[132:135], v[240:243], v[78:81]
	v_mfma_f32_16x16x32_bf16 v[78:81], v[142:145], v[244:247], v[78:81]
	v_mfma_f32_16x16x32_bf16 v[74:77], v[170:173], v[240:243], v[74:77]
	v_mfma_f32_16x16x32_bf16 v[74:77], v[174:177], v[244:247], v[74:77]
	v_mfma_f32_16x16x32_bf16 v[90:93], v[170:173], v[232:235], v[90:93]
	v_mfma_f32_16x16x32_bf16 v[90:93], v[174:177], v[236:239], v[90:93]
	v_mfma_f32_16x16x32_bf16 v[114:117], v[170:173], v[202:205], v[114:117]
	v_mfma_f32_16x16x32_bf16 v[114:117], v[174:177], v[228:231], v[114:117]
	v_mfma_f32_16x16x32_bf16 v[106:109], v[170:173], v[194:197], v[106:109]
	v_mfma_f32_16x16x32_bf16 v[106:109], v[174:177], v[198:201], v[106:109]
	v_mfma_f32_16x16x32_bf16 v[110:113], v[186:189], v[194:197], v[110:113]
	v_mfma_f32_16x16x32_bf16 v[110:113], v[190:193], v[198:201], v[110:113]
	v_mfma_f32_16x16x32_bf16 v[98:101], v[186:189], v[202:205], v[98:101]
	v_mfma_f32_16x16x32_bf16 v[98:101], v[190:193], v[228:231], v[98:101]
	v_mfma_f32_16x16x32_bf16 v[82:85], v[186:189], v[232:235], v[82:85]
	v_mfma_f32_16x16x32_bf16 v[82:85], v[190:193], v[236:239], v[82:85]
	v_mfma_f32_16x16x32_bf16 v[66:69], v[186:189], v[240:243], v[66:69]
	v_mfma_f32_16x16x32_bf16 v[66:69], v[190:193], v[244:247], v[66:69]
	v_mfma_f32_16x16x32_bf16 v[70:73], v[178:181], v[240:243], v[70:73]
	v_mfma_f32_16x16x32_bf16 v[70:73], v[182:185], v[244:247], v[70:73]
	v_mfma_f32_16x16x32_bf16 v[86:89], v[178:181], v[232:235], v[86:89]
	v_mfma_f32_16x16x32_bf16 v[86:89], v[182:185], v[236:239], v[86:89]
	v_mfma_f32_16x16x32_bf16 v[102:105], v[178:181], v[202:205], v[102:105]
	v_mfma_f32_16x16x32_bf16 v[102:105], v[182:185], v[228:231], v[102:105]
	v_mfma_f32_16x16x32_bf16 v[122:125], v[178:181], v[194:197], v[122:125]
	v_mfma_f32_16x16x32_bf16 v[122:125], v[182:185], v[198:201], v[122:125]
	s_barrier
	s_setprio 0
	s_or_b32 s27, s26, 0x80
	s_mov_b32 m0, s36
	ds_read_b128 v[194:197], v141 offset:49152
	buffer_load_dwordx4 v137, s[44:47], s27 offen lds
	s_add_i32 s26, s26, 0x160080
	s_mov_b32 m0, s37
	ds_read_b128 v[198:201], v141 offset:50176
	buffer_load_dwordx4 v139, s[44:47], s27 offen lds
	s_mov_b32 m0, s66
	ds_read_b128 v[202:205], v141 offset:51200
	buffer_load_dwordx4 v137, s[44:47], s26 offen lds
	s_mov_b32 m0, s67
	ds_read_b128 v[228:231], v141 offset:52224
	buffer_load_dwordx4 v139, s[44:47], s26 offen lds
	s_mov_b32 m0, s48
	ds_read_b128 v[232:235], v141 offset:53248
	buffer_load_dwordx4 v136, s[60:63], s23 offen lds
	s_mov_b32 m0, s49
	ds_read_b128 v[236:239], v141 offset:54272
	buffer_load_dwordx4 v138, s[60:63], s23 offen lds
	ds_read_b128 v[240:243], v141 offset:55296
	ds_read_b128 v[244:247], v141 offset:56320
	s_waitcnt vmcnt(8)
	s_waitcnt lgkmcnt(0)
	s_setprio 1
	s_barrier
	v_mfma_f32_16x16x32_bf16 v[62:65], v[132:135], v[194:197], v[62:65]
	v_mfma_f32_16x16x32_bf16 v[62:65], v[142:145], v[198:201], v[62:65]
	v_mfma_f32_16x16x32_bf16 v[46:49], v[132:135], v[202:205], v[46:49]
	v_mfma_f32_16x16x32_bf16 v[46:49], v[142:145], v[228:231], v[46:49]
	v_mfma_f32_16x16x32_bf16 v[30:33], v[132:135], v[232:235], v[30:33]
	v_mfma_f32_16x16x32_bf16 v[30:33], v[142:145], v[236:239], v[30:33]
	v_mfma_f32_16x16x32_bf16 v[14:17], v[132:135], v[240:243], v[14:17]
	v_mfma_f32_16x16x32_bf16 v[14:17], v[142:145], v[244:247], v[14:17]
	v_mfma_f32_16x16x32_bf16 v[10:13], v[170:173], v[240:243], v[10:13]
	v_mfma_f32_16x16x32_bf16 v[10:13], v[174:177], v[244:247], v[10:13]
	v_mfma_f32_16x16x32_bf16 v[26:29], v[170:173], v[232:235], v[26:29]
	v_mfma_f32_16x16x32_bf16 v[26:29], v[174:177], v[236:239], v[26:29]
	v_mfma_f32_16x16x32_bf16 v[42:45], v[170:173], v[202:205], v[42:45]
	v_mfma_f32_16x16x32_bf16 v[42:45], v[174:177], v[228:231], v[42:45]
	v_mfma_f32_16x16x32_bf16 v[58:61], v[170:173], v[194:197], v[58:61]
	v_mfma_f32_16x16x32_bf16 v[58:61], v[174:177], v[198:201], v[58:61]
	v_mfma_f32_16x16x32_bf16 v[50:53], v[186:189], v[194:197], v[50:53]
	v_mfma_f32_16x16x32_bf16 v[50:53], v[190:193], v[198:201], v[50:53]
	v_mfma_f32_16x16x32_bf16 v[34:37], v[186:189], v[202:205], v[34:37]
	v_mfma_f32_16x16x32_bf16 v[34:37], v[190:193], v[228:231], v[34:37]
	v_mfma_f32_16x16x32_bf16 v[18:21], v[186:189], v[232:235], v[18:21]
	v_mfma_f32_16x16x32_bf16 v[18:21], v[190:193], v[236:239], v[18:21]
	v_mfma_f32_16x16x32_bf16 v[2:5], v[186:189], v[240:243], v[2:5]
	v_mfma_f32_16x16x32_bf16 v[2:5], v[190:193], v[244:247], v[2:5]
	v_mfma_f32_16x16x32_bf16 v[6:9], v[178:181], v[240:243], v[6:9]
	v_mfma_f32_16x16x32_bf16 v[6:9], v[182:185], v[244:247], v[6:9]
	v_mfma_f32_16x16x32_bf16 v[22:25], v[178:181], v[232:235], v[22:25]
	v_mfma_f32_16x16x32_bf16 v[22:25], v[182:185], v[236:239], v[22:25]
	v_mfma_f32_16x16x32_bf16 v[38:41], v[178:181], v[202:205], v[38:41]
	v_mfma_f32_16x16x32_bf16 v[38:41], v[182:185], v[228:231], v[38:41]
	v_mfma_f32_16x16x32_bf16 v[54:57], v[178:181], v[194:197], v[54:57]
	v_mfma_f32_16x16x32_bf16 v[54:57], v[182:185], v[198:201], v[54:57]
	s_barrier
	s_setprio 0
	s_addk_i32 s13, 0x100
	s_add_i32 s22, s22, 2
	s_add_i32 s21, s21, 0x10000
	s_cmpk_gt_u32 s22, 0x55
	s_cbranch_scc0 .LBB0_580
	s_and_b64 vcc, exec, s[64:65]
	s_cbranch_vccz .LBB0_583
	s_barrier

.LBB0_858:
	s_lshl_b32 s2, s21, 20
	s_and_b64 s[8:9], s[42:43], exec
	s_cselect_b32 s8, s2, s18
	s_lshl_b32 s82, s71, 20
	s_and_b64 s[26:27], s[42:43], exec
	s_cselect_b32 s9, s82, s19
	s_add_i32 s18, s18, 0x80080
	s_addk_i32 s19, 0x100
	s_mov_b32 s22, -2
	v_add_u32_e32 v146, 0x10000, v195
	ds_read_b128 v[130:133], v146
	ds_read_b128 v[138:141], v146 offset:1024
	ds_read_b128 v[142:145], v146 offset:2048
	ds_read_b128 v[154:157], v146 offset:3072
	v_add_u32_e32 v146, 0x14000, v195
	ds_read_b128 v[170:173], v146
	ds_read_b128 v[174:177], v146 offset:1024
	ds_read_b128 v[178:181], v146 offset:2048
	ds_read_b128 v[182:185], v146 offset:3072
	s_add_i32 s26, s18, 0xfff80080
	s_cmp_eq_u32 s22, 28
	s_cselect_b32 s52, s8, s26
	s_cselect_b32 s27, s9, s19
	s_or_b32 s26, s52, 0x80
	s_mov_b32 m0, s85
	ds_read_b128 v[186:189], v196
	ds_read_b128 v[198:201], v196 offset:1024
	ds_read_b128 v[202:205], v196 offset:2048
	ds_read_b128 v[228:231], v196 offset:3072
	ds_read_b128 v[232:235], v196 offset:4096
	ds_read_b128 v[236:239], v196 offset:5120
	ds_read_b128 v[240:243], v196 offset:6144
	ds_read_b128 v[244:247], v196 offset:7168
	buffer_load_dwordx4 v135, s[44:47], s18 offen lds
	s_mov_b32 m0, s15
	s_nop 0
	buffer_load_dwordx4 v193, s[44:47], s18 offen lds
	s_waitcnt vmcnt(8)
	s_waitcnt lgkmcnt(0)
	s_setprio 1
	s_barrier
	v_mfma_f32_16x16x32_bf16 v[126:129], v[130:133], v[186:189], 0
	v_mfma_f32_16x16x32_bf16 v[126:129], v[138:141], v[198:201], v[126:129]
	v_mfma_f32_16x16x32_bf16 v[110:113], v[130:133], v[202:205], 0
	v_mfma_f32_16x16x32_bf16 v[110:113], v[138:141], v[228:231], v[110:113]
	v_mfma_f32_16x16x32_bf16 v[94:97], v[130:133], v[232:235], 0
	v_mfma_f32_16x16x32_bf16 v[94:97], v[138:141], v[236:239], v[94:97]
	v_mfma_f32_16x16x32_bf16 v[78:81], v[130:133], v[240:243], 0
	v_mfma_f32_16x16x32_bf16 v[78:81], v[138:141], v[244:247], v[78:81]
	v_mfma_f32_16x16x32_bf16 v[74:77], v[142:145], v[240:243], 0
	v_mfma_f32_16x16x32_bf16 v[74:77], v[154:157], v[244:247], v[74:77]
	v_mfma_f32_16x16x32_bf16 v[90:93], v[142:145], v[232:235], 0
	v_mfma_f32_16x16x32_bf16 v[90:93], v[154:157], v[236:239], v[90:93]
	v_mfma_f32_16x16x32_bf16 v[106:109], v[142:145], v[202:205], 0
	v_mfma_f32_16x16x32_bf16 v[106:109], v[154:157], v[228:231], v[106:109]
	v_mfma_f32_16x16x32_bf16 v[122:125], v[142:145], v[186:189], 0
	v_mfma_f32_16x16x32_bf16 v[122:125], v[154:157], v[198:201], v[122:125]
	v_mfma_f32_16x16x32_bf16 v[114:117], v[178:181], v[186:189], 0
	v_mfma_f32_16x16x32_bf16 v[114:117], v[182:185], v[198:201], v[114:117]
	v_mfma_f32_16x16x32_bf16 v[98:101], v[178:181], v[202:205], 0
	v_mfma_f32_16x16x32_bf16 v[98:101], v[182:185], v[228:231], v[98:101]
	v_mfma_f32_16x16x32_bf16 v[82:85], v[178:181], v[232:235], 0
	v_mfma_f32_16x16x32_bf16 v[82:85], v[182:185], v[236:239], v[82:85]
	v_mfma_f32_16x16x32_bf16 v[66:69], v[178:181], v[240:243], 0
	v_mfma_f32_16x16x32_bf16 v[66:69], v[182:185], v[244:247], v[66:69]
	v_mfma_f32_16x16x32_bf16 v[70:73], v[170:173], v[240:243], 0
	v_mfma_f32_16x16x32_bf16 v[70:73], v[174:177], v[244:247], v[70:73]
	v_mfma_f32_16x16x32_bf16 v[86:89], v[170:173], v[232:235], 0
	v_mfma_f32_16x16x32_bf16 v[86:89], v[174:177], v[236:239], v[86:89]
	v_mfma_f32_16x16x32_bf16 v[102:105], v[170:173], v[202:205], 0
	v_mfma_f32_16x16x32_bf16 v[102:105], v[174:177], v[228:231], v[102:105]
	v_mfma_f32_16x16x32_bf16 v[118:121], v[170:173], v[186:189], 0
	v_mfma_f32_16x16x32_bf16 v[118:121], v[174:177], v[198:201], v[118:121]
	s_barrier
	s_setprio 0
	s_mov_b32 s66, s46
	s_mov_b32 s67, s47
	s_mov_b32 m0, s23
	ds_read_b128 v[186:189], v196 offset:16384
	buffer_load_dwordx4 v192, s[64:67], s27 offen lds
	s_add_i32 s53, s27, 0x80000
	s_mov_b32 m0, s24
	ds_read_b128 v[198:201], v196 offset:17408
	buffer_load_dwordx4 v194, s[64:67], s27 offen lds
	s_mov_b32 m0, s25
	ds_read_b128 v[202:205], v196 offset:18432
	buffer_load_dwordx4 v192, s[64:67], s53 offen lds
	s_mov_b32 m0, s33
	ds_read_b128 v[228:231], v196 offset:19456
	buffer_load_dwordx4 v194, s[64:67], s53 offen lds
	s_mov_b32 m0, s13
	ds_read_b128 v[232:235], v196 offset:20480
	buffer_load_dwordx4 v135, s[44:47], s52 offen lds
	s_mov_b32 m0, s34
	ds_read_b128 v[236:239], v196 offset:21504
	buffer_load_dwordx4 v193, s[44:47], s52 offen lds
	ds_read_b128 v[240:243], v196 offset:22528
	ds_read_b128 v[244:247], v196 offset:23552
	s_waitcnt vmcnt(8)
	s_waitcnt lgkmcnt(0)
	s_setprio 1
	s_barrier
	v_mfma_f32_16x16x32_bf16 v[62:65], v[130:133], v[186:189], 0
	v_mfma_f32_16x16x32_bf16 v[62:65], v[138:141], v[198:201], v[62:65]
	v_mfma_f32_16x16x32_bf16 v[46:49], v[130:133], v[202:205], 0
	v_mfma_f32_16x16x32_bf16 v[46:49], v[138:141], v[228:231], v[46:49]
	v_mfma_f32_16x16x32_bf16 v[30:33], v[130:133], v[232:235], 0
	v_mfma_f32_16x16x32_bf16 v[30:33], v[138:141], v[236:239], v[30:33]
	v_mfma_f32_16x16x32_bf16 v[14:17], v[130:133], v[240:243], 0
	v_mfma_f32_16x16x32_bf16 v[14:17], v[138:141], v[244:247], v[14:17]
	v_mfma_f32_16x16x32_bf16 v[10:13], v[142:145], v[240:243], 0
	v_mfma_f32_16x16x32_bf16 v[10:13], v[154:157], v[244:247], v[10:13]
	v_mfma_f32_16x16x32_bf16 v[26:29], v[142:145], v[232:235], 0
	v_mfma_f32_16x16x32_bf16 v[26:29], v[154:157], v[236:239], v[26:29]
	v_mfma_f32_16x16x32_bf16 v[42:45], v[142:145], v[202:205], 0
	v_mfma_f32_16x16x32_bf16 v[42:45], v[154:157], v[228:231], v[42:45]
	v_mfma_f32_16x16x32_bf16 v[58:61], v[142:145], v[186:189], 0
	v_mfma_f32_16x16x32_bf16 v[58:61], v[154:157], v[198:201], v[58:61]
	v_mfma_f32_16x16x32_bf16 v[50:53], v[178:181], v[186:189], 0
	v_mfma_f32_16x16x32_bf16 v[50:53], v[182:185], v[198:201], v[50:53]
	v_mfma_f32_16x16x32_bf16 v[34:37], v[178:181], v[202:205], 0
	v_mfma_f32_16x16x32_bf16 v[34:37], v[182:185], v[228:231], v[34:37]
	v_mfma_f32_16x16x32_bf16 v[18:21], v[178:181], v[232:235], 0
	v_mfma_f32_16x16x32_bf16 v[18:21], v[182:185], v[236:239], v[18:21]
	v_mfma_f32_16x16x32_bf16 v[2:5], v[178:181], v[240:243], 0
	v_mfma_f32_16x16x32_bf16 v[2:5], v[182:185], v[244:247], v[2:5]
	v_mfma_f32_16x16x32_bf16 v[6:9], v[170:173], v[240:243], 0
	v_mfma_f32_16x16x32_bf16 v[6:9], v[174:177], v[244:247], v[6:9]
	v_mfma_f32_16x16x32_bf16 v[22:25], v[170:173], v[232:235], 0
	v_mfma_f32_16x16x32_bf16 v[22:25], v[174:177], v[236:239], v[22:25]
	v_mfma_f32_16x16x32_bf16 v[38:41], v[170:173], v[202:205], 0
	v_mfma_f32_16x16x32_bf16 v[38:41], v[174:177], v[228:231], v[38:41]
	v_mfma_f32_16x16x32_bf16 v[54:57], v[170:173], v[186:189], 0
	v_mfma_f32_16x16x32_bf16 v[54:57], v[174:177], v[198:201], v[54:57]
	s_barrier
	s_setprio 0
	v_add_u32_e32 v146, 0x18000, v195
	ds_read_b128 v[130:133], v146
	ds_read_b128 v[138:141], v146 offset:1024
	ds_read_b128 v[142:145], v146 offset:2048
	ds_read_b128 v[154:157], v146 offset:3072
	v_add_u32_e32 v146, 0x1c000, v195
	ds_read_b128 v[170:173], v146
	ds_read_b128 v[174:177], v146 offset:1024
	ds_read_b128 v[178:181], v146 offset:2048
	ds_read_b128 v[182:185], v146 offset:3072
	s_add_i32 s52, s52, 0x80000
	s_mov_b32 m0, s35
	ds_read_b128 v[186:189], v196 offset:32768
	ds_read_b128 v[198:201], v196 offset:33792
	ds_read_b128 v[202:205], v196 offset:34816
	ds_read_b128 v[228:231], v196 offset:35840
	ds_read_b128 v[232:235], v196 offset:36864
	ds_read_b128 v[236:239], v196 offset:37888
	ds_read_b128 v[240:243], v196 offset:38912
	ds_read_b128 v[244:247], v196 offset:39936
	buffer_load_dwordx4 v135, s[44:47], s52 offen lds
	s_mov_b32 m0, s36
	s_nop 0
	buffer_load_dwordx4 v193, s[44:47], s52 offen lds
	s_waitcnt vmcnt(8)
	s_waitcnt lgkmcnt(0)
	s_setprio 1
	s_barrier
	v_mfma_f32_16x16x32_bf16 v[126:129], v[130:133], v[186:189], v[126:129]
	v_mfma_f32_16x16x32_bf16 v[126:129], v[138:141], v[198:201], v[126:129]
	v_mfma_f32_16x16x32_bf16 v[110:113], v[130:133], v[202:205], v[110:113]
	v_mfma_f32_16x16x32_bf16 v[110:113], v[138:141], v[228:231], v[110:113]
	v_mfma_f32_16x16x32_bf16 v[94:97], v[130:133], v[232:235], v[94:97]
	v_mfma_f32_16x16x32_bf16 v[94:97], v[138:141], v[236:239], v[94:97]
	v_mfma_f32_16x16x32_bf16 v[78:81], v[130:133], v[240:243], v[78:81]
	v_mfma_f32_16x16x32_bf16 v[78:81], v[138:141], v[244:247], v[78:81]
	v_mfma_f32_16x16x32_bf16 v[74:77], v[142:145], v[240:243], v[74:77]
	v_mfma_f32_16x16x32_bf16 v[74:77], v[154:157], v[244:247], v[74:77]
	v_mfma_f32_16x16x32_bf16 v[90:93], v[142:145], v[232:235], v[90:93]
	v_mfma_f32_16x16x32_bf16 v[90:93], v[154:157], v[236:239], v[90:93]
	v_mfma_f32_16x16x32_bf16 v[106:109], v[142:145], v[202:205], v[106:109]
	v_mfma_f32_16x16x32_bf16 v[106:109], v[154:157], v[228:231], v[106:109]
	v_mfma_f32_16x16x32_bf16 v[122:125], v[142:145], v[186:189], v[122:125]
	v_mfma_f32_16x16x32_bf16 v[122:125], v[154:157], v[198:201], v[122:125]
	v_mfma_f32_16x16x32_bf16 v[114:117], v[178:181], v[186:189], v[114:117]
	v_mfma_f32_16x16x32_bf16 v[114:117], v[182:185], v[198:201], v[114:117]
	v_mfma_f32_16x16x32_bf16 v[98:101], v[178:181], v[202:205], v[98:101]
	v_mfma_f32_16x16x32_bf16 v[98:101], v[182:185], v[228:231], v[98:101]
	v_mfma_f32_16x16x32_bf16 v[82:85], v[178:181], v[232:235], v[82:85]
	v_mfma_f32_16x16x32_bf16 v[82:85], v[182:185], v[236:239], v[82:85]
	v_mfma_f32_16x16x32_bf16 v[66:69], v[178:181], v[240:243], v[66:69]
	v_mfma_f32_16x16x32_bf16 v[66:69], v[182:185], v[244:247], v[66:69]
	v_mfma_f32_16x16x32_bf16 v[70:73], v[170:173], v[240:243], v[70:73]
	v_mfma_f32_16x16x32_bf16 v[70:73], v[174:177], v[244:247], v[70:73]
	v_mfma_f32_16x16x32_bf16 v[86:89], v[170:173], v[232:235], v[86:89]
	v_mfma_f32_16x16x32_bf16 v[86:89], v[174:177], v[236:239], v[86:89]
	v_mfma_f32_16x16x32_bf16 v[102:105], v[170:173], v[202:205], v[102:105]
	v_mfma_f32_16x16x32_bf16 v[102:105], v[174:177], v[228:231], v[102:105]
	v_mfma_f32_16x16x32_bf16 v[118:121], v[170:173], v[186:189], v[118:121]
	v_mfma_f32_16x16x32_bf16 v[118:121], v[174:177], v[198:201], v[118:121]
	s_barrier
	s_setprio 0
	s_or_b32 s52, s27, 0x80
	s_mov_b32 m0, s41
	ds_read_b128 v[186:189], v196 offset:49152
	buffer_load_dwordx4 v192, s[64:67], s52 offen lds
	s_add_i32 s27, s27, 0x80080
	s_mov_b32 m0, s48
	ds_read_b128 v[198:201], v196 offset:50176
	buffer_load_dwordx4 v194, s[64:67], s52 offen lds
	s_mov_b32 m0, s69
	ds_read_b128 v[202:205], v196 offset:51200
	buffer_load_dwordx4 v192, s[64:67], s27 offen lds
	s_mov_b32 m0, s72
	ds_read_b128 v[228:231], v196 offset:52224
	buffer_load_dwordx4 v194, s[64:67], s27 offen lds
	s_mov_b32 m0, s49
	ds_read_b128 v[232:235], v196 offset:53248
	buffer_load_dwordx4 v135, s[44:47], s26 offen lds
	s_mov_b32 m0, s68
	ds_read_b128 v[236:239], v196 offset:54272
	buffer_load_dwordx4 v193, s[44:47], s26 offen lds
	ds_read_b128 v[240:243], v196 offset:55296
	ds_read_b128 v[244:247], v196 offset:56320
	s_waitcnt vmcnt(8)
	s_waitcnt lgkmcnt(0)
	s_setprio 1
	s_barrier
	v_mfma_f32_16x16x32_bf16 v[62:65], v[130:133], v[186:189], v[62:65]
	v_mfma_f32_16x16x32_bf16 v[62:65], v[138:141], v[198:201], v[62:65]
	v_mfma_f32_16x16x32_bf16 v[46:49], v[130:133], v[202:205], v[46:49]
	v_mfma_f32_16x16x32_bf16 v[46:49], v[138:141], v[228:231], v[46:49]
	v_mfma_f32_16x16x32_bf16 v[30:33], v[130:133], v[232:235], v[30:33]
	v_mfma_f32_16x16x32_bf16 v[30:33], v[138:141], v[236:239], v[30:33]
	v_mfma_f32_16x16x32_bf16 v[14:17], v[130:133], v[240:243], v[14:17]
	v_mfma_f32_16x16x32_bf16 v[14:17], v[138:141], v[244:247], v[14:17]
	v_mfma_f32_16x16x32_bf16 v[10:13], v[142:145], v[240:243], v[10:13]
	v_mfma_f32_16x16x32_bf16 v[10:13], v[154:157], v[244:247], v[10:13]
	v_mfma_f32_16x16x32_bf16 v[26:29], v[142:145], v[232:235], v[26:29]
	v_mfma_f32_16x16x32_bf16 v[26:29], v[154:157], v[236:239], v[26:29]
	v_mfma_f32_16x16x32_bf16 v[42:45], v[142:145], v[202:205], v[42:45]
	v_mfma_f32_16x16x32_bf16 v[42:45], v[154:157], v[228:231], v[42:45]
	v_mfma_f32_16x16x32_bf16 v[58:61], v[142:145], v[186:189], v[58:61]
	v_mfma_f32_16x16x32_bf16 v[58:61], v[154:157], v[198:201], v[58:61]
	v_mfma_f32_16x16x32_bf16 v[50:53], v[178:181], v[186:189], v[50:53]
	v_mfma_f32_16x16x32_bf16 v[50:53], v[182:185], v[198:201], v[50:53]
	v_mfma_f32_16x16x32_bf16 v[34:37], v[178:181], v[202:205], v[34:37]
	v_mfma_f32_16x16x32_bf16 v[34:37], v[182:185], v[228:231], v[34:37]
	v_mfma_f32_16x16x32_bf16 v[18:21], v[178:181], v[232:235], v[18:21]
	v_mfma_f32_16x16x32_bf16 v[18:21], v[182:185], v[236:239], v[18:21]
	v_mfma_f32_16x16x32_bf16 v[2:5], v[178:181], v[240:243], v[2:5]
	v_mfma_f32_16x16x32_bf16 v[2:5], v[182:185], v[244:247], v[2:5]
	v_mfma_f32_16x16x32_bf16 v[6:9], v[170:173], v[240:243], v[6:9]
	v_mfma_f32_16x16x32_bf16 v[6:9], v[174:177], v[244:247], v[6:9]
	v_mfma_f32_16x16x32_bf16 v[22:25], v[170:173], v[232:235], v[22:25]
	v_mfma_f32_16x16x32_bf16 v[22:25], v[174:177], v[236:239], v[22:25]
	v_mfma_f32_16x16x32_bf16 v[38:41], v[170:173], v[202:205], v[38:41]
	v_mfma_f32_16x16x32_bf16 v[38:41], v[174:177], v[228:231], v[38:41]
	v_mfma_f32_16x16x32_bf16 v[54:57], v[170:173], v[186:189], v[54:57]
	v_mfma_f32_16x16x32_bf16 v[54:57], v[174:177], v[198:201], v[54:57]
	s_barrier
	s_setprio 0
	s_add_i32 s22, s22, 2
	s_addk_i32 s18, 0x100
	s_addk_i32 s19, 0x100
	s_cmp_gt_u32 s22, 29
.LBB0_859:
	v_add_u32_e32 v146, 0x10000, v195
	ds_read_b128 v[130:133], v146
	ds_read_b128 v[138:141], v146 offset:1024
	ds_read_b128 v[142:145], v146 offset:2048
	ds_read_b128 v[154:157], v146 offset:3072
	v_add_u32_e32 v146, 0x14000, v195
	ds_read_b128 v[170:173], v146
	ds_read_b128 v[174:177], v146 offset:1024
	ds_read_b128 v[178:181], v146 offset:2048
	ds_read_b128 v[182:185], v146 offset:3072
	s_add_i32 s26, s18, 0xfff80080
	s_cmp_eq_u32 s22, 28
	s_cselect_b32 s52, s8, s26
	s_cselect_b32 s27, s9, s19
	s_or_b32 s26, s52, 0x80
	s_mov_b32 m0, s85
	ds_read_b128 v[186:189], v196
	ds_read_b128 v[198:201], v196 offset:1024
	ds_read_b128 v[202:205], v196 offset:2048
	ds_read_b128 v[228:231], v196 offset:3072
	ds_read_b128 v[232:235], v196 offset:4096
	ds_read_b128 v[236:239], v196 offset:5120
	ds_read_b128 v[240:243], v196 offset:6144
	ds_read_b128 v[244:247], v196 offset:7168
	buffer_load_dwordx4 v135, s[44:47], s18 offen lds
	s_mov_b32 m0, s15
	s_nop 0
	buffer_load_dwordx4 v193, s[44:47], s18 offen lds
	s_waitcnt vmcnt(8)
	s_waitcnt lgkmcnt(0)
	s_setprio 1
	s_barrier
	v_mfma_f32_16x16x32_bf16 v[126:129], v[130:133], v[186:189], v[126:129]
	v_mfma_f32_16x16x32_bf16 v[126:129], v[138:141], v[198:201], v[126:129]
	v_mfma_f32_16x16x32_bf16 v[110:113], v[130:133], v[202:205], v[110:113]
	v_mfma_f32_16x16x32_bf16 v[110:113], v[138:141], v[228:231], v[110:113]
	v_mfma_f32_16x16x32_bf16 v[94:97], v[130:133], v[232:235], v[94:97]
	v_mfma_f32_16x16x32_bf16 v[94:97], v[138:141], v[236:239], v[94:97]
	v_mfma_f32_16x16x32_bf16 v[78:81], v[130:133], v[240:243], v[78:81]
	v_mfma_f32_16x16x32_bf16 v[78:81], v[138:141], v[244:247], v[78:81]
	v_mfma_f32_16x16x32_bf16 v[74:77], v[142:145], v[240:243], v[74:77]
	v_mfma_f32_16x16x32_bf16 v[74:77], v[154:157], v[244:247], v[74:77]
	v_mfma_f32_16x16x32_bf16 v[90:93], v[142:145], v[232:235], v[90:93]
	v_mfma_f32_16x16x32_bf16 v[90:93], v[154:157], v[236:239], v[90:93]
	v_mfma_f32_16x16x32_bf16 v[106:109], v[142:145], v[202:205], v[106:109]
	v_mfma_f32_16x16x32_bf16 v[106:109], v[154:157], v[228:231], v[106:109]
	v_mfma_f32_16x16x32_bf16 v[122:125], v[142:145], v[186:189], v[122:125]
	v_mfma_f32_16x16x32_bf16 v[122:125], v[154:157], v[198:201], v[122:125]
	v_mfma_f32_16x16x32_bf16 v[114:117], v[178:181], v[186:189], v[114:117]
	v_mfma_f32_16x16x32_bf16 v[114:117], v[182:185], v[198:201], v[114:117]
	v_mfma_f32_16x16x32_bf16 v[98:101], v[178:181], v[202:205], v[98:101]
	v_mfma_f32_16x16x32_bf16 v[98:101], v[182:185], v[228:231], v[98:101]
	v_mfma_f32_16x16x32_bf16 v[82:85], v[178:181], v[232:235], v[82:85]
	v_mfma_f32_16x16x32_bf16 v[82:85], v[182:185], v[236:239], v[82:85]
	v_mfma_f32_16x16x32_bf16 v[66:69], v[178:181], v[240:243], v[66:69]
	v_mfma_f32_16x16x32_bf16 v[66:69], v[182:185], v[244:247], v[66:69]
	v_mfma_f32_16x16x32_bf16 v[70:73], v[170:173], v[240:243], v[70:73]
	v_mfma_f32_16x16x32_bf16 v[70:73], v[174:177], v[244:247], v[70:73]
	v_mfma_f32_16x16x32_bf16 v[86:89], v[170:173], v[232:235], v[86:89]
	v_mfma_f32_16x16x32_bf16 v[86:89], v[174:177], v[236:239], v[86:89]
	v_mfma_f32_16x16x32_bf16 v[102:105], v[170:173], v[202:205], v[102:105]
	v_mfma_f32_16x16x32_bf16 v[102:105], v[174:177], v[228:231], v[102:105]
	v_mfma_f32_16x16x32_bf16 v[118:121], v[170:173], v[186:189], v[118:121]
	v_mfma_f32_16x16x32_bf16 v[118:121], v[174:177], v[198:201], v[118:121]
	s_barrier
	s_setprio 0
	s_mov_b32 s66, s46
	s_mov_b32 s67, s47
	s_mov_b32 m0, s23
	ds_read_b128 v[186:189], v196 offset:16384
	buffer_load_dwordx4 v192, s[64:67], s27 offen lds
	s_add_i32 s53, s27, 0x80000
	s_mov_b32 m0, s24
	ds_read_b128 v[198:201], v196 offset:17408
	buffer_load_dwordx4 v194, s[64:67], s27 offen lds
	s_mov_b32 m0, s25
	ds_read_b128 v[202:205], v196 offset:18432
	buffer_load_dwordx4 v192, s[64:67], s53 offen lds
	s_mov_b32 m0, s33
	ds_read_b128 v[228:231], v196 offset:19456
	buffer_load_dwordx4 v194, s[64:67], s53 offen lds
	s_mov_b32 m0, s13
	ds_read_b128 v[232:235], v196 offset:20480
	buffer_load_dwordx4 v135, s[44:47], s52 offen lds
	s_mov_b32 m0, s34
	ds_read_b128 v[236:239], v196 offset:21504
	buffer_load_dwordx4 v193, s[44:47], s52 offen lds
	ds_read_b128 v[240:243], v196 offset:22528
	ds_read_b128 v[244:247], v196 offset:23552
	s_waitcnt vmcnt(8)
	s_waitcnt lgkmcnt(0)
	s_setprio 1
	s_barrier
	v_mfma_f32_16x16x32_bf16 v[62:65], v[130:133], v[186:189], v[62:65]
	v_mfma_f32_16x16x32_bf16 v[62:65], v[138:141], v[198:201], v[62:65]
	v_mfma_f32_16x16x32_bf16 v[46:49], v[130:133], v[202:205], v[46:49]
	v_mfma_f32_16x16x32_bf16 v[46:49], v[138:141], v[228:231], v[46:49]
	v_mfma_f32_16x16x32_bf16 v[30:33], v[130:133], v[232:235], v[30:33]
	v_mfma_f32_16x16x32_bf16 v[30:33], v[138:141], v[236:239], v[30:33]
	v_mfma_f32_16x16x32_bf16 v[14:17], v[130:133], v[240:243], v[14:17]
	v_mfma_f32_16x16x32_bf16 v[14:17], v[138:141], v[244:247], v[14:17]
	v_mfma_f32_16x16x32_bf16 v[10:13], v[142:145], v[240:243], v[10:13]
	v_mfma_f32_16x16x32_bf16 v[10:13], v[154:157], v[244:247], v[10:13]
	v_mfma_f32_16x16x32_bf16 v[26:29], v[142:145], v[232:235], v[26:29]
	v_mfma_f32_16x16x32_bf16 v[26:29], v[154:157], v[236:239], v[26:29]
	v_mfma_f32_16x16x32_bf16 v[42:45], v[142:145], v[202:205], v[42:45]
	v_mfma_f32_16x16x32_bf16 v[42:45], v[154:157], v[228:231], v[42:45]
	v_mfma_f32_16x16x32_bf16 v[58:61], v[142:145], v[186:189], v[58:61]
	v_mfma_f32_16x16x32_bf16 v[58:61], v[154:157], v[198:201], v[58:61]
	v_mfma_f32_16x16x32_bf16 v[50:53], v[178:181], v[186:189], v[50:53]
	v_mfma_f32_16x16x32_bf16 v[50:53], v[182:185], v[198:201], v[50:53]
	v_mfma_f32_16x16x32_bf16 v[34:37], v[178:181], v[202:205], v[34:37]
	v_mfma_f32_16x16x32_bf16 v[34:37], v[182:185], v[228:231], v[34:37]
	v_mfma_f32_16x16x32_bf16 v[18:21], v[178:181], v[232:235], v[18:21]
	v_mfma_f32_16x16x32_bf16 v[18:21], v[182:185], v[236:239], v[18:21]
	v_mfma_f32_16x16x32_bf16 v[2:5], v[178:181], v[240:243], v[2:5]
	v_mfma_f32_16x16x32_bf16 v[2:5], v[182:185], v[244:247], v[2:5]
	v_mfma_f32_16x16x32_bf16 v[6:9], v[170:173], v[240:243], v[6:9]
	v_mfma_f32_16x16x32_bf16 v[6:9], v[174:177], v[244:247], v[6:9]
	v_mfma_f32_16x16x32_bf16 v[22:25], v[170:173], v[232:235], v[22:25]
	v_mfma_f32_16x16x32_bf16 v[22:25], v[174:177], v[236:239], v[22:25]
	v_mfma_f32_16x16x32_bf16 v[38:41], v[170:173], v[202:205], v[38:41]
	v_mfma_f32_16x16x32_bf16 v[38:41], v[174:177], v[228:231], v[38:41]
	v_mfma_f32_16x16x32_bf16 v[54:57], v[170:173], v[186:189], v[54:57]
	v_mfma_f32_16x16x32_bf16 v[54:57], v[174:177], v[198:201], v[54:57]
	s_barrier
	s_setprio 0
	v_add_u32_e32 v146, 0x18000, v195
	ds_read_b128 v[130:133], v146
	ds_read_b128 v[138:141], v146 offset:1024
	ds_read_b128 v[142:145], v146 offset:2048
	ds_read_b128 v[154:157], v146 offset:3072
	v_add_u32_e32 v146, 0x1c000, v195
	ds_read_b128 v[170:173], v146
	ds_read_b128 v[174:177], v146 offset:1024
	ds_read_b128 v[178:181], v146 offset:2048
	ds_read_b128 v[182:185], v146 offset:3072
	s_add_i32 s52, s52, 0x80000
	s_mov_b32 m0, s35
	ds_read_b128 v[186:189], v196 offset:32768
	ds_read_b128 v[198:201], v196 offset:33792
	ds_read_b128 v[202:205], v196 offset:34816
	ds_read_b128 v[228:231], v196 offset:35840
	ds_read_b128 v[232:235], v196 offset:36864
	ds_read_b128 v[236:239], v196 offset:37888
	ds_read_b128 v[240:243], v196 offset:38912
	ds_read_b128 v[244:247], v196 offset:39936
	buffer_load_dwordx4 v135, s[44:47], s52 offen lds
	s_mov_b32 m0, s36
	s_nop 0
	buffer_load_dwordx4 v193, s[44:47], s52 offen lds
	s_waitcnt vmcnt(8)
	s_waitcnt lgkmcnt(0)
	s_setprio 1
	s_barrier
	v_mfma_f32_16x16x32_bf16 v[126:129], v[130:133], v[186:189], v[126:129]
	v_mfma_f32_16x16x32_bf16 v[126:129], v[138:141], v[198:201], v[126:129]
	v_mfma_f32_16x16x32_bf16 v[110:113], v[130:133], v[202:205], v[110:113]
	v_mfma_f32_16x16x32_bf16 v[110:113], v[138:141], v[228:231], v[110:113]
	v_mfma_f32_16x16x32_bf16 v[94:97], v[130:133], v[232:235], v[94:97]
	v_mfma_f32_16x16x32_bf16 v[94:97], v[138:141], v[236:239], v[94:97]
	v_mfma_f32_16x16x32_bf16 v[78:81], v[130:133], v[240:243], v[78:81]
	v_mfma_f32_16x16x32_bf16 v[78:81], v[138:141], v[244:247], v[78:81]
	v_mfma_f32_16x16x32_bf16 v[74:77], v[142:145], v[240:243], v[74:77]
	v_mfma_f32_16x16x32_bf16 v[74:77], v[154:157], v[244:247], v[74:77]
	v_mfma_f32_16x16x32_bf16 v[90:93], v[142:145], v[232:235], v[90:93]
	v_mfma_f32_16x16x32_bf16 v[90:93], v[154:157], v[236:239], v[90:93]
	v_mfma_f32_16x16x32_bf16 v[106:109], v[142:145], v[202:205], v[106:109]
	v_mfma_f32_16x16x32_bf16 v[106:109], v[154:157], v[228:231], v[106:109]
	v_mfma_f32_16x16x32_bf16 v[122:125], v[142:145], v[186:189], v[122:125]
	v_mfma_f32_16x16x32_bf16 v[122:125], v[154:157], v[198:201], v[122:125]
	v_mfma_f32_16x16x32_bf16 v[114:117], v[178:181], v[186:189], v[114:117]
	v_mfma_f32_16x16x32_bf16 v[114:117], v[182:185], v[198:201], v[114:117]
	v_mfma_f32_16x16x32_bf16 v[98:101], v[178:181], v[202:205], v[98:101]
	v_mfma_f32_16x16x32_bf16 v[98:101], v[182:185], v[228:231], v[98:101]
	v_mfma_f32_16x16x32_bf16 v[82:85], v[178:181], v[232:235], v[82:85]
	v_mfma_f32_16x16x32_bf16 v[82:85], v[182:185], v[236:239], v[82:85]
	v_mfma_f32_16x16x32_bf16 v[66:69], v[178:181], v[240:243], v[66:69]
	v_mfma_f32_16x16x32_bf16 v[66:69], v[182:185], v[244:247], v[66:69]
	v_mfma_f32_16x16x32_bf16 v[70:73], v[170:173], v[240:243], v[70:73]
	v_mfma_f32_16x16x32_bf16 v[70:73], v[174:177], v[244:247], v[70:73]
	v_mfma_f32_16x16x32_bf16 v[86:89], v[170:173], v[232:235], v[86:89]
	v_mfma_f32_16x16x32_bf16 v[86:89], v[174:177], v[236:239], v[86:89]
	v_mfma_f32_16x16x32_bf16 v[102:105], v[170:173], v[202:205], v[102:105]
	v_mfma_f32_16x16x32_bf16 v[102:105], v[174:177], v[228:231], v[102:105]
	v_mfma_f32_16x16x32_bf16 v[118:121], v[170:173], v[186:189], v[118:121]
	v_mfma_f32_16x16x32_bf16 v[118:121], v[174:177], v[198:201], v[118:121]
	s_barrier
	s_setprio 0
	s_or_b32 s52, s27, 0x80
	s_mov_b32 m0, s41
	ds_read_b128 v[186:189], v196 offset:49152
	buffer_load_dwordx4 v192, s[64:67], s52 offen lds
	s_add_i32 s27, s27, 0x80080
	s_mov_b32 m0, s48
	ds_read_b128 v[198:201], v196 offset:50176
	buffer_load_dwordx4 v194, s[64:67], s52 offen lds
	s_mov_b32 m0, s69
	ds_read_b128 v[202:205], v196 offset:51200
	buffer_load_dwordx4 v192, s[64:67], s27 offen lds
	s_mov_b32 m0, s72
	ds_read_b128 v[228:231], v196 offset:52224
	buffer_load_dwordx4 v194, s[64:67], s27 offen lds
	s_mov_b32 m0, s49
	ds_read_b128 v[232:235], v196 offset:53248
	buffer_load_dwordx4 v135, s[44:47], s26 offen lds
	s_mov_b32 m0, s68
	ds_read_b128 v[236:239], v196 offset:54272
	buffer_load_dwordx4 v193, s[44:47], s26 offen lds
	ds_read_b128 v[240:243], v196 offset:55296
	ds_read_b128 v[244:247], v196 offset:56320
	s_waitcnt vmcnt(8)
	s_waitcnt lgkmcnt(0)
	s_setprio 1
	s_barrier
	v_mfma_f32_16x16x32_bf16 v[62:65], v[130:133], v[186:189], v[62:65]
	v_mfma_f32_16x16x32_bf16 v[62:65], v[138:141], v[198:201], v[62:65]
	v_mfma_f32_16x16x32_bf16 v[46:49], v[130:133], v[202:205], v[46:49]
	v_mfma_f32_16x16x32_bf16 v[46:49], v[138:141], v[228:231], v[46:49]
	v_mfma_f32_16x16x32_bf16 v[30:33], v[130:133], v[232:235], v[30:33]
	v_mfma_f32_16x16x32_bf16 v[30:33], v[138:141], v[236:239], v[30:33]
	v_mfma_f32_16x16x32_bf16 v[14:17], v[130:133], v[240:243], v[14:17]
	v_mfma_f32_16x16x32_bf16 v[14:17], v[138:141], v[244:247], v[14:17]
	v_mfma_f32_16x16x32_bf16 v[10:13], v[142:145], v[240:243], v[10:13]
	v_mfma_f32_16x16x32_bf16 v[10:13], v[154:157], v[244:247], v[10:13]
	v_mfma_f32_16x16x32_bf16 v[26:29], v[142:145], v[232:235], v[26:29]
	v_mfma_f32_16x16x32_bf16 v[26:29], v[154:157], v[236:239], v[26:29]
	v_mfma_f32_16x16x32_bf16 v[42:45], v[142:145], v[202:205], v[42:45]
	v_mfma_f32_16x16x32_bf16 v[42:45], v[154:157], v[228:231], v[42:45]
	v_mfma_f32_16x16x32_bf16 v[58:61], v[142:145], v[186:189], v[58:61]
	v_mfma_f32_16x16x32_bf16 v[58:61], v[154:157], v[198:201], v[58:61]
	v_mfma_f32_16x16x32_bf16 v[50:53], v[178:181], v[186:189], v[50:53]
	v_mfma_f32_16x16x32_bf16 v[50:53], v[182:185], v[198:201], v[50:53]
	v_mfma_f32_16x16x32_bf16 v[34:37], v[178:181], v[202:205], v[34:37]
	v_mfma_f32_16x16x32_bf16 v[34:37], v[182:185], v[228:231], v[34:37]
	v_mfma_f32_16x16x32_bf16 v[18:21], v[178:181], v[232:235], v[18:21]
	v_mfma_f32_16x16x32_bf16 v[18:21], v[182:185], v[236:239], v[18:21]
	v_mfma_f32_16x16x32_bf16 v[2:5], v[178:181], v[240:243], v[2:5]
	v_mfma_f32_16x16x32_bf16 v[2:5], v[182:185], v[244:247], v[2:5]
	v_mfma_f32_16x16x32_bf16 v[6:9], v[170:173], v[240:243], v[6:9]
	v_mfma_f32_16x16x32_bf16 v[6:9], v[174:177], v[244:247], v[6:9]
	v_mfma_f32_16x16x32_bf16 v[22:25], v[170:173], v[232:235], v[22:25]
	v_mfma_f32_16x16x32_bf16 v[22:25], v[174:177], v[236:239], v[22:25]
	v_mfma_f32_16x16x32_bf16 v[38:41], v[170:173], v[202:205], v[38:41]
	v_mfma_f32_16x16x32_bf16 v[38:41], v[174:177], v[228:231], v[38:41]
	v_mfma_f32_16x16x32_bf16 v[54:57], v[170:173], v[186:189], v[54:57]
	v_mfma_f32_16x16x32_bf16 v[54:57], v[174:177], v[198:201], v[54:57]
	s_barrier
	s_setprio 0
	s_add_i32 s22, s22, 2
	s_addk_i32 s18, 0x100
	s_addk_i32 s19, 0x100
	s_cmp_gt_u32 s22, 29
	s_cbranch_scc0 .LBB0_859
	s_and_b64 vcc, exec, s[60:61]
	s_cbranch_vccz .LBB0_862
	s_barrier

.LBB0_880:
	s_lshl_b32 s14, s85, 20
	s_and_b64 s[8:9], s[42:43], exec
	s_cselect_b32 s8, s14, s12
	s_lshl_b32 s15, s66, 20
	s_and_b64 s[22:23], s[42:43], exec
	s_cselect_b32 s9, s15, s13
	s_add_i32 s12, s12, 0x80080
	s_addk_i32 s13, 0x100
	s_mov_b32 s16, -2
	v_add_u32_e32 v139, 0x10000, v234
	ds_read_b128 v[130:133], v139
	ds_read_b128 v[140:143], v139 offset:1024
	ds_read_b128 v[170:173], v139 offset:2048
	ds_read_b128 v[174:177], v139 offset:3072
	v_add_u32_e32 v139, 0x14000, v234
	ds_read_b128 v[178:181], v139
	ds_read_b128 v[182:185], v139 offset:1024
	ds_read_b128 v[186:189], v139 offset:2048
	ds_read_b128 v[190:193], v139 offset:3072
	s_add_i32 s21, s12, 0xfff80080
	s_cmp_eq_u32 s16, 28
	s_cselect_b32 s23, s8, s21
	s_cselect_b32 s22, s9, s13
	s_or_b32 s21, s23, 0x80
	s_mov_b32 m0, s72
	ds_read_b128 v[194:197], v235
	ds_read_b128 v[198:201], v235 offset:1024
	ds_read_b128 v[202:205], v235 offset:2048
	ds_read_b128 v[236:239], v235 offset:3072
	ds_read_b128 v[240:243], v235 offset:4096
	ds_read_b128 v[244:247], v235 offset:5120
	ds_read_b128 v[248:251], v235 offset:6144
	ds_read_b128 v[154:157], v235 offset:7168
	buffer_load_dwordx4 v228, s[60:63], s12 offen lds
	s_mov_b32 m0, s73
	s_nop 0
	buffer_load_dwordx4 v230, s[60:63], s12 offen lds
	s_waitcnt vmcnt(8)
	s_waitcnt lgkmcnt(0)
	s_setprio 1
	s_barrier
	v_mfma_f32_16x16x32_bf16 v[126:129], v[130:133], v[194:197], 0
	v_mfma_f32_16x16x32_bf16 v[126:129], v[140:143], v[198:201], v[126:129]
	v_mfma_f32_16x16x32_bf16 v[114:117], v[130:133], v[202:205], 0
	v_mfma_f32_16x16x32_bf16 v[114:117], v[140:143], v[236:239], v[114:117]
	v_mfma_f32_16x16x32_bf16 v[98:101], v[130:133], v[240:243], 0
	v_mfma_f32_16x16x32_bf16 v[98:101], v[140:143], v[244:247], v[98:101]
	v_mfma_f32_16x16x32_bf16 v[82:85], v[130:133], v[248:251], 0
	v_mfma_f32_16x16x32_bf16 v[82:85], v[140:143], v[154:157], v[82:85]
	v_mfma_f32_16x16x32_bf16 v[74:77], v[170:173], v[248:251], 0
	v_mfma_f32_16x16x32_bf16 v[74:77], v[174:177], v[154:157], v[74:77]
	v_mfma_f32_16x16x32_bf16 v[90:93], v[170:173], v[240:243], 0
	v_mfma_f32_16x16x32_bf16 v[90:93], v[174:177], v[244:247], v[90:93]
	v_mfma_f32_16x16x32_bf16 v[106:109], v[170:173], v[202:205], 0
	v_mfma_f32_16x16x32_bf16 v[106:109], v[174:177], v[236:239], v[106:109]
	v_mfma_f32_16x16x32_bf16 v[122:125], v[170:173], v[194:197], 0
	v_mfma_f32_16x16x32_bf16 v[122:125], v[174:177], v[198:201], v[122:125]
	v_mfma_f32_16x16x32_bf16 v[110:113], v[186:189], v[194:197], 0
	v_mfma_f32_16x16x32_bf16 v[110:113], v[190:193], v[198:201], v[110:113]
	v_mfma_f32_16x16x32_bf16 v[94:97], v[186:189], v[202:205], 0
	v_mfma_f32_16x16x32_bf16 v[94:97], v[190:193], v[236:239], v[94:97]
	v_mfma_f32_16x16x32_bf16 v[78:81], v[186:189], v[240:243], 0
	v_mfma_f32_16x16x32_bf16 v[78:81], v[190:193], v[244:247], v[78:81]
	v_mfma_f32_16x16x32_bf16 v[66:69], v[186:189], v[248:251], 0
	v_mfma_f32_16x16x32_bf16 v[66:69], v[190:193], v[154:157], v[66:69]
	v_mfma_f32_16x16x32_bf16 v[70:73], v[178:181], v[248:251], 0
	v_mfma_f32_16x16x32_bf16 v[70:73], v[182:185], v[154:157], v[70:73]
	v_mfma_f32_16x16x32_bf16 v[86:89], v[178:181], v[240:243], 0
	v_mfma_f32_16x16x32_bf16 v[86:89], v[182:185], v[244:247], v[86:89]
	v_mfma_f32_16x16x32_bf16 v[102:105], v[178:181], v[202:205], 0
	v_mfma_f32_16x16x32_bf16 v[102:105], v[182:185], v[236:239], v[102:105]
	v_mfma_f32_16x16x32_bf16 v[118:121], v[178:181], v[194:197], 0
	v_mfma_f32_16x16x32_bf16 v[118:121], v[182:185], v[198:201], v[118:121]
	s_barrier
	s_setprio 0
	s_mov_b32 s46, s62
	s_mov_b32 s47, s63
	s_mov_b32 m0, s26
	ds_read_b128 v[154:157], v235 offset:16384
	buffer_load_dwordx4 v229, s[44:47], s22 offen lds
	s_add_i32 s38, s22, 0x80000
	s_mov_b32 m0, s27
	ds_read_b128 v[194:197], v235 offset:17408
	buffer_load_dwordx4 v231, s[44:47], s22 offen lds
	s_mov_b32 m0, s34
	ds_read_b128 v[198:201], v235 offset:18432
	buffer_load_dwordx4 v229, s[44:47], s38 offen lds
	s_mov_b32 m0, s35
	ds_read_b128 v[202:205], v235 offset:19456
	buffer_load_dwordx4 v231, s[44:47], s38 offen lds
	s_mov_b32 m0, s19
	ds_read_b128 v[236:239], v235 offset:20480
	buffer_load_dwordx4 v228, s[60:63], s23 offen lds
	s_mov_b32 m0, s36
	ds_read_b128 v[240:243], v235 offset:21504
	buffer_load_dwordx4 v230, s[60:63], s23 offen lds
	ds_read_b128 v[244:247], v235 offset:22528
	ds_read_b128 v[248:251], v235 offset:23552
	s_waitcnt vmcnt(8)
	s_waitcnt lgkmcnt(0)
	s_setprio 1
	s_barrier
	v_mfma_f32_16x16x32_bf16 v[62:65], v[130:133], v[154:157], 0
	v_mfma_f32_16x16x32_bf16 v[62:65], v[140:143], v[194:197], v[62:65]
	v_mfma_f32_16x16x32_bf16 v[50:53], v[130:133], v[198:201], 0
	v_mfma_f32_16x16x32_bf16 v[50:53], v[140:143], v[202:205], v[50:53]
	v_mfma_f32_16x16x32_bf16 v[34:37], v[130:133], v[236:239], 0
	v_mfma_f32_16x16x32_bf16 v[34:37], v[140:143], v[240:243], v[34:37]
	v_mfma_f32_16x16x32_bf16 v[18:21], v[130:133], v[244:247], 0
	v_mfma_f32_16x16x32_bf16 v[18:21], v[140:143], v[248:251], v[18:21]
	v_mfma_f32_16x16x32_bf16 v[10:13], v[170:173], v[244:247], 0
	v_mfma_f32_16x16x32_bf16 v[10:13], v[174:177], v[248:251], v[10:13]
	v_mfma_f32_16x16x32_bf16 v[26:29], v[170:173], v[236:239], 0
	v_mfma_f32_16x16x32_bf16 v[26:29], v[174:177], v[240:243], v[26:29]
	v_mfma_f32_16x16x32_bf16 v[42:45], v[170:173], v[198:201], 0
	v_mfma_f32_16x16x32_bf16 v[42:45], v[174:177], v[202:205], v[42:45]
	v_mfma_f32_16x16x32_bf16 v[58:61], v[170:173], v[154:157], 0
	v_mfma_f32_16x16x32_bf16 v[58:61], v[174:177], v[194:197], v[58:61]
	v_mfma_f32_16x16x32_bf16 v[46:49], v[186:189], v[154:157], 0
	v_mfma_f32_16x16x32_bf16 v[46:49], v[190:193], v[194:197], v[46:49]
	v_mfma_f32_16x16x32_bf16 v[30:33], v[186:189], v[198:201], 0
	v_mfma_f32_16x16x32_bf16 v[30:33], v[190:193], v[202:205], v[30:33]
	v_mfma_f32_16x16x32_bf16 v[14:17], v[186:189], v[236:239], 0
	v_mfma_f32_16x16x32_bf16 v[14:17], v[190:193], v[240:243], v[14:17]
	v_mfma_f32_16x16x32_bf16 v[2:5], v[186:189], v[244:247], 0
	v_mfma_f32_16x16x32_bf16 v[2:5], v[190:193], v[248:251], v[2:5]
	v_mfma_f32_16x16x32_bf16 v[6:9], v[178:181], v[244:247], 0
	v_mfma_f32_16x16x32_bf16 v[6:9], v[182:185], v[248:251], v[6:9]
	v_mfma_f32_16x16x32_bf16 v[22:25], v[178:181], v[236:239], 0
	v_mfma_f32_16x16x32_bf16 v[22:25], v[182:185], v[240:243], v[22:25]
	v_mfma_f32_16x16x32_bf16 v[38:41], v[178:181], v[198:201], 0
	v_mfma_f32_16x16x32_bf16 v[38:41], v[182:185], v[202:205], v[38:41]
	v_mfma_f32_16x16x32_bf16 v[54:57], v[178:181], v[154:157], 0
	v_mfma_f32_16x16x32_bf16 v[54:57], v[182:185], v[194:197], v[54:57]
	s_barrier
	s_setprio 0
	v_add_u32_e32 v139, 0x18000, v234
	ds_read_b128 v[130:133], v139
	ds_read_b128 v[140:143], v139 offset:1024
	ds_read_b128 v[154:157], v139 offset:2048
	ds_read_b128 v[170:173], v139 offset:3072
	v_add_u32_e32 v139, 0x1c000, v234
	ds_read_b128 v[174:177], v139
	ds_read_b128 v[178:181], v139 offset:1024
	ds_read_b128 v[182:185], v139 offset:2048
	ds_read_b128 v[186:189], v139 offset:3072
	s_add_i32 s23, s23, 0x80000
	s_mov_b32 m0, s37
	ds_read_b128 v[190:193], v235 offset:32768
	ds_read_b128 v[194:197], v235 offset:33792
	ds_read_b128 v[198:201], v235 offset:34816
	ds_read_b128 v[202:205], v235 offset:35840
	ds_read_b128 v[236:239], v235 offset:36864
	ds_read_b128 v[240:243], v235 offset:37888
	ds_read_b128 v[244:247], v235 offset:38912
	ds_read_b128 v[248:251], v235 offset:39936
	buffer_load_dwordx4 v228, s[60:63], s23 offen lds
	s_mov_b32 m0, s18
	s_nop 0
	buffer_load_dwordx4 v230, s[60:63], s23 offen lds
	s_waitcnt vmcnt(8)
	s_waitcnt lgkmcnt(0)
	s_setprio 1
	s_barrier
	v_mfma_f32_16x16x32_bf16 v[126:129], v[130:133], v[190:193], v[126:129]
	v_mfma_f32_16x16x32_bf16 v[126:129], v[140:143], v[194:197], v[126:129]
	v_mfma_f32_16x16x32_bf16 v[114:117], v[130:133], v[198:201], v[114:117]
	v_mfma_f32_16x16x32_bf16 v[114:117], v[140:143], v[202:205], v[114:117]
	v_mfma_f32_16x16x32_bf16 v[98:101], v[130:133], v[236:239], v[98:101]
	v_mfma_f32_16x16x32_bf16 v[98:101], v[140:143], v[240:243], v[98:101]
	v_mfma_f32_16x16x32_bf16 v[82:85], v[130:133], v[244:247], v[82:85]
	v_mfma_f32_16x16x32_bf16 v[82:85], v[140:143], v[248:251], v[82:85]
	v_mfma_f32_16x16x32_bf16 v[74:77], v[154:157], v[244:247], v[74:77]
	v_mfma_f32_16x16x32_bf16 v[74:77], v[170:173], v[248:251], v[74:77]
	v_mfma_f32_16x16x32_bf16 v[90:93], v[154:157], v[236:239], v[90:93]
	v_mfma_f32_16x16x32_bf16 v[90:93], v[170:173], v[240:243], v[90:93]
	v_mfma_f32_16x16x32_bf16 v[106:109], v[154:157], v[198:201], v[106:109]
	v_mfma_f32_16x16x32_bf16 v[106:109], v[170:173], v[202:205], v[106:109]
	v_mfma_f32_16x16x32_bf16 v[122:125], v[154:157], v[190:193], v[122:125]
	v_mfma_f32_16x16x32_bf16 v[122:125], v[170:173], v[194:197], v[122:125]
	v_mfma_f32_16x16x32_bf16 v[110:113], v[182:185], v[190:193], v[110:113]
	v_mfma_f32_16x16x32_bf16 v[110:113], v[186:189], v[194:197], v[110:113]
	v_mfma_f32_16x16x32_bf16 v[94:97], v[182:185], v[198:201], v[94:97]
	v_mfma_f32_16x16x32_bf16 v[94:97], v[186:189], v[202:205], v[94:97]
	v_mfma_f32_16x16x32_bf16 v[78:81], v[182:185], v[236:239], v[78:81]
	v_mfma_f32_16x16x32_bf16 v[78:81], v[186:189], v[240:243], v[78:81]
	v_mfma_f32_16x16x32_bf16 v[66:69], v[182:185], v[244:247], v[66:69]
	v_mfma_f32_16x16x32_bf16 v[66:69], v[186:189], v[248:251], v[66:69]
	v_mfma_f32_16x16x32_bf16 v[70:73], v[174:177], v[244:247], v[70:73]
	v_mfma_f32_16x16x32_bf16 v[70:73], v[178:181], v[248:251], v[70:73]
	v_mfma_f32_16x16x32_bf16 v[86:89], v[174:177], v[236:239], v[86:89]
	v_mfma_f32_16x16x32_bf16 v[86:89], v[178:181], v[240:243], v[86:89]
	v_mfma_f32_16x16x32_bf16 v[102:105], v[174:177], v[198:201], v[102:105]
	v_mfma_f32_16x16x32_bf16 v[102:105], v[178:181], v[202:205], v[102:105]
	v_mfma_f32_16x16x32_bf16 v[118:121], v[174:177], v[190:193], v[118:121]
	v_mfma_f32_16x16x32_bf16 v[118:121], v[178:181], v[194:197], v[118:121]
	s_barrier
	s_setprio 0
	s_or_b32 s23, s22, 0x80
	s_mov_b32 m0, s24
	ds_read_b128 v[190:193], v235 offset:49152
	buffer_load_dwordx4 v229, s[44:47], s23 offen lds
	s_add_i32 s22, s22, 0x80080
	s_mov_b32 m0, s25
	ds_read_b128 v[194:197], v235 offset:50176
	buffer_load_dwordx4 v231, s[44:47], s23 offen lds
	s_mov_b32 m0, s64
	ds_read_b128 v[198:201], v235 offset:51200
	buffer_load_dwordx4 v229, s[44:47], s22 offen lds
	s_mov_b32 m0, s65
	ds_read_b128 v[202:205], v235 offset:52224
	buffer_load_dwordx4 v231, s[44:47], s22 offen lds
	s_mov_b32 m0, s48
	ds_read_b128 v[236:239], v235 offset:53248
	buffer_load_dwordx4 v228, s[60:63], s21 offen lds
	s_mov_b32 m0, s49
	ds_read_b128 v[240:243], v235 offset:54272
	buffer_load_dwordx4 v230, s[60:63], s21 offen lds
	ds_read_b128 v[244:247], v235 offset:55296
	ds_read_b128 v[248:251], v235 offset:56320
	s_waitcnt vmcnt(8)
	s_waitcnt lgkmcnt(0)
	s_setprio 1
	s_barrier
	v_mfma_f32_16x16x32_bf16 v[62:65], v[130:133], v[190:193], v[62:65]
	v_mfma_f32_16x16x32_bf16 v[62:65], v[140:143], v[194:197], v[62:65]
	v_mfma_f32_16x16x32_bf16 v[50:53], v[130:133], v[198:201], v[50:53]
	v_mfma_f32_16x16x32_bf16 v[50:53], v[140:143], v[202:205], v[50:53]
	v_mfma_f32_16x16x32_bf16 v[34:37], v[130:133], v[236:239], v[34:37]
	v_mfma_f32_16x16x32_bf16 v[34:37], v[140:143], v[240:243], v[34:37]
	v_mfma_f32_16x16x32_bf16 v[18:21], v[130:133], v[244:247], v[18:21]
	v_mfma_f32_16x16x32_bf16 v[18:21], v[140:143], v[248:251], v[18:21]
	v_mfma_f32_16x16x32_bf16 v[10:13], v[154:157], v[244:247], v[10:13]
	v_mfma_f32_16x16x32_bf16 v[10:13], v[170:173], v[248:251], v[10:13]
	v_mfma_f32_16x16x32_bf16 v[26:29], v[154:157], v[236:239], v[26:29]
	v_mfma_f32_16x16x32_bf16 v[26:29], v[170:173], v[240:243], v[26:29]
	v_mfma_f32_16x16x32_bf16 v[42:45], v[154:157], v[198:201], v[42:45]
	v_mfma_f32_16x16x32_bf16 v[42:45], v[170:173], v[202:205], v[42:45]
	v_mfma_f32_16x16x32_bf16 v[58:61], v[154:157], v[190:193], v[58:61]
	v_mfma_f32_16x16x32_bf16 v[58:61], v[170:173], v[194:197], v[58:61]
	v_mfma_f32_16x16x32_bf16 v[46:49], v[182:185], v[190:193], v[46:49]
	v_mfma_f32_16x16x32_bf16 v[46:49], v[186:189], v[194:197], v[46:49]
	v_mfma_f32_16x16x32_bf16 v[30:33], v[182:185], v[198:201], v[30:33]
	v_mfma_f32_16x16x32_bf16 v[30:33], v[186:189], v[202:205], v[30:33]
	v_mfma_f32_16x16x32_bf16 v[14:17], v[182:185], v[236:239], v[14:17]
	v_mfma_f32_16x16x32_bf16 v[14:17], v[186:189], v[240:243], v[14:17]
	v_mfma_f32_16x16x32_bf16 v[2:5], v[182:185], v[244:247], v[2:5]
	v_mfma_f32_16x16x32_bf16 v[2:5], v[186:189], v[248:251], v[2:5]
	v_mfma_f32_16x16x32_bf16 v[6:9], v[174:177], v[244:247], v[6:9]
	v_mfma_f32_16x16x32_bf16 v[6:9], v[178:181], v[248:251], v[6:9]
	v_mfma_f32_16x16x32_bf16 v[22:25], v[174:177], v[236:239], v[22:25]
	v_mfma_f32_16x16x32_bf16 v[22:25], v[178:181], v[240:243], v[22:25]
	v_mfma_f32_16x16x32_bf16 v[38:41], v[174:177], v[198:201], v[38:41]
	v_mfma_f32_16x16x32_bf16 v[38:41], v[178:181], v[202:205], v[38:41]
	v_mfma_f32_16x16x32_bf16 v[54:57], v[174:177], v[190:193], v[54:57]
	v_mfma_f32_16x16x32_bf16 v[54:57], v[178:181], v[194:197], v[54:57]
	s_barrier
	s_setprio 0
	s_add_i32 s16, s16, 2
	s_addk_i32 s12, 0x100
	s_addk_i32 s13, 0x100
	s_cmp_gt_u32 s16, 29
.LBB0_881:
	v_add_u32_e32 v139, 0x10000, v234
	ds_read_b128 v[130:133], v139
	ds_read_b128 v[140:143], v139 offset:1024
	ds_read_b128 v[170:173], v139 offset:2048
	ds_read_b128 v[174:177], v139 offset:3072
	v_add_u32_e32 v139, 0x14000, v234
	ds_read_b128 v[178:181], v139
	ds_read_b128 v[182:185], v139 offset:1024
	ds_read_b128 v[186:189], v139 offset:2048
	ds_read_b128 v[190:193], v139 offset:3072
	s_add_i32 s21, s12, 0xfff80080
	s_cmp_eq_u32 s16, 28
	s_cselect_b32 s23, s8, s21
	s_cselect_b32 s22, s9, s13
	s_or_b32 s21, s23, 0x80
	s_mov_b32 m0, s72
	ds_read_b128 v[194:197], v235
	ds_read_b128 v[198:201], v235 offset:1024
	ds_read_b128 v[202:205], v235 offset:2048
	ds_read_b128 v[236:239], v235 offset:3072
	ds_read_b128 v[240:243], v235 offset:4096
	ds_read_b128 v[244:247], v235 offset:5120
	ds_read_b128 v[248:251], v235 offset:6144
	ds_read_b128 v[154:157], v235 offset:7168
	buffer_load_dwordx4 v228, s[60:63], s12 offen lds
	s_mov_b32 m0, s73
	s_nop 0
	buffer_load_dwordx4 v230, s[60:63], s12 offen lds
	s_waitcnt vmcnt(8)
	s_waitcnt lgkmcnt(0)
	s_setprio 1
	s_barrier
	v_mfma_f32_16x16x32_bf16 v[126:129], v[130:133], v[194:197], v[126:129]
	v_mfma_f32_16x16x32_bf16 v[126:129], v[140:143], v[198:201], v[126:129]
	v_mfma_f32_16x16x32_bf16 v[114:117], v[130:133], v[202:205], v[114:117]
	v_mfma_f32_16x16x32_bf16 v[114:117], v[140:143], v[236:239], v[114:117]
	v_mfma_f32_16x16x32_bf16 v[98:101], v[130:133], v[240:243], v[98:101]
	v_mfma_f32_16x16x32_bf16 v[98:101], v[140:143], v[244:247], v[98:101]
	v_mfma_f32_16x16x32_bf16 v[82:85], v[130:133], v[248:251], v[82:85]
	v_mfma_f32_16x16x32_bf16 v[82:85], v[140:143], v[154:157], v[82:85]
	v_mfma_f32_16x16x32_bf16 v[74:77], v[170:173], v[248:251], v[74:77]
	v_mfma_f32_16x16x32_bf16 v[74:77], v[174:177], v[154:157], v[74:77]
	v_mfma_f32_16x16x32_bf16 v[90:93], v[170:173], v[240:243], v[90:93]
	v_mfma_f32_16x16x32_bf16 v[90:93], v[174:177], v[244:247], v[90:93]
	v_mfma_f32_16x16x32_bf16 v[106:109], v[170:173], v[202:205], v[106:109]
	v_mfma_f32_16x16x32_bf16 v[106:109], v[174:177], v[236:239], v[106:109]
	v_mfma_f32_16x16x32_bf16 v[122:125], v[170:173], v[194:197], v[122:125]
	v_mfma_f32_16x16x32_bf16 v[122:125], v[174:177], v[198:201], v[122:125]
	v_mfma_f32_16x16x32_bf16 v[110:113], v[186:189], v[194:197], v[110:113]
	v_mfma_f32_16x16x32_bf16 v[110:113], v[190:193], v[198:201], v[110:113]
	v_mfma_f32_16x16x32_bf16 v[94:97], v[186:189], v[202:205], v[94:97]
	v_mfma_f32_16x16x32_bf16 v[94:97], v[190:193], v[236:239], v[94:97]
	v_mfma_f32_16x16x32_bf16 v[78:81], v[186:189], v[240:243], v[78:81]
	v_mfma_f32_16x16x32_bf16 v[78:81], v[190:193], v[244:247], v[78:81]
	v_mfma_f32_16x16x32_bf16 v[66:69], v[186:189], v[248:251], v[66:69]
	v_mfma_f32_16x16x32_bf16 v[66:69], v[190:193], v[154:157], v[66:69]
	v_mfma_f32_16x16x32_bf16 v[70:73], v[178:181], v[248:251], v[70:73]
	v_mfma_f32_16x16x32_bf16 v[70:73], v[182:185], v[154:157], v[70:73]
	v_mfma_f32_16x16x32_bf16 v[86:89], v[178:181], v[240:243], v[86:89]
	v_mfma_f32_16x16x32_bf16 v[86:89], v[182:185], v[244:247], v[86:89]
	v_mfma_f32_16x16x32_bf16 v[102:105], v[178:181], v[202:205], v[102:105]
	v_mfma_f32_16x16x32_bf16 v[102:105], v[182:185], v[236:239], v[102:105]
	v_mfma_f32_16x16x32_bf16 v[118:121], v[178:181], v[194:197], v[118:121]
	v_mfma_f32_16x16x32_bf16 v[118:121], v[182:185], v[198:201], v[118:121]
	s_barrier
	s_setprio 0
	s_mov_b32 s46, s62
	s_mov_b32 s47, s63
	s_mov_b32 m0, s26
	ds_read_b128 v[154:157], v235 offset:16384
	buffer_load_dwordx4 v229, s[44:47], s22 offen lds
	s_add_i32 s38, s22, 0x80000
	s_mov_b32 m0, s27
	ds_read_b128 v[194:197], v235 offset:17408
	buffer_load_dwordx4 v231, s[44:47], s22 offen lds
	s_mov_b32 m0, s34
	ds_read_b128 v[198:201], v235 offset:18432
	buffer_load_dwordx4 v229, s[44:47], s38 offen lds
	s_mov_b32 m0, s35
	ds_read_b128 v[202:205], v235 offset:19456
	buffer_load_dwordx4 v231, s[44:47], s38 offen lds
	s_mov_b32 m0, s19
	ds_read_b128 v[236:239], v235 offset:20480
	buffer_load_dwordx4 v228, s[60:63], s23 offen lds
	s_mov_b32 m0, s36
	ds_read_b128 v[240:243], v235 offset:21504
	buffer_load_dwordx4 v230, s[60:63], s23 offen lds
	ds_read_b128 v[244:247], v235 offset:22528
	ds_read_b128 v[248:251], v235 offset:23552
	s_waitcnt vmcnt(8)
	s_waitcnt lgkmcnt(0)
	s_setprio 1
	s_barrier
	v_mfma_f32_16x16x32_bf16 v[62:65], v[130:133], v[154:157], v[62:65]
	v_mfma_f32_16x16x32_bf16 v[62:65], v[140:143], v[194:197], v[62:65]
	v_mfma_f32_16x16x32_bf16 v[50:53], v[130:133], v[198:201], v[50:53]
	v_mfma_f32_16x16x32_bf16 v[50:53], v[140:143], v[202:205], v[50:53]
	v_mfma_f32_16x16x32_bf16 v[34:37], v[130:133], v[236:239], v[34:37]
	v_mfma_f32_16x16x32_bf16 v[34:37], v[140:143], v[240:243], v[34:37]
	v_mfma_f32_16x16x32_bf16 v[18:21], v[130:133], v[244:247], v[18:21]
	v_mfma_f32_16x16x32_bf16 v[18:21], v[140:143], v[248:251], v[18:21]
	v_mfma_f32_16x16x32_bf16 v[10:13], v[170:173], v[244:247], v[10:13]
	v_mfma_f32_16x16x32_bf16 v[10:13], v[174:177], v[248:251], v[10:13]
	v_mfma_f32_16x16x32_bf16 v[26:29], v[170:173], v[236:239], v[26:29]
	v_mfma_f32_16x16x32_bf16 v[26:29], v[174:177], v[240:243], v[26:29]
	v_mfma_f32_16x16x32_bf16 v[42:45], v[170:173], v[198:201], v[42:45]
	v_mfma_f32_16x16x32_bf16 v[42:45], v[174:177], v[202:205], v[42:45]
	v_mfma_f32_16x16x32_bf16 v[58:61], v[170:173], v[154:157], v[58:61]
	v_mfma_f32_16x16x32_bf16 v[58:61], v[174:177], v[194:197], v[58:61]
	v_mfma_f32_16x16x32_bf16 v[46:49], v[186:189], v[154:157], v[46:49]
	v_mfma_f32_16x16x32_bf16 v[46:49], v[190:193], v[194:197], v[46:49]
	v_mfma_f32_16x16x32_bf16 v[30:33], v[186:189], v[198:201], v[30:33]
	v_mfma_f32_16x16x32_bf16 v[30:33], v[190:193], v[202:205], v[30:33]
	v_mfma_f32_16x16x32_bf16 v[14:17], v[186:189], v[236:239], v[14:17]
	v_mfma_f32_16x16x32_bf16 v[14:17], v[190:193], v[240:243], v[14:17]
	v_mfma_f32_16x16x32_bf16 v[2:5], v[186:189], v[244:247], v[2:5]
	v_mfma_f32_16x16x32_bf16 v[2:5], v[190:193], v[248:251], v[2:5]
	v_mfma_f32_16x16x32_bf16 v[6:9], v[178:181], v[244:247], v[6:9]
	v_mfma_f32_16x16x32_bf16 v[6:9], v[182:185], v[248:251], v[6:9]
	v_mfma_f32_16x16x32_bf16 v[22:25], v[178:181], v[236:239], v[22:25]
	v_mfma_f32_16x16x32_bf16 v[22:25], v[182:185], v[240:243], v[22:25]
	v_mfma_f32_16x16x32_bf16 v[38:41], v[178:181], v[198:201], v[38:41]
	v_mfma_f32_16x16x32_bf16 v[38:41], v[182:185], v[202:205], v[38:41]
	v_mfma_f32_16x16x32_bf16 v[54:57], v[178:181], v[154:157], v[54:57]
	v_mfma_f32_16x16x32_bf16 v[54:57], v[182:185], v[194:197], v[54:57]
	s_barrier
	s_setprio 0
	v_add_u32_e32 v139, 0x18000, v234
	ds_read_b128 v[130:133], v139
	ds_read_b128 v[140:143], v139 offset:1024
	ds_read_b128 v[154:157], v139 offset:2048
	ds_read_b128 v[170:173], v139 offset:3072
	v_add_u32_e32 v139, 0x1c000, v234
	ds_read_b128 v[174:177], v139
	ds_read_b128 v[178:181], v139 offset:1024
	ds_read_b128 v[182:185], v139 offset:2048
	ds_read_b128 v[186:189], v139 offset:3072
	s_add_i32 s23, s23, 0x80000
	s_mov_b32 m0, s37
	ds_read_b128 v[190:193], v235 offset:32768
	ds_read_b128 v[194:197], v235 offset:33792
	ds_read_b128 v[198:201], v235 offset:34816
	ds_read_b128 v[202:205], v235 offset:35840
	ds_read_b128 v[236:239], v235 offset:36864
	ds_read_b128 v[240:243], v235 offset:37888
	ds_read_b128 v[244:247], v235 offset:38912
	ds_read_b128 v[248:251], v235 offset:39936
	buffer_load_dwordx4 v228, s[60:63], s23 offen lds
	s_mov_b32 m0, s18
	s_nop 0
	buffer_load_dwordx4 v230, s[60:63], s23 offen lds
	s_waitcnt vmcnt(8)
	s_waitcnt lgkmcnt(0)
	s_setprio 1
	s_barrier
	v_mfma_f32_16x16x32_bf16 v[126:129], v[130:133], v[190:193], v[126:129]
	v_mfma_f32_16x16x32_bf16 v[126:129], v[140:143], v[194:197], v[126:129]
	v_mfma_f32_16x16x32_bf16 v[114:117], v[130:133], v[198:201], v[114:117]
	v_mfma_f32_16x16x32_bf16 v[114:117], v[140:143], v[202:205], v[114:117]
	v_mfma_f32_16x16x32_bf16 v[98:101], v[130:133], v[236:239], v[98:101]
	v_mfma_f32_16x16x32_bf16 v[98:101], v[140:143], v[240:243], v[98:101]
	v_mfma_f32_16x16x32_bf16 v[82:85], v[130:133], v[244:247], v[82:85]
	v_mfma_f32_16x16x32_bf16 v[82:85], v[140:143], v[248:251], v[82:85]
	v_mfma_f32_16x16x32_bf16 v[74:77], v[154:157], v[244:247], v[74:77]
	v_mfma_f32_16x16x32_bf16 v[74:77], v[170:173], v[248:251], v[74:77]
	v_mfma_f32_16x16x32_bf16 v[90:93], v[154:157], v[236:239], v[90:93]
	v_mfma_f32_16x16x32_bf16 v[90:93], v[170:173], v[240:243], v[90:93]
	v_mfma_f32_16x16x32_bf16 v[106:109], v[154:157], v[198:201], v[106:109]
	v_mfma_f32_16x16x32_bf16 v[106:109], v[170:173], v[202:205], v[106:109]
	v_mfma_f32_16x16x32_bf16 v[122:125], v[154:157], v[190:193], v[122:125]
	v_mfma_f32_16x16x32_bf16 v[122:125], v[170:173], v[194:197], v[122:125]
	v_mfma_f32_16x16x32_bf16 v[110:113], v[182:185], v[190:193], v[110:113]
	v_mfma_f32_16x16x32_bf16 v[110:113], v[186:189], v[194:197], v[110:113]
	v_mfma_f32_16x16x32_bf16 v[94:97], v[182:185], v[198:201], v[94:97]
	v_mfma_f32_16x16x32_bf16 v[94:97], v[186:189], v[202:205], v[94:97]
	v_mfma_f32_16x16x32_bf16 v[78:81], v[182:185], v[236:239], v[78:81]
	v_mfma_f32_16x16x32_bf16 v[78:81], v[186:189], v[240:243], v[78:81]
	v_mfma_f32_16x16x32_bf16 v[66:69], v[182:185], v[244:247], v[66:69]
	v_mfma_f32_16x16x32_bf16 v[66:69], v[186:189], v[248:251], v[66:69]
	v_mfma_f32_16x16x32_bf16 v[70:73], v[174:177], v[244:247], v[70:73]
	v_mfma_f32_16x16x32_bf16 v[70:73], v[178:181], v[248:251], v[70:73]
	v_mfma_f32_16x16x32_bf16 v[86:89], v[174:177], v[236:239], v[86:89]
	v_mfma_f32_16x16x32_bf16 v[86:89], v[178:181], v[240:243], v[86:89]
	v_mfma_f32_16x16x32_bf16 v[102:105], v[174:177], v[198:201], v[102:105]
	v_mfma_f32_16x16x32_bf16 v[102:105], v[178:181], v[202:205], v[102:105]
	v_mfma_f32_16x16x32_bf16 v[118:121], v[174:177], v[190:193], v[118:121]
	v_mfma_f32_16x16x32_bf16 v[118:121], v[178:181], v[194:197], v[118:121]
	s_barrier
	s_setprio 0
	s_or_b32 s23, s22, 0x80
	s_mov_b32 m0, s24
	ds_read_b128 v[190:193], v235 offset:49152
	buffer_load_dwordx4 v229, s[44:47], s23 offen lds
	s_add_i32 s22, s22, 0x80080
	s_mov_b32 m0, s25
	ds_read_b128 v[194:197], v235 offset:50176
	buffer_load_dwordx4 v231, s[44:47], s23 offen lds
	s_mov_b32 m0, s64
	ds_read_b128 v[198:201], v235 offset:51200
	buffer_load_dwordx4 v229, s[44:47], s22 offen lds
	s_mov_b32 m0, s65
	ds_read_b128 v[202:205], v235 offset:52224
	buffer_load_dwordx4 v231, s[44:47], s22 offen lds
	s_mov_b32 m0, s48
	ds_read_b128 v[236:239], v235 offset:53248
	buffer_load_dwordx4 v228, s[60:63], s21 offen lds
	s_mov_b32 m0, s49
	ds_read_b128 v[240:243], v235 offset:54272
	buffer_load_dwordx4 v230, s[60:63], s21 offen lds
	ds_read_b128 v[244:247], v235 offset:55296
	ds_read_b128 v[248:251], v235 offset:56320
	s_waitcnt vmcnt(8)
	s_waitcnt lgkmcnt(0)
	s_setprio 1
	s_barrier
	v_mfma_f32_16x16x32_bf16 v[62:65], v[130:133], v[190:193], v[62:65]
	v_mfma_f32_16x16x32_bf16 v[62:65], v[140:143], v[194:197], v[62:65]
	v_mfma_f32_16x16x32_bf16 v[50:53], v[130:133], v[198:201], v[50:53]
	v_mfma_f32_16x16x32_bf16 v[50:53], v[140:143], v[202:205], v[50:53]
	v_mfma_f32_16x16x32_bf16 v[34:37], v[130:133], v[236:239], v[34:37]
	v_mfma_f32_16x16x32_bf16 v[34:37], v[140:143], v[240:243], v[34:37]
	v_mfma_f32_16x16x32_bf16 v[18:21], v[130:133], v[244:247], v[18:21]
	v_mfma_f32_16x16x32_bf16 v[18:21], v[140:143], v[248:251], v[18:21]
	v_mfma_f32_16x16x32_bf16 v[10:13], v[154:157], v[244:247], v[10:13]
	v_mfma_f32_16x16x32_bf16 v[10:13], v[170:173], v[248:251], v[10:13]
	v_mfma_f32_16x16x32_bf16 v[26:29], v[154:157], v[236:239], v[26:29]
	v_mfma_f32_16x16x32_bf16 v[26:29], v[170:173], v[240:243], v[26:29]
	v_mfma_f32_16x16x32_bf16 v[42:45], v[154:157], v[198:201], v[42:45]
	v_mfma_f32_16x16x32_bf16 v[42:45], v[170:173], v[202:205], v[42:45]
	v_mfma_f32_16x16x32_bf16 v[58:61], v[154:157], v[190:193], v[58:61]
	v_mfma_f32_16x16x32_bf16 v[58:61], v[170:173], v[194:197], v[58:61]
	v_mfma_f32_16x16x32_bf16 v[46:49], v[182:185], v[190:193], v[46:49]
	v_mfma_f32_16x16x32_bf16 v[46:49], v[186:189], v[194:197], v[46:49]
	v_mfma_f32_16x16x32_bf16 v[30:33], v[182:185], v[198:201], v[30:33]
	v_mfma_f32_16x16x32_bf16 v[30:33], v[186:189], v[202:205], v[30:33]
	v_mfma_f32_16x16x32_bf16 v[14:17], v[182:185], v[236:239], v[14:17]
	v_mfma_f32_16x16x32_bf16 v[14:17], v[186:189], v[240:243], v[14:17]
	v_mfma_f32_16x16x32_bf16 v[2:5], v[182:185], v[244:247], v[2:5]
	v_mfma_f32_16x16x32_bf16 v[2:5], v[186:189], v[248:251], v[2:5]
	v_mfma_f32_16x16x32_bf16 v[6:9], v[174:177], v[244:247], v[6:9]
	v_mfma_f32_16x16x32_bf16 v[6:9], v[178:181], v[248:251], v[6:9]
	v_mfma_f32_16x16x32_bf16 v[22:25], v[174:177], v[236:239], v[22:25]
	v_mfma_f32_16x16x32_bf16 v[22:25], v[178:181], v[240:243], v[22:25]
	v_mfma_f32_16x16x32_bf16 v[38:41], v[174:177], v[198:201], v[38:41]
	v_mfma_f32_16x16x32_bf16 v[38:41], v[178:181], v[202:205], v[38:41]
	v_mfma_f32_16x16x32_bf16 v[54:57], v[174:177], v[190:193], v[54:57]
	v_mfma_f32_16x16x32_bf16 v[54:57], v[178:181], v[194:197], v[54:57]
	s_barrier
	s_setprio 0
	s_add_i32 s16, s16, 2
	s_addk_i32 s12, 0x100
	s_addk_i32 s13, 0x100
	s_cmp_gt_u32 s16, 29
	s_cbranch_scc0 .LBB0_881
	v_readlane_b32 s8, v255, 44
	v_readlane_b32 s9, v255, 45
	s_and_b64 vcc, exec, s[8:9]
	s_cbranch_vccz .LBB0_884
	s_barrier

.LBB0_904:
	s_lshl_b32 s73, s72, 20
	s_and_b64 s[8:9], s[42:43], exec
	s_cselect_b32 s8, s73, s13
	s_lshl_b32 s84, s71, 20
	s_and_b64 s[22:23], s[42:43], exec
	s_cselect_b32 s9, s84, s21
	s_add_i32 s13, s13, 0x80080
	s_addk_i32 s21, 0x100
	s_mov_b32 s22, -2
	v_add_u32_e32 v133, 0x10000, v178
	ds_read_b128 v[134:137], v133
	ds_read_b128 v[138:141], v133 offset:1024
	ds_read_b128 v[142:145], v133 offset:2048
	ds_read_b128 v[154:157], v133 offset:3072
	v_add_u32_e32 v133, 0x14000, v178
	ds_read_b128 v[170:173], v133
	ds_read_b128 v[180:183], v133 offset:1024
	ds_read_b128 v[184:187], v133 offset:2048
	ds_read_b128 v[188:191], v133 offset:3072
	s_add_i32 s23, s13, 0xfff80080
	s_cmp_eq_u32 s22, 28
	s_cselect_b32 s27, s8, s23
	s_cselect_b32 s26, s9, s21
	s_or_b32 s23, s27, 0x80
	s_mov_b32 s46, s62
	s_mov_b32 s47, s63
	s_mov_b32 m0, s68
	ds_read_b128 v[192:195], v179
	ds_read_b128 v[196:199], v179 offset:1024
	ds_read_b128 v[200:203], v179 offset:2048
	ds_read_b128 v[204:207], v179 offset:3072
	ds_read_b128 v[228:231], v179 offset:4096
	ds_read_b128 v[232:235], v179 offset:5120
	ds_read_b128 v[236:239], v179 offset:6144
	ds_read_b128 v[240:243], v179 offset:7168
	buffer_load_dwordx4 v174, s[44:47], s13 offen lds
	s_mov_b32 m0, s69
	s_nop 0
	buffer_load_dwordx4 v176, s[44:47], s13 offen lds
	s_waitcnt vmcnt(8)
	s_waitcnt lgkmcnt(0)
	s_setprio 1
	s_barrier
	v_mfma_f32_16x16x32_bf16 v[126:129], v[134:137], v[192:195], 0
	v_mfma_f32_16x16x32_bf16 v[126:129], v[138:141], v[196:199], v[126:129]
	v_mfma_f32_16x16x32_bf16 v[110:113], v[134:137], v[200:203], 0
	v_mfma_f32_16x16x32_bf16 v[110:113], v[138:141], v[204:207], v[110:113]
	v_mfma_f32_16x16x32_bf16 v[94:97], v[134:137], v[228:231], 0
	v_mfma_f32_16x16x32_bf16 v[94:97], v[138:141], v[232:235], v[94:97]
	v_mfma_f32_16x16x32_bf16 v[78:81], v[134:137], v[236:239], 0
	v_mfma_f32_16x16x32_bf16 v[78:81], v[138:141], v[240:243], v[78:81]
	v_mfma_f32_16x16x32_bf16 v[74:77], v[142:145], v[236:239], 0
	v_mfma_f32_16x16x32_bf16 v[74:77], v[154:157], v[240:243], v[74:77]
	v_mfma_f32_16x16x32_bf16 v[90:93], v[142:145], v[228:231], 0
	v_mfma_f32_16x16x32_bf16 v[90:93], v[154:157], v[232:235], v[90:93]
	v_mfma_f32_16x16x32_bf16 v[106:109], v[142:145], v[200:203], 0
	v_mfma_f32_16x16x32_bf16 v[106:109], v[154:157], v[204:207], v[106:109]
	v_mfma_f32_16x16x32_bf16 v[122:125], v[142:145], v[192:195], 0
	v_mfma_f32_16x16x32_bf16 v[122:125], v[154:157], v[196:199], v[122:125]
	v_mfma_f32_16x16x32_bf16 v[114:117], v[184:187], v[192:195], 0
	v_mfma_f32_16x16x32_bf16 v[114:117], v[188:191], v[196:199], v[114:117]
	v_mfma_f32_16x16x32_bf16 v[98:101], v[184:187], v[200:203], 0
	v_mfma_f32_16x16x32_bf16 v[98:101], v[188:191], v[204:207], v[98:101]
	v_mfma_f32_16x16x32_bf16 v[82:85], v[184:187], v[228:231], 0
	v_mfma_f32_16x16x32_bf16 v[82:85], v[188:191], v[232:235], v[82:85]
	v_mfma_f32_16x16x32_bf16 v[66:69], v[184:187], v[236:239], 0
	v_mfma_f32_16x16x32_bf16 v[66:69], v[188:191], v[240:243], v[66:69]
	v_mfma_f32_16x16x32_bf16 v[70:73], v[170:173], v[236:239], 0
	v_mfma_f32_16x16x32_bf16 v[70:73], v[180:183], v[240:243], v[70:73]
	v_mfma_f32_16x16x32_bf16 v[86:89], v[170:173], v[228:231], 0
	v_mfma_f32_16x16x32_bf16 v[86:89], v[180:183], v[232:235], v[86:89]
	v_mfma_f32_16x16x32_bf16 v[102:105], v[170:173], v[200:203], 0
	v_mfma_f32_16x16x32_bf16 v[102:105], v[180:183], v[204:207], v[102:105]
	v_mfma_f32_16x16x32_bf16 v[118:121], v[170:173], v[192:195], 0
	v_mfma_f32_16x16x32_bf16 v[118:121], v[180:183], v[196:199], v[118:121]
	s_barrier
	s_setprio 0
	s_mov_b32 m0, s15
	ds_read_b128 v[192:195], v179 offset:16384
	buffer_load_dwordx4 v175, s[60:63], s26 offen lds
	s_add_i32 s34, s26, 0x80000
	s_mov_b32 m0, s16
	ds_read_b128 v[196:199], v179 offset:17408
	buffer_load_dwordx4 v177, s[60:63], s26 offen lds
	s_mov_b32 m0, s18
	ds_read_b128 v[200:203], v179 offset:18432
	buffer_load_dwordx4 v175, s[60:63], s34 offen lds
	s_mov_b32 m0, s19
	ds_read_b128 v[204:207], v179 offset:19456
	buffer_load_dwordx4 v177, s[60:63], s34 offen lds
	s_mov_b32 m0, s14
	ds_read_b128 v[228:231], v179 offset:20480
	buffer_load_dwordx4 v174, s[44:47], s27 offen lds
	s_mov_b32 m0, s24
	ds_read_b128 v[232:235], v179 offset:21504
	buffer_load_dwordx4 v176, s[44:47], s27 offen lds
	ds_read_b128 v[236:239], v179 offset:22528
	ds_read_b128 v[240:243], v179 offset:23552
	s_waitcnt vmcnt(8)
	s_waitcnt lgkmcnt(0)
	s_setprio 1
	s_barrier
	v_mfma_f32_16x16x32_bf16 v[62:65], v[134:137], v[192:195], 0
	v_mfma_f32_16x16x32_bf16 v[62:65], v[138:141], v[196:199], v[62:65]
	v_mfma_f32_16x16x32_bf16 v[46:49], v[134:137], v[200:203], 0
	v_mfma_f32_16x16x32_bf16 v[46:49], v[138:141], v[204:207], v[46:49]
	v_mfma_f32_16x16x32_bf16 v[30:33], v[134:137], v[228:231], 0
	v_mfma_f32_16x16x32_bf16 v[30:33], v[138:141], v[232:235], v[30:33]
	v_mfma_f32_16x16x32_bf16 v[14:17], v[134:137], v[236:239], 0
	v_mfma_f32_16x16x32_bf16 v[14:17], v[138:141], v[240:243], v[14:17]
	v_mfma_f32_16x16x32_bf16 v[10:13], v[142:145], v[236:239], 0
	v_mfma_f32_16x16x32_bf16 v[10:13], v[154:157], v[240:243], v[10:13]
	v_mfma_f32_16x16x32_bf16 v[26:29], v[142:145], v[228:231], 0
	v_mfma_f32_16x16x32_bf16 v[26:29], v[154:157], v[232:235], v[26:29]
	v_mfma_f32_16x16x32_bf16 v[42:45], v[142:145], v[200:203], 0
	v_mfma_f32_16x16x32_bf16 v[42:45], v[154:157], v[204:207], v[42:45]
	v_mfma_f32_16x16x32_bf16 v[58:61], v[142:145], v[192:195], 0
	v_mfma_f32_16x16x32_bf16 v[58:61], v[154:157], v[196:199], v[58:61]
	v_mfma_f32_16x16x32_bf16 v[50:53], v[184:187], v[192:195], 0
	v_mfma_f32_16x16x32_bf16 v[50:53], v[188:191], v[196:199], v[50:53]
	v_mfma_f32_16x16x32_bf16 v[34:37], v[184:187], v[200:203], 0
	v_mfma_f32_16x16x32_bf16 v[34:37], v[188:191], v[204:207], v[34:37]
	v_mfma_f32_16x16x32_bf16 v[18:21], v[184:187], v[228:231], 0
	v_mfma_f32_16x16x32_bf16 v[18:21], v[188:191], v[232:235], v[18:21]
	v_mfma_f32_16x16x32_bf16 v[2:5], v[184:187], v[236:239], 0
	v_mfma_f32_16x16x32_bf16 v[2:5], v[188:191], v[240:243], v[2:5]
	v_mfma_f32_16x16x32_bf16 v[6:9], v[170:173], v[236:239], 0
	v_mfma_f32_16x16x32_bf16 v[6:9], v[180:183], v[240:243], v[6:9]
	v_mfma_f32_16x16x32_bf16 v[22:25], v[170:173], v[228:231], 0
	v_mfma_f32_16x16x32_bf16 v[22:25], v[180:183], v[232:235], v[22:25]
	v_mfma_f32_16x16x32_bf16 v[38:41], v[170:173], v[200:203], 0
	v_mfma_f32_16x16x32_bf16 v[38:41], v[180:183], v[204:207], v[38:41]
	v_mfma_f32_16x16x32_bf16 v[54:57], v[170:173], v[192:195], 0
	v_mfma_f32_16x16x32_bf16 v[54:57], v[180:183], v[196:199], v[54:57]
	s_barrier
	s_setprio 0
	v_add_u32_e32 v133, 0x18000, v178
	ds_read_b128 v[134:137], v133
	ds_read_b128 v[138:141], v133 offset:1024
	ds_read_b128 v[142:145], v133 offset:2048
	ds_read_b128 v[154:157], v133 offset:3072
	v_add_u32_e32 v133, 0x1c000, v178
	ds_read_b128 v[170:173], v133
	ds_read_b128 v[180:183], v133 offset:1024
	ds_read_b128 v[184:187], v133 offset:2048
	ds_read_b128 v[188:191], v133 offset:3072
	s_add_i32 s27, s27, 0x80000
	s_mov_b32 m0, s25
	ds_read_b128 v[192:195], v179 offset:32768
	ds_read_b128 v[196:199], v179 offset:33792
	ds_read_b128 v[200:203], v179 offset:34816
	ds_read_b128 v[204:207], v179 offset:35840
	ds_read_b128 v[228:231], v179 offset:36864
	ds_read_b128 v[232:235], v179 offset:37888
	ds_read_b128 v[236:239], v179 offset:38912
	ds_read_b128 v[240:243], v179 offset:39936
	buffer_load_dwordx4 v174, s[44:47], s27 offen lds
	s_mov_b32 m0, s30
	s_nop 0
	buffer_load_dwordx4 v176, s[44:47], s27 offen lds
	s_waitcnt vmcnt(8)
	s_waitcnt lgkmcnt(0)
	s_setprio 1
	s_barrier
	v_mfma_f32_16x16x32_bf16 v[126:129], v[134:137], v[192:195], v[126:129]
	v_mfma_f32_16x16x32_bf16 v[126:129], v[138:141], v[196:199], v[126:129]
	v_mfma_f32_16x16x32_bf16 v[110:113], v[134:137], v[200:203], v[110:113]
	v_mfma_f32_16x16x32_bf16 v[110:113], v[138:141], v[204:207], v[110:113]
	v_mfma_f32_16x16x32_bf16 v[94:97], v[134:137], v[228:231], v[94:97]
	v_mfma_f32_16x16x32_bf16 v[94:97], v[138:141], v[232:235], v[94:97]
	v_mfma_f32_16x16x32_bf16 v[78:81], v[134:137], v[236:239], v[78:81]
	v_mfma_f32_16x16x32_bf16 v[78:81], v[138:141], v[240:243], v[78:81]
	v_mfma_f32_16x16x32_bf16 v[74:77], v[142:145], v[236:239], v[74:77]
	v_mfma_f32_16x16x32_bf16 v[74:77], v[154:157], v[240:243], v[74:77]
	v_mfma_f32_16x16x32_bf16 v[90:93], v[142:145], v[228:231], v[90:93]
	v_mfma_f32_16x16x32_bf16 v[90:93], v[154:157], v[232:235], v[90:93]
	v_mfma_f32_16x16x32_bf16 v[106:109], v[142:145], v[200:203], v[106:109]
	v_mfma_f32_16x16x32_bf16 v[106:109], v[154:157], v[204:207], v[106:109]
	v_mfma_f32_16x16x32_bf16 v[122:125], v[142:145], v[192:195], v[122:125]
	v_mfma_f32_16x16x32_bf16 v[122:125], v[154:157], v[196:199], v[122:125]
	v_mfma_f32_16x16x32_bf16 v[114:117], v[184:187], v[192:195], v[114:117]
	v_mfma_f32_16x16x32_bf16 v[114:117], v[188:191], v[196:199], v[114:117]
	v_mfma_f32_16x16x32_bf16 v[98:101], v[184:187], v[200:203], v[98:101]
	v_mfma_f32_16x16x32_bf16 v[98:101], v[188:191], v[204:207], v[98:101]
	v_mfma_f32_16x16x32_bf16 v[82:85], v[184:187], v[228:231], v[82:85]
	v_mfma_f32_16x16x32_bf16 v[82:85], v[188:191], v[232:235], v[82:85]
	v_mfma_f32_16x16x32_bf16 v[66:69], v[184:187], v[236:239], v[66:69]
	v_mfma_f32_16x16x32_bf16 v[66:69], v[188:191], v[240:243], v[66:69]
	v_mfma_f32_16x16x32_bf16 v[70:73], v[170:173], v[236:239], v[70:73]
	v_mfma_f32_16x16x32_bf16 v[70:73], v[180:183], v[240:243], v[70:73]
	v_mfma_f32_16x16x32_bf16 v[86:89], v[170:173], v[228:231], v[86:89]
	v_mfma_f32_16x16x32_bf16 v[86:89], v[180:183], v[232:235], v[86:89]
	v_mfma_f32_16x16x32_bf16 v[102:105], v[170:173], v[200:203], v[102:105]
	v_mfma_f32_16x16x32_bf16 v[102:105], v[180:183], v[204:207], v[102:105]
	v_mfma_f32_16x16x32_bf16 v[118:121], v[170:173], v[192:195], v[118:121]
	v_mfma_f32_16x16x32_bf16 v[118:121], v[180:183], v[196:199], v[118:121]
	s_barrier
	s_setprio 0
	s_or_b32 s27, s26, 0x80
	s_mov_b32 m0, s36
	ds_read_b128 v[192:195], v179 offset:49152
	buffer_load_dwordx4 v175, s[60:63], s27 offen lds
	s_add_i32 s26, s26, 0x80080
	s_mov_b32 m0, s37
	ds_read_b128 v[196:199], v179 offset:50176
	buffer_load_dwordx4 v177, s[60:63], s27 offen lds
	s_mov_b32 m0, s48
	ds_read_b128 v[200:203], v179 offset:51200
	buffer_load_dwordx4 v175, s[60:63], s26 offen lds
	s_mov_b32 m0, s49
	ds_read_b128 v[204:207], v179 offset:52224
	buffer_load_dwordx4 v177, s[60:63], s26 offen lds
	s_mov_b32 m0, s40
	ds_read_b128 v[228:231], v179 offset:53248
	buffer_load_dwordx4 v174, s[44:47], s23 offen lds
	s_mov_b32 m0, s41
	ds_read_b128 v[232:235], v179 offset:54272
	buffer_load_dwordx4 v176, s[44:47], s23 offen lds
	ds_read_b128 v[236:239], v179 offset:55296
	ds_read_b128 v[240:243], v179 offset:56320
	s_waitcnt vmcnt(8)
	s_waitcnt lgkmcnt(0)
	s_setprio 1
	s_barrier
	v_mfma_f32_16x16x32_bf16 v[62:65], v[134:137], v[192:195], v[62:65]
	v_mfma_f32_16x16x32_bf16 v[62:65], v[138:141], v[196:199], v[62:65]
	v_mfma_f32_16x16x32_bf16 v[46:49], v[134:137], v[200:203], v[46:49]
	v_mfma_f32_16x16x32_bf16 v[46:49], v[138:141], v[204:207], v[46:49]
	v_mfma_f32_16x16x32_bf16 v[30:33], v[134:137], v[228:231], v[30:33]
	v_mfma_f32_16x16x32_bf16 v[30:33], v[138:141], v[232:235], v[30:33]
	v_mfma_f32_16x16x32_bf16 v[14:17], v[134:137], v[236:239], v[14:17]
	v_mfma_f32_16x16x32_bf16 v[14:17], v[138:141], v[240:243], v[14:17]
	v_mfma_f32_16x16x32_bf16 v[10:13], v[142:145], v[236:239], v[10:13]
	v_mfma_f32_16x16x32_bf16 v[10:13], v[154:157], v[240:243], v[10:13]
	v_mfma_f32_16x16x32_bf16 v[26:29], v[142:145], v[228:231], v[26:29]
	v_mfma_f32_16x16x32_bf16 v[26:29], v[154:157], v[232:235], v[26:29]
	v_mfma_f32_16x16x32_bf16 v[42:45], v[142:145], v[200:203], v[42:45]
	v_mfma_f32_16x16x32_bf16 v[42:45], v[154:157], v[204:207], v[42:45]
	v_mfma_f32_16x16x32_bf16 v[58:61], v[142:145], v[192:195], v[58:61]
	v_mfma_f32_16x16x32_bf16 v[58:61], v[154:157], v[196:199], v[58:61]
	v_mfma_f32_16x16x32_bf16 v[50:53], v[184:187], v[192:195], v[50:53]
	v_mfma_f32_16x16x32_bf16 v[50:53], v[188:191], v[196:199], v[50:53]
	v_mfma_f32_16x16x32_bf16 v[34:37], v[184:187], v[200:203], v[34:37]
	v_mfma_f32_16x16x32_bf16 v[34:37], v[188:191], v[204:207], v[34:37]
	v_mfma_f32_16x16x32_bf16 v[18:21], v[184:187], v[228:231], v[18:21]
	v_mfma_f32_16x16x32_bf16 v[18:21], v[188:191], v[232:235], v[18:21]
	v_mfma_f32_16x16x32_bf16 v[2:5], v[184:187], v[236:239], v[2:5]
	v_mfma_f32_16x16x32_bf16 v[2:5], v[188:191], v[240:243], v[2:5]
	v_mfma_f32_16x16x32_bf16 v[6:9], v[170:173], v[236:239], v[6:9]
	v_mfma_f32_16x16x32_bf16 v[6:9], v[180:183], v[240:243], v[6:9]
	v_mfma_f32_16x16x32_bf16 v[22:25], v[170:173], v[228:231], v[22:25]
	v_mfma_f32_16x16x32_bf16 v[22:25], v[180:183], v[232:235], v[22:25]
	v_mfma_f32_16x16x32_bf16 v[38:41], v[170:173], v[200:203], v[38:41]
	v_mfma_f32_16x16x32_bf16 v[38:41], v[180:183], v[204:207], v[38:41]
	v_mfma_f32_16x16x32_bf16 v[54:57], v[170:173], v[192:195], v[54:57]
	v_mfma_f32_16x16x32_bf16 v[54:57], v[180:183], v[196:199], v[54:57]
	s_barrier
	s_setprio 0
	s_add_i32 s22, s22, 2
	s_addk_i32 s13, 0x100
	s_addk_i32 s21, 0x100
	s_cmp_gt_u32 s22, 29
.LBB0_905:
	v_add_u32_e32 v133, 0x10000, v178
	ds_read_b128 v[134:137], v133
	ds_read_b128 v[138:141], v133 offset:1024
	ds_read_b128 v[142:145], v133 offset:2048
	ds_read_b128 v[154:157], v133 offset:3072
	v_add_u32_e32 v133, 0x14000, v178
	ds_read_b128 v[170:173], v133
	ds_read_b128 v[180:183], v133 offset:1024
	ds_read_b128 v[184:187], v133 offset:2048
	ds_read_b128 v[188:191], v133 offset:3072
	s_add_i32 s23, s13, 0xfff80080
	s_cmp_eq_u32 s22, 28
	s_cselect_b32 s27, s8, s23
	s_cselect_b32 s26, s9, s21
	s_or_b32 s23, s27, 0x80
	s_mov_b32 s46, s62
	s_mov_b32 s47, s63
	s_mov_b32 m0, s68
	ds_read_b128 v[192:195], v179
	ds_read_b128 v[196:199], v179 offset:1024
	ds_read_b128 v[200:203], v179 offset:2048
	ds_read_b128 v[204:207], v179 offset:3072
	ds_read_b128 v[228:231], v179 offset:4096
	ds_read_b128 v[232:235], v179 offset:5120
	ds_read_b128 v[236:239], v179 offset:6144
	ds_read_b128 v[240:243], v179 offset:7168
	buffer_load_dwordx4 v174, s[44:47], s13 offen lds
	s_mov_b32 m0, s69
	s_nop 0
	buffer_load_dwordx4 v176, s[44:47], s13 offen lds
	s_waitcnt vmcnt(8)
	s_waitcnt lgkmcnt(0)
	s_setprio 1
	s_barrier
	v_mfma_f32_16x16x32_bf16 v[126:129], v[134:137], v[192:195], v[126:129]
	v_mfma_f32_16x16x32_bf16 v[126:129], v[138:141], v[196:199], v[126:129]
	v_mfma_f32_16x16x32_bf16 v[110:113], v[134:137], v[200:203], v[110:113]
	v_mfma_f32_16x16x32_bf16 v[110:113], v[138:141], v[204:207], v[110:113]
	v_mfma_f32_16x16x32_bf16 v[94:97], v[134:137], v[228:231], v[94:97]
	v_mfma_f32_16x16x32_bf16 v[94:97], v[138:141], v[232:235], v[94:97]
	v_mfma_f32_16x16x32_bf16 v[78:81], v[134:137], v[236:239], v[78:81]
	v_mfma_f32_16x16x32_bf16 v[78:81], v[138:141], v[240:243], v[78:81]
	v_mfma_f32_16x16x32_bf16 v[74:77], v[142:145], v[236:239], v[74:77]
	v_mfma_f32_16x16x32_bf16 v[74:77], v[154:157], v[240:243], v[74:77]
	v_mfma_f32_16x16x32_bf16 v[90:93], v[142:145], v[228:231], v[90:93]
	v_mfma_f32_16x16x32_bf16 v[90:93], v[154:157], v[232:235], v[90:93]
	v_mfma_f32_16x16x32_bf16 v[106:109], v[142:145], v[200:203], v[106:109]
	v_mfma_f32_16x16x32_bf16 v[106:109], v[154:157], v[204:207], v[106:109]
	v_mfma_f32_16x16x32_bf16 v[122:125], v[142:145], v[192:195], v[122:125]
	v_mfma_f32_16x16x32_bf16 v[122:125], v[154:157], v[196:199], v[122:125]
	v_mfma_f32_16x16x32_bf16 v[114:117], v[184:187], v[192:195], v[114:117]
	v_mfma_f32_16x16x32_bf16 v[114:117], v[188:191], v[196:199], v[114:117]
	v_mfma_f32_16x16x32_bf16 v[98:101], v[184:187], v[200:203], v[98:101]
	v_mfma_f32_16x16x32_bf16 v[98:101], v[188:191], v[204:207], v[98:101]
	v_mfma_f32_16x16x32_bf16 v[82:85], v[184:187], v[228:231], v[82:85]
	v_mfma_f32_16x16x32_bf16 v[82:85], v[188:191], v[232:235], v[82:85]
	v_mfma_f32_16x16x32_bf16 v[66:69], v[184:187], v[236:239], v[66:69]
	v_mfma_f32_16x16x32_bf16 v[66:69], v[188:191], v[240:243], v[66:69]
	v_mfma_f32_16x16x32_bf16 v[70:73], v[170:173], v[236:239], v[70:73]
	v_mfma_f32_16x16x32_bf16 v[70:73], v[180:183], v[240:243], v[70:73]
	v_mfma_f32_16x16x32_bf16 v[86:89], v[170:173], v[228:231], v[86:89]
	v_mfma_f32_16x16x32_bf16 v[86:89], v[180:183], v[232:235], v[86:89]
	v_mfma_f32_16x16x32_bf16 v[102:105], v[170:173], v[200:203], v[102:105]
	v_mfma_f32_16x16x32_bf16 v[102:105], v[180:183], v[204:207], v[102:105]
	v_mfma_f32_16x16x32_bf16 v[118:121], v[170:173], v[192:195], v[118:121]
	v_mfma_f32_16x16x32_bf16 v[118:121], v[180:183], v[196:199], v[118:121]
	s_barrier
	s_setprio 0
	s_mov_b32 m0, s15
	ds_read_b128 v[192:195], v179 offset:16384
	buffer_load_dwordx4 v175, s[60:63], s26 offen lds
	s_add_i32 s34, s26, 0x80000
	s_mov_b32 m0, s16
	ds_read_b128 v[196:199], v179 offset:17408
	buffer_load_dwordx4 v177, s[60:63], s26 offen lds
	s_mov_b32 m0, s18
	ds_read_b128 v[200:203], v179 offset:18432
	buffer_load_dwordx4 v175, s[60:63], s34 offen lds
	s_mov_b32 m0, s19
	ds_read_b128 v[204:207], v179 offset:19456
	buffer_load_dwordx4 v177, s[60:63], s34 offen lds
	s_mov_b32 m0, s14
	ds_read_b128 v[228:231], v179 offset:20480
	buffer_load_dwordx4 v174, s[44:47], s27 offen lds
	s_mov_b32 m0, s24
	ds_read_b128 v[232:235], v179 offset:21504
	buffer_load_dwordx4 v176, s[44:47], s27 offen lds
	ds_read_b128 v[236:239], v179 offset:22528
	ds_read_b128 v[240:243], v179 offset:23552
	s_waitcnt vmcnt(8)
	s_waitcnt lgkmcnt(0)
	s_setprio 1
	s_barrier
	v_mfma_f32_16x16x32_bf16 v[62:65], v[134:137], v[192:195], v[62:65]
	v_mfma_f32_16x16x32_bf16 v[62:65], v[138:141], v[196:199], v[62:65]
	v_mfma_f32_16x16x32_bf16 v[46:49], v[134:137], v[200:203], v[46:49]
	v_mfma_f32_16x16x32_bf16 v[46:49], v[138:141], v[204:207], v[46:49]
	v_mfma_f32_16x16x32_bf16 v[30:33], v[134:137], v[228:231], v[30:33]
	v_mfma_f32_16x16x32_bf16 v[30:33], v[138:141], v[232:235], v[30:33]
	v_mfma_f32_16x16x32_bf16 v[14:17], v[134:137], v[236:239], v[14:17]
	v_mfma_f32_16x16x32_bf16 v[14:17], v[138:141], v[240:243], v[14:17]
	v_mfma_f32_16x16x32_bf16 v[10:13], v[142:145], v[236:239], v[10:13]
	v_mfma_f32_16x16x32_bf16 v[10:13], v[154:157], v[240:243], v[10:13]
	v_mfma_f32_16x16x32_bf16 v[26:29], v[142:145], v[228:231], v[26:29]
	v_mfma_f32_16x16x32_bf16 v[26:29], v[154:157], v[232:235], v[26:29]
	v_mfma_f32_16x16x32_bf16 v[42:45], v[142:145], v[200:203], v[42:45]
	v_mfma_f32_16x16x32_bf16 v[42:45], v[154:157], v[204:207], v[42:45]
	v_mfma_f32_16x16x32_bf16 v[58:61], v[142:145], v[192:195], v[58:61]
	v_mfma_f32_16x16x32_bf16 v[58:61], v[154:157], v[196:199], v[58:61]
	v_mfma_f32_16x16x32_bf16 v[50:53], v[184:187], v[192:195], v[50:53]
	v_mfma_f32_16x16x32_bf16 v[50:53], v[188:191], v[196:199], v[50:53]
	v_mfma_f32_16x16x32_bf16 v[34:37], v[184:187], v[200:203], v[34:37]
	v_mfma_f32_16x16x32_bf16 v[34:37], v[188:191], v[204:207], v[34:37]
	v_mfma_f32_16x16x32_bf16 v[18:21], v[184:187], v[228:231], v[18:21]
	v_mfma_f32_16x16x32_bf16 v[18:21], v[188:191], v[232:235], v[18:21]
	v_mfma_f32_16x16x32_bf16 v[2:5], v[184:187], v[236:239], v[2:5]
	v_mfma_f32_16x16x32_bf16 v[2:5], v[188:191], v[240:243], v[2:5]
	v_mfma_f32_16x16x32_bf16 v[6:9], v[170:173], v[236:239], v[6:9]
	v_mfma_f32_16x16x32_bf16 v[6:9], v[180:183], v[240:243], v[6:9]
	v_mfma_f32_16x16x32_bf16 v[22:25], v[170:173], v[228:231], v[22:25]
	v_mfma_f32_16x16x32_bf16 v[22:25], v[180:183], v[232:235], v[22:25]
	v_mfma_f32_16x16x32_bf16 v[38:41], v[170:173], v[200:203], v[38:41]
	v_mfma_f32_16x16x32_bf16 v[38:41], v[180:183], v[204:207], v[38:41]
	v_mfma_f32_16x16x32_bf16 v[54:57], v[170:173], v[192:195], v[54:57]
	v_mfma_f32_16x16x32_bf16 v[54:57], v[180:183], v[196:199], v[54:57]
	s_barrier
	s_setprio 0
	v_add_u32_e32 v133, 0x18000, v178
	ds_read_b128 v[134:137], v133
	ds_read_b128 v[138:141], v133 offset:1024
	ds_read_b128 v[142:145], v133 offset:2048
	ds_read_b128 v[154:157], v133 offset:3072
	v_add_u32_e32 v133, 0x1c000, v178
	ds_read_b128 v[170:173], v133
	ds_read_b128 v[180:183], v133 offset:1024
	ds_read_b128 v[184:187], v133 offset:2048
	ds_read_b128 v[188:191], v133 offset:3072
	s_add_i32 s27, s27, 0x80000
	s_mov_b32 m0, s25
	ds_read_b128 v[192:195], v179 offset:32768
	ds_read_b128 v[196:199], v179 offset:33792
	ds_read_b128 v[200:203], v179 offset:34816
	ds_read_b128 v[204:207], v179 offset:35840
	ds_read_b128 v[228:231], v179 offset:36864
	ds_read_b128 v[232:235], v179 offset:37888
	ds_read_b128 v[236:239], v179 offset:38912
	ds_read_b128 v[240:243], v179 offset:39936
	buffer_load_dwordx4 v174, s[44:47], s27 offen lds
	s_mov_b32 m0, s30
	s_nop 0
	buffer_load_dwordx4 v176, s[44:47], s27 offen lds
	s_waitcnt vmcnt(8)
	s_waitcnt lgkmcnt(0)
	s_setprio 1
	s_barrier
	v_mfma_f32_16x16x32_bf16 v[126:129], v[134:137], v[192:195], v[126:129]
	v_mfma_f32_16x16x32_bf16 v[126:129], v[138:141], v[196:199], v[126:129]
	v_mfma_f32_16x16x32_bf16 v[110:113], v[134:137], v[200:203], v[110:113]
	v_mfma_f32_16x16x32_bf16 v[110:113], v[138:141], v[204:207], v[110:113]
	v_mfma_f32_16x16x32_bf16 v[94:97], v[134:137], v[228:231], v[94:97]
	v_mfma_f32_16x16x32_bf16 v[94:97], v[138:141], v[232:235], v[94:97]
	v_mfma_f32_16x16x32_bf16 v[78:81], v[134:137], v[236:239], v[78:81]
	v_mfma_f32_16x16x32_bf16 v[78:81], v[138:141], v[240:243], v[78:81]
	v_mfma_f32_16x16x32_bf16 v[74:77], v[142:145], v[236:239], v[74:77]
	v_mfma_f32_16x16x32_bf16 v[74:77], v[154:157], v[240:243], v[74:77]
	v_mfma_f32_16x16x32_bf16 v[90:93], v[142:145], v[228:231], v[90:93]
	v_mfma_f32_16x16x32_bf16 v[90:93], v[154:157], v[232:235], v[90:93]
	v_mfma_f32_16x16x32_bf16 v[106:109], v[142:145], v[200:203], v[106:109]
	v_mfma_f32_16x16x32_bf16 v[106:109], v[154:157], v[204:207], v[106:109]
	v_mfma_f32_16x16x32_bf16 v[122:125], v[142:145], v[192:195], v[122:125]
	v_mfma_f32_16x16x32_bf16 v[122:125], v[154:157], v[196:199], v[122:125]
	v_mfma_f32_16x16x32_bf16 v[114:117], v[184:187], v[192:195], v[114:117]
	v_mfma_f32_16x16x32_bf16 v[114:117], v[188:191], v[196:199], v[114:117]
	v_mfma_f32_16x16x32_bf16 v[98:101], v[184:187], v[200:203], v[98:101]
	v_mfma_f32_16x16x32_bf16 v[98:101], v[188:191], v[204:207], v[98:101]
	v_mfma_f32_16x16x32_bf16 v[82:85], v[184:187], v[228:231], v[82:85]
	v_mfma_f32_16x16x32_bf16 v[82:85], v[188:191], v[232:235], v[82:85]
	v_mfma_f32_16x16x32_bf16 v[66:69], v[184:187], v[236:239], v[66:69]
	v_mfma_f32_16x16x32_bf16 v[66:69], v[188:191], v[240:243], v[66:69]
	v_mfma_f32_16x16x32_bf16 v[70:73], v[170:173], v[236:239], v[70:73]
	v_mfma_f32_16x16x32_bf16 v[70:73], v[180:183], v[240:243], v[70:73]
	v_mfma_f32_16x16x32_bf16 v[86:89], v[170:173], v[228:231], v[86:89]
	v_mfma_f32_16x16x32_bf16 v[86:89], v[180:183], v[232:235], v[86:89]
	v_mfma_f32_16x16x32_bf16 v[102:105], v[170:173], v[200:203], v[102:105]
	v_mfma_f32_16x16x32_bf16 v[102:105], v[180:183], v[204:207], v[102:105]
	v_mfma_f32_16x16x32_bf16 v[118:121], v[170:173], v[192:195], v[118:121]
	v_mfma_f32_16x16x32_bf16 v[118:121], v[180:183], v[196:199], v[118:121]
	s_barrier
	s_setprio 0
	s_or_b32 s27, s26, 0x80
	s_mov_b32 m0, s36
	ds_read_b128 v[192:195], v179 offset:49152
	buffer_load_dwordx4 v175, s[60:63], s27 offen lds
	s_add_i32 s26, s26, 0x80080
	s_mov_b32 m0, s37
	ds_read_b128 v[196:199], v179 offset:50176
	buffer_load_dwordx4 v177, s[60:63], s27 offen lds
	s_mov_b32 m0, s48
	ds_read_b128 v[200:203], v179 offset:51200
	buffer_load_dwordx4 v175, s[60:63], s26 offen lds
	s_mov_b32 m0, s49
	ds_read_b128 v[204:207], v179 offset:52224
	buffer_load_dwordx4 v177, s[60:63], s26 offen lds
	s_mov_b32 m0, s40
	ds_read_b128 v[228:231], v179 offset:53248
	buffer_load_dwordx4 v174, s[44:47], s23 offen lds
	s_mov_b32 m0, s41
	ds_read_b128 v[232:235], v179 offset:54272
	buffer_load_dwordx4 v176, s[44:47], s23 offen lds
	ds_read_b128 v[236:239], v179 offset:55296
	ds_read_b128 v[240:243], v179 offset:56320
	s_waitcnt vmcnt(8)
	s_waitcnt lgkmcnt(0)
	s_setprio 1
	s_barrier
	v_mfma_f32_16x16x32_bf16 v[62:65], v[134:137], v[192:195], v[62:65]
	v_mfma_f32_16x16x32_bf16 v[62:65], v[138:141], v[196:199], v[62:65]
	v_mfma_f32_16x16x32_bf16 v[46:49], v[134:137], v[200:203], v[46:49]
	v_mfma_f32_16x16x32_bf16 v[46:49], v[138:141], v[204:207], v[46:49]
	v_mfma_f32_16x16x32_bf16 v[30:33], v[134:137], v[228:231], v[30:33]
	v_mfma_f32_16x16x32_bf16 v[30:33], v[138:141], v[232:235], v[30:33]
	v_mfma_f32_16x16x32_bf16 v[14:17], v[134:137], v[236:239], v[14:17]
	v_mfma_f32_16x16x32_bf16 v[14:17], v[138:141], v[240:243], v[14:17]
	v_mfma_f32_16x16x32_bf16 v[10:13], v[142:145], v[236:239], v[10:13]
	v_mfma_f32_16x16x32_bf16 v[10:13], v[154:157], v[240:243], v[10:13]
	v_mfma_f32_16x16x32_bf16 v[26:29], v[142:145], v[228:231], v[26:29]
	v_mfma_f32_16x16x32_bf16 v[26:29], v[154:157], v[232:235], v[26:29]
	v_mfma_f32_16x16x32_bf16 v[42:45], v[142:145], v[200:203], v[42:45]
	v_mfma_f32_16x16x32_bf16 v[42:45], v[154:157], v[204:207], v[42:45]
	v_mfma_f32_16x16x32_bf16 v[58:61], v[142:145], v[192:195], v[58:61]
	v_mfma_f32_16x16x32_bf16 v[58:61], v[154:157], v[196:199], v[58:61]
	v_mfma_f32_16x16x32_bf16 v[50:53], v[184:187], v[192:195], v[50:53]
	v_mfma_f32_16x16x32_bf16 v[50:53], v[188:191], v[196:199], v[50:53]
	v_mfma_f32_16x16x32_bf16 v[34:37], v[184:187], v[200:203], v[34:37]
	v_mfma_f32_16x16x32_bf16 v[34:37], v[188:191], v[204:207], v[34:37]
	v_mfma_f32_16x16x32_bf16 v[18:21], v[184:187], v[228:231], v[18:21]
	v_mfma_f32_16x16x32_bf16 v[18:21], v[188:191], v[232:235], v[18:21]
	v_mfma_f32_16x16x32_bf16 v[2:5], v[184:187], v[236:239], v[2:5]
	v_mfma_f32_16x16x32_bf16 v[2:5], v[188:191], v[240:243], v[2:5]
	v_mfma_f32_16x16x32_bf16 v[6:9], v[170:173], v[236:239], v[6:9]
	v_mfma_f32_16x16x32_bf16 v[6:9], v[180:183], v[240:243], v[6:9]
	v_mfma_f32_16x16x32_bf16 v[22:25], v[170:173], v[228:231], v[22:25]
	v_mfma_f32_16x16x32_bf16 v[22:25], v[180:183], v[232:235], v[22:25]
	v_mfma_f32_16x16x32_bf16 v[38:41], v[170:173], v[200:203], v[38:41]
	v_mfma_f32_16x16x32_bf16 v[38:41], v[180:183], v[204:207], v[38:41]
	v_mfma_f32_16x16x32_bf16 v[54:57], v[170:173], v[192:195], v[54:57]
	v_mfma_f32_16x16x32_bf16 v[54:57], v[180:183], v[196:199], v[54:57]
	s_barrier
	s_setprio 0
	s_add_i32 s22, s22, 2
	s_addk_i32 s13, 0x100
	s_addk_i32 s21, 0x100
	s_cmp_gt_u32 s22, 29
	s_cbranch_scc0 .LBB0_905
	s_and_b64 vcc, exec, s[64:65]
	s_cbranch_vccz .LBB0_908
	s_barrier

.LBB0_1192:
	s_lshl_b32 s12, s70, 22
	s_and_b64 s[8:9], s[26:27], exec
	s_cselect_b32 s8, s12, s30
	s_lshl_b32 s22, s71, 22
	s_and_b64 s[66:67], s[26:27], exec
	s_cselect_b32 s9, s22, s31
	s_add_i32 s30, s30, 0x200080
	s_addk_i32 s31, 0x100
	s_mov_b32 s72, -2
	v_add_u32_e32 v141, 0x10000, v139
	ds_read_b128 v[142:145], v141
	ds_read_b128 v[154:157], v141 offset:1024
	ds_read_b128 v[170:173], v141 offset:2048
	ds_read_b128 v[174:177], v141 offset:3072
	v_add_u32_e32 v141, 0x14000, v139
	ds_read_b128 v[178:181], v141
	ds_read_b128 v[182:185], v141 offset:1024
	ds_read_b128 v[186:189], v141 offset:2048
	ds_read_b128 v[190:193], v141 offset:3072
	s_add_i32 s52, s30, 0xffe00080
	s_cmpk_eq_i32 s72, 0x7c
	s_cselect_b32 s52, s8, s52
	s_cselect_b32 s82, s9, s31
	s_or_b32 s73, s52, 0x80
	s_mov_b32 m0, s69
	ds_read_b128 v[194:197], v140
	ds_read_b128 v[198:201], v140 offset:1024
	ds_read_b128 v[202:205], v140 offset:2048
	ds_read_b128 v[228:231], v140 offset:3072
	ds_read_b128 v[232:235], v140 offset:4096
	ds_read_b128 v[236:239], v140 offset:5120
	ds_read_b128 v[240:243], v140 offset:6144
	ds_read_b128 v[244:247], v140 offset:7168
	buffer_load_dwordx4 v131, s[60:63], s30 offen lds
	s_mov_b32 m0, s46
	s_nop 0
	buffer_load_dwordx4 v135, s[60:63], s30 offen lds
	s_waitcnt vmcnt(8)
	s_waitcnt lgkmcnt(0)
	s_setprio 1
	s_barrier
	v_mfma_f32_16x16x32_bf16 v[126:129], v[142:145], v[194:197], 0
	v_mfma_f32_16x16x32_bf16 v[126:129], v[154:157], v[198:201], v[126:129]
	v_mfma_f32_16x16x32_bf16 v[118:121], v[142:145], v[202:205], 0
	v_mfma_f32_16x16x32_bf16 v[118:121], v[154:157], v[228:231], v[118:121]
	v_mfma_f32_16x16x32_bf16 v[110:113], v[142:145], v[232:235], 0
	v_mfma_f32_16x16x32_bf16 v[110:113], v[154:157], v[236:239], v[110:113]
	v_mfma_f32_16x16x32_bf16 v[102:105], v[142:145], v[240:243], 0
	v_mfma_f32_16x16x32_bf16 v[102:105], v[154:157], v[244:247], v[102:105]
	v_mfma_f32_16x16x32_bf16 v[98:101], v[170:173], v[240:243], 0
	v_mfma_f32_16x16x32_bf16 v[98:101], v[174:177], v[244:247], v[98:101]
	v_mfma_f32_16x16x32_bf16 v[106:109], v[170:173], v[232:235], 0
	v_mfma_f32_16x16x32_bf16 v[106:109], v[174:177], v[236:239], v[106:109]
	v_mfma_f32_16x16x32_bf16 v[114:117], v[170:173], v[202:205], 0
	v_mfma_f32_16x16x32_bf16 v[114:117], v[174:177], v[228:231], v[114:117]
	v_mfma_f32_16x16x32_bf16 v[122:125], v[170:173], v[194:197], 0
	v_mfma_f32_16x16x32_bf16 v[122:125], v[174:177], v[198:201], v[122:125]
	v_mfma_f32_16x16x32_bf16 v[58:61], v[186:189], v[194:197], 0
	v_mfma_f32_16x16x32_bf16 v[58:61], v[190:193], v[198:201], v[58:61]
	v_mfma_f32_16x16x32_bf16 v[50:53], v[186:189], v[202:205], 0
	v_mfma_f32_16x16x32_bf16 v[50:53], v[190:193], v[228:231], v[50:53]
	v_mfma_f32_16x16x32_bf16 v[42:45], v[186:189], v[232:235], 0
	v_mfma_f32_16x16x32_bf16 v[42:45], v[190:193], v[236:239], v[42:45]
	v_mfma_f32_16x16x32_bf16 v[34:37], v[186:189], v[240:243], 0
	v_mfma_f32_16x16x32_bf16 v[34:37], v[190:193], v[244:247], v[34:37]
	v_mfma_f32_16x16x32_bf16 v[38:41], v[178:181], v[240:243], 0
	v_mfma_f32_16x16x32_bf16 v[38:41], v[182:185], v[244:247], v[38:41]
	v_mfma_f32_16x16x32_bf16 v[46:49], v[178:181], v[232:235], 0
	v_mfma_f32_16x16x32_bf16 v[46:49], v[182:185], v[236:239], v[46:49]
	v_mfma_f32_16x16x32_bf16 v[54:57], v[178:181], v[202:205], 0
	v_mfma_f32_16x16x32_bf16 v[54:57], v[182:185], v[228:231], v[54:57]
	v_mfma_f32_16x16x32_bf16 v[62:65], v[178:181], v[194:197], 0
	v_mfma_f32_16x16x32_bf16 v[62:65], v[182:185], v[198:201], v[62:65]
	s_barrier
	s_setprio 0
	s_mov_b32 s66, s62
	s_mov_b32 s67, s63
	s_mov_b32 m0, s15
	ds_read_b128 v[194:197], v140 offset:16384
	buffer_load_dwordx4 v134, s[64:67], s82 offen lds
	s_add_i32 s53, s82, 0x200000
	s_mov_b32 m0, s16
	ds_read_b128 v[198:201], v140 offset:17408
	buffer_load_dwordx4 v136, s[64:67], s82 offen lds
	s_mov_b32 m0, s21
	ds_read_b128 v[202:205], v140 offset:18432
	buffer_load_dwordx4 v134, s[64:67], s53 offen lds
	s_mov_b32 m0, s23
	ds_read_b128 v[228:231], v140 offset:19456
	buffer_load_dwordx4 v136, s[64:67], s53 offen lds
	s_mov_b32 m0, s2
	ds_read_b128 v[232:235], v140 offset:20480
	buffer_load_dwordx4 v131, s[60:63], s52 offen lds
	s_mov_b32 m0, s24
	ds_read_b128 v[236:239], v140 offset:21504
	buffer_load_dwordx4 v135, s[60:63], s52 offen lds
	ds_read_b128 v[240:243], v140 offset:22528
	ds_read_b128 v[244:247], v140 offset:23552
	s_waitcnt vmcnt(8)
	s_waitcnt lgkmcnt(0)
	s_setprio 1
	s_barrier
	v_mfma_f32_16x16x32_bf16 v[94:97], v[142:145], v[194:197], 0
	v_mfma_f32_16x16x32_bf16 v[94:97], v[154:157], v[198:201], v[94:97]
	v_mfma_f32_16x16x32_bf16 v[86:89], v[142:145], v[202:205], 0
	v_mfma_f32_16x16x32_bf16 v[86:89], v[154:157], v[228:231], v[86:89]
	v_mfma_f32_16x16x32_bf16 v[78:81], v[142:145], v[232:235], 0
	v_mfma_f32_16x16x32_bf16 v[78:81], v[154:157], v[236:239], v[78:81]
	v_mfma_f32_16x16x32_bf16 v[70:73], v[142:145], v[240:243], 0
	v_mfma_f32_16x16x32_bf16 v[70:73], v[154:157], v[244:247], v[70:73]
	v_mfma_f32_16x16x32_bf16 v[66:69], v[170:173], v[240:243], 0
	v_mfma_f32_16x16x32_bf16 v[66:69], v[174:177], v[244:247], v[66:69]
	v_mfma_f32_16x16x32_bf16 v[74:77], v[170:173], v[232:235], 0
	v_mfma_f32_16x16x32_bf16 v[74:77], v[174:177], v[236:239], v[74:77]
	v_mfma_f32_16x16x32_bf16 v[82:85], v[170:173], v[202:205], 0
	v_mfma_f32_16x16x32_bf16 v[82:85], v[174:177], v[228:231], v[82:85]
	v_mfma_f32_16x16x32_bf16 v[90:93], v[170:173], v[194:197], 0
	v_mfma_f32_16x16x32_bf16 v[90:93], v[174:177], v[198:201], v[90:93]
	v_mfma_f32_16x16x32_bf16 v[26:29], v[186:189], v[194:197], 0
	v_mfma_f32_16x16x32_bf16 v[26:29], v[190:193], v[198:201], v[26:29]
	v_mfma_f32_16x16x32_bf16 v[18:21], v[186:189], v[202:205], 0
	v_mfma_f32_16x16x32_bf16 v[18:21], v[190:193], v[228:231], v[18:21]
	v_mfma_f32_16x16x32_bf16 v[10:13], v[186:189], v[232:235], 0
	v_mfma_f32_16x16x32_bf16 v[10:13], v[190:193], v[236:239], v[10:13]
	v_mfma_f32_16x16x32_bf16 v[2:5], v[186:189], v[240:243], 0
	v_mfma_f32_16x16x32_bf16 v[2:5], v[190:193], v[244:247], v[2:5]
	v_mfma_f32_16x16x32_bf16 v[6:9], v[178:181], v[240:243], 0
	v_mfma_f32_16x16x32_bf16 v[6:9], v[182:185], v[244:247], v[6:9]
	v_mfma_f32_16x16x32_bf16 v[14:17], v[178:181], v[232:235], 0
	v_mfma_f32_16x16x32_bf16 v[14:17], v[182:185], v[236:239], v[14:17]
	v_mfma_f32_16x16x32_bf16 v[22:25], v[178:181], v[202:205], 0
	v_mfma_f32_16x16x32_bf16 v[22:25], v[182:185], v[228:231], v[22:25]
	v_mfma_f32_16x16x32_bf16 v[30:33], v[178:181], v[194:197], 0
	v_mfma_f32_16x16x32_bf16 v[30:33], v[182:185], v[198:201], v[30:33]
	s_barrier
	s_setprio 0
	v_add_u32_e32 v141, 0x18000, v139
	ds_read_b128 v[142:145], v141
	ds_read_b128 v[154:157], v141 offset:1024
	ds_read_b128 v[170:173], v141 offset:2048
	ds_read_b128 v[174:177], v141 offset:3072
	v_add_u32_e32 v141, 0x1c000, v139
	ds_read_b128 v[178:181], v141
	ds_read_b128 v[182:185], v141 offset:1024
	ds_read_b128 v[186:189], v141 offset:2048
	ds_read_b128 v[190:193], v141 offset:3072
	s_add_i32 s52, s52, 0x200000
	s_mov_b32 m0, s25
	ds_read_b128 v[194:197], v140 offset:32768
	ds_read_b128 v[198:201], v140 offset:33792
	ds_read_b128 v[202:205], v140 offset:34816
	ds_read_b128 v[228:231], v140 offset:35840
	ds_read_b128 v[232:235], v140 offset:36864
	ds_read_b128 v[236:239], v140 offset:37888
	ds_read_b128 v[240:243], v140 offset:38912
	ds_read_b128 v[244:247], v140 offset:39936
	buffer_load_dwordx4 v131, s[60:63], s52 offen lds
	s_mov_b32 m0, s33
	s_nop 0
	buffer_load_dwordx4 v135, s[60:63], s52 offen lds
	s_waitcnt vmcnt(8)
	s_waitcnt lgkmcnt(0)
	s_setprio 1
	s_barrier
	v_mfma_f32_16x16x32_bf16 v[126:129], v[142:145], v[194:197], v[126:129]
	v_mfma_f32_16x16x32_bf16 v[126:129], v[154:157], v[198:201], v[126:129]
	v_mfma_f32_16x16x32_bf16 v[118:121], v[142:145], v[202:205], v[118:121]
	v_mfma_f32_16x16x32_bf16 v[118:121], v[154:157], v[228:231], v[118:121]
	v_mfma_f32_16x16x32_bf16 v[110:113], v[142:145], v[232:235], v[110:113]
	v_mfma_f32_16x16x32_bf16 v[110:113], v[154:157], v[236:239], v[110:113]
	v_mfma_f32_16x16x32_bf16 v[102:105], v[142:145], v[240:243], v[102:105]
	v_mfma_f32_16x16x32_bf16 v[102:105], v[154:157], v[244:247], v[102:105]
	v_mfma_f32_16x16x32_bf16 v[98:101], v[170:173], v[240:243], v[98:101]
	v_mfma_f32_16x16x32_bf16 v[98:101], v[174:177], v[244:247], v[98:101]
	v_mfma_f32_16x16x32_bf16 v[106:109], v[170:173], v[232:235], v[106:109]
	v_mfma_f32_16x16x32_bf16 v[106:109], v[174:177], v[236:239], v[106:109]
	v_mfma_f32_16x16x32_bf16 v[114:117], v[170:173], v[202:205], v[114:117]
	v_mfma_f32_16x16x32_bf16 v[114:117], v[174:177], v[228:231], v[114:117]
	v_mfma_f32_16x16x32_bf16 v[122:125], v[170:173], v[194:197], v[122:125]
	v_mfma_f32_16x16x32_bf16 v[122:125], v[174:177], v[198:201], v[122:125]
	v_mfma_f32_16x16x32_bf16 v[58:61], v[186:189], v[194:197], v[58:61]
	v_mfma_f32_16x16x32_bf16 v[58:61], v[190:193], v[198:201], v[58:61]
	v_mfma_f32_16x16x32_bf16 v[50:53], v[186:189], v[202:205], v[50:53]
	v_mfma_f32_16x16x32_bf16 v[50:53], v[190:193], v[228:231], v[50:53]
	v_mfma_f32_16x16x32_bf16 v[42:45], v[186:189], v[232:235], v[42:45]
	v_mfma_f32_16x16x32_bf16 v[42:45], v[190:193], v[236:239], v[42:45]
	v_mfma_f32_16x16x32_bf16 v[34:37], v[186:189], v[240:243], v[34:37]
	v_mfma_f32_16x16x32_bf16 v[34:37], v[190:193], v[244:247], v[34:37]
	v_mfma_f32_16x16x32_bf16 v[38:41], v[178:181], v[240:243], v[38:41]
	v_mfma_f32_16x16x32_bf16 v[38:41], v[182:185], v[244:247], v[38:41]
	v_mfma_f32_16x16x32_bf16 v[46:49], v[178:181], v[232:235], v[46:49]
	v_mfma_f32_16x16x32_bf16 v[46:49], v[182:185], v[236:239], v[46:49]
	v_mfma_f32_16x16x32_bf16 v[54:57], v[178:181], v[202:205], v[54:57]
	v_mfma_f32_16x16x32_bf16 v[54:57], v[182:185], v[228:231], v[54:57]
	v_mfma_f32_16x16x32_bf16 v[62:65], v[178:181], v[194:197], v[62:65]
	v_mfma_f32_16x16x32_bf16 v[62:65], v[182:185], v[198:201], v[62:65]
	s_barrier
	s_setprio 0
	s_or_b32 s52, s82, 0x80
	s_mov_b32 m0, s34
	ds_read_b128 v[194:197], v140 offset:49152
	buffer_load_dwordx4 v134, s[64:67], s52 offen lds
	s_add_i32 s82, s82, 0x200080
	s_mov_b32 m0, s35
	ds_read_b128 v[198:201], v140 offset:50176
	buffer_load_dwordx4 v136, s[64:67], s52 offen lds
	s_mov_b32 m0, s37
	ds_read_b128 v[202:205], v140 offset:51200
	buffer_load_dwordx4 v134, s[64:67], s82 offen lds
	s_mov_b32 m0, s44
	ds_read_b128 v[228:231], v140 offset:52224
	buffer_load_dwordx4 v136, s[64:67], s82 offen lds
	s_mov_b32 m0, s14
	ds_read_b128 v[232:235], v140 offset:53248
	buffer_load_dwordx4 v131, s[60:63], s73 offen lds
	s_mov_b32 m0, s36
	ds_read_b128 v[236:239], v140 offset:54272
	buffer_load_dwordx4 v135, s[60:63], s73 offen lds
	ds_read_b128 v[240:243], v140 offset:55296
	ds_read_b128 v[244:247], v140 offset:56320
	s_waitcnt vmcnt(8)
	s_waitcnt lgkmcnt(0)
	s_setprio 1
	s_barrier
	v_mfma_f32_16x16x32_bf16 v[94:97], v[142:145], v[194:197], v[94:97]
	v_mfma_f32_16x16x32_bf16 v[94:97], v[154:157], v[198:201], v[94:97]
	v_mfma_f32_16x16x32_bf16 v[86:89], v[142:145], v[202:205], v[86:89]
	v_mfma_f32_16x16x32_bf16 v[86:89], v[154:157], v[228:231], v[86:89]
	v_mfma_f32_16x16x32_bf16 v[78:81], v[142:145], v[232:235], v[78:81]
	v_mfma_f32_16x16x32_bf16 v[78:81], v[154:157], v[236:239], v[78:81]
	v_mfma_f32_16x16x32_bf16 v[70:73], v[142:145], v[240:243], v[70:73]
	v_mfma_f32_16x16x32_bf16 v[70:73], v[154:157], v[244:247], v[70:73]
	v_mfma_f32_16x16x32_bf16 v[66:69], v[170:173], v[240:243], v[66:69]
	v_mfma_f32_16x16x32_bf16 v[66:69], v[174:177], v[244:247], v[66:69]
	v_mfma_f32_16x16x32_bf16 v[74:77], v[170:173], v[232:235], v[74:77]
	v_mfma_f32_16x16x32_bf16 v[74:77], v[174:177], v[236:239], v[74:77]
	v_mfma_f32_16x16x32_bf16 v[82:85], v[170:173], v[202:205], v[82:85]
	v_mfma_f32_16x16x32_bf16 v[82:85], v[174:177], v[228:231], v[82:85]
	v_mfma_f32_16x16x32_bf16 v[90:93], v[170:173], v[194:197], v[90:93]
	v_mfma_f32_16x16x32_bf16 v[90:93], v[174:177], v[198:201], v[90:93]
	v_mfma_f32_16x16x32_bf16 v[26:29], v[186:189], v[194:197], v[26:29]
	v_mfma_f32_16x16x32_bf16 v[26:29], v[190:193], v[198:201], v[26:29]
	v_mfma_f32_16x16x32_bf16 v[18:21], v[186:189], v[202:205], v[18:21]
	v_mfma_f32_16x16x32_bf16 v[18:21], v[190:193], v[228:231], v[18:21]
	v_mfma_f32_16x16x32_bf16 v[10:13], v[186:189], v[232:235], v[10:13]
	v_mfma_f32_16x16x32_bf16 v[10:13], v[190:193], v[236:239], v[10:13]
	v_mfma_f32_16x16x32_bf16 v[2:5], v[186:189], v[240:243], v[2:5]
	v_mfma_f32_16x16x32_bf16 v[2:5], v[190:193], v[244:247], v[2:5]
	v_mfma_f32_16x16x32_bf16 v[6:9], v[178:181], v[240:243], v[6:9]
	v_mfma_f32_16x16x32_bf16 v[6:9], v[182:185], v[244:247], v[6:9]
	v_mfma_f32_16x16x32_bf16 v[14:17], v[178:181], v[232:235], v[14:17]
	v_mfma_f32_16x16x32_bf16 v[14:17], v[182:185], v[236:239], v[14:17]
	v_mfma_f32_16x16x32_bf16 v[22:25], v[178:181], v[202:205], v[22:25]
	v_mfma_f32_16x16x32_bf16 v[22:25], v[182:185], v[228:231], v[22:25]
	v_mfma_f32_16x16x32_bf16 v[30:33], v[178:181], v[194:197], v[30:33]
	v_mfma_f32_16x16x32_bf16 v[30:33], v[182:185], v[198:201], v[30:33]
	s_barrier
	s_setprio 0
	s_add_i32 s72, s72, 2
	s_addk_i32 s30, 0x100
	s_addk_i32 s31, 0x100
	s_cmpk_gt_u32 s72, 0x7d
.LBB0_1193:
	v_add_u32_e32 v141, 0x10000, v139
	ds_read_b128 v[142:145], v141
	ds_read_b128 v[154:157], v141 offset:1024
	ds_read_b128 v[170:173], v141 offset:2048
	ds_read_b128 v[174:177], v141 offset:3072
	v_add_u32_e32 v141, 0x14000, v139
	ds_read_b128 v[178:181], v141
	ds_read_b128 v[182:185], v141 offset:1024
	ds_read_b128 v[186:189], v141 offset:2048
	ds_read_b128 v[190:193], v141 offset:3072
	s_add_i32 s52, s30, 0xffe00080
	s_cmpk_eq_i32 s72, 0x7c
	s_cselect_b32 s52, s8, s52
	s_cselect_b32 s82, s9, s31
	s_or_b32 s73, s52, 0x80
	s_mov_b32 m0, s69
	ds_read_b128 v[194:197], v140
	ds_read_b128 v[198:201], v140 offset:1024
	ds_read_b128 v[202:205], v140 offset:2048
	ds_read_b128 v[228:231], v140 offset:3072
	ds_read_b128 v[232:235], v140 offset:4096
	ds_read_b128 v[236:239], v140 offset:5120
	ds_read_b128 v[240:243], v140 offset:6144
	ds_read_b128 v[244:247], v140 offset:7168
	buffer_load_dwordx4 v131, s[60:63], s30 offen lds
	s_mov_b32 m0, s46
	s_nop 0
	buffer_load_dwordx4 v135, s[60:63], s30 offen lds
	s_waitcnt vmcnt(8)
	s_waitcnt lgkmcnt(0)
	s_setprio 1
	s_barrier
	v_mfma_f32_16x16x32_bf16 v[126:129], v[142:145], v[194:197], v[126:129]
	v_mfma_f32_16x16x32_bf16 v[126:129], v[154:157], v[198:201], v[126:129]
	v_mfma_f32_16x16x32_bf16 v[118:121], v[142:145], v[202:205], v[118:121]
	v_mfma_f32_16x16x32_bf16 v[118:121], v[154:157], v[228:231], v[118:121]
	v_mfma_f32_16x16x32_bf16 v[110:113], v[142:145], v[232:235], v[110:113]
	v_mfma_f32_16x16x32_bf16 v[110:113], v[154:157], v[236:239], v[110:113]
	v_mfma_f32_16x16x32_bf16 v[102:105], v[142:145], v[240:243], v[102:105]
	v_mfma_f32_16x16x32_bf16 v[102:105], v[154:157], v[244:247], v[102:105]
	v_mfma_f32_16x16x32_bf16 v[98:101], v[170:173], v[240:243], v[98:101]
	v_mfma_f32_16x16x32_bf16 v[98:101], v[174:177], v[244:247], v[98:101]
	v_mfma_f32_16x16x32_bf16 v[106:109], v[170:173], v[232:235], v[106:109]
	v_mfma_f32_16x16x32_bf16 v[106:109], v[174:177], v[236:239], v[106:109]
	v_mfma_f32_16x16x32_bf16 v[114:117], v[170:173], v[202:205], v[114:117]
	v_mfma_f32_16x16x32_bf16 v[114:117], v[174:177], v[228:231], v[114:117]
	v_mfma_f32_16x16x32_bf16 v[122:125], v[170:173], v[194:197], v[122:125]
	v_mfma_f32_16x16x32_bf16 v[122:125], v[174:177], v[198:201], v[122:125]
	v_mfma_f32_16x16x32_bf16 v[58:61], v[186:189], v[194:197], v[58:61]
	v_mfma_f32_16x16x32_bf16 v[58:61], v[190:193], v[198:201], v[58:61]
	v_mfma_f32_16x16x32_bf16 v[50:53], v[186:189], v[202:205], v[50:53]
	v_mfma_f32_16x16x32_bf16 v[50:53], v[190:193], v[228:231], v[50:53]
	v_mfma_f32_16x16x32_bf16 v[42:45], v[186:189], v[232:235], v[42:45]
	v_mfma_f32_16x16x32_bf16 v[42:45], v[190:193], v[236:239], v[42:45]
	v_mfma_f32_16x16x32_bf16 v[34:37], v[186:189], v[240:243], v[34:37]
	v_mfma_f32_16x16x32_bf16 v[34:37], v[190:193], v[244:247], v[34:37]
	v_mfma_f32_16x16x32_bf16 v[38:41], v[178:181], v[240:243], v[38:41]
	v_mfma_f32_16x16x32_bf16 v[38:41], v[182:185], v[244:247], v[38:41]
	v_mfma_f32_16x16x32_bf16 v[46:49], v[178:181], v[232:235], v[46:49]
	v_mfma_f32_16x16x32_bf16 v[46:49], v[182:185], v[236:239], v[46:49]
	v_mfma_f32_16x16x32_bf16 v[54:57], v[178:181], v[202:205], v[54:57]
	v_mfma_f32_16x16x32_bf16 v[54:57], v[182:185], v[228:231], v[54:57]
	v_mfma_f32_16x16x32_bf16 v[62:65], v[178:181], v[194:197], v[62:65]
	v_mfma_f32_16x16x32_bf16 v[62:65], v[182:185], v[198:201], v[62:65]
	s_barrier
	s_setprio 0
	s_mov_b32 s66, s62
	s_mov_b32 s67, s63
	s_mov_b32 m0, s15
	ds_read_b128 v[194:197], v140 offset:16384
	buffer_load_dwordx4 v134, s[64:67], s82 offen lds
	s_add_i32 s53, s82, 0x200000
	s_mov_b32 m0, s16
	ds_read_b128 v[198:201], v140 offset:17408
	buffer_load_dwordx4 v136, s[64:67], s82 offen lds
	s_mov_b32 m0, s21
	ds_read_b128 v[202:205], v140 offset:18432
	buffer_load_dwordx4 v134, s[64:67], s53 offen lds
	s_mov_b32 m0, s23
	ds_read_b128 v[228:231], v140 offset:19456
	buffer_load_dwordx4 v136, s[64:67], s53 offen lds
	s_mov_b32 m0, s2
	ds_read_b128 v[232:235], v140 offset:20480
	buffer_load_dwordx4 v131, s[60:63], s52 offen lds
	s_mov_b32 m0, s24
	ds_read_b128 v[236:239], v140 offset:21504
	buffer_load_dwordx4 v135, s[60:63], s52 offen lds
	ds_read_b128 v[240:243], v140 offset:22528
	ds_read_b128 v[244:247], v140 offset:23552
	s_waitcnt vmcnt(8)
	s_waitcnt lgkmcnt(0)
	s_setprio 1
	s_barrier
	v_mfma_f32_16x16x32_bf16 v[94:97], v[142:145], v[194:197], v[94:97]
	v_mfma_f32_16x16x32_bf16 v[94:97], v[154:157], v[198:201], v[94:97]
	v_mfma_f32_16x16x32_bf16 v[86:89], v[142:145], v[202:205], v[86:89]
	v_mfma_f32_16x16x32_bf16 v[86:89], v[154:157], v[228:231], v[86:89]
	v_mfma_f32_16x16x32_bf16 v[78:81], v[142:145], v[232:235], v[78:81]
	v_mfma_f32_16x16x32_bf16 v[78:81], v[154:157], v[236:239], v[78:81]
	v_mfma_f32_16x16x32_bf16 v[70:73], v[142:145], v[240:243], v[70:73]
	v_mfma_f32_16x16x32_bf16 v[70:73], v[154:157], v[244:247], v[70:73]
	v_mfma_f32_16x16x32_bf16 v[66:69], v[170:173], v[240:243], v[66:69]
	v_mfma_f32_16x16x32_bf16 v[66:69], v[174:177], v[244:247], v[66:69]
	v_mfma_f32_16x16x32_bf16 v[74:77], v[170:173], v[232:235], v[74:77]
	v_mfma_f32_16x16x32_bf16 v[74:77], v[174:177], v[236:239], v[74:77]
	v_mfma_f32_16x16x32_bf16 v[82:85], v[170:173], v[202:205], v[82:85]
	v_mfma_f32_16x16x32_bf16 v[82:85], v[174:177], v[228:231], v[82:85]
	v_mfma_f32_16x16x32_bf16 v[90:93], v[170:173], v[194:197], v[90:93]
	v_mfma_f32_16x16x32_bf16 v[90:93], v[174:177], v[198:201], v[90:93]
	v_mfma_f32_16x16x32_bf16 v[26:29], v[186:189], v[194:197], v[26:29]
	v_mfma_f32_16x16x32_bf16 v[26:29], v[190:193], v[198:201], v[26:29]
	v_mfma_f32_16x16x32_bf16 v[18:21], v[186:189], v[202:205], v[18:21]
	v_mfma_f32_16x16x32_bf16 v[18:21], v[190:193], v[228:231], v[18:21]
	v_mfma_f32_16x16x32_bf16 v[10:13], v[186:189], v[232:235], v[10:13]
	v_mfma_f32_16x16x32_bf16 v[10:13], v[190:193], v[236:239], v[10:13]
	v_mfma_f32_16x16x32_bf16 v[2:5], v[186:189], v[240:243], v[2:5]
	v_mfma_f32_16x16x32_bf16 v[2:5], v[190:193], v[244:247], v[2:5]
	v_mfma_f32_16x16x32_bf16 v[6:9], v[178:181], v[240:243], v[6:9]
	v_mfma_f32_16x16x32_bf16 v[6:9], v[182:185], v[244:247], v[6:9]
	v_mfma_f32_16x16x32_bf16 v[14:17], v[178:181], v[232:235], v[14:17]
	v_mfma_f32_16x16x32_bf16 v[14:17], v[182:185], v[236:239], v[14:17]
	v_mfma_f32_16x16x32_bf16 v[22:25], v[178:181], v[202:205], v[22:25]
	v_mfma_f32_16x16x32_bf16 v[22:25], v[182:185], v[228:231], v[22:25]
	v_mfma_f32_16x16x32_bf16 v[30:33], v[178:181], v[194:197], v[30:33]
	v_mfma_f32_16x16x32_bf16 v[30:33], v[182:185], v[198:201], v[30:33]
	s_barrier
	s_setprio 0
	v_add_u32_e32 v141, 0x18000, v139
	ds_read_b128 v[142:145], v141
	ds_read_b128 v[154:157], v141 offset:1024
	ds_read_b128 v[170:173], v141 offset:2048
	ds_read_b128 v[174:177], v141 offset:3072
	v_add_u32_e32 v141, 0x1c000, v139
	ds_read_b128 v[178:181], v141
	ds_read_b128 v[182:185], v141 offset:1024
	ds_read_b128 v[186:189], v141 offset:2048
	ds_read_b128 v[190:193], v141 offset:3072
	s_add_i32 s52, s52, 0x200000
	s_mov_b32 m0, s25
	ds_read_b128 v[194:197], v140 offset:32768
	ds_read_b128 v[198:201], v140 offset:33792
	ds_read_b128 v[202:205], v140 offset:34816
	ds_read_b128 v[228:231], v140 offset:35840
	ds_read_b128 v[232:235], v140 offset:36864
	ds_read_b128 v[236:239], v140 offset:37888
	ds_read_b128 v[240:243], v140 offset:38912
	ds_read_b128 v[244:247], v140 offset:39936
	buffer_load_dwordx4 v131, s[60:63], s52 offen lds
	s_mov_b32 m0, s33
	s_nop 0
	buffer_load_dwordx4 v135, s[60:63], s52 offen lds
	s_waitcnt vmcnt(8)
	s_waitcnt lgkmcnt(0)
	s_setprio 1
	s_barrier
	v_mfma_f32_16x16x32_bf16 v[126:129], v[142:145], v[194:197], v[126:129]
	v_mfma_f32_16x16x32_bf16 v[126:129], v[154:157], v[198:201], v[126:129]
	v_mfma_f32_16x16x32_bf16 v[118:121], v[142:145], v[202:205], v[118:121]
	v_mfma_f32_16x16x32_bf16 v[118:121], v[154:157], v[228:231], v[118:121]
	v_mfma_f32_16x16x32_bf16 v[110:113], v[142:145], v[232:235], v[110:113]
	v_mfma_f32_16x16x32_bf16 v[110:113], v[154:157], v[236:239], v[110:113]
	v_mfma_f32_16x16x32_bf16 v[102:105], v[142:145], v[240:243], v[102:105]
	v_mfma_f32_16x16x32_bf16 v[102:105], v[154:157], v[244:247], v[102:105]
	v_mfma_f32_16x16x32_bf16 v[98:101], v[170:173], v[240:243], v[98:101]
	v_mfma_f32_16x16x32_bf16 v[98:101], v[174:177], v[244:247], v[98:101]
	v_mfma_f32_16x16x32_bf16 v[106:109], v[170:173], v[232:235], v[106:109]
	v_mfma_f32_16x16x32_bf16 v[106:109], v[174:177], v[236:239], v[106:109]
	v_mfma_f32_16x16x32_bf16 v[114:117], v[170:173], v[202:205], v[114:117]
	v_mfma_f32_16x16x32_bf16 v[114:117], v[174:177], v[228:231], v[114:117]
	v_mfma_f32_16x16x32_bf16 v[122:125], v[170:173], v[194:197], v[122:125]
	v_mfma_f32_16x16x32_bf16 v[122:125], v[174:177], v[198:201], v[122:125]
	v_mfma_f32_16x16x32_bf16 v[58:61], v[186:189], v[194:197], v[58:61]
	v_mfma_f32_16x16x32_bf16 v[58:61], v[190:193], v[198:201], v[58:61]
	v_mfma_f32_16x16x32_bf16 v[50:53], v[186:189], v[202:205], v[50:53]
	v_mfma_f32_16x16x32_bf16 v[50:53], v[190:193], v[228:231], v[50:53]
	v_mfma_f32_16x16x32_bf16 v[42:45], v[186:189], v[232:235], v[42:45]
	v_mfma_f32_16x16x32_bf16 v[42:45], v[190:193], v[236:239], v[42:45]
	v_mfma_f32_16x16x32_bf16 v[34:37], v[186:189], v[240:243], v[34:37]
	v_mfma_f32_16x16x32_bf16 v[34:37], v[190:193], v[244:247], v[34:37]
	v_mfma_f32_16x16x32_bf16 v[38:41], v[178:181], v[240:243], v[38:41]
	v_mfma_f32_16x16x32_bf16 v[38:41], v[182:185], v[244:247], v[38:41]
	v_mfma_f32_16x16x32_bf16 v[46:49], v[178:181], v[232:235], v[46:49]
	v_mfma_f32_16x16x32_bf16 v[46:49], v[182:185], v[236:239], v[46:49]
	v_mfma_f32_16x16x32_bf16 v[54:57], v[178:181], v[202:205], v[54:57]
	v_mfma_f32_16x16x32_bf16 v[54:57], v[182:185], v[228:231], v[54:57]
	v_mfma_f32_16x16x32_bf16 v[62:65], v[178:181], v[194:197], v[62:65]
	v_mfma_f32_16x16x32_bf16 v[62:65], v[182:185], v[198:201], v[62:65]
	s_barrier
	s_setprio 0
	s_or_b32 s52, s82, 0x80
	s_mov_b32 m0, s34
	ds_read_b128 v[194:197], v140 offset:49152
	buffer_load_dwordx4 v134, s[64:67], s52 offen lds
	s_add_i32 s82, s82, 0x200080
	s_mov_b32 m0, s35
	ds_read_b128 v[198:201], v140 offset:50176
	buffer_load_dwordx4 v136, s[64:67], s52 offen lds
	s_mov_b32 m0, s37
	ds_read_b128 v[202:205], v140 offset:51200
	buffer_load_dwordx4 v134, s[64:67], s82 offen lds
	s_mov_b32 m0, s44
	ds_read_b128 v[228:231], v140 offset:52224
	buffer_load_dwordx4 v136, s[64:67], s82 offen lds
	s_mov_b32 m0, s14
	ds_read_b128 v[232:235], v140 offset:53248
	buffer_load_dwordx4 v131, s[60:63], s73 offen lds
	s_mov_b32 m0, s36
	ds_read_b128 v[236:239], v140 offset:54272
	buffer_load_dwordx4 v135, s[60:63], s73 offen lds
	ds_read_b128 v[240:243], v140 offset:55296
	ds_read_b128 v[244:247], v140 offset:56320
	s_waitcnt vmcnt(8)
	s_waitcnt lgkmcnt(0)
	s_setprio 1
	s_barrier
	v_mfma_f32_16x16x32_bf16 v[94:97], v[142:145], v[194:197], v[94:97]
	v_mfma_f32_16x16x32_bf16 v[94:97], v[154:157], v[198:201], v[94:97]
	v_mfma_f32_16x16x32_bf16 v[86:89], v[142:145], v[202:205], v[86:89]
	v_mfma_f32_16x16x32_bf16 v[86:89], v[154:157], v[228:231], v[86:89]
	v_mfma_f32_16x16x32_bf16 v[78:81], v[142:145], v[232:235], v[78:81]
	v_mfma_f32_16x16x32_bf16 v[78:81], v[154:157], v[236:239], v[78:81]
	v_mfma_f32_16x16x32_bf16 v[70:73], v[142:145], v[240:243], v[70:73]
	v_mfma_f32_16x16x32_bf16 v[70:73], v[154:157], v[244:247], v[70:73]
	v_mfma_f32_16x16x32_bf16 v[66:69], v[170:173], v[240:243], v[66:69]
	v_mfma_f32_16x16x32_bf16 v[66:69], v[174:177], v[244:247], v[66:69]
	v_mfma_f32_16x16x32_bf16 v[74:77], v[170:173], v[232:235], v[74:77]
	v_mfma_f32_16x16x32_bf16 v[74:77], v[174:177], v[236:239], v[74:77]
	v_mfma_f32_16x16x32_bf16 v[82:85], v[170:173], v[202:205], v[82:85]
	v_mfma_f32_16x16x32_bf16 v[82:85], v[174:177], v[228:231], v[82:85]
	v_mfma_f32_16x16x32_bf16 v[90:93], v[170:173], v[194:197], v[90:93]
	v_mfma_f32_16x16x32_bf16 v[90:93], v[174:177], v[198:201], v[90:93]
	v_mfma_f32_16x16x32_bf16 v[26:29], v[186:189], v[194:197], v[26:29]
	v_mfma_f32_16x16x32_bf16 v[26:29], v[190:193], v[198:201], v[26:29]
	v_mfma_f32_16x16x32_bf16 v[18:21], v[186:189], v[202:205], v[18:21]
	v_mfma_f32_16x16x32_bf16 v[18:21], v[190:193], v[228:231], v[18:21]
	v_mfma_f32_16x16x32_bf16 v[10:13], v[186:189], v[232:235], v[10:13]
	v_mfma_f32_16x16x32_bf16 v[10:13], v[190:193], v[236:239], v[10:13]
	v_mfma_f32_16x16x32_bf16 v[2:5], v[186:189], v[240:243], v[2:5]
	v_mfma_f32_16x16x32_bf16 v[2:5], v[190:193], v[244:247], v[2:5]
	v_mfma_f32_16x16x32_bf16 v[6:9], v[178:181], v[240:243], v[6:9]
	v_mfma_f32_16x16x32_bf16 v[6:9], v[182:185], v[244:247], v[6:9]
	v_mfma_f32_16x16x32_bf16 v[14:17], v[178:181], v[232:235], v[14:17]
	v_mfma_f32_16x16x32_bf16 v[14:17], v[182:185], v[236:239], v[14:17]
	v_mfma_f32_16x16x32_bf16 v[22:25], v[178:181], v[202:205], v[22:25]
	v_mfma_f32_16x16x32_bf16 v[22:25], v[182:185], v[228:231], v[22:25]
	v_mfma_f32_16x16x32_bf16 v[30:33], v[178:181], v[194:197], v[30:33]
	v_mfma_f32_16x16x32_bf16 v[30:33], v[182:185], v[198:201], v[30:33]
	s_barrier
	s_setprio 0
	s_add_i32 s72, s72, 2
	s_addk_i32 s30, 0x100
	s_addk_i32 s31, 0x100
	s_cmpk_gt_u32 s72, 0x7d
	s_cbranch_scc0 .LBB0_1193
	s_and_b64 vcc, exec, s[42:43]
	s_cbranch_vccz .LBB0_1196
	s_barrier

.LBB0_1222:
	s_lshl_b32 s14, s82, 22
	s_and_b64 s[8:9], s[44:45], exec
	s_cselect_b32 s8, s14, s19
	s_lshl_b32 s46, s84, 22
	s_and_b64 s[26:27], s[44:45], exec
	s_cselect_b32 s9, s46, s22
	s_add_i32 s19, s19, 0x200080
	s_addk_i32 s22, 0x100
	s_mov_b32 s26, -2
	v_add_u32_e32 v141, 0x10000, v139
	ds_read_b128 v[142:145], v141
	ds_read_b128 v[154:157], v141 offset:1024
	ds_read_b128 v[170:173], v141 offset:2048
	ds_read_b128 v[174:177], v141 offset:3072
	v_add_u32_e32 v141, 0x14000, v139
	ds_read_b128 v[178:181], v141
	ds_read_b128 v[182:185], v141 offset:1024
	ds_read_b128 v[186:189], v141 offset:2048
	ds_read_b128 v[190:193], v141 offset:3072
	s_add_i32 s27, s19, 0xffe00080
	s_cmpk_eq_i32 s26, 0x7c
	s_cselect_b32 s52, s8, s27
	s_cselect_b32 s47, s9, s22
	s_or_b32 s27, s52, 0x80
	s_mov_b32 m0, s71
	ds_read_b128 v[194:197], v140
	ds_read_b128 v[198:201], v140 offset:1024
	ds_read_b128 v[202:205], v140 offset:2048
	ds_read_b128 v[228:231], v140 offset:3072
	ds_read_b128 v[232:235], v140 offset:4096
	ds_read_b128 v[236:239], v140 offset:5120
	ds_read_b128 v[240:243], v140 offset:6144
	ds_read_b128 v[244:247], v140 offset:7168
	buffer_load_dwordx4 v131, s[60:63], s19 offen lds
	s_mov_b32 m0, s72
	s_nop 0
	buffer_load_dwordx4 v135, s[60:63], s19 offen lds
	s_waitcnt vmcnt(8)
	s_waitcnt lgkmcnt(0)
	s_setprio 1
	s_barrier
	v_mfma_f32_16x16x32_bf16 v[126:129], v[142:145], v[194:197], 0
	v_mfma_f32_16x16x32_bf16 v[126:129], v[154:157], v[198:201], v[126:129]
	v_mfma_f32_16x16x32_bf16 v[118:121], v[142:145], v[202:205], 0
	v_mfma_f32_16x16x32_bf16 v[118:121], v[154:157], v[228:231], v[118:121]
	v_mfma_f32_16x16x32_bf16 v[110:113], v[142:145], v[232:235], 0
	v_mfma_f32_16x16x32_bf16 v[110:113], v[154:157], v[236:239], v[110:113]
	v_mfma_f32_16x16x32_bf16 v[102:105], v[142:145], v[240:243], 0
	v_mfma_f32_16x16x32_bf16 v[102:105], v[154:157], v[244:247], v[102:105]
	v_mfma_f32_16x16x32_bf16 v[98:101], v[170:173], v[240:243], 0
	v_mfma_f32_16x16x32_bf16 v[98:101], v[174:177], v[244:247], v[98:101]
	v_mfma_f32_16x16x32_bf16 v[106:109], v[170:173], v[232:235], 0
	v_mfma_f32_16x16x32_bf16 v[106:109], v[174:177], v[236:239], v[106:109]
	v_mfma_f32_16x16x32_bf16 v[114:117], v[170:173], v[202:205], 0
	v_mfma_f32_16x16x32_bf16 v[114:117], v[174:177], v[228:231], v[114:117]
	v_mfma_f32_16x16x32_bf16 v[122:125], v[170:173], v[194:197], 0
	v_mfma_f32_16x16x32_bf16 v[122:125], v[174:177], v[198:201], v[122:125]
	v_mfma_f32_16x16x32_bf16 v[58:61], v[186:189], v[194:197], 0
	v_mfma_f32_16x16x32_bf16 v[58:61], v[190:193], v[198:201], v[58:61]
	v_mfma_f32_16x16x32_bf16 v[50:53], v[186:189], v[202:205], 0
	v_mfma_f32_16x16x32_bf16 v[50:53], v[190:193], v[228:231], v[50:53]
	v_mfma_f32_16x16x32_bf16 v[42:45], v[186:189], v[232:235], 0
	v_mfma_f32_16x16x32_bf16 v[42:45], v[190:193], v[236:239], v[42:45]
	v_mfma_f32_16x16x32_bf16 v[34:37], v[186:189], v[240:243], 0
	v_mfma_f32_16x16x32_bf16 v[34:37], v[190:193], v[244:247], v[34:37]
	v_mfma_f32_16x16x32_bf16 v[38:41], v[178:181], v[240:243], 0
	v_mfma_f32_16x16x32_bf16 v[38:41], v[182:185], v[244:247], v[38:41]
	v_mfma_f32_16x16x32_bf16 v[46:49], v[178:181], v[232:235], 0
	v_mfma_f32_16x16x32_bf16 v[46:49], v[182:185], v[236:239], v[46:49]
	v_mfma_f32_16x16x32_bf16 v[54:57], v[178:181], v[202:205], 0
	v_mfma_f32_16x16x32_bf16 v[54:57], v[182:185], v[228:231], v[54:57]
	v_mfma_f32_16x16x32_bf16 v[62:65], v[178:181], v[194:197], 0
	v_mfma_f32_16x16x32_bf16 v[62:65], v[182:185], v[198:201], v[62:65]
	s_barrier
	s_setprio 0
	s_mov_b32 s66, s62
	s_mov_b32 s67, s63
	s_mov_b32 m0, s2
	ds_read_b128 v[194:197], v140 offset:16384
	buffer_load_dwordx4 v134, s[64:67], s47 offen lds
	s_add_i32 s53, s47, 0x200000
	s_mov_b32 m0, s21
	ds_read_b128 v[198:201], v140 offset:17408
	buffer_load_dwordx4 v136, s[64:67], s47 offen lds
	s_mov_b32 m0, s23
	ds_read_b128 v[202:205], v140 offset:18432
	buffer_load_dwordx4 v134, s[64:67], s53 offen lds
	s_mov_b32 m0, s24
	ds_read_b128 v[228:231], v140 offset:19456
	buffer_load_dwordx4 v136, s[64:67], s53 offen lds
	s_mov_b32 m0, s16
	ds_read_b128 v[232:235], v140 offset:20480
	buffer_load_dwordx4 v131, s[60:63], s52 offen lds
	s_mov_b32 m0, s25
	ds_read_b128 v[236:239], v140 offset:21504
	buffer_load_dwordx4 v135, s[60:63], s52 offen lds
	ds_read_b128 v[240:243], v140 offset:22528
	ds_read_b128 v[244:247], v140 offset:23552
	s_waitcnt vmcnt(8)
	s_waitcnt lgkmcnt(0)
	s_setprio 1
	s_barrier
	v_mfma_f32_16x16x32_bf16 v[94:97], v[142:145], v[194:197], 0
	v_mfma_f32_16x16x32_bf16 v[94:97], v[154:157], v[198:201], v[94:97]
	v_mfma_f32_16x16x32_bf16 v[86:89], v[142:145], v[202:205], 0
	v_mfma_f32_16x16x32_bf16 v[86:89], v[154:157], v[228:231], v[86:89]
	v_mfma_f32_16x16x32_bf16 v[78:81], v[142:145], v[232:235], 0
	v_mfma_f32_16x16x32_bf16 v[78:81], v[154:157], v[236:239], v[78:81]
	v_mfma_f32_16x16x32_bf16 v[70:73], v[142:145], v[240:243], 0
	v_mfma_f32_16x16x32_bf16 v[70:73], v[154:157], v[244:247], v[70:73]
	v_mfma_f32_16x16x32_bf16 v[66:69], v[170:173], v[240:243], 0
	v_mfma_f32_16x16x32_bf16 v[66:69], v[174:177], v[244:247], v[66:69]
	v_mfma_f32_16x16x32_bf16 v[74:77], v[170:173], v[232:235], 0
	v_mfma_f32_16x16x32_bf16 v[74:77], v[174:177], v[236:239], v[74:77]
	v_mfma_f32_16x16x32_bf16 v[82:85], v[170:173], v[202:205], 0
	v_mfma_f32_16x16x32_bf16 v[82:85], v[174:177], v[228:231], v[82:85]
	v_mfma_f32_16x16x32_bf16 v[90:93], v[170:173], v[194:197], 0
	v_mfma_f32_16x16x32_bf16 v[90:93], v[174:177], v[198:201], v[90:93]
	v_mfma_f32_16x16x32_bf16 v[26:29], v[186:189], v[194:197], 0
	v_mfma_f32_16x16x32_bf16 v[26:29], v[190:193], v[198:201], v[26:29]
	v_mfma_f32_16x16x32_bf16 v[18:21], v[186:189], v[202:205], 0
	v_mfma_f32_16x16x32_bf16 v[18:21], v[190:193], v[228:231], v[18:21]
	v_mfma_f32_16x16x32_bf16 v[10:13], v[186:189], v[232:235], 0
	v_mfma_f32_16x16x32_bf16 v[10:13], v[190:193], v[236:239], v[10:13]
	v_mfma_f32_16x16x32_bf16 v[2:5], v[186:189], v[240:243], 0
	v_mfma_f32_16x16x32_bf16 v[2:5], v[190:193], v[244:247], v[2:5]
	v_mfma_f32_16x16x32_bf16 v[6:9], v[178:181], v[240:243], 0
	v_mfma_f32_16x16x32_bf16 v[6:9], v[182:185], v[244:247], v[6:9]
	v_mfma_f32_16x16x32_bf16 v[14:17], v[178:181], v[232:235], 0
	v_mfma_f32_16x16x32_bf16 v[14:17], v[182:185], v[236:239], v[14:17]
	v_mfma_f32_16x16x32_bf16 v[22:25], v[178:181], v[202:205], 0
	v_mfma_f32_16x16x32_bf16 v[22:25], v[182:185], v[228:231], v[22:25]
	v_mfma_f32_16x16x32_bf16 v[30:33], v[178:181], v[194:197], 0
	v_mfma_f32_16x16x32_bf16 v[30:33], v[182:185], v[198:201], v[30:33]
	s_barrier
	s_setprio 0
	v_add_u32_e32 v141, 0x18000, v139
	ds_read_b128 v[142:145], v141
	ds_read_b128 v[154:157], v141 offset:1024
	ds_read_b128 v[170:173], v141 offset:2048
	ds_read_b128 v[174:177], v141 offset:3072
	v_add_u32_e32 v141, 0x1c000, v139
	ds_read_b128 v[178:181], v141
	ds_read_b128 v[182:185], v141 offset:1024
	ds_read_b128 v[186:189], v141 offset:2048
	ds_read_b128 v[190:193], v141 offset:3072
	s_add_i32 s52, s52, 0x200000
	s_mov_b32 m0, s30
	ds_read_b128 v[194:197], v140 offset:32768
	ds_read_b128 v[198:201], v140 offset:33792
	ds_read_b128 v[202:205], v140 offset:34816
	ds_read_b128 v[228:231], v140 offset:35840
	ds_read_b128 v[232:235], v140 offset:36864
	ds_read_b128 v[236:239], v140 offset:37888
	ds_read_b128 v[240:243], v140 offset:38912
	ds_read_b128 v[244:247], v140 offset:39936
	buffer_load_dwordx4 v131, s[60:63], s52 offen lds
	s_mov_b32 m0, s31
	s_nop 0
	buffer_load_dwordx4 v135, s[60:63], s52 offen lds
	s_waitcnt vmcnt(8)
	s_waitcnt lgkmcnt(0)
	s_setprio 1
	s_barrier
	v_mfma_f32_16x16x32_bf16 v[126:129], v[142:145], v[194:197], v[126:129]
	v_mfma_f32_16x16x32_bf16 v[126:129], v[154:157], v[198:201], v[126:129]
	v_mfma_f32_16x16x32_bf16 v[118:121], v[142:145], v[202:205], v[118:121]
	v_mfma_f32_16x16x32_bf16 v[118:121], v[154:157], v[228:231], v[118:121]
	v_mfma_f32_16x16x32_bf16 v[110:113], v[142:145], v[232:235], v[110:113]
	v_mfma_f32_16x16x32_bf16 v[110:113], v[154:157], v[236:239], v[110:113]
	v_mfma_f32_16x16x32_bf16 v[102:105], v[142:145], v[240:243], v[102:105]
	v_mfma_f32_16x16x32_bf16 v[102:105], v[154:157], v[244:247], v[102:105]
	v_mfma_f32_16x16x32_bf16 v[98:101], v[170:173], v[240:243], v[98:101]
	v_mfma_f32_16x16x32_bf16 v[98:101], v[174:177], v[244:247], v[98:101]
	v_mfma_f32_16x16x32_bf16 v[106:109], v[170:173], v[232:235], v[106:109]
	v_mfma_f32_16x16x32_bf16 v[106:109], v[174:177], v[236:239], v[106:109]
	v_mfma_f32_16x16x32_bf16 v[114:117], v[170:173], v[202:205], v[114:117]
	v_mfma_f32_16x16x32_bf16 v[114:117], v[174:177], v[228:231], v[114:117]
	v_mfma_f32_16x16x32_bf16 v[122:125], v[170:173], v[194:197], v[122:125]
	v_mfma_f32_16x16x32_bf16 v[122:125], v[174:177], v[198:201], v[122:125]
	v_mfma_f32_16x16x32_bf16 v[58:61], v[186:189], v[194:197], v[58:61]
	v_mfma_f32_16x16x32_bf16 v[58:61], v[190:193], v[198:201], v[58:61]
	v_mfma_f32_16x16x32_bf16 v[50:53], v[186:189], v[202:205], v[50:53]
	v_mfma_f32_16x16x32_bf16 v[50:53], v[190:193], v[228:231], v[50:53]
	v_mfma_f32_16x16x32_bf16 v[42:45], v[186:189], v[232:235], v[42:45]
	v_mfma_f32_16x16x32_bf16 v[42:45], v[190:193], v[236:239], v[42:45]
	v_mfma_f32_16x16x32_bf16 v[34:37], v[186:189], v[240:243], v[34:37]
	v_mfma_f32_16x16x32_bf16 v[34:37], v[190:193], v[244:247], v[34:37]
	v_mfma_f32_16x16x32_bf16 v[38:41], v[178:181], v[240:243], v[38:41]
	v_mfma_f32_16x16x32_bf16 v[38:41], v[182:185], v[244:247], v[38:41]
	v_mfma_f32_16x16x32_bf16 v[46:49], v[178:181], v[232:235], v[46:49]
	v_mfma_f32_16x16x32_bf16 v[46:49], v[182:185], v[236:239], v[46:49]
	v_mfma_f32_16x16x32_bf16 v[54:57], v[178:181], v[202:205], v[54:57]
	v_mfma_f32_16x16x32_bf16 v[54:57], v[182:185], v[228:231], v[54:57]
	v_mfma_f32_16x16x32_bf16 v[62:65], v[178:181], v[194:197], v[62:65]
	v_mfma_f32_16x16x32_bf16 v[62:65], v[182:185], v[198:201], v[62:65]
	s_barrier
	s_setprio 0
	s_or_b32 s52, s47, 0x80
	s_mov_b32 m0, s33
	ds_read_b128 v[194:197], v140 offset:49152
	buffer_load_dwordx4 v134, s[64:67], s52 offen lds
	s_add_i32 s47, s47, 0x200080
	s_mov_b32 m0, s34
	ds_read_b128 v[198:201], v140 offset:50176
	buffer_load_dwordx4 v136, s[64:67], s52 offen lds
	s_mov_b32 m0, s37
	ds_read_b128 v[202:205], v140 offset:51200
	buffer_load_dwordx4 v134, s[64:67], s47 offen lds
	s_mov_b32 m0, s68
	ds_read_b128 v[228:231], v140 offset:52224
	buffer_load_dwordx4 v136, s[64:67], s47 offen lds
	s_mov_b32 m0, s35
	ds_read_b128 v[232:235], v140 offset:53248
	buffer_load_dwordx4 v131, s[60:63], s27 offen lds
	s_mov_b32 m0, s36
	ds_read_b128 v[236:239], v140 offset:54272
	buffer_load_dwordx4 v135, s[60:63], s27 offen lds
	ds_read_b128 v[240:243], v140 offset:55296
	ds_read_b128 v[244:247], v140 offset:56320
	s_waitcnt vmcnt(8)
	s_waitcnt lgkmcnt(0)
	s_setprio 1
	s_barrier
	v_mfma_f32_16x16x32_bf16 v[94:97], v[142:145], v[194:197], v[94:97]
	v_mfma_f32_16x16x32_bf16 v[94:97], v[154:157], v[198:201], v[94:97]
	v_mfma_f32_16x16x32_bf16 v[86:89], v[142:145], v[202:205], v[86:89]
	v_mfma_f32_16x16x32_bf16 v[86:89], v[154:157], v[228:231], v[86:89]
	v_mfma_f32_16x16x32_bf16 v[78:81], v[142:145], v[232:235], v[78:81]
	v_mfma_f32_16x16x32_bf16 v[78:81], v[154:157], v[236:239], v[78:81]
	v_mfma_f32_16x16x32_bf16 v[70:73], v[142:145], v[240:243], v[70:73]
	v_mfma_f32_16x16x32_bf16 v[70:73], v[154:157], v[244:247], v[70:73]
	v_mfma_f32_16x16x32_bf16 v[66:69], v[170:173], v[240:243], v[66:69]
	v_mfma_f32_16x16x32_bf16 v[66:69], v[174:177], v[244:247], v[66:69]
	v_mfma_f32_16x16x32_bf16 v[74:77], v[170:173], v[232:235], v[74:77]
	v_mfma_f32_16x16x32_bf16 v[74:77], v[174:177], v[236:239], v[74:77]
	v_mfma_f32_16x16x32_bf16 v[82:85], v[170:173], v[202:205], v[82:85]
	v_mfma_f32_16x16x32_bf16 v[82:85], v[174:177], v[228:231], v[82:85]
	v_mfma_f32_16x16x32_bf16 v[90:93], v[170:173], v[194:197], v[90:93]
	v_mfma_f32_16x16x32_bf16 v[90:93], v[174:177], v[198:201], v[90:93]
	v_mfma_f32_16x16x32_bf16 v[26:29], v[186:189], v[194:197], v[26:29]
	v_mfma_f32_16x16x32_bf16 v[26:29], v[190:193], v[198:201], v[26:29]
	v_mfma_f32_16x16x32_bf16 v[18:21], v[186:189], v[202:205], v[18:21]
	v_mfma_f32_16x16x32_bf16 v[18:21], v[190:193], v[228:231], v[18:21]
	v_mfma_f32_16x16x32_bf16 v[10:13], v[186:189], v[232:235], v[10:13]
	v_mfma_f32_16x16x32_bf16 v[10:13], v[190:193], v[236:239], v[10:13]
	v_mfma_f32_16x16x32_bf16 v[2:5], v[186:189], v[240:243], v[2:5]
	v_mfma_f32_16x16x32_bf16 v[2:5], v[190:193], v[244:247], v[2:5]
	v_mfma_f32_16x16x32_bf16 v[6:9], v[178:181], v[240:243], v[6:9]
	v_mfma_f32_16x16x32_bf16 v[6:9], v[182:185], v[244:247], v[6:9]
	v_mfma_f32_16x16x32_bf16 v[14:17], v[178:181], v[232:235], v[14:17]
	v_mfma_f32_16x16x32_bf16 v[14:17], v[182:185], v[236:239], v[14:17]
	v_mfma_f32_16x16x32_bf16 v[22:25], v[178:181], v[202:205], v[22:25]
	v_mfma_f32_16x16x32_bf16 v[22:25], v[182:185], v[228:231], v[22:25]
	v_mfma_f32_16x16x32_bf16 v[30:33], v[178:181], v[194:197], v[30:33]
	v_mfma_f32_16x16x32_bf16 v[30:33], v[182:185], v[198:201], v[30:33]
	s_barrier
	s_setprio 0
	s_add_i32 s26, s26, 2
	s_addk_i32 s19, 0x100
	s_addk_i32 s22, 0x100
	s_cmpk_gt_u32 s26, 0x7d
.LBB0_1223:
	v_add_u32_e32 v141, 0x10000, v139
	ds_read_b128 v[142:145], v141
	ds_read_b128 v[154:157], v141 offset:1024
	ds_read_b128 v[170:173], v141 offset:2048
	ds_read_b128 v[174:177], v141 offset:3072
	v_add_u32_e32 v141, 0x14000, v139
	ds_read_b128 v[178:181], v141
	ds_read_b128 v[182:185], v141 offset:1024
	ds_read_b128 v[186:189], v141 offset:2048
	ds_read_b128 v[190:193], v141 offset:3072
	s_add_i32 s27, s19, 0xffe00080
	s_cmpk_eq_i32 s26, 0x7c
	s_cselect_b32 s52, s8, s27
	s_cselect_b32 s47, s9, s22
	s_or_b32 s27, s52, 0x80
	s_mov_b32 m0, s71
	ds_read_b128 v[194:197], v140
	ds_read_b128 v[198:201], v140 offset:1024
	ds_read_b128 v[202:205], v140 offset:2048
	ds_read_b128 v[228:231], v140 offset:3072
	ds_read_b128 v[232:235], v140 offset:4096
	ds_read_b128 v[236:239], v140 offset:5120
	ds_read_b128 v[240:243], v140 offset:6144
	ds_read_b128 v[244:247], v140 offset:7168
	buffer_load_dwordx4 v131, s[60:63], s19 offen lds
	s_mov_b32 m0, s72
	s_nop 0
	buffer_load_dwordx4 v135, s[60:63], s19 offen lds
	s_waitcnt vmcnt(8)
	s_waitcnt lgkmcnt(0)
	s_setprio 1
	s_barrier
	v_mfma_f32_16x16x32_bf16 v[126:129], v[142:145], v[194:197], v[126:129]
	v_mfma_f32_16x16x32_bf16 v[126:129], v[154:157], v[198:201], v[126:129]
	v_mfma_f32_16x16x32_bf16 v[118:121], v[142:145], v[202:205], v[118:121]
	v_mfma_f32_16x16x32_bf16 v[118:121], v[154:157], v[228:231], v[118:121]
	v_mfma_f32_16x16x32_bf16 v[110:113], v[142:145], v[232:235], v[110:113]
	v_mfma_f32_16x16x32_bf16 v[110:113], v[154:157], v[236:239], v[110:113]
	v_mfma_f32_16x16x32_bf16 v[102:105], v[142:145], v[240:243], v[102:105]
	v_mfma_f32_16x16x32_bf16 v[102:105], v[154:157], v[244:247], v[102:105]
	v_mfma_f32_16x16x32_bf16 v[98:101], v[170:173], v[240:243], v[98:101]
	v_mfma_f32_16x16x32_bf16 v[98:101], v[174:177], v[244:247], v[98:101]
	v_mfma_f32_16x16x32_bf16 v[106:109], v[170:173], v[232:235], v[106:109]
	v_mfma_f32_16x16x32_bf16 v[106:109], v[174:177], v[236:239], v[106:109]
	v_mfma_f32_16x16x32_bf16 v[114:117], v[170:173], v[202:205], v[114:117]
	v_mfma_f32_16x16x32_bf16 v[114:117], v[174:177], v[228:231], v[114:117]
	v_mfma_f32_16x16x32_bf16 v[122:125], v[170:173], v[194:197], v[122:125]
	v_mfma_f32_16x16x32_bf16 v[122:125], v[174:177], v[198:201], v[122:125]
	v_mfma_f32_16x16x32_bf16 v[58:61], v[186:189], v[194:197], v[58:61]
	v_mfma_f32_16x16x32_bf16 v[58:61], v[190:193], v[198:201], v[58:61]
	v_mfma_f32_16x16x32_bf16 v[50:53], v[186:189], v[202:205], v[50:53]
	v_mfma_f32_16x16x32_bf16 v[50:53], v[190:193], v[228:231], v[50:53]
	v_mfma_f32_16x16x32_bf16 v[42:45], v[186:189], v[232:235], v[42:45]
	v_mfma_f32_16x16x32_bf16 v[42:45], v[190:193], v[236:239], v[42:45]
	v_mfma_f32_16x16x32_bf16 v[34:37], v[186:189], v[240:243], v[34:37]
	v_mfma_f32_16x16x32_bf16 v[34:37], v[190:193], v[244:247], v[34:37]
	v_mfma_f32_16x16x32_bf16 v[38:41], v[178:181], v[240:243], v[38:41]
	v_mfma_f32_16x16x32_bf16 v[38:41], v[182:185], v[244:247], v[38:41]
	v_mfma_f32_16x16x32_bf16 v[46:49], v[178:181], v[232:235], v[46:49]
	v_mfma_f32_16x16x32_bf16 v[46:49], v[182:185], v[236:239], v[46:49]
	v_mfma_f32_16x16x32_bf16 v[54:57], v[178:181], v[202:205], v[54:57]
	v_mfma_f32_16x16x32_bf16 v[54:57], v[182:185], v[228:231], v[54:57]
	v_mfma_f32_16x16x32_bf16 v[62:65], v[178:181], v[194:197], v[62:65]
	v_mfma_f32_16x16x32_bf16 v[62:65], v[182:185], v[198:201], v[62:65]
	s_barrier
	s_setprio 0
	s_mov_b32 s66, s62
	s_mov_b32 s67, s63
	s_mov_b32 m0, s2
	ds_read_b128 v[194:197], v140 offset:16384
	buffer_load_dwordx4 v134, s[64:67], s47 offen lds
	s_add_i32 s53, s47, 0x200000
	s_mov_b32 m0, s21
	ds_read_b128 v[198:201], v140 offset:17408
	buffer_load_dwordx4 v136, s[64:67], s47 offen lds
	s_mov_b32 m0, s23
	ds_read_b128 v[202:205], v140 offset:18432
	buffer_load_dwordx4 v134, s[64:67], s53 offen lds
	s_mov_b32 m0, s24
	ds_read_b128 v[228:231], v140 offset:19456
	buffer_load_dwordx4 v136, s[64:67], s53 offen lds
	s_mov_b32 m0, s16
	ds_read_b128 v[232:235], v140 offset:20480
	buffer_load_dwordx4 v131, s[60:63], s52 offen lds
	s_mov_b32 m0, s25
	ds_read_b128 v[236:239], v140 offset:21504
	buffer_load_dwordx4 v135, s[60:63], s52 offen lds
	ds_read_b128 v[240:243], v140 offset:22528
	ds_read_b128 v[244:247], v140 offset:23552
	s_waitcnt vmcnt(8)
	s_waitcnt lgkmcnt(0)
	s_setprio 1
	s_barrier
	v_mfma_f32_16x16x32_bf16 v[94:97], v[142:145], v[194:197], v[94:97]
	v_mfma_f32_16x16x32_bf16 v[94:97], v[154:157], v[198:201], v[94:97]
	v_mfma_f32_16x16x32_bf16 v[86:89], v[142:145], v[202:205], v[86:89]
	v_mfma_f32_16x16x32_bf16 v[86:89], v[154:157], v[228:231], v[86:89]
	v_mfma_f32_16x16x32_bf16 v[78:81], v[142:145], v[232:235], v[78:81]
	v_mfma_f32_16x16x32_bf16 v[78:81], v[154:157], v[236:239], v[78:81]
	v_mfma_f32_16x16x32_bf16 v[70:73], v[142:145], v[240:243], v[70:73]
	v_mfma_f32_16x16x32_bf16 v[70:73], v[154:157], v[244:247], v[70:73]
	v_mfma_f32_16x16x32_bf16 v[66:69], v[170:173], v[240:243], v[66:69]
	v_mfma_f32_16x16x32_bf16 v[66:69], v[174:177], v[244:247], v[66:69]
	v_mfma_f32_16x16x32_bf16 v[74:77], v[170:173], v[232:235], v[74:77]
	v_mfma_f32_16x16x32_bf16 v[74:77], v[174:177], v[236:239], v[74:77]
	v_mfma_f32_16x16x32_bf16 v[82:85], v[170:173], v[202:205], v[82:85]
	v_mfma_f32_16x16x32_bf16 v[82:85], v[174:177], v[228:231], v[82:85]
	v_mfma_f32_16x16x32_bf16 v[90:93], v[170:173], v[194:197], v[90:93]
	v_mfma_f32_16x16x32_bf16 v[90:93], v[174:177], v[198:201], v[90:93]
	v_mfma_f32_16x16x32_bf16 v[26:29], v[186:189], v[194:197], v[26:29]
	v_mfma_f32_16x16x32_bf16 v[26:29], v[190:193], v[198:201], v[26:29]
	v_mfma_f32_16x16x32_bf16 v[18:21], v[186:189], v[202:205], v[18:21]
	v_mfma_f32_16x16x32_bf16 v[18:21], v[190:193], v[228:231], v[18:21]
	v_mfma_f32_16x16x32_bf16 v[10:13], v[186:189], v[232:235], v[10:13]
	v_mfma_f32_16x16x32_bf16 v[10:13], v[190:193], v[236:239], v[10:13]
	v_mfma_f32_16x16x32_bf16 v[2:5], v[186:189], v[240:243], v[2:5]
	v_mfma_f32_16x16x32_bf16 v[2:5], v[190:193], v[244:247], v[2:5]
	v_mfma_f32_16x16x32_bf16 v[6:9], v[178:181], v[240:243], v[6:9]
	v_mfma_f32_16x16x32_bf16 v[6:9], v[182:185], v[244:247], v[6:9]
	v_mfma_f32_16x16x32_bf16 v[14:17], v[178:181], v[232:235], v[14:17]
	v_mfma_f32_16x16x32_bf16 v[14:17], v[182:185], v[236:239], v[14:17]
	v_mfma_f32_16x16x32_bf16 v[22:25], v[178:181], v[202:205], v[22:25]
	v_mfma_f32_16x16x32_bf16 v[22:25], v[182:185], v[228:231], v[22:25]
	v_mfma_f32_16x16x32_bf16 v[30:33], v[178:181], v[194:197], v[30:33]
	v_mfma_f32_16x16x32_bf16 v[30:33], v[182:185], v[198:201], v[30:33]
	s_barrier
	s_setprio 0
	v_add_u32_e32 v141, 0x18000, v139
	ds_read_b128 v[142:145], v141
	ds_read_b128 v[154:157], v141 offset:1024
	ds_read_b128 v[170:173], v141 offset:2048
	ds_read_b128 v[174:177], v141 offset:3072
	v_add_u32_e32 v141, 0x1c000, v139
	ds_read_b128 v[178:181], v141
	ds_read_b128 v[182:185], v141 offset:1024
	ds_read_b128 v[186:189], v141 offset:2048
	ds_read_b128 v[190:193], v141 offset:3072
	s_add_i32 s52, s52, 0x200000
	s_mov_b32 m0, s30
	ds_read_b128 v[194:197], v140 offset:32768
	ds_read_b128 v[198:201], v140 offset:33792
	ds_read_b128 v[202:205], v140 offset:34816
	ds_read_b128 v[228:231], v140 offset:35840
	ds_read_b128 v[232:235], v140 offset:36864
	ds_read_b128 v[236:239], v140 offset:37888
	ds_read_b128 v[240:243], v140 offset:38912
	ds_read_b128 v[244:247], v140 offset:39936
	buffer_load_dwordx4 v131, s[60:63], s52 offen lds
	s_mov_b32 m0, s31
	s_nop 0
	buffer_load_dwordx4 v135, s[60:63], s52 offen lds
	s_waitcnt vmcnt(8)
	s_waitcnt lgkmcnt(0)
	s_setprio 1
	s_barrier
	v_mfma_f32_16x16x32_bf16 v[126:129], v[142:145], v[194:197], v[126:129]
	v_mfma_f32_16x16x32_bf16 v[126:129], v[154:157], v[198:201], v[126:129]
	v_mfma_f32_16x16x32_bf16 v[118:121], v[142:145], v[202:205], v[118:121]
	v_mfma_f32_16x16x32_bf16 v[118:121], v[154:157], v[228:231], v[118:121]
	v_mfma_f32_16x16x32_bf16 v[110:113], v[142:145], v[232:235], v[110:113]
	v_mfma_f32_16x16x32_bf16 v[110:113], v[154:157], v[236:239], v[110:113]
	v_mfma_f32_16x16x32_bf16 v[102:105], v[142:145], v[240:243], v[102:105]
	v_mfma_f32_16x16x32_bf16 v[102:105], v[154:157], v[244:247], v[102:105]
	v_mfma_f32_16x16x32_bf16 v[98:101], v[170:173], v[240:243], v[98:101]
	v_mfma_f32_16x16x32_bf16 v[98:101], v[174:177], v[244:247], v[98:101]
	v_mfma_f32_16x16x32_bf16 v[106:109], v[170:173], v[232:235], v[106:109]
	v_mfma_f32_16x16x32_bf16 v[106:109], v[174:177], v[236:239], v[106:109]
	v_mfma_f32_16x16x32_bf16 v[114:117], v[170:173], v[202:205], v[114:117]
	v_mfma_f32_16x16x32_bf16 v[114:117], v[174:177], v[228:231], v[114:117]
	v_mfma_f32_16x16x32_bf16 v[122:125], v[170:173], v[194:197], v[122:125]
	v_mfma_f32_16x16x32_bf16 v[122:125], v[174:177], v[198:201], v[122:125]
	v_mfma_f32_16x16x32_bf16 v[58:61], v[186:189], v[194:197], v[58:61]
	v_mfma_f32_16x16x32_bf16 v[58:61], v[190:193], v[198:201], v[58:61]
	v_mfma_f32_16x16x32_bf16 v[50:53], v[186:189], v[202:205], v[50:53]
	v_mfma_f32_16x16x32_bf16 v[50:53], v[190:193], v[228:231], v[50:53]
	v_mfma_f32_16x16x32_bf16 v[42:45], v[186:189], v[232:235], v[42:45]
	v_mfma_f32_16x16x32_bf16 v[42:45], v[190:193], v[236:239], v[42:45]
	v_mfma_f32_16x16x32_bf16 v[34:37], v[186:189], v[240:243], v[34:37]
	v_mfma_f32_16x16x32_bf16 v[34:37], v[190:193], v[244:247], v[34:37]
	v_mfma_f32_16x16x32_bf16 v[38:41], v[178:181], v[240:243], v[38:41]
	v_mfma_f32_16x16x32_bf16 v[38:41], v[182:185], v[244:247], v[38:41]
	v_mfma_f32_16x16x32_bf16 v[46:49], v[178:181], v[232:235], v[46:49]
	v_mfma_f32_16x16x32_bf16 v[46:49], v[182:185], v[236:239], v[46:49]
	v_mfma_f32_16x16x32_bf16 v[54:57], v[178:181], v[202:205], v[54:57]
	v_mfma_f32_16x16x32_bf16 v[54:57], v[182:185], v[228:231], v[54:57]
	v_mfma_f32_16x16x32_bf16 v[62:65], v[178:181], v[194:197], v[62:65]
	v_mfma_f32_16x16x32_bf16 v[62:65], v[182:185], v[198:201], v[62:65]
	s_barrier
	s_setprio 0
	s_or_b32 s52, s47, 0x80
	s_mov_b32 m0, s33
	ds_read_b128 v[194:197], v140 offset:49152
	buffer_load_dwordx4 v134, s[64:67], s52 offen lds
	s_add_i32 s47, s47, 0x200080
	s_mov_b32 m0, s34
	ds_read_b128 v[198:201], v140 offset:50176
	buffer_load_dwordx4 v136, s[64:67], s52 offen lds
	s_mov_b32 m0, s37
	ds_read_b128 v[202:205], v140 offset:51200
	buffer_load_dwordx4 v134, s[64:67], s47 offen lds
	s_mov_b32 m0, s68
	ds_read_b128 v[228:231], v140 offset:52224
	buffer_load_dwordx4 v136, s[64:67], s47 offen lds
	s_mov_b32 m0, s35
	ds_read_b128 v[232:235], v140 offset:53248
	buffer_load_dwordx4 v131, s[60:63], s27 offen lds
	s_mov_b32 m0, s36
	ds_read_b128 v[236:239], v140 offset:54272
	buffer_load_dwordx4 v135, s[60:63], s27 offen lds
	ds_read_b128 v[240:243], v140 offset:55296
	ds_read_b128 v[244:247], v140 offset:56320
	s_waitcnt vmcnt(8)
	s_waitcnt lgkmcnt(0)
	s_setprio 1
	s_barrier
	v_mfma_f32_16x16x32_bf16 v[94:97], v[142:145], v[194:197], v[94:97]
	v_mfma_f32_16x16x32_bf16 v[94:97], v[154:157], v[198:201], v[94:97]
	v_mfma_f32_16x16x32_bf16 v[86:89], v[142:145], v[202:205], v[86:89]
	v_mfma_f32_16x16x32_bf16 v[86:89], v[154:157], v[228:231], v[86:89]
	v_mfma_f32_16x16x32_bf16 v[78:81], v[142:145], v[232:235], v[78:81]
	v_mfma_f32_16x16x32_bf16 v[78:81], v[154:157], v[236:239], v[78:81]
	v_mfma_f32_16x16x32_bf16 v[70:73], v[142:145], v[240:243], v[70:73]
	v_mfma_f32_16x16x32_bf16 v[70:73], v[154:157], v[244:247], v[70:73]
	v_mfma_f32_16x16x32_bf16 v[66:69], v[170:173], v[240:243], v[66:69]
	v_mfma_f32_16x16x32_bf16 v[66:69], v[174:177], v[244:247], v[66:69]
	v_mfma_f32_16x16x32_bf16 v[74:77], v[170:173], v[232:235], v[74:77]
	v_mfma_f32_16x16x32_bf16 v[74:77], v[174:177], v[236:239], v[74:77]
	v_mfma_f32_16x16x32_bf16 v[82:85], v[170:173], v[202:205], v[82:85]
	v_mfma_f32_16x16x32_bf16 v[82:85], v[174:177], v[228:231], v[82:85]
	v_mfma_f32_16x16x32_bf16 v[90:93], v[170:173], v[194:197], v[90:93]
	v_mfma_f32_16x16x32_bf16 v[90:93], v[174:177], v[198:201], v[90:93]
	v_mfma_f32_16x16x32_bf16 v[26:29], v[186:189], v[194:197], v[26:29]
	v_mfma_f32_16x16x32_bf16 v[26:29], v[190:193], v[198:201], v[26:29]
	v_mfma_f32_16x16x32_bf16 v[18:21], v[186:189], v[202:205], v[18:21]
	v_mfma_f32_16x16x32_bf16 v[18:21], v[190:193], v[228:231], v[18:21]
	v_mfma_f32_16x16x32_bf16 v[10:13], v[186:189], v[232:235], v[10:13]
	v_mfma_f32_16x16x32_bf16 v[10:13], v[190:193], v[236:239], v[10:13]
	v_mfma_f32_16x16x32_bf16 v[2:5], v[186:189], v[240:243], v[2:5]
	v_mfma_f32_16x16x32_bf16 v[2:5], v[190:193], v[244:247], v[2:5]
	v_mfma_f32_16x16x32_bf16 v[6:9], v[178:181], v[240:243], v[6:9]
	v_mfma_f32_16x16x32_bf16 v[6:9], v[182:185], v[244:247], v[6:9]
	v_mfma_f32_16x16x32_bf16 v[14:17], v[178:181], v[232:235], v[14:17]
	v_mfma_f32_16x16x32_bf16 v[14:17], v[182:185], v[236:239], v[14:17]
	v_mfma_f32_16x16x32_bf16 v[22:25], v[178:181], v[202:205], v[22:25]
	v_mfma_f32_16x16x32_bf16 v[22:25], v[182:185], v[228:231], v[22:25]
	v_mfma_f32_16x16x32_bf16 v[30:33], v[178:181], v[194:197], v[30:33]
	v_mfma_f32_16x16x32_bf16 v[30:33], v[182:185], v[198:201], v[30:33]
	s_barrier
	s_setprio 0
	s_add_i32 s26, s26, 2
	s_addk_i32 s19, 0x100
	s_addk_i32 s22, 0x100
	s_cmpk_gt_u32 s26, 0x7d
	s_cbranch_scc0 .LBB0_1223
	s_and_b64 vcc, exec, s[42:43]
	s_cbranch_vccz .LBB0_1226
	s_barrier

.LBB0_1252:
	s_lshl_b32 s12, s73, 20
	s_and_b64 s[8:9], s[40:41], exec
	s_cselect_b32 s8, s12, s26
	s_lshl_b32 s22, s82, 20
	s_and_b64 s[70:71], s[40:41], exec
	s_cselect_b32 s9, s22, s27
	s_add_i32 s26, s26, 0x80080
	s_addk_i32 s27, 0x100
	s_mov_b32 s83, -2
	v_add_u32_e32 v141, 0x10000, v139
	ds_read_b128 v[142:145], v141
	ds_read_b128 v[154:157], v141 offset:1024
	ds_read_b128 v[170:173], v141 offset:2048
	ds_read_b128 v[174:177], v141 offset:3072
	v_add_u32_e32 v141, 0x14000, v139
	ds_read_b128 v[178:181], v141
	ds_read_b128 v[182:185], v141 offset:1024
	ds_read_b128 v[186:189], v141 offset:2048
	ds_read_b128 v[190:193], v141 offset:3072
	s_add_i32 s52, s26, 0xfff80080
	s_cmp_eq_u32 s83, 28
	s_cselect_b32 s52, s8, s52
	s_cselect_b32 s85, s9, s27
	s_or_b32 s84, s52, 0x80
	s_mov_b32 m0, s72
	ds_read_b128 v[194:197], v140
	ds_read_b128 v[198:201], v140 offset:1024
	ds_read_b128 v[202:205], v140 offset:2048
	ds_read_b128 v[228:231], v140 offset:3072
	ds_read_b128 v[232:235], v140 offset:4096
	ds_read_b128 v[236:239], v140 offset:5120
	ds_read_b128 v[240:243], v140 offset:6144
	ds_read_b128 v[244:247], v140 offset:7168
	buffer_load_dwordx4 v131, s[60:63], s26 offen lds
	s_mov_b32 m0, s46
	s_nop 0
	buffer_load_dwordx4 v135, s[60:63], s26 offen lds
	s_waitcnt vmcnt(8)
	s_waitcnt lgkmcnt(0)
	s_setprio 1
	s_barrier
	v_mfma_f32_16x16x32_bf16 v[126:129], v[142:145], v[194:197], 0
	v_mfma_f32_16x16x32_bf16 v[126:129], v[154:157], v[198:201], v[126:129]
	v_mfma_f32_16x16x32_bf16 v[118:121], v[142:145], v[202:205], 0
	v_mfma_f32_16x16x32_bf16 v[118:121], v[154:157], v[228:231], v[118:121]
	v_mfma_f32_16x16x32_bf16 v[110:113], v[142:145], v[232:235], 0
	v_mfma_f32_16x16x32_bf16 v[110:113], v[154:157], v[236:239], v[110:113]
	v_mfma_f32_16x16x32_bf16 v[102:105], v[142:145], v[240:243], 0
	v_mfma_f32_16x16x32_bf16 v[102:105], v[154:157], v[244:247], v[102:105]
	v_mfma_f32_16x16x32_bf16 v[98:101], v[170:173], v[240:243], 0
	v_mfma_f32_16x16x32_bf16 v[98:101], v[174:177], v[244:247], v[98:101]
	v_mfma_f32_16x16x32_bf16 v[106:109], v[170:173], v[232:235], 0
	v_mfma_f32_16x16x32_bf16 v[106:109], v[174:177], v[236:239], v[106:109]
	v_mfma_f32_16x16x32_bf16 v[114:117], v[170:173], v[202:205], 0
	v_mfma_f32_16x16x32_bf16 v[114:117], v[174:177], v[228:231], v[114:117]
	v_mfma_f32_16x16x32_bf16 v[122:125], v[170:173], v[194:197], 0
	v_mfma_f32_16x16x32_bf16 v[122:125], v[174:177], v[198:201], v[122:125]
	v_mfma_f32_16x16x32_bf16 v[58:61], v[186:189], v[194:197], 0
	v_mfma_f32_16x16x32_bf16 v[58:61], v[190:193], v[198:201], v[58:61]
	v_mfma_f32_16x16x32_bf16 v[50:53], v[186:189], v[202:205], 0
	v_mfma_f32_16x16x32_bf16 v[50:53], v[190:193], v[228:231], v[50:53]
	v_mfma_f32_16x16x32_bf16 v[42:45], v[186:189], v[232:235], 0
	v_mfma_f32_16x16x32_bf16 v[42:45], v[190:193], v[236:239], v[42:45]
	v_mfma_f32_16x16x32_bf16 v[34:37], v[186:189], v[240:243], 0
	v_mfma_f32_16x16x32_bf16 v[34:37], v[190:193], v[244:247], v[34:37]
	v_mfma_f32_16x16x32_bf16 v[38:41], v[178:181], v[240:243], 0
	v_mfma_f32_16x16x32_bf16 v[38:41], v[182:185], v[244:247], v[38:41]
	v_mfma_f32_16x16x32_bf16 v[46:49], v[178:181], v[232:235], 0
	v_mfma_f32_16x16x32_bf16 v[46:49], v[182:185], v[236:239], v[46:49]
	v_mfma_f32_16x16x32_bf16 v[54:57], v[178:181], v[202:205], 0
	v_mfma_f32_16x16x32_bf16 v[54:57], v[182:185], v[228:231], v[54:57]
	v_mfma_f32_16x16x32_bf16 v[62:65], v[178:181], v[194:197], 0
	v_mfma_f32_16x16x32_bf16 v[62:65], v[182:185], v[198:201], v[62:65]
	s_barrier
	s_setprio 0
	s_mov_b32 s70, s62
	s_mov_b32 s71, s63
	s_mov_b32 m0, s21
	ds_read_b128 v[194:197], v140 offset:16384
	buffer_load_dwordx4 v134, s[68:71], s85 offen lds
	s_add_i32 s53, s85, 0x80000
	s_mov_b32 m0, s23
	ds_read_b128 v[198:201], v140 offset:17408
	buffer_load_dwordx4 v136, s[68:71], s85 offen lds
	s_mov_b32 m0, s24
	ds_read_b128 v[202:205], v140 offset:18432
	buffer_load_dwordx4 v134, s[68:71], s53 offen lds
	s_mov_b32 m0, s25
	ds_read_b128 v[228:231], v140 offset:19456
	buffer_load_dwordx4 v136, s[68:71], s53 offen lds
	s_mov_b32 m0, s16
	ds_read_b128 v[232:235], v140 offset:20480
	buffer_load_dwordx4 v131, s[60:63], s52 offen lds
	s_mov_b32 m0, s30
	ds_read_b128 v[236:239], v140 offset:21504
	buffer_load_dwordx4 v135, s[60:63], s52 offen lds
	ds_read_b128 v[240:243], v140 offset:22528
	ds_read_b128 v[244:247], v140 offset:23552
	s_waitcnt vmcnt(8)
	s_waitcnt lgkmcnt(0)
	s_setprio 1
	s_barrier
	v_mfma_f32_16x16x32_bf16 v[94:97], v[142:145], v[194:197], 0
	v_mfma_f32_16x16x32_bf16 v[94:97], v[154:157], v[198:201], v[94:97]
	v_mfma_f32_16x16x32_bf16 v[86:89], v[142:145], v[202:205], 0
	v_mfma_f32_16x16x32_bf16 v[86:89], v[154:157], v[228:231], v[86:89]
	v_mfma_f32_16x16x32_bf16 v[78:81], v[142:145], v[232:235], 0
	v_mfma_f32_16x16x32_bf16 v[78:81], v[154:157], v[236:239], v[78:81]
	v_mfma_f32_16x16x32_bf16 v[70:73], v[142:145], v[240:243], 0
	v_mfma_f32_16x16x32_bf16 v[70:73], v[154:157], v[244:247], v[70:73]
	v_mfma_f32_16x16x32_bf16 v[66:69], v[170:173], v[240:243], 0
	v_mfma_f32_16x16x32_bf16 v[66:69], v[174:177], v[244:247], v[66:69]
	v_mfma_f32_16x16x32_bf16 v[74:77], v[170:173], v[232:235], 0
	v_mfma_f32_16x16x32_bf16 v[74:77], v[174:177], v[236:239], v[74:77]
	v_mfma_f32_16x16x32_bf16 v[82:85], v[170:173], v[202:205], 0
	v_mfma_f32_16x16x32_bf16 v[82:85], v[174:177], v[228:231], v[82:85]
	v_mfma_f32_16x16x32_bf16 v[90:93], v[170:173], v[194:197], 0
	v_mfma_f32_16x16x32_bf16 v[90:93], v[174:177], v[198:201], v[90:93]
	v_mfma_f32_16x16x32_bf16 v[26:29], v[186:189], v[194:197], 0
	v_mfma_f32_16x16x32_bf16 v[26:29], v[190:193], v[198:201], v[26:29]
	v_mfma_f32_16x16x32_bf16 v[18:21], v[186:189], v[202:205], 0
	v_mfma_f32_16x16x32_bf16 v[18:21], v[190:193], v[228:231], v[18:21]
	v_mfma_f32_16x16x32_bf16 v[10:13], v[186:189], v[232:235], 0
	v_mfma_f32_16x16x32_bf16 v[10:13], v[190:193], v[236:239], v[10:13]
	v_mfma_f32_16x16x32_bf16 v[2:5], v[186:189], v[240:243], 0
	v_mfma_f32_16x16x32_bf16 v[2:5], v[190:193], v[244:247], v[2:5]
	v_mfma_f32_16x16x32_bf16 v[6:9], v[178:181], v[240:243], 0
	v_mfma_f32_16x16x32_bf16 v[6:9], v[182:185], v[244:247], v[6:9]
	v_mfma_f32_16x16x32_bf16 v[14:17], v[178:181], v[232:235], 0
	v_mfma_f32_16x16x32_bf16 v[14:17], v[182:185], v[236:239], v[14:17]
	v_mfma_f32_16x16x32_bf16 v[22:25], v[178:181], v[202:205], 0
	v_mfma_f32_16x16x32_bf16 v[22:25], v[182:185], v[228:231], v[22:25]
	v_mfma_f32_16x16x32_bf16 v[30:33], v[178:181], v[194:197], 0
	v_mfma_f32_16x16x32_bf16 v[30:33], v[182:185], v[198:201], v[30:33]
	s_barrier
	s_setprio 0
	v_add_u32_e32 v141, 0x18000, v139
	ds_read_b128 v[142:145], v141
	ds_read_b128 v[154:157], v141 offset:1024
	ds_read_b128 v[170:173], v141 offset:2048
	ds_read_b128 v[174:177], v141 offset:3072
	v_add_u32_e32 v141, 0x1c000, v139
	ds_read_b128 v[178:181], v141
	ds_read_b128 v[182:185], v141 offset:1024
	ds_read_b128 v[186:189], v141 offset:2048
	ds_read_b128 v[190:193], v141 offset:3072
	s_add_i32 s52, s52, 0x80000
	s_mov_b32 m0, s31
	ds_read_b128 v[194:197], v140 offset:32768
	ds_read_b128 v[198:201], v140 offset:33792
	ds_read_b128 v[202:205], v140 offset:34816
	ds_read_b128 v[228:231], v140 offset:35840
	ds_read_b128 v[232:235], v140 offset:36864
	ds_read_b128 v[236:239], v140 offset:37888
	ds_read_b128 v[240:243], v140 offset:38912
	ds_read_b128 v[244:247], v140 offset:39936
	buffer_load_dwordx4 v131, s[60:63], s52 offen lds
	s_mov_b32 m0, s33
	s_nop 0
	buffer_load_dwordx4 v135, s[60:63], s52 offen lds
	s_waitcnt vmcnt(8)
	s_waitcnt lgkmcnt(0)
	s_setprio 1
	s_barrier
	v_mfma_f32_16x16x32_bf16 v[126:129], v[142:145], v[194:197], v[126:129]
	v_mfma_f32_16x16x32_bf16 v[126:129], v[154:157], v[198:201], v[126:129]
	v_mfma_f32_16x16x32_bf16 v[118:121], v[142:145], v[202:205], v[118:121]
	v_mfma_f32_16x16x32_bf16 v[118:121], v[154:157], v[228:231], v[118:121]
	v_mfma_f32_16x16x32_bf16 v[110:113], v[142:145], v[232:235], v[110:113]
	v_mfma_f32_16x16x32_bf16 v[110:113], v[154:157], v[236:239], v[110:113]
	v_mfma_f32_16x16x32_bf16 v[102:105], v[142:145], v[240:243], v[102:105]
	v_mfma_f32_16x16x32_bf16 v[102:105], v[154:157], v[244:247], v[102:105]
	v_mfma_f32_16x16x32_bf16 v[98:101], v[170:173], v[240:243], v[98:101]
	v_mfma_f32_16x16x32_bf16 v[98:101], v[174:177], v[244:247], v[98:101]
	v_mfma_f32_16x16x32_bf16 v[106:109], v[170:173], v[232:235], v[106:109]
	v_mfma_f32_16x16x32_bf16 v[106:109], v[174:177], v[236:239], v[106:109]
	v_mfma_f32_16x16x32_bf16 v[114:117], v[170:173], v[202:205], v[114:117]
	v_mfma_f32_16x16x32_bf16 v[114:117], v[174:177], v[228:231], v[114:117]
	v_mfma_f32_16x16x32_bf16 v[122:125], v[170:173], v[194:197], v[122:125]
	v_mfma_f32_16x16x32_bf16 v[122:125], v[174:177], v[198:201], v[122:125]
	v_mfma_f32_16x16x32_bf16 v[58:61], v[186:189], v[194:197], v[58:61]
	v_mfma_f32_16x16x32_bf16 v[58:61], v[190:193], v[198:201], v[58:61]
	v_mfma_f32_16x16x32_bf16 v[50:53], v[186:189], v[202:205], v[50:53]
	v_mfma_f32_16x16x32_bf16 v[50:53], v[190:193], v[228:231], v[50:53]
	v_mfma_f32_16x16x32_bf16 v[42:45], v[186:189], v[232:235], v[42:45]
	v_mfma_f32_16x16x32_bf16 v[42:45], v[190:193], v[236:239], v[42:45]
	v_mfma_f32_16x16x32_bf16 v[34:37], v[186:189], v[240:243], v[34:37]
	v_mfma_f32_16x16x32_bf16 v[34:37], v[190:193], v[244:247], v[34:37]
	v_mfma_f32_16x16x32_bf16 v[38:41], v[178:181], v[240:243], v[38:41]
	v_mfma_f32_16x16x32_bf16 v[38:41], v[182:185], v[244:247], v[38:41]
	v_mfma_f32_16x16x32_bf16 v[46:49], v[178:181], v[232:235], v[46:49]
	v_mfma_f32_16x16x32_bf16 v[46:49], v[182:185], v[236:239], v[46:49]
	v_mfma_f32_16x16x32_bf16 v[54:57], v[178:181], v[202:205], v[54:57]
	v_mfma_f32_16x16x32_bf16 v[54:57], v[182:185], v[228:231], v[54:57]
	v_mfma_f32_16x16x32_bf16 v[62:65], v[178:181], v[194:197], v[62:65]
	v_mfma_f32_16x16x32_bf16 v[62:65], v[182:185], v[198:201], v[62:65]
	s_barrier
	s_setprio 0
	s_or_b32 s52, s85, 0x80
	s_mov_b32 m0, s34
	ds_read_b128 v[194:197], v140 offset:49152
	buffer_load_dwordx4 v134, s[68:71], s52 offen lds
	s_add_i32 s85, s85, 0x80080
	s_mov_b32 m0, s35
	ds_read_b128 v[198:201], v140 offset:50176
	buffer_load_dwordx4 v136, s[68:71], s52 offen lds
	s_mov_b32 m0, s37
	ds_read_b128 v[202:205], v140 offset:51200
	buffer_load_dwordx4 v134, s[68:71], s85 offen lds
	s_mov_b32 m0, s65
	ds_read_b128 v[228:231], v140 offset:52224
	buffer_load_dwordx4 v136, s[68:71], s85 offen lds
	s_mov_b32 m0, s14
	ds_read_b128 v[232:235], v140 offset:53248
	buffer_load_dwordx4 v131, s[60:63], s84 offen lds
	s_mov_b32 m0, s36
	ds_read_b128 v[236:239], v140 offset:54272
	buffer_load_dwordx4 v135, s[60:63], s84 offen lds
	ds_read_b128 v[240:243], v140 offset:55296
	ds_read_b128 v[244:247], v140 offset:56320
	s_waitcnt vmcnt(8)
	s_waitcnt lgkmcnt(0)
	s_setprio 1
	s_barrier
	v_mfma_f32_16x16x32_bf16 v[94:97], v[142:145], v[194:197], v[94:97]
	v_mfma_f32_16x16x32_bf16 v[94:97], v[154:157], v[198:201], v[94:97]
	v_mfma_f32_16x16x32_bf16 v[86:89], v[142:145], v[202:205], v[86:89]
	v_mfma_f32_16x16x32_bf16 v[86:89], v[154:157], v[228:231], v[86:89]
	v_mfma_f32_16x16x32_bf16 v[78:81], v[142:145], v[232:235], v[78:81]
	v_mfma_f32_16x16x32_bf16 v[78:81], v[154:157], v[236:239], v[78:81]
	v_mfma_f32_16x16x32_bf16 v[70:73], v[142:145], v[240:243], v[70:73]
	v_mfma_f32_16x16x32_bf16 v[70:73], v[154:157], v[244:247], v[70:73]
	v_mfma_f32_16x16x32_bf16 v[66:69], v[170:173], v[240:243], v[66:69]
	v_mfma_f32_16x16x32_bf16 v[66:69], v[174:177], v[244:247], v[66:69]
	v_mfma_f32_16x16x32_bf16 v[74:77], v[170:173], v[232:235], v[74:77]
	v_mfma_f32_16x16x32_bf16 v[74:77], v[174:177], v[236:239], v[74:77]
	v_mfma_f32_16x16x32_bf16 v[82:85], v[170:173], v[202:205], v[82:85]
	v_mfma_f32_16x16x32_bf16 v[82:85], v[174:177], v[228:231], v[82:85]
	v_mfma_f32_16x16x32_bf16 v[90:93], v[170:173], v[194:197], v[90:93]
	v_mfma_f32_16x16x32_bf16 v[90:93], v[174:177], v[198:201], v[90:93]
	v_mfma_f32_16x16x32_bf16 v[26:29], v[186:189], v[194:197], v[26:29]
	v_mfma_f32_16x16x32_bf16 v[26:29], v[190:193], v[198:201], v[26:29]
	v_mfma_f32_16x16x32_bf16 v[18:21], v[186:189], v[202:205], v[18:21]
	v_mfma_f32_16x16x32_bf16 v[18:21], v[190:193], v[228:231], v[18:21]
	v_mfma_f32_16x16x32_bf16 v[10:13], v[186:189], v[232:235], v[10:13]
	v_mfma_f32_16x16x32_bf16 v[10:13], v[190:193], v[236:239], v[10:13]
	v_mfma_f32_16x16x32_bf16 v[2:5], v[186:189], v[240:243], v[2:5]
	v_mfma_f32_16x16x32_bf16 v[2:5], v[190:193], v[244:247], v[2:5]
	v_mfma_f32_16x16x32_bf16 v[6:9], v[178:181], v[240:243], v[6:9]
	v_mfma_f32_16x16x32_bf16 v[6:9], v[182:185], v[244:247], v[6:9]
	v_mfma_f32_16x16x32_bf16 v[14:17], v[178:181], v[232:235], v[14:17]
	v_mfma_f32_16x16x32_bf16 v[14:17], v[182:185], v[236:239], v[14:17]
	v_mfma_f32_16x16x32_bf16 v[22:25], v[178:181], v[202:205], v[22:25]
	v_mfma_f32_16x16x32_bf16 v[22:25], v[182:185], v[228:231], v[22:25]
	v_mfma_f32_16x16x32_bf16 v[30:33], v[178:181], v[194:197], v[30:33]
	v_mfma_f32_16x16x32_bf16 v[30:33], v[182:185], v[198:201], v[30:33]
	s_barrier
	s_setprio 0
	s_add_i32 s83, s83, 2
	s_addk_i32 s26, 0x100
	s_addk_i32 s27, 0x100
	s_cmp_gt_u32 s83, 29
.LBB0_1253:
	v_add_u32_e32 v141, 0x10000, v139
	ds_read_b128 v[142:145], v141
	ds_read_b128 v[154:157], v141 offset:1024
	ds_read_b128 v[170:173], v141 offset:2048
	ds_read_b128 v[174:177], v141 offset:3072
	v_add_u32_e32 v141, 0x14000, v139
	ds_read_b128 v[178:181], v141
	ds_read_b128 v[182:185], v141 offset:1024
	ds_read_b128 v[186:189], v141 offset:2048
	ds_read_b128 v[190:193], v141 offset:3072
	s_add_i32 s52, s26, 0xfff80080
	s_cmp_eq_u32 s83, 28
	s_cselect_b32 s52, s8, s52
	s_cselect_b32 s85, s9, s27
	s_or_b32 s84, s52, 0x80
	s_mov_b32 m0, s72
	ds_read_b128 v[194:197], v140
	ds_read_b128 v[198:201], v140 offset:1024
	ds_read_b128 v[202:205], v140 offset:2048
	ds_read_b128 v[228:231], v140 offset:3072
	ds_read_b128 v[232:235], v140 offset:4096
	ds_read_b128 v[236:239], v140 offset:5120
	ds_read_b128 v[240:243], v140 offset:6144
	ds_read_b128 v[244:247], v140 offset:7168
	buffer_load_dwordx4 v131, s[60:63], s26 offen lds
	s_mov_b32 m0, s46
	s_nop 0
	buffer_load_dwordx4 v135, s[60:63], s26 offen lds
	s_waitcnt vmcnt(8)
	s_waitcnt lgkmcnt(0)
	s_setprio 1
	s_barrier
	v_mfma_f32_16x16x32_bf16 v[126:129], v[142:145], v[194:197], v[126:129]
	v_mfma_f32_16x16x32_bf16 v[126:129], v[154:157], v[198:201], v[126:129]
	v_mfma_f32_16x16x32_bf16 v[118:121], v[142:145], v[202:205], v[118:121]
	v_mfma_f32_16x16x32_bf16 v[118:121], v[154:157], v[228:231], v[118:121]
	v_mfma_f32_16x16x32_bf16 v[110:113], v[142:145], v[232:235], v[110:113]
	v_mfma_f32_16x16x32_bf16 v[110:113], v[154:157], v[236:239], v[110:113]
	v_mfma_f32_16x16x32_bf16 v[102:105], v[142:145], v[240:243], v[102:105]
	v_mfma_f32_16x16x32_bf16 v[102:105], v[154:157], v[244:247], v[102:105]
	v_mfma_f32_16x16x32_bf16 v[98:101], v[170:173], v[240:243], v[98:101]
	v_mfma_f32_16x16x32_bf16 v[98:101], v[174:177], v[244:247], v[98:101]
	v_mfma_f32_16x16x32_bf16 v[106:109], v[170:173], v[232:235], v[106:109]
	v_mfma_f32_16x16x32_bf16 v[106:109], v[174:177], v[236:239], v[106:109]
	v_mfma_f32_16x16x32_bf16 v[114:117], v[170:173], v[202:205], v[114:117]
	v_mfma_f32_16x16x32_bf16 v[114:117], v[174:177], v[228:231], v[114:117]
	v_mfma_f32_16x16x32_bf16 v[122:125], v[170:173], v[194:197], v[122:125]
	v_mfma_f32_16x16x32_bf16 v[122:125], v[174:177], v[198:201], v[122:125]
	v_mfma_f32_16x16x32_bf16 v[58:61], v[186:189], v[194:197], v[58:61]
	v_mfma_f32_16x16x32_bf16 v[58:61], v[190:193], v[198:201], v[58:61]
	v_mfma_f32_16x16x32_bf16 v[50:53], v[186:189], v[202:205], v[50:53]
	v_mfma_f32_16x16x32_bf16 v[50:53], v[190:193], v[228:231], v[50:53]
	v_mfma_f32_16x16x32_bf16 v[42:45], v[186:189], v[232:235], v[42:45]
	v_mfma_f32_16x16x32_bf16 v[42:45], v[190:193], v[236:239], v[42:45]
	v_mfma_f32_16x16x32_bf16 v[34:37], v[186:189], v[240:243], v[34:37]
	v_mfma_f32_16x16x32_bf16 v[34:37], v[190:193], v[244:247], v[34:37]
	v_mfma_f32_16x16x32_bf16 v[38:41], v[178:181], v[240:243], v[38:41]
	v_mfma_f32_16x16x32_bf16 v[38:41], v[182:185], v[244:247], v[38:41]
	v_mfma_f32_16x16x32_bf16 v[46:49], v[178:181], v[232:235], v[46:49]
	v_mfma_f32_16x16x32_bf16 v[46:49], v[182:185], v[236:239], v[46:49]
	v_mfma_f32_16x16x32_bf16 v[54:57], v[178:181], v[202:205], v[54:57]
	v_mfma_f32_16x16x32_bf16 v[54:57], v[182:185], v[228:231], v[54:57]
	v_mfma_f32_16x16x32_bf16 v[62:65], v[178:181], v[194:197], v[62:65]
	v_mfma_f32_16x16x32_bf16 v[62:65], v[182:185], v[198:201], v[62:65]
	s_barrier
	s_setprio 0
	s_mov_b32 s70, s62
	s_mov_b32 s71, s63
	s_mov_b32 m0, s21
	ds_read_b128 v[194:197], v140 offset:16384
	buffer_load_dwordx4 v134, s[68:71], s85 offen lds
	s_add_i32 s53, s85, 0x80000
	s_mov_b32 m0, s23
	ds_read_b128 v[198:201], v140 offset:17408
	buffer_load_dwordx4 v136, s[68:71], s85 offen lds
	s_mov_b32 m0, s24
	ds_read_b128 v[202:205], v140 offset:18432
	buffer_load_dwordx4 v134, s[68:71], s53 offen lds
	s_mov_b32 m0, s25
	ds_read_b128 v[228:231], v140 offset:19456
	buffer_load_dwordx4 v136, s[68:71], s53 offen lds
	s_mov_b32 m0, s16
	ds_read_b128 v[232:235], v140 offset:20480
	buffer_load_dwordx4 v131, s[60:63], s52 offen lds
	s_mov_b32 m0, s30
	ds_read_b128 v[236:239], v140 offset:21504
	buffer_load_dwordx4 v135, s[60:63], s52 offen lds
	ds_read_b128 v[240:243], v140 offset:22528
	ds_read_b128 v[244:247], v140 offset:23552
	s_waitcnt vmcnt(8)
	s_waitcnt lgkmcnt(0)
	s_setprio 1
	s_barrier
	v_mfma_f32_16x16x32_bf16 v[94:97], v[142:145], v[194:197], v[94:97]
	v_mfma_f32_16x16x32_bf16 v[94:97], v[154:157], v[198:201], v[94:97]
	v_mfma_f32_16x16x32_bf16 v[86:89], v[142:145], v[202:205], v[86:89]
	v_mfma_f32_16x16x32_bf16 v[86:89], v[154:157], v[228:231], v[86:89]
	v_mfma_f32_16x16x32_bf16 v[78:81], v[142:145], v[232:235], v[78:81]
	v_mfma_f32_16x16x32_bf16 v[78:81], v[154:157], v[236:239], v[78:81]
	v_mfma_f32_16x16x32_bf16 v[70:73], v[142:145], v[240:243], v[70:73]
	v_mfma_f32_16x16x32_bf16 v[70:73], v[154:157], v[244:247], v[70:73]
	v_mfma_f32_16x16x32_bf16 v[66:69], v[170:173], v[240:243], v[66:69]
	v_mfma_f32_16x16x32_bf16 v[66:69], v[174:177], v[244:247], v[66:69]
	v_mfma_f32_16x16x32_bf16 v[74:77], v[170:173], v[232:235], v[74:77]
	v_mfma_f32_16x16x32_bf16 v[74:77], v[174:177], v[236:239], v[74:77]
	v_mfma_f32_16x16x32_bf16 v[82:85], v[170:173], v[202:205], v[82:85]
	v_mfma_f32_16x16x32_bf16 v[82:85], v[174:177], v[228:231], v[82:85]
	v_mfma_f32_16x16x32_bf16 v[90:93], v[170:173], v[194:197], v[90:93]
	v_mfma_f32_16x16x32_bf16 v[90:93], v[174:177], v[198:201], v[90:93]
	v_mfma_f32_16x16x32_bf16 v[26:29], v[186:189], v[194:197], v[26:29]
	v_mfma_f32_16x16x32_bf16 v[26:29], v[190:193], v[198:201], v[26:29]
	v_mfma_f32_16x16x32_bf16 v[18:21], v[186:189], v[202:205], v[18:21]
	v_mfma_f32_16x16x32_bf16 v[18:21], v[190:193], v[228:231], v[18:21]
	v_mfma_f32_16x16x32_bf16 v[10:13], v[186:189], v[232:235], v[10:13]
	v_mfma_f32_16x16x32_bf16 v[10:13], v[190:193], v[236:239], v[10:13]
	v_mfma_f32_16x16x32_bf16 v[2:5], v[186:189], v[240:243], v[2:5]
	v_mfma_f32_16x16x32_bf16 v[2:5], v[190:193], v[244:247], v[2:5]
	v_mfma_f32_16x16x32_bf16 v[6:9], v[178:181], v[240:243], v[6:9]
	v_mfma_f32_16x16x32_bf16 v[6:9], v[182:185], v[244:247], v[6:9]
	v_mfma_f32_16x16x32_bf16 v[14:17], v[178:181], v[232:235], v[14:17]
	v_mfma_f32_16x16x32_bf16 v[14:17], v[182:185], v[236:239], v[14:17]
	v_mfma_f32_16x16x32_bf16 v[22:25], v[178:181], v[202:205], v[22:25]
	v_mfma_f32_16x16x32_bf16 v[22:25], v[182:185], v[228:231], v[22:25]
	v_mfma_f32_16x16x32_bf16 v[30:33], v[178:181], v[194:197], v[30:33]
	v_mfma_f32_16x16x32_bf16 v[30:33], v[182:185], v[198:201], v[30:33]
	s_barrier
	s_setprio 0
	v_add_u32_e32 v141, 0x18000, v139
	ds_read_b128 v[142:145], v141
	ds_read_b128 v[154:157], v141 offset:1024
	ds_read_b128 v[170:173], v141 offset:2048
	ds_read_b128 v[174:177], v141 offset:3072
	v_add_u32_e32 v141, 0x1c000, v139
	ds_read_b128 v[178:181], v141
	ds_read_b128 v[182:185], v141 offset:1024
	ds_read_b128 v[186:189], v141 offset:2048
	ds_read_b128 v[190:193], v141 offset:3072
	s_add_i32 s52, s52, 0x80000
	s_mov_b32 m0, s31
	ds_read_b128 v[194:197], v140 offset:32768
	ds_read_b128 v[198:201], v140 offset:33792
	ds_read_b128 v[202:205], v140 offset:34816
	ds_read_b128 v[228:231], v140 offset:35840
	ds_read_b128 v[232:235], v140 offset:36864
	ds_read_b128 v[236:239], v140 offset:37888
	ds_read_b128 v[240:243], v140 offset:38912
	ds_read_b128 v[244:247], v140 offset:39936
	buffer_load_dwordx4 v131, s[60:63], s52 offen lds
	s_mov_b32 m0, s33
	s_nop 0
	buffer_load_dwordx4 v135, s[60:63], s52 offen lds
	s_waitcnt vmcnt(8)
	s_waitcnt lgkmcnt(0)
	s_setprio 1
	s_barrier
	v_mfma_f32_16x16x32_bf16 v[126:129], v[142:145], v[194:197], v[126:129]
	v_mfma_f32_16x16x32_bf16 v[126:129], v[154:157], v[198:201], v[126:129]
	v_mfma_f32_16x16x32_bf16 v[118:121], v[142:145], v[202:205], v[118:121]
	v_mfma_f32_16x16x32_bf16 v[118:121], v[154:157], v[228:231], v[118:121]
	v_mfma_f32_16x16x32_bf16 v[110:113], v[142:145], v[232:235], v[110:113]
	v_mfma_f32_16x16x32_bf16 v[110:113], v[154:157], v[236:239], v[110:113]
	v_mfma_f32_16x16x32_bf16 v[102:105], v[142:145], v[240:243], v[102:105]
	v_mfma_f32_16x16x32_bf16 v[102:105], v[154:157], v[244:247], v[102:105]
	v_mfma_f32_16x16x32_bf16 v[98:101], v[170:173], v[240:243], v[98:101]
	v_mfma_f32_16x16x32_bf16 v[98:101], v[174:177], v[244:247], v[98:101]
	v_mfma_f32_16x16x32_bf16 v[106:109], v[170:173], v[232:235], v[106:109]
	v_mfma_f32_16x16x32_bf16 v[106:109], v[174:177], v[236:239], v[106:109]
	v_mfma_f32_16x16x32_bf16 v[114:117], v[170:173], v[202:205], v[114:117]
	v_mfma_f32_16x16x32_bf16 v[114:117], v[174:177], v[228:231], v[114:117]
	v_mfma_f32_16x16x32_bf16 v[122:125], v[170:173], v[194:197], v[122:125]
	v_mfma_f32_16x16x32_bf16 v[122:125], v[174:177], v[198:201], v[122:125]
	v_mfma_f32_16x16x32_bf16 v[58:61], v[186:189], v[194:197], v[58:61]
	v_mfma_f32_16x16x32_bf16 v[58:61], v[190:193], v[198:201], v[58:61]
	v_mfma_f32_16x16x32_bf16 v[50:53], v[186:189], v[202:205], v[50:53]
	v_mfma_f32_16x16x32_bf16 v[50:53], v[190:193], v[228:231], v[50:53]
	v_mfma_f32_16x16x32_bf16 v[42:45], v[186:189], v[232:235], v[42:45]
	v_mfma_f32_16x16x32_bf16 v[42:45], v[190:193], v[236:239], v[42:45]
	v_mfma_f32_16x16x32_bf16 v[34:37], v[186:189], v[240:243], v[34:37]
	v_mfma_f32_16x16x32_bf16 v[34:37], v[190:193], v[244:247], v[34:37]
	v_mfma_f32_16x16x32_bf16 v[38:41], v[178:181], v[240:243], v[38:41]
	v_mfma_f32_16x16x32_bf16 v[38:41], v[182:185], v[244:247], v[38:41]
	v_mfma_f32_16x16x32_bf16 v[46:49], v[178:181], v[232:235], v[46:49]
	v_mfma_f32_16x16x32_bf16 v[46:49], v[182:185], v[236:239], v[46:49]
	v_mfma_f32_16x16x32_bf16 v[54:57], v[178:181], v[202:205], v[54:57]
	v_mfma_f32_16x16x32_bf16 v[54:57], v[182:185], v[228:231], v[54:57]
	v_mfma_f32_16x16x32_bf16 v[62:65], v[178:181], v[194:197], v[62:65]
	v_mfma_f32_16x16x32_bf16 v[62:65], v[182:185], v[198:201], v[62:65]
	s_barrier
	s_setprio 0
	s_or_b32 s52, s85, 0x80
	s_mov_b32 m0, s34
	ds_read_b128 v[194:197], v140 offset:49152
	buffer_load_dwordx4 v134, s[68:71], s52 offen lds
	s_add_i32 s85, s85, 0x80080
	s_mov_b32 m0, s35
	ds_read_b128 v[198:201], v140 offset:50176
	buffer_load_dwordx4 v136, s[68:71], s52 offen lds
	s_mov_b32 m0, s37
	ds_read_b128 v[202:205], v140 offset:51200
	buffer_load_dwordx4 v134, s[68:71], s85 offen lds
	s_mov_b32 m0, s65
	ds_read_b128 v[228:231], v140 offset:52224
	buffer_load_dwordx4 v136, s[68:71], s85 offen lds
	s_mov_b32 m0, s14
	ds_read_b128 v[232:235], v140 offset:53248
	buffer_load_dwordx4 v131, s[60:63], s84 offen lds
	s_mov_b32 m0, s36
	ds_read_b128 v[236:239], v140 offset:54272
	buffer_load_dwordx4 v135, s[60:63], s84 offen lds
	ds_read_b128 v[240:243], v140 offset:55296
	ds_read_b128 v[244:247], v140 offset:56320
	s_waitcnt vmcnt(8)
	s_waitcnt lgkmcnt(0)
	s_setprio 1
	s_barrier
	v_mfma_f32_16x16x32_bf16 v[94:97], v[142:145], v[194:197], v[94:97]
	v_mfma_f32_16x16x32_bf16 v[94:97], v[154:157], v[198:201], v[94:97]
	v_mfma_f32_16x16x32_bf16 v[86:89], v[142:145], v[202:205], v[86:89]
	v_mfma_f32_16x16x32_bf16 v[86:89], v[154:157], v[228:231], v[86:89]
	v_mfma_f32_16x16x32_bf16 v[78:81], v[142:145], v[232:235], v[78:81]
	v_mfma_f32_16x16x32_bf16 v[78:81], v[154:157], v[236:239], v[78:81]
	v_mfma_f32_16x16x32_bf16 v[70:73], v[142:145], v[240:243], v[70:73]
	v_mfma_f32_16x16x32_bf16 v[70:73], v[154:157], v[244:247], v[70:73]
	v_mfma_f32_16x16x32_bf16 v[66:69], v[170:173], v[240:243], v[66:69]
	v_mfma_f32_16x16x32_bf16 v[66:69], v[174:177], v[244:247], v[66:69]
	v_mfma_f32_16x16x32_bf16 v[74:77], v[170:173], v[232:235], v[74:77]
	v_mfma_f32_16x16x32_bf16 v[74:77], v[174:177], v[236:239], v[74:77]
	v_mfma_f32_16x16x32_bf16 v[82:85], v[170:173], v[202:205], v[82:85]
	v_mfma_f32_16x16x32_bf16 v[82:85], v[174:177], v[228:231], v[82:85]
	v_mfma_f32_16x16x32_bf16 v[90:93], v[170:173], v[194:197], v[90:93]
	v_mfma_f32_16x16x32_bf16 v[90:93], v[174:177], v[198:201], v[90:93]
	v_mfma_f32_16x16x32_bf16 v[26:29], v[186:189], v[194:197], v[26:29]
	v_mfma_f32_16x16x32_bf16 v[26:29], v[190:193], v[198:201], v[26:29]
	v_mfma_f32_16x16x32_bf16 v[18:21], v[186:189], v[202:205], v[18:21]
	v_mfma_f32_16x16x32_bf16 v[18:21], v[190:193], v[228:231], v[18:21]
	v_mfma_f32_16x16x32_bf16 v[10:13], v[186:189], v[232:235], v[10:13]
	v_mfma_f32_16x16x32_bf16 v[10:13], v[190:193], v[236:239], v[10:13]
	v_mfma_f32_16x16x32_bf16 v[2:5], v[186:189], v[240:243], v[2:5]
	v_mfma_f32_16x16x32_bf16 v[2:5], v[190:193], v[244:247], v[2:5]
	v_mfma_f32_16x16x32_bf16 v[6:9], v[178:181], v[240:243], v[6:9]
	v_mfma_f32_16x16x32_bf16 v[6:9], v[182:185], v[244:247], v[6:9]
	v_mfma_f32_16x16x32_bf16 v[14:17], v[178:181], v[232:235], v[14:17]
	v_mfma_f32_16x16x32_bf16 v[14:17], v[182:185], v[236:239], v[14:17]
	v_mfma_f32_16x16x32_bf16 v[22:25], v[178:181], v[202:205], v[22:25]
	v_mfma_f32_16x16x32_bf16 v[22:25], v[182:185], v[228:231], v[22:25]
	v_mfma_f32_16x16x32_bf16 v[30:33], v[178:181], v[194:197], v[30:33]
	v_mfma_f32_16x16x32_bf16 v[30:33], v[182:185], v[198:201], v[30:33]
	s_barrier
	s_setprio 0
	s_add_i32 s83, s83, 2
	s_addk_i32 s26, 0x100
	s_addk_i32 s27, 0x100
	s_cmp_gt_u32 s83, 29
	s_cbranch_scc0 .LBB0_1253
	s_and_b64 vcc, exec, s[44:45]
	s_cbranch_vccz .LBB0_1256
	s_barrier

.LBB0_1282:
	s_lshl_b32 s46, s85, 20
	s_and_b64 s[8:9], s[40:41], exec
	s_cselect_b32 s8, s46, s19
	s_lshl_b32 s47, s14, 20
	s_and_b64 s[26:27], s[40:41], exec
	s_cselect_b32 s9, s47, s22
	s_add_i32 s19, s19, 0x80080
	s_addk_i32 s22, 0x100
	s_mov_b32 s26, -2
	v_add_u32_e32 v141, 0x10000, v139
	ds_read_b128 v[142:145], v141
	ds_read_b128 v[154:157], v141 offset:1024
	ds_read_b128 v[170:173], v141 offset:2048
	ds_read_b128 v[174:177], v141 offset:3072
	v_add_u32_e32 v141, 0x14000, v139
	ds_read_b128 v[178:181], v141
	ds_read_b128 v[182:185], v141 offset:1024
	ds_read_b128 v[186:189], v141 offset:2048
	ds_read_b128 v[190:193], v141 offset:3072
	s_add_i32 s27, s19, 0xfff80080
	s_cmp_eq_u32 s26, 28
	s_cselect_b32 s52, s8, s27
	s_cselect_b32 s83, s9, s22
	s_or_b32 s27, s52, 0x80
	s_mov_b32 m0, s73
	ds_read_b128 v[194:197], v140
	ds_read_b128 v[198:201], v140 offset:1024
	ds_read_b128 v[202:205], v140 offset:2048
	ds_read_b128 v[228:231], v140 offset:3072
	ds_read_b128 v[232:235], v140 offset:4096
	ds_read_b128 v[236:239], v140 offset:5120
	ds_read_b128 v[240:243], v140 offset:6144
	ds_read_b128 v[244:247], v140 offset:7168
	buffer_load_dwordx4 v131, s[60:63], s19 offen lds
	s_mov_b32 m0, s82
	s_nop 0
	buffer_load_dwordx4 v135, s[60:63], s19 offen lds
	s_waitcnt vmcnt(8)
	s_waitcnt lgkmcnt(0)
	s_setprio 1
	s_barrier
	v_mfma_f32_16x16x32_bf16 v[126:129], v[142:145], v[194:197], 0
	v_mfma_f32_16x16x32_bf16 v[126:129], v[154:157], v[198:201], v[126:129]
	v_mfma_f32_16x16x32_bf16 v[118:121], v[142:145], v[202:205], 0
	v_mfma_f32_16x16x32_bf16 v[118:121], v[154:157], v[228:231], v[118:121]
	v_mfma_f32_16x16x32_bf16 v[110:113], v[142:145], v[232:235], 0
	v_mfma_f32_16x16x32_bf16 v[110:113], v[154:157], v[236:239], v[110:113]
	v_mfma_f32_16x16x32_bf16 v[102:105], v[142:145], v[240:243], 0
	v_mfma_f32_16x16x32_bf16 v[102:105], v[154:157], v[244:247], v[102:105]
	v_mfma_f32_16x16x32_bf16 v[98:101], v[170:173], v[240:243], 0
	v_mfma_f32_16x16x32_bf16 v[98:101], v[174:177], v[244:247], v[98:101]
	v_mfma_f32_16x16x32_bf16 v[106:109], v[170:173], v[232:235], 0
	v_mfma_f32_16x16x32_bf16 v[106:109], v[174:177], v[236:239], v[106:109]
	v_mfma_f32_16x16x32_bf16 v[114:117], v[170:173], v[202:205], 0
	v_mfma_f32_16x16x32_bf16 v[114:117], v[174:177], v[228:231], v[114:117]
	v_mfma_f32_16x16x32_bf16 v[122:125], v[170:173], v[194:197], 0
	v_mfma_f32_16x16x32_bf16 v[122:125], v[174:177], v[198:201], v[122:125]
	v_mfma_f32_16x16x32_bf16 v[58:61], v[186:189], v[194:197], 0
	v_mfma_f32_16x16x32_bf16 v[58:61], v[190:193], v[198:201], v[58:61]
	v_mfma_f32_16x16x32_bf16 v[50:53], v[186:189], v[202:205], 0
	v_mfma_f32_16x16x32_bf16 v[50:53], v[190:193], v[228:231], v[50:53]
	v_mfma_f32_16x16x32_bf16 v[42:45], v[186:189], v[232:235], 0
	v_mfma_f32_16x16x32_bf16 v[42:45], v[190:193], v[236:239], v[42:45]
	v_mfma_f32_16x16x32_bf16 v[34:37], v[186:189], v[240:243], 0
	v_mfma_f32_16x16x32_bf16 v[34:37], v[190:193], v[244:247], v[34:37]
	v_mfma_f32_16x16x32_bf16 v[38:41], v[178:181], v[240:243], 0
	v_mfma_f32_16x16x32_bf16 v[38:41], v[182:185], v[244:247], v[38:41]
	v_mfma_f32_16x16x32_bf16 v[46:49], v[178:181], v[232:235], 0
	v_mfma_f32_16x16x32_bf16 v[46:49], v[182:185], v[236:239], v[46:49]
	v_mfma_f32_16x16x32_bf16 v[54:57], v[178:181], v[202:205], 0
	v_mfma_f32_16x16x32_bf16 v[54:57], v[182:185], v[228:231], v[54:57]
	v_mfma_f32_16x16x32_bf16 v[62:65], v[178:181], v[194:197], 0
	v_mfma_f32_16x16x32_bf16 v[62:65], v[182:185], v[198:201], v[62:65]
	s_barrier
	s_setprio 0
	s_mov_b32 s70, s62
	s_mov_b32 s71, s63
	s_mov_b32 m0, s21
	ds_read_b128 v[194:197], v140 offset:16384
	buffer_load_dwordx4 v134, s[68:71], s83 offen lds
	s_add_i32 s53, s83, 0x80000
	s_mov_b32 m0, s23
	ds_read_b128 v[198:201], v140 offset:17408
	buffer_load_dwordx4 v136, s[68:71], s83 offen lds
	s_mov_b32 m0, s24
	ds_read_b128 v[202:205], v140 offset:18432
	buffer_load_dwordx4 v134, s[68:71], s53 offen lds
	s_mov_b32 m0, s25
	ds_read_b128 v[228:231], v140 offset:19456
	buffer_load_dwordx4 v136, s[68:71], s53 offen lds
	s_mov_b32 m0, s2
	ds_read_b128 v[232:235], v140 offset:20480
	buffer_load_dwordx4 v131, s[60:63], s52 offen lds
	s_mov_b32 m0, s30
	ds_read_b128 v[236:239], v140 offset:21504
	buffer_load_dwordx4 v135, s[60:63], s52 offen lds
	ds_read_b128 v[240:243], v140 offset:22528
	ds_read_b128 v[244:247], v140 offset:23552
	s_waitcnt vmcnt(8)
	s_waitcnt lgkmcnt(0)
	s_setprio 1
	s_barrier
	v_mfma_f32_16x16x32_bf16 v[94:97], v[142:145], v[194:197], 0
	v_mfma_f32_16x16x32_bf16 v[94:97], v[154:157], v[198:201], v[94:97]
	v_mfma_f32_16x16x32_bf16 v[86:89], v[142:145], v[202:205], 0
	v_mfma_f32_16x16x32_bf16 v[86:89], v[154:157], v[228:231], v[86:89]
	v_mfma_f32_16x16x32_bf16 v[78:81], v[142:145], v[232:235], 0
	v_mfma_f32_16x16x32_bf16 v[78:81], v[154:157], v[236:239], v[78:81]
	v_mfma_f32_16x16x32_bf16 v[70:73], v[142:145], v[240:243], 0
	v_mfma_f32_16x16x32_bf16 v[70:73], v[154:157], v[244:247], v[70:73]
	v_mfma_f32_16x16x32_bf16 v[66:69], v[170:173], v[240:243], 0
	v_mfma_f32_16x16x32_bf16 v[66:69], v[174:177], v[244:247], v[66:69]
	v_mfma_f32_16x16x32_bf16 v[74:77], v[170:173], v[232:235], 0
	v_mfma_f32_16x16x32_bf16 v[74:77], v[174:177], v[236:239], v[74:77]
	v_mfma_f32_16x16x32_bf16 v[82:85], v[170:173], v[202:205], 0
	v_mfma_f32_16x16x32_bf16 v[82:85], v[174:177], v[228:231], v[82:85]
	v_mfma_f32_16x16x32_bf16 v[90:93], v[170:173], v[194:197], 0
	v_mfma_f32_16x16x32_bf16 v[90:93], v[174:177], v[198:201], v[90:93]
	v_mfma_f32_16x16x32_bf16 v[26:29], v[186:189], v[194:197], 0
	v_mfma_f32_16x16x32_bf16 v[26:29], v[190:193], v[198:201], v[26:29]
	v_mfma_f32_16x16x32_bf16 v[18:21], v[186:189], v[202:205], 0
	v_mfma_f32_16x16x32_bf16 v[18:21], v[190:193], v[228:231], v[18:21]
	v_mfma_f32_16x16x32_bf16 v[10:13], v[186:189], v[232:235], 0
	v_mfma_f32_16x16x32_bf16 v[10:13], v[190:193], v[236:239], v[10:13]
	v_mfma_f32_16x16x32_bf16 v[2:5], v[186:189], v[240:243], 0
	v_mfma_f32_16x16x32_bf16 v[2:5], v[190:193], v[244:247], v[2:5]
	v_mfma_f32_16x16x32_bf16 v[6:9], v[178:181], v[240:243], 0
	v_mfma_f32_16x16x32_bf16 v[6:9], v[182:185], v[244:247], v[6:9]
	v_mfma_f32_16x16x32_bf16 v[14:17], v[178:181], v[232:235], 0
	v_mfma_f32_16x16x32_bf16 v[14:17], v[182:185], v[236:239], v[14:17]
	v_mfma_f32_16x16x32_bf16 v[22:25], v[178:181], v[202:205], 0
	v_mfma_f32_16x16x32_bf16 v[22:25], v[182:185], v[228:231], v[22:25]
	v_mfma_f32_16x16x32_bf16 v[30:33], v[178:181], v[194:197], 0
	v_mfma_f32_16x16x32_bf16 v[30:33], v[182:185], v[198:201], v[30:33]
	s_barrier
	s_setprio 0
	v_add_u32_e32 v141, 0x18000, v139
	ds_read_b128 v[142:145], v141
	ds_read_b128 v[154:157], v141 offset:1024
	ds_read_b128 v[170:173], v141 offset:2048
	ds_read_b128 v[174:177], v141 offset:3072
	v_add_u32_e32 v141, 0x1c000, v139
	ds_read_b128 v[178:181], v141
	ds_read_b128 v[182:185], v141 offset:1024
	ds_read_b128 v[186:189], v141 offset:2048
	ds_read_b128 v[190:193], v141 offset:3072
	s_add_i32 s52, s52, 0x80000
	s_mov_b32 m0, s31
	ds_read_b128 v[194:197], v140 offset:32768
	ds_read_b128 v[198:201], v140 offset:33792
	ds_read_b128 v[202:205], v140 offset:34816
	ds_read_b128 v[228:231], v140 offset:35840
	ds_read_b128 v[232:235], v140 offset:36864
	ds_read_b128 v[236:239], v140 offset:37888
	ds_read_b128 v[240:243], v140 offset:38912
	ds_read_b128 v[244:247], v140 offset:39936
	buffer_load_dwordx4 v131, s[60:63], s52 offen lds
	s_mov_b32 m0, s33
	s_nop 0
	buffer_load_dwordx4 v135, s[60:63], s52 offen lds
	s_waitcnt vmcnt(8)
	s_waitcnt lgkmcnt(0)
	s_setprio 1
	s_barrier
	v_mfma_f32_16x16x32_bf16 v[126:129], v[142:145], v[194:197], v[126:129]
	v_mfma_f32_16x16x32_bf16 v[126:129], v[154:157], v[198:201], v[126:129]
	v_mfma_f32_16x16x32_bf16 v[118:121], v[142:145], v[202:205], v[118:121]
	v_mfma_f32_16x16x32_bf16 v[118:121], v[154:157], v[228:231], v[118:121]
	v_mfma_f32_16x16x32_bf16 v[110:113], v[142:145], v[232:235], v[110:113]
	v_mfma_f32_16x16x32_bf16 v[110:113], v[154:157], v[236:239], v[110:113]
	v_mfma_f32_16x16x32_bf16 v[102:105], v[142:145], v[240:243], v[102:105]
	v_mfma_f32_16x16x32_bf16 v[102:105], v[154:157], v[244:247], v[102:105]
	v_mfma_f32_16x16x32_bf16 v[98:101], v[170:173], v[240:243], v[98:101]
	v_mfma_f32_16x16x32_bf16 v[98:101], v[174:177], v[244:247], v[98:101]
	v_mfma_f32_16x16x32_bf16 v[106:109], v[170:173], v[232:235], v[106:109]
	v_mfma_f32_16x16x32_bf16 v[106:109], v[174:177], v[236:239], v[106:109]
	v_mfma_f32_16x16x32_bf16 v[114:117], v[170:173], v[202:205], v[114:117]
	v_mfma_f32_16x16x32_bf16 v[114:117], v[174:177], v[228:231], v[114:117]
	v_mfma_f32_16x16x32_bf16 v[122:125], v[170:173], v[194:197], v[122:125]
	v_mfma_f32_16x16x32_bf16 v[122:125], v[174:177], v[198:201], v[122:125]
	v_mfma_f32_16x16x32_bf16 v[58:61], v[186:189], v[194:197], v[58:61]
	v_mfma_f32_16x16x32_bf16 v[58:61], v[190:193], v[198:201], v[58:61]
	v_mfma_f32_16x16x32_bf16 v[50:53], v[186:189], v[202:205], v[50:53]
	v_mfma_f32_16x16x32_bf16 v[50:53], v[190:193], v[228:231], v[50:53]
	v_mfma_f32_16x16x32_bf16 v[42:45], v[186:189], v[232:235], v[42:45]
	v_mfma_f32_16x16x32_bf16 v[42:45], v[190:193], v[236:239], v[42:45]
	v_mfma_f32_16x16x32_bf16 v[34:37], v[186:189], v[240:243], v[34:37]
	v_mfma_f32_16x16x32_bf16 v[34:37], v[190:193], v[244:247], v[34:37]
	v_mfma_f32_16x16x32_bf16 v[38:41], v[178:181], v[240:243], v[38:41]
	v_mfma_f32_16x16x32_bf16 v[38:41], v[182:185], v[244:247], v[38:41]
	v_mfma_f32_16x16x32_bf16 v[46:49], v[178:181], v[232:235], v[46:49]
	v_mfma_f32_16x16x32_bf16 v[46:49], v[182:185], v[236:239], v[46:49]
	v_mfma_f32_16x16x32_bf16 v[54:57], v[178:181], v[202:205], v[54:57]
	v_mfma_f32_16x16x32_bf16 v[54:57], v[182:185], v[228:231], v[54:57]
	v_mfma_f32_16x16x32_bf16 v[62:65], v[178:181], v[194:197], v[62:65]
	v_mfma_f32_16x16x32_bf16 v[62:65], v[182:185], v[198:201], v[62:65]
	s_barrier
	s_setprio 0
	s_or_b32 s52, s83, 0x80
	s_mov_b32 m0, s34
	ds_read_b128 v[194:197], v140 offset:49152
	buffer_load_dwordx4 v134, s[68:71], s52 offen lds
	s_add_i32 s83, s83, 0x80080
	s_mov_b32 m0, s35
	ds_read_b128 v[198:201], v140 offset:50176
	buffer_load_dwordx4 v136, s[68:71], s52 offen lds
	s_mov_b32 m0, s65
	ds_read_b128 v[202:205], v140 offset:51200
	buffer_load_dwordx4 v134, s[68:71], s83 offen lds
	s_mov_b32 m0, s66
	ds_read_b128 v[228:231], v140 offset:52224
	buffer_load_dwordx4 v136, s[68:71], s83 offen lds
	s_mov_b32 m0, s36
	ds_read_b128 v[232:235], v140 offset:53248
	buffer_load_dwordx4 v131, s[60:63], s27 offen lds
	s_mov_b32 m0, s37
	ds_read_b128 v[236:239], v140 offset:54272
	buffer_load_dwordx4 v135, s[60:63], s27 offen lds
	ds_read_b128 v[240:243], v140 offset:55296
	ds_read_b128 v[244:247], v140 offset:56320
	s_waitcnt vmcnt(8)
	s_waitcnt lgkmcnt(0)
	s_setprio 1
	s_barrier
	v_mfma_f32_16x16x32_bf16 v[94:97], v[142:145], v[194:197], v[94:97]
	v_mfma_f32_16x16x32_bf16 v[94:97], v[154:157], v[198:201], v[94:97]
	v_mfma_f32_16x16x32_bf16 v[86:89], v[142:145], v[202:205], v[86:89]
	v_mfma_f32_16x16x32_bf16 v[86:89], v[154:157], v[228:231], v[86:89]
	v_mfma_f32_16x16x32_bf16 v[78:81], v[142:145], v[232:235], v[78:81]
	v_mfma_f32_16x16x32_bf16 v[78:81], v[154:157], v[236:239], v[78:81]
	v_mfma_f32_16x16x32_bf16 v[70:73], v[142:145], v[240:243], v[70:73]
	v_mfma_f32_16x16x32_bf16 v[70:73], v[154:157], v[244:247], v[70:73]
	v_mfma_f32_16x16x32_bf16 v[66:69], v[170:173], v[240:243], v[66:69]
	v_mfma_f32_16x16x32_bf16 v[66:69], v[174:177], v[244:247], v[66:69]
	v_mfma_f32_16x16x32_bf16 v[74:77], v[170:173], v[232:235], v[74:77]
	v_mfma_f32_16x16x32_bf16 v[74:77], v[174:177], v[236:239], v[74:77]
	v_mfma_f32_16x16x32_bf16 v[82:85], v[170:173], v[202:205], v[82:85]
	v_mfma_f32_16x16x32_bf16 v[82:85], v[174:177], v[228:231], v[82:85]
	v_mfma_f32_16x16x32_bf16 v[90:93], v[170:173], v[194:197], v[90:93]
	v_mfma_f32_16x16x32_bf16 v[90:93], v[174:177], v[198:201], v[90:93]
	v_mfma_f32_16x16x32_bf16 v[26:29], v[186:189], v[194:197], v[26:29]
	v_mfma_f32_16x16x32_bf16 v[26:29], v[190:193], v[198:201], v[26:29]
	v_mfma_f32_16x16x32_bf16 v[18:21], v[186:189], v[202:205], v[18:21]
	v_mfma_f32_16x16x32_bf16 v[18:21], v[190:193], v[228:231], v[18:21]
	v_mfma_f32_16x16x32_bf16 v[10:13], v[186:189], v[232:235], v[10:13]
	v_mfma_f32_16x16x32_bf16 v[10:13], v[190:193], v[236:239], v[10:13]
	v_mfma_f32_16x16x32_bf16 v[2:5], v[186:189], v[240:243], v[2:5]
	v_mfma_f32_16x16x32_bf16 v[2:5], v[190:193], v[244:247], v[2:5]
	v_mfma_f32_16x16x32_bf16 v[6:9], v[178:181], v[240:243], v[6:9]
	v_mfma_f32_16x16x32_bf16 v[6:9], v[182:185], v[244:247], v[6:9]
	v_mfma_f32_16x16x32_bf16 v[14:17], v[178:181], v[232:235], v[14:17]
	v_mfma_f32_16x16x32_bf16 v[14:17], v[182:185], v[236:239], v[14:17]
	v_mfma_f32_16x16x32_bf16 v[22:25], v[178:181], v[202:205], v[22:25]
	v_mfma_f32_16x16x32_bf16 v[22:25], v[182:185], v[228:231], v[22:25]
	v_mfma_f32_16x16x32_bf16 v[30:33], v[178:181], v[194:197], v[30:33]
	v_mfma_f32_16x16x32_bf16 v[30:33], v[182:185], v[198:201], v[30:33]
	s_barrier
	s_setprio 0
	s_add_i32 s26, s26, 2
	s_addk_i32 s19, 0x100
	s_addk_i32 s22, 0x100
	s_cmp_gt_u32 s26, 29
.LBB0_1283:
	v_add_u32_e32 v141, 0x10000, v139
	ds_read_b128 v[142:145], v141
	ds_read_b128 v[154:157], v141 offset:1024
	ds_read_b128 v[170:173], v141 offset:2048
	ds_read_b128 v[174:177], v141 offset:3072
	v_add_u32_e32 v141, 0x14000, v139
	ds_read_b128 v[178:181], v141
	ds_read_b128 v[182:185], v141 offset:1024
	ds_read_b128 v[186:189], v141 offset:2048
	ds_read_b128 v[190:193], v141 offset:3072
	s_add_i32 s27, s19, 0xfff80080
	s_cmp_eq_u32 s26, 28
	s_cselect_b32 s52, s8, s27
	s_cselect_b32 s83, s9, s22
	s_or_b32 s27, s52, 0x80
	s_mov_b32 m0, s73
	ds_read_b128 v[194:197], v140
	ds_read_b128 v[198:201], v140 offset:1024
	ds_read_b128 v[202:205], v140 offset:2048
	ds_read_b128 v[228:231], v140 offset:3072
	ds_read_b128 v[232:235], v140 offset:4096
	ds_read_b128 v[236:239], v140 offset:5120
	ds_read_b128 v[240:243], v140 offset:6144
	ds_read_b128 v[244:247], v140 offset:7168
	buffer_load_dwordx4 v131, s[60:63], s19 offen lds
	s_mov_b32 m0, s82
	s_nop 0
	buffer_load_dwordx4 v135, s[60:63], s19 offen lds
	s_waitcnt vmcnt(8)
	s_waitcnt lgkmcnt(0)
	s_setprio 1
	s_barrier
	v_mfma_f32_16x16x32_bf16 v[126:129], v[142:145], v[194:197], v[126:129]
	v_mfma_f32_16x16x32_bf16 v[126:129], v[154:157], v[198:201], v[126:129]
	v_mfma_f32_16x16x32_bf16 v[118:121], v[142:145], v[202:205], v[118:121]
	v_mfma_f32_16x16x32_bf16 v[118:121], v[154:157], v[228:231], v[118:121]
	v_mfma_f32_16x16x32_bf16 v[110:113], v[142:145], v[232:235], v[110:113]
	v_mfma_f32_16x16x32_bf16 v[110:113], v[154:157], v[236:239], v[110:113]
	v_mfma_f32_16x16x32_bf16 v[102:105], v[142:145], v[240:243], v[102:105]
	v_mfma_f32_16x16x32_bf16 v[102:105], v[154:157], v[244:247], v[102:105]
	v_mfma_f32_16x16x32_bf16 v[98:101], v[170:173], v[240:243], v[98:101]
	v_mfma_f32_16x16x32_bf16 v[98:101], v[174:177], v[244:247], v[98:101]
	v_mfma_f32_16x16x32_bf16 v[106:109], v[170:173], v[232:235], v[106:109]
	v_mfma_f32_16x16x32_bf16 v[106:109], v[174:177], v[236:239], v[106:109]
	v_mfma_f32_16x16x32_bf16 v[114:117], v[170:173], v[202:205], v[114:117]
	v_mfma_f32_16x16x32_bf16 v[114:117], v[174:177], v[228:231], v[114:117]
	v_mfma_f32_16x16x32_bf16 v[122:125], v[170:173], v[194:197], v[122:125]
	v_mfma_f32_16x16x32_bf16 v[122:125], v[174:177], v[198:201], v[122:125]
	v_mfma_f32_16x16x32_bf16 v[58:61], v[186:189], v[194:197], v[58:61]
	v_mfma_f32_16x16x32_bf16 v[58:61], v[190:193], v[198:201], v[58:61]
	v_mfma_f32_16x16x32_bf16 v[50:53], v[186:189], v[202:205], v[50:53]
	v_mfma_f32_16x16x32_bf16 v[50:53], v[190:193], v[228:231], v[50:53]
	v_mfma_f32_16x16x32_bf16 v[42:45], v[186:189], v[232:235], v[42:45]
	v_mfma_f32_16x16x32_bf16 v[42:45], v[190:193], v[236:239], v[42:45]
	v_mfma_f32_16x16x32_bf16 v[34:37], v[186:189], v[240:243], v[34:37]
	v_mfma_f32_16x16x32_bf16 v[34:37], v[190:193], v[244:247], v[34:37]
	v_mfma_f32_16x16x32_bf16 v[38:41], v[178:181], v[240:243], v[38:41]
	v_mfma_f32_16x16x32_bf16 v[38:41], v[182:185], v[244:247], v[38:41]
	v_mfma_f32_16x16x32_bf16 v[46:49], v[178:181], v[232:235], v[46:49]
	v_mfma_f32_16x16x32_bf16 v[46:49], v[182:185], v[236:239], v[46:49]
	v_mfma_f32_16x16x32_bf16 v[54:57], v[178:181], v[202:205], v[54:57]
	v_mfma_f32_16x16x32_bf16 v[54:57], v[182:185], v[228:231], v[54:57]
	v_mfma_f32_16x16x32_bf16 v[62:65], v[178:181], v[194:197], v[62:65]
	v_mfma_f32_16x16x32_bf16 v[62:65], v[182:185], v[198:201], v[62:65]
	s_barrier
	s_setprio 0
	s_mov_b32 s70, s62
	s_mov_b32 s71, s63
	s_mov_b32 m0, s21
	ds_read_b128 v[194:197], v140 offset:16384
	buffer_load_dwordx4 v134, s[68:71], s83 offen lds
	s_add_i32 s53, s83, 0x80000
	s_mov_b32 m0, s23
	ds_read_b128 v[198:201], v140 offset:17408
	buffer_load_dwordx4 v136, s[68:71], s83 offen lds
	s_mov_b32 m0, s24
	ds_read_b128 v[202:205], v140 offset:18432
	buffer_load_dwordx4 v134, s[68:71], s53 offen lds
	s_mov_b32 m0, s25
	ds_read_b128 v[228:231], v140 offset:19456
	buffer_load_dwordx4 v136, s[68:71], s53 offen lds
	s_mov_b32 m0, s2
	ds_read_b128 v[232:235], v140 offset:20480
	buffer_load_dwordx4 v131, s[60:63], s52 offen lds
	s_mov_b32 m0, s30
	ds_read_b128 v[236:239], v140 offset:21504
	buffer_load_dwordx4 v135, s[60:63], s52 offen lds
	ds_read_b128 v[240:243], v140 offset:22528
	ds_read_b128 v[244:247], v140 offset:23552
	s_waitcnt vmcnt(8)
	s_waitcnt lgkmcnt(0)
	s_setprio 1
	s_barrier
	v_mfma_f32_16x16x32_bf16 v[94:97], v[142:145], v[194:197], v[94:97]
	v_mfma_f32_16x16x32_bf16 v[94:97], v[154:157], v[198:201], v[94:97]
	v_mfma_f32_16x16x32_bf16 v[86:89], v[142:145], v[202:205], v[86:89]
	v_mfma_f32_16x16x32_bf16 v[86:89], v[154:157], v[228:231], v[86:89]
	v_mfma_f32_16x16x32_bf16 v[78:81], v[142:145], v[232:235], v[78:81]
	v_mfma_f32_16x16x32_bf16 v[78:81], v[154:157], v[236:239], v[78:81]
	v_mfma_f32_16x16x32_bf16 v[70:73], v[142:145], v[240:243], v[70:73]
	v_mfma_f32_16x16x32_bf16 v[70:73], v[154:157], v[244:247], v[70:73]
	v_mfma_f32_16x16x32_bf16 v[66:69], v[170:173], v[240:243], v[66:69]
	v_mfma_f32_16x16x32_bf16 v[66:69], v[174:177], v[244:247], v[66:69]
	v_mfma_f32_16x16x32_bf16 v[74:77], v[170:173], v[232:235], v[74:77]
	v_mfma_f32_16x16x32_bf16 v[74:77], v[174:177], v[236:239], v[74:77]
	v_mfma_f32_16x16x32_bf16 v[82:85], v[170:173], v[202:205], v[82:85]
	v_mfma_f32_16x16x32_bf16 v[82:85], v[174:177], v[228:231], v[82:85]
	v_mfma_f32_16x16x32_bf16 v[90:93], v[170:173], v[194:197], v[90:93]
	v_mfma_f32_16x16x32_bf16 v[90:93], v[174:177], v[198:201], v[90:93]
	v_mfma_f32_16x16x32_bf16 v[26:29], v[186:189], v[194:197], v[26:29]
	v_mfma_f32_16x16x32_bf16 v[26:29], v[190:193], v[198:201], v[26:29]
	v_mfma_f32_16x16x32_bf16 v[18:21], v[186:189], v[202:205], v[18:21]
	v_mfma_f32_16x16x32_bf16 v[18:21], v[190:193], v[228:231], v[18:21]
	v_mfma_f32_16x16x32_bf16 v[10:13], v[186:189], v[232:235], v[10:13]
	v_mfma_f32_16x16x32_bf16 v[10:13], v[190:193], v[236:239], v[10:13]
	v_mfma_f32_16x16x32_bf16 v[2:5], v[186:189], v[240:243], v[2:5]
	v_mfma_f32_16x16x32_bf16 v[2:5], v[190:193], v[244:247], v[2:5]
	v_mfma_f32_16x16x32_bf16 v[6:9], v[178:181], v[240:243], v[6:9]
	v_mfma_f32_16x16x32_bf16 v[6:9], v[182:185], v[244:247], v[6:9]
	v_mfma_f32_16x16x32_bf16 v[14:17], v[178:181], v[232:235], v[14:17]
	v_mfma_f32_16x16x32_bf16 v[14:17], v[182:185], v[236:239], v[14:17]
	v_mfma_f32_16x16x32_bf16 v[22:25], v[178:181], v[202:205], v[22:25]
	v_mfma_f32_16x16x32_bf16 v[22:25], v[182:185], v[228:231], v[22:25]
	v_mfma_f32_16x16x32_bf16 v[30:33], v[178:181], v[194:197], v[30:33]
	v_mfma_f32_16x16x32_bf16 v[30:33], v[182:185], v[198:201], v[30:33]
	s_barrier
	s_setprio 0
	v_add_u32_e32 v141, 0x18000, v139
	ds_read_b128 v[142:145], v141
	ds_read_b128 v[154:157], v141 offset:1024
	ds_read_b128 v[170:173], v141 offset:2048
	ds_read_b128 v[174:177], v141 offset:3072
	v_add_u32_e32 v141, 0x1c000, v139
	ds_read_b128 v[178:181], v141
	ds_read_b128 v[182:185], v141 offset:1024
	ds_read_b128 v[186:189], v141 offset:2048
	ds_read_b128 v[190:193], v141 offset:3072
	s_add_i32 s52, s52, 0x80000
	s_mov_b32 m0, s31
	ds_read_b128 v[194:197], v140 offset:32768
	ds_read_b128 v[198:201], v140 offset:33792
	ds_read_b128 v[202:205], v140 offset:34816
	ds_read_b128 v[228:231], v140 offset:35840
	ds_read_b128 v[232:235], v140 offset:36864
	ds_read_b128 v[236:239], v140 offset:37888
	ds_read_b128 v[240:243], v140 offset:38912
	ds_read_b128 v[244:247], v140 offset:39936
	buffer_load_dwordx4 v131, s[60:63], s52 offen lds
	s_mov_b32 m0, s33
	s_nop 0
	buffer_load_dwordx4 v135, s[60:63], s52 offen lds
	s_waitcnt vmcnt(8)
	s_waitcnt lgkmcnt(0)
	s_setprio 1
	s_barrier
	v_mfma_f32_16x16x32_bf16 v[126:129], v[142:145], v[194:197], v[126:129]
	v_mfma_f32_16x16x32_bf16 v[126:129], v[154:157], v[198:201], v[126:129]
	v_mfma_f32_16x16x32_bf16 v[118:121], v[142:145], v[202:205], v[118:121]
	v_mfma_f32_16x16x32_bf16 v[118:121], v[154:157], v[228:231], v[118:121]
	v_mfma_f32_16x16x32_bf16 v[110:113], v[142:145], v[232:235], v[110:113]
	v_mfma_f32_16x16x32_bf16 v[110:113], v[154:157], v[236:239], v[110:113]
	v_mfma_f32_16x16x32_bf16 v[102:105], v[142:145], v[240:243], v[102:105]
	v_mfma_f32_16x16x32_bf16 v[102:105], v[154:157], v[244:247], v[102:105]
	v_mfma_f32_16x16x32_bf16 v[98:101], v[170:173], v[240:243], v[98:101]
	v_mfma_f32_16x16x32_bf16 v[98:101], v[174:177], v[244:247], v[98:101]
	v_mfma_f32_16x16x32_bf16 v[106:109], v[170:173], v[232:235], v[106:109]
	v_mfma_f32_16x16x32_bf16 v[106:109], v[174:177], v[236:239], v[106:109]
	v_mfma_f32_16x16x32_bf16 v[114:117], v[170:173], v[202:205], v[114:117]
	v_mfma_f32_16x16x32_bf16 v[114:117], v[174:177], v[228:231], v[114:117]
	v_mfma_f32_16x16x32_bf16 v[122:125], v[170:173], v[194:197], v[122:125]
	v_mfma_f32_16x16x32_bf16 v[122:125], v[174:177], v[198:201], v[122:125]
	v_mfma_f32_16x16x32_bf16 v[58:61], v[186:189], v[194:197], v[58:61]
	v_mfma_f32_16x16x32_bf16 v[58:61], v[190:193], v[198:201], v[58:61]
	v_mfma_f32_16x16x32_bf16 v[50:53], v[186:189], v[202:205], v[50:53]
	v_mfma_f32_16x16x32_bf16 v[50:53], v[190:193], v[228:231], v[50:53]
	v_mfma_f32_16x16x32_bf16 v[42:45], v[186:189], v[232:235], v[42:45]
	v_mfma_f32_16x16x32_bf16 v[42:45], v[190:193], v[236:239], v[42:45]
	v_mfma_f32_16x16x32_bf16 v[34:37], v[186:189], v[240:243], v[34:37]
	v_mfma_f32_16x16x32_bf16 v[34:37], v[190:193], v[244:247], v[34:37]
	v_mfma_f32_16x16x32_bf16 v[38:41], v[178:181], v[240:243], v[38:41]
	v_mfma_f32_16x16x32_bf16 v[38:41], v[182:185], v[244:247], v[38:41]
	v_mfma_f32_16x16x32_bf16 v[46:49], v[178:181], v[232:235], v[46:49]
	v_mfma_f32_16x16x32_bf16 v[46:49], v[182:185], v[236:239], v[46:49]
	v_mfma_f32_16x16x32_bf16 v[54:57], v[178:181], v[202:205], v[54:57]
	v_mfma_f32_16x16x32_bf16 v[54:57], v[182:185], v[228:231], v[54:57]
	v_mfma_f32_16x16x32_bf16 v[62:65], v[178:181], v[194:197], v[62:65]
	v_mfma_f32_16x16x32_bf16 v[62:65], v[182:185], v[198:201], v[62:65]
	s_barrier
	s_setprio 0
	s_or_b32 s52, s83, 0x80
	s_mov_b32 m0, s34
	ds_read_b128 v[194:197], v140 offset:49152
	buffer_load_dwordx4 v134, s[68:71], s52 offen lds
	s_add_i32 s83, s83, 0x80080
	s_mov_b32 m0, s35
	ds_read_b128 v[198:201], v140 offset:50176
	buffer_load_dwordx4 v136, s[68:71], s52 offen lds
	s_mov_b32 m0, s65
	ds_read_b128 v[202:205], v140 offset:51200
	buffer_load_dwordx4 v134, s[68:71], s83 offen lds
	s_mov_b32 m0, s66
	ds_read_b128 v[228:231], v140 offset:52224
	buffer_load_dwordx4 v136, s[68:71], s83 offen lds
	s_mov_b32 m0, s36
	ds_read_b128 v[232:235], v140 offset:53248
	buffer_load_dwordx4 v131, s[60:63], s27 offen lds
	s_mov_b32 m0, s37
	ds_read_b128 v[236:239], v140 offset:54272
	buffer_load_dwordx4 v135, s[60:63], s27 offen lds
	ds_read_b128 v[240:243], v140 offset:55296
	ds_read_b128 v[244:247], v140 offset:56320
	s_waitcnt vmcnt(8)
	s_waitcnt lgkmcnt(0)
	s_setprio 1
	s_barrier
	v_mfma_f32_16x16x32_bf16 v[94:97], v[142:145], v[194:197], v[94:97]
	v_mfma_f32_16x16x32_bf16 v[94:97], v[154:157], v[198:201], v[94:97]
	v_mfma_f32_16x16x32_bf16 v[86:89], v[142:145], v[202:205], v[86:89]
	v_mfma_f32_16x16x32_bf16 v[86:89], v[154:157], v[228:231], v[86:89]
	v_mfma_f32_16x16x32_bf16 v[78:81], v[142:145], v[232:235], v[78:81]
	v_mfma_f32_16x16x32_bf16 v[78:81], v[154:157], v[236:239], v[78:81]
	v_mfma_f32_16x16x32_bf16 v[70:73], v[142:145], v[240:243], v[70:73]
	v_mfma_f32_16x16x32_bf16 v[70:73], v[154:157], v[244:247], v[70:73]
	v_mfma_f32_16x16x32_bf16 v[66:69], v[170:173], v[240:243], v[66:69]
	v_mfma_f32_16x16x32_bf16 v[66:69], v[174:177], v[244:247], v[66:69]
	v_mfma_f32_16x16x32_bf16 v[74:77], v[170:173], v[232:235], v[74:77]
	v_mfma_f32_16x16x32_bf16 v[74:77], v[174:177], v[236:239], v[74:77]
	v_mfma_f32_16x16x32_bf16 v[82:85], v[170:173], v[202:205], v[82:85]
	v_mfma_f32_16x16x32_bf16 v[82:85], v[174:177], v[228:231], v[82:85]
	v_mfma_f32_16x16x32_bf16 v[90:93], v[170:173], v[194:197], v[90:93]
	v_mfma_f32_16x16x32_bf16 v[90:93], v[174:177], v[198:201], v[90:93]
	v_mfma_f32_16x16x32_bf16 v[26:29], v[186:189], v[194:197], v[26:29]
	v_mfma_f32_16x16x32_bf16 v[26:29], v[190:193], v[198:201], v[26:29]
	v_mfma_f32_16x16x32_bf16 v[18:21], v[186:189], v[202:205], v[18:21]
	v_mfma_f32_16x16x32_bf16 v[18:21], v[190:193], v[228:231], v[18:21]
	v_mfma_f32_16x16x32_bf16 v[10:13], v[186:189], v[232:235], v[10:13]
	v_mfma_f32_16x16x32_bf16 v[10:13], v[190:193], v[236:239], v[10:13]
	v_mfma_f32_16x16x32_bf16 v[2:5], v[186:189], v[240:243], v[2:5]
	v_mfma_f32_16x16x32_bf16 v[2:5], v[190:193], v[244:247], v[2:5]
	v_mfma_f32_16x16x32_bf16 v[6:9], v[178:181], v[240:243], v[6:9]
	v_mfma_f32_16x16x32_bf16 v[6:9], v[182:185], v[244:247], v[6:9]
	v_mfma_f32_16x16x32_bf16 v[14:17], v[178:181], v[232:235], v[14:17]
	v_mfma_f32_16x16x32_bf16 v[14:17], v[182:185], v[236:239], v[14:17]
	v_mfma_f32_16x16x32_bf16 v[22:25], v[178:181], v[202:205], v[22:25]
	v_mfma_f32_16x16x32_bf16 v[22:25], v[182:185], v[228:231], v[22:25]
	v_mfma_f32_16x16x32_bf16 v[30:33], v[178:181], v[194:197], v[30:33]
	v_mfma_f32_16x16x32_bf16 v[30:33], v[182:185], v[198:201], v[30:33]
	s_barrier
	s_setprio 0
	s_add_i32 s26, s26, 2
	s_addk_i32 s19, 0x100
	s_addk_i32 s22, 0x100
	s_cmp_gt_u32 s26, 29
	s_cbranch_scc0 .LBB0_1283
	s_and_b64 vcc, exec, s[44:45]
	s_cbranch_vccz .LBB0_1286
	s_barrier

.LBB0_1588:
	s_lshl_b32 s85, s84, 20
	s_and_b64 s[8:9], s[42:43], exec
	s_cselect_b32 s8, s85, s13
	s_lshl_b32 s48, s73, 20
	s_and_b64 s[22:23], s[42:43], exec
	s_cselect_b32 s9, s48, s21
	s_add_i32 s13, s13, 0x80080
	s_addk_i32 s21, 0x100
	s_mov_b32 s22, -2
	s_waitcnt lgkmcnt(0)
	v_add_u32_e32 v170, 0x10000, v140
	v_add_u32_e32 v186, 0x14000, v140
	ds_read_b128 v[132:135], v170
	ds_read_b128 v[142:145], v170 offset:1024
	ds_read_b128 v[154:157], v170 offset:2048
	ds_read_b128 v[170:173], v170 offset:3072
	ds_read_b128 v[174:177], v186
	ds_read_b128 v[178:181], v186 offset:1024
	ds_read_b128 v[182:185], v186 offset:2048
	ds_read_b128 v[186:189], v186 offset:3072
	s_add_i32 s23, s13, 0xfff80080
	s_cmp_eq_u32 s22, 28
	s_cselect_b32 s27, s8, s23
	s_cselect_b32 s26, s9, s21
	s_or_b32 s23, s27, 0x80
	s_mov_b32 m0, s70
	ds_read_b128 v[190:193], v141
	ds_read_b128 v[194:197], v141 offset:1024
	ds_read_b128 v[198:201], v141 offset:2048
	ds_read_b128 v[202:205], v141 offset:3072
	ds_read_b128 v[228:231], v141 offset:4096
	ds_read_b128 v[232:235], v141 offset:5120
	ds_read_b128 v[236:239], v141 offset:6144
	ds_read_b128 v[240:243], v141 offset:7168
	buffer_load_dwordx4 v136, s[60:63], s13 offen lds
	s_mov_b32 m0, s72
	s_nop 0
	buffer_load_dwordx4 v138, s[60:63], s13 offen lds
	s_waitcnt vmcnt(8)
	s_waitcnt lgkmcnt(0)
	s_setprio 1
	s_barrier
	v_mfma_f32_16x16x32_bf16 v[126:129], v[132:135], v[190:193], 0
	v_mfma_f32_16x16x32_bf16 v[126:129], v[142:145], v[194:197], v[126:129]
	v_mfma_f32_16x16x32_bf16 v[118:121], v[132:135], v[198:201], 0
	v_mfma_f32_16x16x32_bf16 v[118:121], v[142:145], v[202:205], v[118:121]
	v_mfma_f32_16x16x32_bf16 v[94:97], v[132:135], v[228:231], 0
	v_mfma_f32_16x16x32_bf16 v[94:97], v[142:145], v[232:235], v[94:97]
	v_mfma_f32_16x16x32_bf16 v[78:81], v[132:135], v[236:239], 0
	v_mfma_f32_16x16x32_bf16 v[78:81], v[142:145], v[240:243], v[78:81]
	v_mfma_f32_16x16x32_bf16 v[74:77], v[154:157], v[236:239], 0
	v_mfma_f32_16x16x32_bf16 v[74:77], v[170:173], v[240:243], v[74:77]
	v_mfma_f32_16x16x32_bf16 v[90:93], v[154:157], v[228:231], 0
	v_mfma_f32_16x16x32_bf16 v[90:93], v[170:173], v[232:235], v[90:93]
	v_mfma_f32_16x16x32_bf16 v[114:117], v[154:157], v[198:201], 0
	v_mfma_f32_16x16x32_bf16 v[114:117], v[170:173], v[202:205], v[114:117]
	v_mfma_f32_16x16x32_bf16 v[106:109], v[154:157], v[190:193], 0
	v_mfma_f32_16x16x32_bf16 v[106:109], v[170:173], v[194:197], v[106:109]
	v_mfma_f32_16x16x32_bf16 v[110:113], v[182:185], v[190:193], 0
	v_mfma_f32_16x16x32_bf16 v[110:113], v[186:189], v[194:197], v[110:113]
	v_mfma_f32_16x16x32_bf16 v[98:101], v[182:185], v[198:201], 0
	v_mfma_f32_16x16x32_bf16 v[98:101], v[186:189], v[202:205], v[98:101]
	v_mfma_f32_16x16x32_bf16 v[82:85], v[182:185], v[228:231], 0
	v_mfma_f32_16x16x32_bf16 v[82:85], v[186:189], v[232:235], v[82:85]
	v_mfma_f32_16x16x32_bf16 v[66:69], v[182:185], v[236:239], 0
	v_mfma_f32_16x16x32_bf16 v[66:69], v[186:189], v[240:243], v[66:69]
	v_mfma_f32_16x16x32_bf16 v[70:73], v[174:177], v[236:239], 0
	v_mfma_f32_16x16x32_bf16 v[70:73], v[178:181], v[240:243], v[70:73]
	v_mfma_f32_16x16x32_bf16 v[86:89], v[174:177], v[228:231], 0
	v_mfma_f32_16x16x32_bf16 v[86:89], v[178:181], v[232:235], v[86:89]
	v_mfma_f32_16x16x32_bf16 v[102:105], v[174:177], v[198:201], 0
	v_mfma_f32_16x16x32_bf16 v[102:105], v[178:181], v[202:205], v[102:105]
	v_mfma_f32_16x16x32_bf16 v[122:125], v[174:177], v[190:193], 0
	v_mfma_f32_16x16x32_bf16 v[122:125], v[178:181], v[194:197], v[122:125]
	s_barrier
	s_setprio 0
	s_mov_b32 s46, s62
	s_mov_b32 s47, s63
	s_mov_b32 m0, s15
	ds_read_b128 v[190:193], v141 offset:16384
	buffer_load_dwordx4 v137, s[44:47], s26 offen lds
	s_add_i32 s49, s26, 0x80000
	s_mov_b32 m0, s16
	ds_read_b128 v[194:197], v141 offset:17408
	buffer_load_dwordx4 v139, s[44:47], s26 offen lds
	s_mov_b32 m0, s18
	ds_read_b128 v[198:201], v141 offset:18432
	buffer_load_dwordx4 v137, s[44:47], s49 offen lds
	s_mov_b32 m0, s19
	ds_read_b128 v[202:205], v141 offset:19456
	buffer_load_dwordx4 v139, s[44:47], s49 offen lds
	s_mov_b32 m0, s14
	ds_read_b128 v[228:231], v141 offset:20480
	buffer_load_dwordx4 v136, s[60:63], s27 offen lds
	s_mov_b32 m0, s24
	ds_read_b128 v[232:235], v141 offset:21504
	buffer_load_dwordx4 v138, s[60:63], s27 offen lds
	ds_read_b128 v[236:239], v141 offset:22528
	ds_read_b128 v[240:243], v141 offset:23552
	s_waitcnt vmcnt(8)
	s_waitcnt lgkmcnt(0)
	s_setprio 1
	s_barrier
	v_mfma_f32_16x16x32_bf16 v[62:65], v[132:135], v[190:193], 0
	v_mfma_f32_16x16x32_bf16 v[62:65], v[142:145], v[194:197], v[62:65]
	v_mfma_f32_16x16x32_bf16 v[46:49], v[132:135], v[198:201], 0
	v_mfma_f32_16x16x32_bf16 v[46:49], v[142:145], v[202:205], v[46:49]
	v_mfma_f32_16x16x32_bf16 v[30:33], v[132:135], v[228:231], 0
	v_mfma_f32_16x16x32_bf16 v[30:33], v[142:145], v[232:235], v[30:33]
	v_mfma_f32_16x16x32_bf16 v[14:17], v[132:135], v[236:239], 0
	v_mfma_f32_16x16x32_bf16 v[14:17], v[142:145], v[240:243], v[14:17]
	v_mfma_f32_16x16x32_bf16 v[10:13], v[154:157], v[236:239], 0
	v_mfma_f32_16x16x32_bf16 v[10:13], v[170:173], v[240:243], v[10:13]
	v_mfma_f32_16x16x32_bf16 v[26:29], v[154:157], v[228:231], 0
	v_mfma_f32_16x16x32_bf16 v[26:29], v[170:173], v[232:235], v[26:29]
	v_mfma_f32_16x16x32_bf16 v[42:45], v[154:157], v[198:201], 0
	v_mfma_f32_16x16x32_bf16 v[42:45], v[170:173], v[202:205], v[42:45]
	v_mfma_f32_16x16x32_bf16 v[58:61], v[154:157], v[190:193], 0
	v_mfma_f32_16x16x32_bf16 v[58:61], v[170:173], v[194:197], v[58:61]
	v_mfma_f32_16x16x32_bf16 v[50:53], v[182:185], v[190:193], 0
	v_mfma_f32_16x16x32_bf16 v[50:53], v[186:189], v[194:197], v[50:53]
	v_mfma_f32_16x16x32_bf16 v[34:37], v[182:185], v[198:201], 0
	v_mfma_f32_16x16x32_bf16 v[34:37], v[186:189], v[202:205], v[34:37]
	v_mfma_f32_16x16x32_bf16 v[18:21], v[182:185], v[228:231], 0
	v_mfma_f32_16x16x32_bf16 v[18:21], v[186:189], v[232:235], v[18:21]
	v_mfma_f32_16x16x32_bf16 v[2:5], v[182:185], v[236:239], 0
	v_mfma_f32_16x16x32_bf16 v[2:5], v[186:189], v[240:243], v[2:5]
	v_mfma_f32_16x16x32_bf16 v[6:9], v[174:177], v[236:239], 0
	v_mfma_f32_16x16x32_bf16 v[6:9], v[178:181], v[240:243], v[6:9]
	v_mfma_f32_16x16x32_bf16 v[22:25], v[174:177], v[228:231], 0
	v_mfma_f32_16x16x32_bf16 v[22:25], v[178:181], v[232:235], v[22:25]
	v_mfma_f32_16x16x32_bf16 v[38:41], v[174:177], v[198:201], 0
	v_mfma_f32_16x16x32_bf16 v[38:41], v[178:181], v[202:205], v[38:41]
	v_mfma_f32_16x16x32_bf16 v[54:57], v[174:177], v[190:193], 0
	v_mfma_f32_16x16x32_bf16 v[54:57], v[178:181], v[194:197], v[54:57]
	s_barrier
	s_setprio 0
	v_add_u32_e32 v170, 0x18000, v140
	v_add_u32_e32 v186, 0x1c000, v140
	ds_read_b128 v[132:135], v170
	ds_read_b128 v[142:145], v170 offset:1024
	ds_read_b128 v[154:157], v170 offset:2048
	ds_read_b128 v[170:173], v170 offset:3072
	ds_read_b128 v[174:177], v186
	ds_read_b128 v[178:181], v186 offset:1024
	ds_read_b128 v[182:185], v186 offset:2048
	ds_read_b128 v[186:189], v186 offset:3072
	s_add_i32 s27, s27, 0x80000
	s_mov_b32 m0, s25
	ds_read_b128 v[190:193], v141 offset:32768
	ds_read_b128 v[194:197], v141 offset:33792
	ds_read_b128 v[198:201], v141 offset:34816
	ds_read_b128 v[202:205], v141 offset:35840
	ds_read_b128 v[228:231], v141 offset:36864
	ds_read_b128 v[232:235], v141 offset:37888
	ds_read_b128 v[236:239], v141 offset:38912
	ds_read_b128 v[240:243], v141 offset:39936
	buffer_load_dwordx4 v136, s[60:63], s27 offen lds
	s_mov_b32 m0, s30
	s_nop 0
	buffer_load_dwordx4 v138, s[60:63], s27 offen lds
	s_waitcnt vmcnt(8)
	s_waitcnt lgkmcnt(0)
	s_setprio 1
	s_barrier
	v_mfma_f32_16x16x32_bf16 v[126:129], v[132:135], v[190:193], v[126:129]
	v_mfma_f32_16x16x32_bf16 v[126:129], v[142:145], v[194:197], v[126:129]
	v_mfma_f32_16x16x32_bf16 v[118:121], v[132:135], v[198:201], v[118:121]
	v_mfma_f32_16x16x32_bf16 v[118:121], v[142:145], v[202:205], v[118:121]
	v_mfma_f32_16x16x32_bf16 v[94:97], v[132:135], v[228:231], v[94:97]
	v_mfma_f32_16x16x32_bf16 v[94:97], v[142:145], v[232:235], v[94:97]
	v_mfma_f32_16x16x32_bf16 v[78:81], v[132:135], v[236:239], v[78:81]
	v_mfma_f32_16x16x32_bf16 v[78:81], v[142:145], v[240:243], v[78:81]
	v_mfma_f32_16x16x32_bf16 v[74:77], v[154:157], v[236:239], v[74:77]
	v_mfma_f32_16x16x32_bf16 v[74:77], v[170:173], v[240:243], v[74:77]
	v_mfma_f32_16x16x32_bf16 v[90:93], v[154:157], v[228:231], v[90:93]
	v_mfma_f32_16x16x32_bf16 v[90:93], v[170:173], v[232:235], v[90:93]
	v_mfma_f32_16x16x32_bf16 v[114:117], v[154:157], v[198:201], v[114:117]
	v_mfma_f32_16x16x32_bf16 v[114:117], v[170:173], v[202:205], v[114:117]
	v_mfma_f32_16x16x32_bf16 v[106:109], v[154:157], v[190:193], v[106:109]
	v_mfma_f32_16x16x32_bf16 v[106:109], v[170:173], v[194:197], v[106:109]
	v_mfma_f32_16x16x32_bf16 v[110:113], v[182:185], v[190:193], v[110:113]
	v_mfma_f32_16x16x32_bf16 v[110:113], v[186:189], v[194:197], v[110:113]
	v_mfma_f32_16x16x32_bf16 v[98:101], v[182:185], v[198:201], v[98:101]
	v_mfma_f32_16x16x32_bf16 v[98:101], v[186:189], v[202:205], v[98:101]
	v_mfma_f32_16x16x32_bf16 v[82:85], v[182:185], v[228:231], v[82:85]
	v_mfma_f32_16x16x32_bf16 v[82:85], v[186:189], v[232:235], v[82:85]
	v_mfma_f32_16x16x32_bf16 v[66:69], v[182:185], v[236:239], v[66:69]
	v_mfma_f32_16x16x32_bf16 v[66:69], v[186:189], v[240:243], v[66:69]
	v_mfma_f32_16x16x32_bf16 v[70:73], v[174:177], v[236:239], v[70:73]
	v_mfma_f32_16x16x32_bf16 v[70:73], v[178:181], v[240:243], v[70:73]
	v_mfma_f32_16x16x32_bf16 v[86:89], v[174:177], v[228:231], v[86:89]
	v_mfma_f32_16x16x32_bf16 v[86:89], v[178:181], v[232:235], v[86:89]
	v_mfma_f32_16x16x32_bf16 v[102:105], v[174:177], v[198:201], v[102:105]
	v_mfma_f32_16x16x32_bf16 v[102:105], v[178:181], v[202:205], v[102:105]
	v_mfma_f32_16x16x32_bf16 v[122:125], v[174:177], v[190:193], v[122:125]
	v_mfma_f32_16x16x32_bf16 v[122:125], v[178:181], v[194:197], v[122:125]
	s_barrier
	s_setprio 0
	s_or_b32 s27, s26, 0x80
	s_mov_b32 m0, s36
	ds_read_b128 v[190:193], v141 offset:49152
	buffer_load_dwordx4 v137, s[44:47], s27 offen lds
	s_add_i32 s26, s26, 0x80080
	s_mov_b32 m0, s37
	ds_read_b128 v[194:197], v141 offset:50176
	buffer_load_dwordx4 v139, s[44:47], s27 offen lds
	s_mov_b32 m0, s68
	ds_read_b128 v[198:201], v141 offset:51200
	buffer_load_dwordx4 v137, s[44:47], s26 offen lds
	s_mov_b32 m0, s69
	ds_read_b128 v[202:205], v141 offset:52224
	buffer_load_dwordx4 v139, s[44:47], s26 offen lds
	s_mov_b32 m0, s66
	ds_read_b128 v[228:231], v141 offset:53248
	buffer_load_dwordx4 v136, s[60:63], s23 offen lds
	s_mov_b32 m0, s67
	ds_read_b128 v[232:235], v141 offset:54272
	buffer_load_dwordx4 v138, s[60:63], s23 offen lds
	ds_read_b128 v[236:239], v141 offset:55296
	ds_read_b128 v[240:243], v141 offset:56320
	s_waitcnt vmcnt(8)
	s_waitcnt lgkmcnt(0)
	s_setprio 1
	s_barrier
	v_mfma_f32_16x16x32_bf16 v[62:65], v[132:135], v[190:193], v[62:65]
	v_mfma_f32_16x16x32_bf16 v[62:65], v[142:145], v[194:197], v[62:65]
	v_mfma_f32_16x16x32_bf16 v[46:49], v[132:135], v[198:201], v[46:49]
	v_mfma_f32_16x16x32_bf16 v[46:49], v[142:145], v[202:205], v[46:49]
	v_mfma_f32_16x16x32_bf16 v[30:33], v[132:135], v[228:231], v[30:33]
	v_mfma_f32_16x16x32_bf16 v[30:33], v[142:145], v[232:235], v[30:33]
	v_mfma_f32_16x16x32_bf16 v[14:17], v[132:135], v[236:239], v[14:17]
	v_mfma_f32_16x16x32_bf16 v[14:17], v[142:145], v[240:243], v[14:17]
	v_mfma_f32_16x16x32_bf16 v[10:13], v[154:157], v[236:239], v[10:13]
	v_mfma_f32_16x16x32_bf16 v[10:13], v[170:173], v[240:243], v[10:13]
	v_mfma_f32_16x16x32_bf16 v[26:29], v[154:157], v[228:231], v[26:29]
	v_mfma_f32_16x16x32_bf16 v[26:29], v[170:173], v[232:235], v[26:29]
	v_mfma_f32_16x16x32_bf16 v[42:45], v[154:157], v[198:201], v[42:45]
	v_mfma_f32_16x16x32_bf16 v[42:45], v[170:173], v[202:205], v[42:45]
	v_mfma_f32_16x16x32_bf16 v[58:61], v[154:157], v[190:193], v[58:61]
	v_mfma_f32_16x16x32_bf16 v[58:61], v[170:173], v[194:197], v[58:61]
	v_mfma_f32_16x16x32_bf16 v[50:53], v[182:185], v[190:193], v[50:53]
	v_mfma_f32_16x16x32_bf16 v[50:53], v[186:189], v[194:197], v[50:53]
	v_mfma_f32_16x16x32_bf16 v[34:37], v[182:185], v[198:201], v[34:37]
	v_mfma_f32_16x16x32_bf16 v[34:37], v[186:189], v[202:205], v[34:37]
	v_mfma_f32_16x16x32_bf16 v[18:21], v[182:185], v[228:231], v[18:21]
	v_mfma_f32_16x16x32_bf16 v[18:21], v[186:189], v[232:235], v[18:21]
	v_mfma_f32_16x16x32_bf16 v[2:5], v[182:185], v[236:239], v[2:5]
	v_mfma_f32_16x16x32_bf16 v[2:5], v[186:189], v[240:243], v[2:5]
	v_mfma_f32_16x16x32_bf16 v[6:9], v[174:177], v[236:239], v[6:9]
	v_mfma_f32_16x16x32_bf16 v[6:9], v[178:181], v[240:243], v[6:9]
	v_mfma_f32_16x16x32_bf16 v[22:25], v[174:177], v[228:231], v[22:25]
	v_mfma_f32_16x16x32_bf16 v[22:25], v[178:181], v[232:235], v[22:25]
	v_mfma_f32_16x16x32_bf16 v[38:41], v[174:177], v[198:201], v[38:41]
	v_mfma_f32_16x16x32_bf16 v[38:41], v[178:181], v[202:205], v[38:41]
	v_mfma_f32_16x16x32_bf16 v[54:57], v[174:177], v[190:193], v[54:57]
	v_mfma_f32_16x16x32_bf16 v[54:57], v[178:181], v[194:197], v[54:57]
	s_barrier
	s_setprio 0
	s_add_i32 s22, s22, 2
	s_addk_i32 s13, 0x100
	s_addk_i32 s21, 0x100
	s_cmp_gt_u32 s22, 29
.LBB0_1589:
	v_add_u32_e32 v170, 0x10000, v140
	v_add_u32_e32 v186, 0x14000, v140
	ds_read_b128 v[132:135], v170
	ds_read_b128 v[142:145], v170 offset:1024
	ds_read_b128 v[154:157], v170 offset:2048
	ds_read_b128 v[170:173], v170 offset:3072
	ds_read_b128 v[174:177], v186
	ds_read_b128 v[178:181], v186 offset:1024
	ds_read_b128 v[182:185], v186 offset:2048
	ds_read_b128 v[186:189], v186 offset:3072
	s_add_i32 s23, s13, 0xfff80080
	s_cmp_eq_u32 s22, 28
	s_cselect_b32 s27, s8, s23
	s_cselect_b32 s26, s9, s21
	s_or_b32 s23, s27, 0x80
	s_mov_b32 m0, s70
	ds_read_b128 v[190:193], v141
	ds_read_b128 v[194:197], v141 offset:1024
	ds_read_b128 v[198:201], v141 offset:2048
	ds_read_b128 v[202:205], v141 offset:3072
	ds_read_b128 v[228:231], v141 offset:4096
	ds_read_b128 v[232:235], v141 offset:5120
	ds_read_b128 v[236:239], v141 offset:6144
	ds_read_b128 v[240:243], v141 offset:7168
	buffer_load_dwordx4 v136, s[60:63], s13 offen lds
	s_mov_b32 m0, s72
	s_nop 0
	buffer_load_dwordx4 v138, s[60:63], s13 offen lds
	s_waitcnt vmcnt(8)
	s_waitcnt lgkmcnt(0)
	s_setprio 1
	s_barrier
	v_mfma_f32_16x16x32_bf16 v[126:129], v[132:135], v[190:193], v[126:129]
	v_mfma_f32_16x16x32_bf16 v[126:129], v[142:145], v[194:197], v[126:129]
	v_mfma_f32_16x16x32_bf16 v[118:121], v[132:135], v[198:201], v[118:121]
	v_mfma_f32_16x16x32_bf16 v[118:121], v[142:145], v[202:205], v[118:121]
	v_mfma_f32_16x16x32_bf16 v[94:97], v[132:135], v[228:231], v[94:97]
	v_mfma_f32_16x16x32_bf16 v[94:97], v[142:145], v[232:235], v[94:97]
	v_mfma_f32_16x16x32_bf16 v[78:81], v[132:135], v[236:239], v[78:81]
	v_mfma_f32_16x16x32_bf16 v[78:81], v[142:145], v[240:243], v[78:81]
	v_mfma_f32_16x16x32_bf16 v[74:77], v[154:157], v[236:239], v[74:77]
	v_mfma_f32_16x16x32_bf16 v[74:77], v[170:173], v[240:243], v[74:77]
	v_mfma_f32_16x16x32_bf16 v[90:93], v[154:157], v[228:231], v[90:93]
	v_mfma_f32_16x16x32_bf16 v[90:93], v[170:173], v[232:235], v[90:93]
	v_mfma_f32_16x16x32_bf16 v[114:117], v[154:157], v[198:201], v[114:117]
	v_mfma_f32_16x16x32_bf16 v[114:117], v[170:173], v[202:205], v[114:117]
	v_mfma_f32_16x16x32_bf16 v[106:109], v[154:157], v[190:193], v[106:109]
	v_mfma_f32_16x16x32_bf16 v[106:109], v[170:173], v[194:197], v[106:109]
	v_mfma_f32_16x16x32_bf16 v[110:113], v[182:185], v[190:193], v[110:113]
	v_mfma_f32_16x16x32_bf16 v[110:113], v[186:189], v[194:197], v[110:113]
	v_mfma_f32_16x16x32_bf16 v[98:101], v[182:185], v[198:201], v[98:101]
	v_mfma_f32_16x16x32_bf16 v[98:101], v[186:189], v[202:205], v[98:101]
	v_mfma_f32_16x16x32_bf16 v[82:85], v[182:185], v[228:231], v[82:85]
	v_mfma_f32_16x16x32_bf16 v[82:85], v[186:189], v[232:235], v[82:85]
	v_mfma_f32_16x16x32_bf16 v[66:69], v[182:185], v[236:239], v[66:69]
	v_mfma_f32_16x16x32_bf16 v[66:69], v[186:189], v[240:243], v[66:69]
	v_mfma_f32_16x16x32_bf16 v[70:73], v[174:177], v[236:239], v[70:73]
	v_mfma_f32_16x16x32_bf16 v[70:73], v[178:181], v[240:243], v[70:73]
	v_mfma_f32_16x16x32_bf16 v[86:89], v[174:177], v[228:231], v[86:89]
	v_mfma_f32_16x16x32_bf16 v[86:89], v[178:181], v[232:235], v[86:89]
	v_mfma_f32_16x16x32_bf16 v[102:105], v[174:177], v[198:201], v[102:105]
	v_mfma_f32_16x16x32_bf16 v[102:105], v[178:181], v[202:205], v[102:105]
	v_mfma_f32_16x16x32_bf16 v[122:125], v[174:177], v[190:193], v[122:125]
	v_mfma_f32_16x16x32_bf16 v[122:125], v[178:181], v[194:197], v[122:125]
	s_barrier
	s_setprio 0
	s_mov_b32 s46, s62
	s_mov_b32 s47, s63
	s_mov_b32 m0, s15
	ds_read_b128 v[190:193], v141 offset:16384
	buffer_load_dwordx4 v137, s[44:47], s26 offen lds
	s_add_i32 s49, s26, 0x80000
	s_mov_b32 m0, s16
	ds_read_b128 v[194:197], v141 offset:17408
	buffer_load_dwordx4 v139, s[44:47], s26 offen lds
	s_mov_b32 m0, s18
	ds_read_b128 v[198:201], v141 offset:18432
	buffer_load_dwordx4 v137, s[44:47], s49 offen lds
	s_mov_b32 m0, s19
	ds_read_b128 v[202:205], v141 offset:19456
	buffer_load_dwordx4 v139, s[44:47], s49 offen lds
	s_mov_b32 m0, s14
	ds_read_b128 v[228:231], v141 offset:20480
	buffer_load_dwordx4 v136, s[60:63], s27 offen lds
	s_mov_b32 m0, s24
	ds_read_b128 v[232:235], v141 offset:21504
	buffer_load_dwordx4 v138, s[60:63], s27 offen lds
	ds_read_b128 v[236:239], v141 offset:22528
	ds_read_b128 v[240:243], v141 offset:23552
	s_waitcnt vmcnt(8)
	s_waitcnt lgkmcnt(0)
	s_setprio 1
	s_barrier
	v_mfma_f32_16x16x32_bf16 v[62:65], v[132:135], v[190:193], v[62:65]
	v_mfma_f32_16x16x32_bf16 v[62:65], v[142:145], v[194:197], v[62:65]
	v_mfma_f32_16x16x32_bf16 v[46:49], v[132:135], v[198:201], v[46:49]
	v_mfma_f32_16x16x32_bf16 v[46:49], v[142:145], v[202:205], v[46:49]
	v_mfma_f32_16x16x32_bf16 v[30:33], v[132:135], v[228:231], v[30:33]
	v_mfma_f32_16x16x32_bf16 v[30:33], v[142:145], v[232:235], v[30:33]
	v_mfma_f32_16x16x32_bf16 v[14:17], v[132:135], v[236:239], v[14:17]
	v_mfma_f32_16x16x32_bf16 v[14:17], v[142:145], v[240:243], v[14:17]
	v_mfma_f32_16x16x32_bf16 v[10:13], v[154:157], v[236:239], v[10:13]
	v_mfma_f32_16x16x32_bf16 v[10:13], v[170:173], v[240:243], v[10:13]
	v_mfma_f32_16x16x32_bf16 v[26:29], v[154:157], v[228:231], v[26:29]
	v_mfma_f32_16x16x32_bf16 v[26:29], v[170:173], v[232:235], v[26:29]
	v_mfma_f32_16x16x32_bf16 v[42:45], v[154:157], v[198:201], v[42:45]
	v_mfma_f32_16x16x32_bf16 v[42:45], v[170:173], v[202:205], v[42:45]
	v_mfma_f32_16x16x32_bf16 v[58:61], v[154:157], v[190:193], v[58:61]
	v_mfma_f32_16x16x32_bf16 v[58:61], v[170:173], v[194:197], v[58:61]
	v_mfma_f32_16x16x32_bf16 v[50:53], v[182:185], v[190:193], v[50:53]
	v_mfma_f32_16x16x32_bf16 v[50:53], v[186:189], v[194:197], v[50:53]
	v_mfma_f32_16x16x32_bf16 v[34:37], v[182:185], v[198:201], v[34:37]
	v_mfma_f32_16x16x32_bf16 v[34:37], v[186:189], v[202:205], v[34:37]
	v_mfma_f32_16x16x32_bf16 v[18:21], v[182:185], v[228:231], v[18:21]
	v_mfma_f32_16x16x32_bf16 v[18:21], v[186:189], v[232:235], v[18:21]
	v_mfma_f32_16x16x32_bf16 v[2:5], v[182:185], v[236:239], v[2:5]
	v_mfma_f32_16x16x32_bf16 v[2:5], v[186:189], v[240:243], v[2:5]
	v_mfma_f32_16x16x32_bf16 v[6:9], v[174:177], v[236:239], v[6:9]
	v_mfma_f32_16x16x32_bf16 v[6:9], v[178:181], v[240:243], v[6:9]
	v_mfma_f32_16x16x32_bf16 v[22:25], v[174:177], v[228:231], v[22:25]
	v_mfma_f32_16x16x32_bf16 v[22:25], v[178:181], v[232:235], v[22:25]
	v_mfma_f32_16x16x32_bf16 v[38:41], v[174:177], v[198:201], v[38:41]
	v_mfma_f32_16x16x32_bf16 v[38:41], v[178:181], v[202:205], v[38:41]
	v_mfma_f32_16x16x32_bf16 v[54:57], v[174:177], v[190:193], v[54:57]
	v_mfma_f32_16x16x32_bf16 v[54:57], v[178:181], v[194:197], v[54:57]
	s_barrier
	s_setprio 0
	v_add_u32_e32 v170, 0x18000, v140
	v_add_u32_e32 v186, 0x1c000, v140
	ds_read_b128 v[132:135], v170
	ds_read_b128 v[142:145], v170 offset:1024
	ds_read_b128 v[154:157], v170 offset:2048
	ds_read_b128 v[170:173], v170 offset:3072
	ds_read_b128 v[174:177], v186
	ds_read_b128 v[178:181], v186 offset:1024
	ds_read_b128 v[182:185], v186 offset:2048
	ds_read_b128 v[186:189], v186 offset:3072
	s_add_i32 s27, s27, 0x80000
	s_mov_b32 m0, s25
	ds_read_b128 v[190:193], v141 offset:32768
	ds_read_b128 v[194:197], v141 offset:33792
	ds_read_b128 v[198:201], v141 offset:34816
	ds_read_b128 v[202:205], v141 offset:35840
	ds_read_b128 v[228:231], v141 offset:36864
	ds_read_b128 v[232:235], v141 offset:37888
	ds_read_b128 v[236:239], v141 offset:38912
	ds_read_b128 v[240:243], v141 offset:39936
	buffer_load_dwordx4 v136, s[60:63], s27 offen lds
	s_mov_b32 m0, s30
	s_nop 0
	buffer_load_dwordx4 v138, s[60:63], s27 offen lds
	s_waitcnt vmcnt(8)
	s_waitcnt lgkmcnt(0)
	s_setprio 1
	s_barrier
	v_mfma_f32_16x16x32_bf16 v[126:129], v[132:135], v[190:193], v[126:129]
	v_mfma_f32_16x16x32_bf16 v[126:129], v[142:145], v[194:197], v[126:129]
	v_mfma_f32_16x16x32_bf16 v[118:121], v[132:135], v[198:201], v[118:121]
	v_mfma_f32_16x16x32_bf16 v[118:121], v[142:145], v[202:205], v[118:121]
	v_mfma_f32_16x16x32_bf16 v[94:97], v[132:135], v[228:231], v[94:97]
	v_mfma_f32_16x16x32_bf16 v[94:97], v[142:145], v[232:235], v[94:97]
	v_mfma_f32_16x16x32_bf16 v[78:81], v[132:135], v[236:239], v[78:81]
	v_mfma_f32_16x16x32_bf16 v[78:81], v[142:145], v[240:243], v[78:81]
	v_mfma_f32_16x16x32_bf16 v[74:77], v[154:157], v[236:239], v[74:77]
	v_mfma_f32_16x16x32_bf16 v[74:77], v[170:173], v[240:243], v[74:77]
	v_mfma_f32_16x16x32_bf16 v[90:93], v[154:157], v[228:231], v[90:93]
	v_mfma_f32_16x16x32_bf16 v[90:93], v[170:173], v[232:235], v[90:93]
	v_mfma_f32_16x16x32_bf16 v[114:117], v[154:157], v[198:201], v[114:117]
	v_mfma_f32_16x16x32_bf16 v[114:117], v[170:173], v[202:205], v[114:117]
	v_mfma_f32_16x16x32_bf16 v[106:109], v[154:157], v[190:193], v[106:109]
	v_mfma_f32_16x16x32_bf16 v[106:109], v[170:173], v[194:197], v[106:109]
	v_mfma_f32_16x16x32_bf16 v[110:113], v[182:185], v[190:193], v[110:113]
	v_mfma_f32_16x16x32_bf16 v[110:113], v[186:189], v[194:197], v[110:113]
	v_mfma_f32_16x16x32_bf16 v[98:101], v[182:185], v[198:201], v[98:101]
	v_mfma_f32_16x16x32_bf16 v[98:101], v[186:189], v[202:205], v[98:101]
	v_mfma_f32_16x16x32_bf16 v[82:85], v[182:185], v[228:231], v[82:85]
	v_mfma_f32_16x16x32_bf16 v[82:85], v[186:189], v[232:235], v[82:85]
	v_mfma_f32_16x16x32_bf16 v[66:69], v[182:185], v[236:239], v[66:69]
	v_mfma_f32_16x16x32_bf16 v[66:69], v[186:189], v[240:243], v[66:69]
	v_mfma_f32_16x16x32_bf16 v[70:73], v[174:177], v[236:239], v[70:73]
	v_mfma_f32_16x16x32_bf16 v[70:73], v[178:181], v[240:243], v[70:73]
	v_mfma_f32_16x16x32_bf16 v[86:89], v[174:177], v[228:231], v[86:89]
	v_mfma_f32_16x16x32_bf16 v[86:89], v[178:181], v[232:235], v[86:89]
	v_mfma_f32_16x16x32_bf16 v[102:105], v[174:177], v[198:201], v[102:105]
	v_mfma_f32_16x16x32_bf16 v[102:105], v[178:181], v[202:205], v[102:105]
	v_mfma_f32_16x16x32_bf16 v[122:125], v[174:177], v[190:193], v[122:125]
	v_mfma_f32_16x16x32_bf16 v[122:125], v[178:181], v[194:197], v[122:125]
	s_barrier
	s_setprio 0
	s_or_b32 s27, s26, 0x80
	s_mov_b32 m0, s36
	ds_read_b128 v[190:193], v141 offset:49152
	buffer_load_dwordx4 v137, s[44:47], s27 offen lds
	s_add_i32 s26, s26, 0x80080
	s_mov_b32 m0, s37
	ds_read_b128 v[194:197], v141 offset:50176
	buffer_load_dwordx4 v139, s[44:47], s27 offen lds
	s_mov_b32 m0, s68
	ds_read_b128 v[198:201], v141 offset:51200
	buffer_load_dwordx4 v137, s[44:47], s26 offen lds
	s_mov_b32 m0, s69
	ds_read_b128 v[202:205], v141 offset:52224
	buffer_load_dwordx4 v139, s[44:47], s26 offen lds
	s_mov_b32 m0, s66
	ds_read_b128 v[228:231], v141 offset:53248
	buffer_load_dwordx4 v136, s[60:63], s23 offen lds
	s_mov_b32 m0, s67
	ds_read_b128 v[232:235], v141 offset:54272
	buffer_load_dwordx4 v138, s[60:63], s23 offen lds
	ds_read_b128 v[236:239], v141 offset:55296
	ds_read_b128 v[240:243], v141 offset:56320
	s_waitcnt vmcnt(8)
	s_waitcnt lgkmcnt(0)
	s_setprio 1
	s_barrier
	v_mfma_f32_16x16x32_bf16 v[62:65], v[132:135], v[190:193], v[62:65]
	v_mfma_f32_16x16x32_bf16 v[62:65], v[142:145], v[194:197], v[62:65]
	v_mfma_f32_16x16x32_bf16 v[46:49], v[132:135], v[198:201], v[46:49]
	v_mfma_f32_16x16x32_bf16 v[46:49], v[142:145], v[202:205], v[46:49]
	v_mfma_f32_16x16x32_bf16 v[30:33], v[132:135], v[228:231], v[30:33]
	v_mfma_f32_16x16x32_bf16 v[30:33], v[142:145], v[232:235], v[30:33]
	v_mfma_f32_16x16x32_bf16 v[14:17], v[132:135], v[236:239], v[14:17]
	v_mfma_f32_16x16x32_bf16 v[14:17], v[142:145], v[240:243], v[14:17]
	v_mfma_f32_16x16x32_bf16 v[10:13], v[154:157], v[236:239], v[10:13]
	v_mfma_f32_16x16x32_bf16 v[10:13], v[170:173], v[240:243], v[10:13]
	v_mfma_f32_16x16x32_bf16 v[26:29], v[154:157], v[228:231], v[26:29]
	v_mfma_f32_16x16x32_bf16 v[26:29], v[170:173], v[232:235], v[26:29]
	v_mfma_f32_16x16x32_bf16 v[42:45], v[154:157], v[198:201], v[42:45]
	v_mfma_f32_16x16x32_bf16 v[42:45], v[170:173], v[202:205], v[42:45]
	v_mfma_f32_16x16x32_bf16 v[58:61], v[154:157], v[190:193], v[58:61]
	v_mfma_f32_16x16x32_bf16 v[58:61], v[170:173], v[194:197], v[58:61]
	v_mfma_f32_16x16x32_bf16 v[50:53], v[182:185], v[190:193], v[50:53]
	v_mfma_f32_16x16x32_bf16 v[50:53], v[186:189], v[194:197], v[50:53]
	v_mfma_f32_16x16x32_bf16 v[34:37], v[182:185], v[198:201], v[34:37]
	v_mfma_f32_16x16x32_bf16 v[34:37], v[186:189], v[202:205], v[34:37]
	v_mfma_f32_16x16x32_bf16 v[18:21], v[182:185], v[228:231], v[18:21]
	v_mfma_f32_16x16x32_bf16 v[18:21], v[186:189], v[232:235], v[18:21]
	v_mfma_f32_16x16x32_bf16 v[2:5], v[182:185], v[236:239], v[2:5]
	v_mfma_f32_16x16x32_bf16 v[2:5], v[186:189], v[240:243], v[2:5]
	v_mfma_f32_16x16x32_bf16 v[6:9], v[174:177], v[236:239], v[6:9]
	v_mfma_f32_16x16x32_bf16 v[6:9], v[178:181], v[240:243], v[6:9]
	v_mfma_f32_16x16x32_bf16 v[22:25], v[174:177], v[228:231], v[22:25]
	v_mfma_f32_16x16x32_bf16 v[22:25], v[178:181], v[232:235], v[22:25]
	v_mfma_f32_16x16x32_bf16 v[38:41], v[174:177], v[198:201], v[38:41]
	v_mfma_f32_16x16x32_bf16 v[38:41], v[178:181], v[202:205], v[38:41]
	v_mfma_f32_16x16x32_bf16 v[54:57], v[174:177], v[190:193], v[54:57]
	v_mfma_f32_16x16x32_bf16 v[54:57], v[178:181], v[194:197], v[54:57]
	s_barrier
	s_setprio 0
	s_add_i32 s22, s22, 2
	s_addk_i32 s13, 0x100
	s_addk_i32 s21, 0x100
	s_cmp_gt_u32 s22, 29
	s_cbranch_scc0 .LBB0_1589
	s_and_b64 vcc, exec, s[64:65]
	s_cbranch_vccz .LBB0_1592
	s_barrier

.LBB0_1879:
	s_lshl_b32 s18, s91, 20
	s_and_b64 s[8:9], s[48:49], exec
	s_cselect_b32 s8, s18, s95
	s_lshl_b32 s19, s92, 20
	s_and_b64 s[42:43], s[48:49], exec
	s_cselect_b32 s9, s19, s94
	s_add_i32 vcc_lo, s95, 0x80080
	s_add_i32 vcc_hi, s94, 0x100
	s_mov_b32 s94, -2
	v_add_u32_e32 v139, 0x10000, v136
	ds_read_b128 v[140:143], v139
	ds_read_b128 v[154:157], v139 offset:1024
	ds_read_b128 v[170:173], v139 offset:2048
	ds_read_b128 v[174:177], v139 offset:3072
	v_add_u32_e32 v139, 0x14000, v136
	ds_read_b128 v[178:181], v139
	ds_read_b128 v[182:185], v139 offset:1024
	ds_read_b128 v[186:189], v139 offset:2048
	ds_read_b128 v[190:193], v139 offset:3072
	s_add_i32 s42, vcc_lo, 0xfff80080
	s_cmp_eq_u32 s94, 28
	s_cselect_b32 s52, s8, s42
	s_cselect_b32 s96, s9, vcc_hi
	s_or_b32 s95, s52, 0x80
	s_mov_b32 m0, s72
	ds_read_b128 v[194:197], v137
	ds_read_b128 v[198:201], v137 offset:1024
	ds_read_b128 v[202:205], v137 offset:2048
	ds_read_b128 v[228:231], v137 offset:3072
	ds_read_b128 v[232:235], v137 offset:4096
	ds_read_b128 v[236:239], v137 offset:5120
	ds_read_b128 v[240:243], v137 offset:6144
	ds_read_b128 v[244:247], v137 offset:7168
	buffer_load_dwordx4 v132, s[60:63], vcc_lo offen lds
	s_mov_b32 m0, s47
	s_nop 0
	buffer_load_dwordx4 v134, s[60:63], vcc_lo offen lds
	s_waitcnt vmcnt(8)
	s_waitcnt lgkmcnt(0)
	s_setprio 1
	s_barrier
	v_mfma_f32_16x16x32_bf16 v[114:117], v[140:143], v[194:197], 0
	v_mfma_f32_16x16x32_bf16 v[114:117], v[154:157], v[198:201], v[114:117]
	v_mfma_f32_16x16x32_bf16 v[106:109], v[140:143], v[202:205], 0
	v_mfma_f32_16x16x32_bf16 v[106:109], v[154:157], v[228:231], v[106:109]
	v_mfma_f32_16x16x32_bf16 v[94:97], v[140:143], v[232:235], 0
	v_mfma_f32_16x16x32_bf16 v[94:97], v[154:157], v[236:239], v[94:97]
	v_mfma_f32_16x16x32_bf16 v[78:81], v[140:143], v[240:243], 0
	v_mfma_f32_16x16x32_bf16 v[78:81], v[154:157], v[244:247], v[78:81]
	v_mfma_f32_16x16x32_bf16 v[70:73], v[170:173], v[240:243], 0
	v_mfma_f32_16x16x32_bf16 v[70:73], v[174:177], v[244:247], v[70:73]
	v_mfma_f32_16x16x32_bf16 v[86:89], v[170:173], v[232:235], 0
	v_mfma_f32_16x16x32_bf16 v[86:89], v[174:177], v[236:239], v[86:89]
	v_mfma_f32_16x16x32_bf16 v[102:105], v[170:173], v[202:205], 0
	v_mfma_f32_16x16x32_bf16 v[102:105], v[174:177], v[228:231], v[102:105]
	v_mfma_f32_16x16x32_bf16 v[110:113], v[170:173], v[194:197], 0
	v_mfma_f32_16x16x32_bf16 v[110:113], v[174:177], v[198:201], v[110:113]
	v_mfma_f32_16x16x32_bf16 v[122:125], v[186:189], v[194:197], 0
	v_mfma_f32_16x16x32_bf16 v[122:125], v[190:193], v[198:201], v[122:125]
	v_mfma_f32_16x16x32_bf16 v[98:101], v[186:189], v[202:205], 0
	v_mfma_f32_16x16x32_bf16 v[98:101], v[190:193], v[228:231], v[98:101]
	v_mfma_f32_16x16x32_bf16 v[82:85], v[186:189], v[232:235], 0
	v_mfma_f32_16x16x32_bf16 v[82:85], v[190:193], v[236:239], v[82:85]
	v_mfma_f32_16x16x32_bf16 v[66:69], v[186:189], v[240:243], 0
	v_mfma_f32_16x16x32_bf16 v[66:69], v[190:193], v[244:247], v[66:69]
	v_mfma_f32_16x16x32_bf16 v[74:77], v[178:181], v[240:243], 0
	v_mfma_f32_16x16x32_bf16 v[74:77], v[182:185], v[244:247], v[74:77]
	v_mfma_f32_16x16x32_bf16 v[90:93], v[178:181], v[232:235], 0
	v_mfma_f32_16x16x32_bf16 v[90:93], v[182:185], v[236:239], v[90:93]
	v_mfma_f32_16x16x32_bf16 v[118:121], v[178:181], v[202:205], 0
	v_mfma_f32_16x16x32_bf16 v[118:121], v[182:185], v[228:231], v[118:121]
	v_mfma_f32_16x16x32_bf16 v[126:129], v[178:181], v[194:197], 0
	v_mfma_f32_16x16x32_bf16 v[126:129], v[182:185], v[198:201], v[126:129]
	s_barrier
	s_setprio 0
	s_mov_b32 s42, s62
	s_mov_b32 s43, s63
	s_mov_b32 m0, s13
	ds_read_b128 v[194:197], v137 offset:16384
	buffer_load_dwordx4 v133, s[40:43], s96 offen lds
	s_add_i32 s53, s96, 0x80000
	s_mov_b32 m0, s14
	ds_read_b128 v[198:201], v137 offset:17408
	buffer_load_dwordx4 v135, s[40:43], s96 offen lds
	s_mov_b32 m0, s15
	ds_read_b128 v[202:205], v137 offset:18432
	buffer_load_dwordx4 v133, s[40:43], s53 offen lds
	s_mov_b32 m0, s16
	ds_read_b128 v[228:231], v137 offset:19456
	buffer_load_dwordx4 v135, s[40:43], s53 offen lds
	s_mov_b32 m0, s2
	ds_read_b128 v[232:235], v137 offset:20480
	buffer_load_dwordx4 v132, s[60:63], s52 offen lds
	s_mov_b32 m0, s21
	ds_read_b128 v[236:239], v137 offset:21504
	buffer_load_dwordx4 v134, s[60:63], s52 offen lds
	ds_read_b128 v[240:243], v137 offset:22528
	ds_read_b128 v[244:247], v137 offset:23552
	s_waitcnt vmcnt(8)
	s_waitcnt lgkmcnt(0)
	s_setprio 1
	s_barrier
	v_mfma_f32_16x16x32_bf16 v[62:65], v[140:143], v[194:197], 0
	v_mfma_f32_16x16x32_bf16 v[62:65], v[154:157], v[198:201], v[62:65]
	v_mfma_f32_16x16x32_bf16 v[46:49], v[140:143], v[202:205], 0
	v_mfma_f32_16x16x32_bf16 v[46:49], v[154:157], v[228:231], v[46:49]
	v_mfma_f32_16x16x32_bf16 v[30:33], v[140:143], v[232:235], 0
	v_mfma_f32_16x16x32_bf16 v[30:33], v[154:157], v[236:239], v[30:33]
	v_mfma_f32_16x16x32_bf16 v[14:17], v[140:143], v[240:243], 0
	v_mfma_f32_16x16x32_bf16 v[14:17], v[154:157], v[244:247], v[14:17]
	v_mfma_f32_16x16x32_bf16 v[6:9], v[170:173], v[240:243], 0
	v_mfma_f32_16x16x32_bf16 v[6:9], v[174:177], v[244:247], v[6:9]
	v_mfma_f32_16x16x32_bf16 v[22:25], v[170:173], v[232:235], 0
	v_mfma_f32_16x16x32_bf16 v[22:25], v[174:177], v[236:239], v[22:25]
	v_mfma_f32_16x16x32_bf16 v[38:41], v[170:173], v[202:205], 0
	v_mfma_f32_16x16x32_bf16 v[38:41], v[174:177], v[228:231], v[38:41]
	v_mfma_f32_16x16x32_bf16 v[54:57], v[170:173], v[194:197], 0
	v_mfma_f32_16x16x32_bf16 v[54:57], v[174:177], v[198:201], v[54:57]
	v_mfma_f32_16x16x32_bf16 v[50:53], v[186:189], v[194:197], 0
	v_mfma_f32_16x16x32_bf16 v[50:53], v[190:193], v[198:201], v[50:53]
	v_mfma_f32_16x16x32_bf16 v[34:37], v[186:189], v[202:205], 0
	v_mfma_f32_16x16x32_bf16 v[34:37], v[190:193], v[228:231], v[34:37]
	v_mfma_f32_16x16x32_bf16 v[18:21], v[186:189], v[232:235], 0
	v_mfma_f32_16x16x32_bf16 v[18:21], v[190:193], v[236:239], v[18:21]
	v_mfma_f32_16x16x32_bf16 v[2:5], v[186:189], v[240:243], 0
	v_mfma_f32_16x16x32_bf16 v[2:5], v[190:193], v[244:247], v[2:5]
	v_mfma_f32_16x16x32_bf16 v[10:13], v[178:181], v[240:243], 0
	v_mfma_f32_16x16x32_bf16 v[10:13], v[182:185], v[244:247], v[10:13]
	v_mfma_f32_16x16x32_bf16 v[26:29], v[178:181], v[232:235], 0
	v_mfma_f32_16x16x32_bf16 v[26:29], v[182:185], v[236:239], v[26:29]
	v_mfma_f32_16x16x32_bf16 v[42:45], v[178:181], v[202:205], 0
	v_mfma_f32_16x16x32_bf16 v[42:45], v[182:185], v[228:231], v[42:45]
	v_mfma_f32_16x16x32_bf16 v[58:61], v[178:181], v[194:197], 0
	v_mfma_f32_16x16x32_bf16 v[58:61], v[182:185], v[198:201], v[58:61]
	s_barrier
	s_setprio 0
	v_add_u32_e32 v139, 0x18000, v136
	ds_read_b128 v[140:143], v139
	ds_read_b128 v[154:157], v139 offset:1024
	ds_read_b128 v[170:173], v139 offset:2048
	ds_read_b128 v[174:177], v139 offset:3072
	v_add_u32_e32 v139, 0x1c000, v136
	ds_read_b128 v[178:181], v139
	ds_read_b128 v[182:185], v139 offset:1024
	ds_read_b128 v[186:189], v139 offset:2048
	ds_read_b128 v[190:193], v139 offset:3072
	s_add_i32 s52, s52, 0x80000
	s_mov_b32 m0, s23
	ds_read_b128 v[194:197], v137 offset:32768
	ds_read_b128 v[198:201], v137 offset:33792
	ds_read_b128 v[202:205], v137 offset:34816
	ds_read_b128 v[228:231], v137 offset:35840
	ds_read_b128 v[232:235], v137 offset:36864
	ds_read_b128 v[236:239], v137 offset:37888
	ds_read_b128 v[240:243], v137 offset:38912
	ds_read_b128 v[244:247], v137 offset:39936
	buffer_load_dwordx4 v132, s[60:63], s52 offen lds
	s_mov_b32 m0, s24
	s_nop 0
	buffer_load_dwordx4 v134, s[60:63], s52 offen lds
	s_waitcnt vmcnt(8)
	s_waitcnt lgkmcnt(0)
	s_setprio 1
	s_barrier
	v_mfma_f32_16x16x32_bf16 v[114:117], v[140:143], v[194:197], v[114:117]
	v_mfma_f32_16x16x32_bf16 v[114:117], v[154:157], v[198:201], v[114:117]
	v_mfma_f32_16x16x32_bf16 v[106:109], v[140:143], v[202:205], v[106:109]
	v_mfma_f32_16x16x32_bf16 v[106:109], v[154:157], v[228:231], v[106:109]
	v_mfma_f32_16x16x32_bf16 v[94:97], v[140:143], v[232:235], v[94:97]
	v_mfma_f32_16x16x32_bf16 v[94:97], v[154:157], v[236:239], v[94:97]
	v_mfma_f32_16x16x32_bf16 v[78:81], v[140:143], v[240:243], v[78:81]
	v_mfma_f32_16x16x32_bf16 v[78:81], v[154:157], v[244:247], v[78:81]
	v_mfma_f32_16x16x32_bf16 v[70:73], v[170:173], v[240:243], v[70:73]
	v_mfma_f32_16x16x32_bf16 v[70:73], v[174:177], v[244:247], v[70:73]
	v_mfma_f32_16x16x32_bf16 v[86:89], v[170:173], v[232:235], v[86:89]
	v_mfma_f32_16x16x32_bf16 v[86:89], v[174:177], v[236:239], v[86:89]
	v_mfma_f32_16x16x32_bf16 v[102:105], v[170:173], v[202:205], v[102:105]
	v_mfma_f32_16x16x32_bf16 v[102:105], v[174:177], v[228:231], v[102:105]
	v_mfma_f32_16x16x32_bf16 v[110:113], v[170:173], v[194:197], v[110:113]
	v_mfma_f32_16x16x32_bf16 v[110:113], v[174:177], v[198:201], v[110:113]
	v_mfma_f32_16x16x32_bf16 v[122:125], v[186:189], v[194:197], v[122:125]
	v_mfma_f32_16x16x32_bf16 v[122:125], v[190:193], v[198:201], v[122:125]
	v_mfma_f32_16x16x32_bf16 v[98:101], v[186:189], v[202:205], v[98:101]
	v_mfma_f32_16x16x32_bf16 v[98:101], v[190:193], v[228:231], v[98:101]
	v_mfma_f32_16x16x32_bf16 v[82:85], v[186:189], v[232:235], v[82:85]
	v_mfma_f32_16x16x32_bf16 v[82:85], v[190:193], v[236:239], v[82:85]
	v_mfma_f32_16x16x32_bf16 v[66:69], v[186:189], v[240:243], v[66:69]
	v_mfma_f32_16x16x32_bf16 v[66:69], v[190:193], v[244:247], v[66:69]
	v_mfma_f32_16x16x32_bf16 v[74:77], v[178:181], v[240:243], v[74:77]
	v_mfma_f32_16x16x32_bf16 v[74:77], v[182:185], v[244:247], v[74:77]
	v_mfma_f32_16x16x32_bf16 v[90:93], v[178:181], v[232:235], v[90:93]
	v_mfma_f32_16x16x32_bf16 v[90:93], v[182:185], v[236:239], v[90:93]
	v_mfma_f32_16x16x32_bf16 v[118:121], v[178:181], v[202:205], v[118:121]
	v_mfma_f32_16x16x32_bf16 v[118:121], v[182:185], v[228:231], v[118:121]
	v_mfma_f32_16x16x32_bf16 v[126:129], v[178:181], v[194:197], v[126:129]
	v_mfma_f32_16x16x32_bf16 v[126:129], v[182:185], v[198:201], v[126:129]
	s_barrier
	s_setprio 0
	s_or_b32 s52, s96, 0x80
	s_mov_b32 m0, s31
	ds_read_b128 v[194:197], v137 offset:49152
	buffer_load_dwordx4 v133, s[40:43], s52 offen lds
	s_add_i32 s96, s96, 0x80080
	s_mov_b32 m0, s33
	ds_read_b128 v[198:201], v137 offset:50176
	buffer_load_dwordx4 v135, s[40:43], s52 offen lds
	s_mov_b32 m0, s36
	ds_read_b128 v[202:205], v137 offset:51200
	buffer_load_dwordx4 v133, s[40:43], s96 offen lds
	s_mov_b32 m0, s37
	ds_read_b128 v[228:231], v137 offset:52224
	buffer_load_dwordx4 v135, s[40:43], s96 offen lds
	s_mov_b32 m0, s34
	ds_read_b128 v[232:235], v137 offset:53248
	buffer_load_dwordx4 v132, s[60:63], s95 offen lds
	s_mov_b32 m0, s35
	ds_read_b128 v[236:239], v137 offset:54272
	buffer_load_dwordx4 v134, s[60:63], s95 offen lds
	ds_read_b128 v[240:243], v137 offset:55296
	ds_read_b128 v[244:247], v137 offset:56320
	s_waitcnt vmcnt(8)
	s_waitcnt lgkmcnt(0)
	s_setprio 1
	s_barrier
	v_mfma_f32_16x16x32_bf16 v[62:65], v[140:143], v[194:197], v[62:65]
	v_mfma_f32_16x16x32_bf16 v[62:65], v[154:157], v[198:201], v[62:65]
	v_mfma_f32_16x16x32_bf16 v[46:49], v[140:143], v[202:205], v[46:49]
	v_mfma_f32_16x16x32_bf16 v[46:49], v[154:157], v[228:231], v[46:49]
	v_mfma_f32_16x16x32_bf16 v[30:33], v[140:143], v[232:235], v[30:33]
	v_mfma_f32_16x16x32_bf16 v[30:33], v[154:157], v[236:239], v[30:33]
	v_mfma_f32_16x16x32_bf16 v[14:17], v[140:143], v[240:243], v[14:17]
	v_mfma_f32_16x16x32_bf16 v[14:17], v[154:157], v[244:247], v[14:17]
	v_mfma_f32_16x16x32_bf16 v[6:9], v[170:173], v[240:243], v[6:9]
	v_mfma_f32_16x16x32_bf16 v[6:9], v[174:177], v[244:247], v[6:9]
	v_mfma_f32_16x16x32_bf16 v[22:25], v[170:173], v[232:235], v[22:25]
	v_mfma_f32_16x16x32_bf16 v[22:25], v[174:177], v[236:239], v[22:25]
	v_mfma_f32_16x16x32_bf16 v[38:41], v[170:173], v[202:205], v[38:41]
	v_mfma_f32_16x16x32_bf16 v[38:41], v[174:177], v[228:231], v[38:41]
	v_mfma_f32_16x16x32_bf16 v[54:57], v[170:173], v[194:197], v[54:57]
	v_mfma_f32_16x16x32_bf16 v[54:57], v[174:177], v[198:201], v[54:57]
	v_mfma_f32_16x16x32_bf16 v[50:53], v[186:189], v[194:197], v[50:53]
	v_mfma_f32_16x16x32_bf16 v[50:53], v[190:193], v[198:201], v[50:53]
	v_mfma_f32_16x16x32_bf16 v[34:37], v[186:189], v[202:205], v[34:37]
	v_mfma_f32_16x16x32_bf16 v[34:37], v[190:193], v[228:231], v[34:37]
	v_mfma_f32_16x16x32_bf16 v[18:21], v[186:189], v[232:235], v[18:21]
	v_mfma_f32_16x16x32_bf16 v[18:21], v[190:193], v[236:239], v[18:21]
	v_mfma_f32_16x16x32_bf16 v[2:5], v[186:189], v[240:243], v[2:5]
	v_mfma_f32_16x16x32_bf16 v[2:5], v[190:193], v[244:247], v[2:5]
	v_mfma_f32_16x16x32_bf16 v[10:13], v[178:181], v[240:243], v[10:13]
	v_mfma_f32_16x16x32_bf16 v[10:13], v[182:185], v[244:247], v[10:13]
	v_mfma_f32_16x16x32_bf16 v[26:29], v[178:181], v[232:235], v[26:29]
	v_mfma_f32_16x16x32_bf16 v[26:29], v[182:185], v[236:239], v[26:29]
	v_mfma_f32_16x16x32_bf16 v[42:45], v[178:181], v[202:205], v[42:45]
	v_mfma_f32_16x16x32_bf16 v[42:45], v[182:185], v[228:231], v[42:45]
	v_mfma_f32_16x16x32_bf16 v[58:61], v[178:181], v[194:197], v[58:61]
	v_mfma_f32_16x16x32_bf16 v[58:61], v[182:185], v[198:201], v[58:61]
	s_barrier
	s_setprio 0
	s_add_i32 s94, s94, 2
	s_addk_i32 vcc_lo, 0x100
	s_addk_i32 vcc_hi, 0x100
	s_cmp_gt_u32 s94, 29
.LBB0_1880:
	v_add_u32_e32 v139, 0x10000, v136
	ds_read_b128 v[140:143], v139
	ds_read_b128 v[154:157], v139 offset:1024
	ds_read_b128 v[170:173], v139 offset:2048
	ds_read_b128 v[174:177], v139 offset:3072
	v_add_u32_e32 v139, 0x14000, v136
	ds_read_b128 v[178:181], v139
	ds_read_b128 v[182:185], v139 offset:1024
	ds_read_b128 v[186:189], v139 offset:2048
	ds_read_b128 v[190:193], v139 offset:3072
	s_add_i32 s42, vcc_lo, 0xfff80080
	s_cmp_eq_u32 s94, 28
	s_cselect_b32 s52, s8, s42
	s_cselect_b32 s96, s9, vcc_hi
	s_or_b32 s95, s52, 0x80
	s_mov_b32 m0, s72
	ds_read_b128 v[194:197], v137
	ds_read_b128 v[198:201], v137 offset:1024
	ds_read_b128 v[202:205], v137 offset:2048
	ds_read_b128 v[228:231], v137 offset:3072
	ds_read_b128 v[232:235], v137 offset:4096
	ds_read_b128 v[236:239], v137 offset:5120
	ds_read_b128 v[240:243], v137 offset:6144
	ds_read_b128 v[244:247], v137 offset:7168
	buffer_load_dwordx4 v132, s[60:63], vcc_lo offen lds
	s_mov_b32 m0, s47
	s_nop 0
	buffer_load_dwordx4 v134, s[60:63], vcc_lo offen lds
	s_waitcnt vmcnt(8)
	s_waitcnt lgkmcnt(0)
	s_setprio 1
	s_barrier
	v_mfma_f32_16x16x32_bf16 v[114:117], v[140:143], v[194:197], v[114:117]
	v_mfma_f32_16x16x32_bf16 v[114:117], v[154:157], v[198:201], v[114:117]
	v_mfma_f32_16x16x32_bf16 v[106:109], v[140:143], v[202:205], v[106:109]
	v_mfma_f32_16x16x32_bf16 v[106:109], v[154:157], v[228:231], v[106:109]
	v_mfma_f32_16x16x32_bf16 v[94:97], v[140:143], v[232:235], v[94:97]
	v_mfma_f32_16x16x32_bf16 v[94:97], v[154:157], v[236:239], v[94:97]
	v_mfma_f32_16x16x32_bf16 v[78:81], v[140:143], v[240:243], v[78:81]
	v_mfma_f32_16x16x32_bf16 v[78:81], v[154:157], v[244:247], v[78:81]
	v_mfma_f32_16x16x32_bf16 v[70:73], v[170:173], v[240:243], v[70:73]
	v_mfma_f32_16x16x32_bf16 v[70:73], v[174:177], v[244:247], v[70:73]
	v_mfma_f32_16x16x32_bf16 v[86:89], v[170:173], v[232:235], v[86:89]
	v_mfma_f32_16x16x32_bf16 v[86:89], v[174:177], v[236:239], v[86:89]
	v_mfma_f32_16x16x32_bf16 v[102:105], v[170:173], v[202:205], v[102:105]
	v_mfma_f32_16x16x32_bf16 v[102:105], v[174:177], v[228:231], v[102:105]
	v_mfma_f32_16x16x32_bf16 v[110:113], v[170:173], v[194:197], v[110:113]
	v_mfma_f32_16x16x32_bf16 v[110:113], v[174:177], v[198:201], v[110:113]
	v_mfma_f32_16x16x32_bf16 v[122:125], v[186:189], v[194:197], v[122:125]
	v_mfma_f32_16x16x32_bf16 v[122:125], v[190:193], v[198:201], v[122:125]
	v_mfma_f32_16x16x32_bf16 v[98:101], v[186:189], v[202:205], v[98:101]
	v_mfma_f32_16x16x32_bf16 v[98:101], v[190:193], v[228:231], v[98:101]
	v_mfma_f32_16x16x32_bf16 v[82:85], v[186:189], v[232:235], v[82:85]
	v_mfma_f32_16x16x32_bf16 v[82:85], v[190:193], v[236:239], v[82:85]
	v_mfma_f32_16x16x32_bf16 v[66:69], v[186:189], v[240:243], v[66:69]
	v_mfma_f32_16x16x32_bf16 v[66:69], v[190:193], v[244:247], v[66:69]
	v_mfma_f32_16x16x32_bf16 v[74:77], v[178:181], v[240:243], v[74:77]
	v_mfma_f32_16x16x32_bf16 v[74:77], v[182:185], v[244:247], v[74:77]
	v_mfma_f32_16x16x32_bf16 v[90:93], v[178:181], v[232:235], v[90:93]
	v_mfma_f32_16x16x32_bf16 v[90:93], v[182:185], v[236:239], v[90:93]
	v_mfma_f32_16x16x32_bf16 v[118:121], v[178:181], v[202:205], v[118:121]
	v_mfma_f32_16x16x32_bf16 v[118:121], v[182:185], v[228:231], v[118:121]
	v_mfma_f32_16x16x32_bf16 v[126:129], v[178:181], v[194:197], v[126:129]
	v_mfma_f32_16x16x32_bf16 v[126:129], v[182:185], v[198:201], v[126:129]
	s_barrier
	s_setprio 0
	s_mov_b32 s42, s62
	s_mov_b32 s43, s63
	s_mov_b32 m0, s13
	ds_read_b128 v[194:197], v137 offset:16384
	buffer_load_dwordx4 v133, s[40:43], s96 offen lds
	s_add_i32 s53, s96, 0x80000
	s_mov_b32 m0, s14
	ds_read_b128 v[198:201], v137 offset:17408
	buffer_load_dwordx4 v135, s[40:43], s96 offen lds
	s_mov_b32 m0, s15
	ds_read_b128 v[202:205], v137 offset:18432
	buffer_load_dwordx4 v133, s[40:43], s53 offen lds
	s_mov_b32 m0, s16
	ds_read_b128 v[228:231], v137 offset:19456
	buffer_load_dwordx4 v135, s[40:43], s53 offen lds
	s_mov_b32 m0, s2
	ds_read_b128 v[232:235], v137 offset:20480
	buffer_load_dwordx4 v132, s[60:63], s52 offen lds
	s_mov_b32 m0, s21
	ds_read_b128 v[236:239], v137 offset:21504
	buffer_load_dwordx4 v134, s[60:63], s52 offen lds
	ds_read_b128 v[240:243], v137 offset:22528
	ds_read_b128 v[244:247], v137 offset:23552
	s_waitcnt vmcnt(8)
	s_waitcnt lgkmcnt(0)
	s_setprio 1
	s_barrier
	v_mfma_f32_16x16x32_bf16 v[62:65], v[140:143], v[194:197], v[62:65]
	v_mfma_f32_16x16x32_bf16 v[62:65], v[154:157], v[198:201], v[62:65]
	v_mfma_f32_16x16x32_bf16 v[46:49], v[140:143], v[202:205], v[46:49]
	v_mfma_f32_16x16x32_bf16 v[46:49], v[154:157], v[228:231], v[46:49]
	v_mfma_f32_16x16x32_bf16 v[30:33], v[140:143], v[232:235], v[30:33]
	v_mfma_f32_16x16x32_bf16 v[30:33], v[154:157], v[236:239], v[30:33]
	v_mfma_f32_16x16x32_bf16 v[14:17], v[140:143], v[240:243], v[14:17]
	v_mfma_f32_16x16x32_bf16 v[14:17], v[154:157], v[244:247], v[14:17]
	v_mfma_f32_16x16x32_bf16 v[6:9], v[170:173], v[240:243], v[6:9]
	v_mfma_f32_16x16x32_bf16 v[6:9], v[174:177], v[244:247], v[6:9]
	v_mfma_f32_16x16x32_bf16 v[22:25], v[170:173], v[232:235], v[22:25]
	v_mfma_f32_16x16x32_bf16 v[22:25], v[174:177], v[236:239], v[22:25]
	v_mfma_f32_16x16x32_bf16 v[38:41], v[170:173], v[202:205], v[38:41]
	v_mfma_f32_16x16x32_bf16 v[38:41], v[174:177], v[228:231], v[38:41]
	v_mfma_f32_16x16x32_bf16 v[54:57], v[170:173], v[194:197], v[54:57]
	v_mfma_f32_16x16x32_bf16 v[54:57], v[174:177], v[198:201], v[54:57]
	v_mfma_f32_16x16x32_bf16 v[50:53], v[186:189], v[194:197], v[50:53]
	v_mfma_f32_16x16x32_bf16 v[50:53], v[190:193], v[198:201], v[50:53]
	v_mfma_f32_16x16x32_bf16 v[34:37], v[186:189], v[202:205], v[34:37]
	v_mfma_f32_16x16x32_bf16 v[34:37], v[190:193], v[228:231], v[34:37]
	v_mfma_f32_16x16x32_bf16 v[18:21], v[186:189], v[232:235], v[18:21]
	v_mfma_f32_16x16x32_bf16 v[18:21], v[190:193], v[236:239], v[18:21]
	v_mfma_f32_16x16x32_bf16 v[2:5], v[186:189], v[240:243], v[2:5]
	v_mfma_f32_16x16x32_bf16 v[2:5], v[190:193], v[244:247], v[2:5]
	v_mfma_f32_16x16x32_bf16 v[10:13], v[178:181], v[240:243], v[10:13]
	v_mfma_f32_16x16x32_bf16 v[10:13], v[182:185], v[244:247], v[10:13]
	v_mfma_f32_16x16x32_bf16 v[26:29], v[178:181], v[232:235], v[26:29]
	v_mfma_f32_16x16x32_bf16 v[26:29], v[182:185], v[236:239], v[26:29]
	v_mfma_f32_16x16x32_bf16 v[42:45], v[178:181], v[202:205], v[42:45]
	v_mfma_f32_16x16x32_bf16 v[42:45], v[182:185], v[228:231], v[42:45]
	v_mfma_f32_16x16x32_bf16 v[58:61], v[178:181], v[194:197], v[58:61]
	v_mfma_f32_16x16x32_bf16 v[58:61], v[182:185], v[198:201], v[58:61]
	s_barrier
	s_setprio 0
	v_add_u32_e32 v139, 0x18000, v136
	ds_read_b128 v[140:143], v139
	ds_read_b128 v[154:157], v139 offset:1024
	ds_read_b128 v[170:173], v139 offset:2048
	ds_read_b128 v[174:177], v139 offset:3072
	v_add_u32_e32 v139, 0x1c000, v136
	ds_read_b128 v[178:181], v139
	ds_read_b128 v[182:185], v139 offset:1024
	ds_read_b128 v[186:189], v139 offset:2048
	ds_read_b128 v[190:193], v139 offset:3072
	s_add_i32 s52, s52, 0x80000
	s_mov_b32 m0, s23
	ds_read_b128 v[194:197], v137 offset:32768
	ds_read_b128 v[198:201], v137 offset:33792
	ds_read_b128 v[202:205], v137 offset:34816
	ds_read_b128 v[228:231], v137 offset:35840
	ds_read_b128 v[232:235], v137 offset:36864
	ds_read_b128 v[236:239], v137 offset:37888
	ds_read_b128 v[240:243], v137 offset:38912
	ds_read_b128 v[244:247], v137 offset:39936
	buffer_load_dwordx4 v132, s[60:63], s52 offen lds
	s_mov_b32 m0, s24
	s_nop 0
	buffer_load_dwordx4 v134, s[60:63], s52 offen lds
	s_waitcnt vmcnt(8)
	s_waitcnt lgkmcnt(0)
	s_setprio 1
	s_barrier
	v_mfma_f32_16x16x32_bf16 v[114:117], v[140:143], v[194:197], v[114:117]
	v_mfma_f32_16x16x32_bf16 v[114:117], v[154:157], v[198:201], v[114:117]
	v_mfma_f32_16x16x32_bf16 v[106:109], v[140:143], v[202:205], v[106:109]
	v_mfma_f32_16x16x32_bf16 v[106:109], v[154:157], v[228:231], v[106:109]
	v_mfma_f32_16x16x32_bf16 v[94:97], v[140:143], v[232:235], v[94:97]
	v_mfma_f32_16x16x32_bf16 v[94:97], v[154:157], v[236:239], v[94:97]
	v_mfma_f32_16x16x32_bf16 v[78:81], v[140:143], v[240:243], v[78:81]
	v_mfma_f32_16x16x32_bf16 v[78:81], v[154:157], v[244:247], v[78:81]
	v_mfma_f32_16x16x32_bf16 v[70:73], v[170:173], v[240:243], v[70:73]
	v_mfma_f32_16x16x32_bf16 v[70:73], v[174:177], v[244:247], v[70:73]
	v_mfma_f32_16x16x32_bf16 v[86:89], v[170:173], v[232:235], v[86:89]
	v_mfma_f32_16x16x32_bf16 v[86:89], v[174:177], v[236:239], v[86:89]
	v_mfma_f32_16x16x32_bf16 v[102:105], v[170:173], v[202:205], v[102:105]
	v_mfma_f32_16x16x32_bf16 v[102:105], v[174:177], v[228:231], v[102:105]
	v_mfma_f32_16x16x32_bf16 v[110:113], v[170:173], v[194:197], v[110:113]
	v_mfma_f32_16x16x32_bf16 v[110:113], v[174:177], v[198:201], v[110:113]
	v_mfma_f32_16x16x32_bf16 v[122:125], v[186:189], v[194:197], v[122:125]
	v_mfma_f32_16x16x32_bf16 v[122:125], v[190:193], v[198:201], v[122:125]
	v_mfma_f32_16x16x32_bf16 v[98:101], v[186:189], v[202:205], v[98:101]
	v_mfma_f32_16x16x32_bf16 v[98:101], v[190:193], v[228:231], v[98:101]
	v_mfma_f32_16x16x32_bf16 v[82:85], v[186:189], v[232:235], v[82:85]
	v_mfma_f32_16x16x32_bf16 v[82:85], v[190:193], v[236:239], v[82:85]
	v_mfma_f32_16x16x32_bf16 v[66:69], v[186:189], v[240:243], v[66:69]
	v_mfma_f32_16x16x32_bf16 v[66:69], v[190:193], v[244:247], v[66:69]
	v_mfma_f32_16x16x32_bf16 v[74:77], v[178:181], v[240:243], v[74:77]
	v_mfma_f32_16x16x32_bf16 v[74:77], v[182:185], v[244:247], v[74:77]
	v_mfma_f32_16x16x32_bf16 v[90:93], v[178:181], v[232:235], v[90:93]
	v_mfma_f32_16x16x32_bf16 v[90:93], v[182:185], v[236:239], v[90:93]
	v_mfma_f32_16x16x32_bf16 v[118:121], v[178:181], v[202:205], v[118:121]
	v_mfma_f32_16x16x32_bf16 v[118:121], v[182:185], v[228:231], v[118:121]
	v_mfma_f32_16x16x32_bf16 v[126:129], v[178:181], v[194:197], v[126:129]
	v_mfma_f32_16x16x32_bf16 v[126:129], v[182:185], v[198:201], v[126:129]
	s_barrier
	s_setprio 0
	s_or_b32 s52, s96, 0x80
	s_mov_b32 m0, s31
	ds_read_b128 v[194:197], v137 offset:49152
	buffer_load_dwordx4 v133, s[40:43], s52 offen lds
	s_add_i32 s96, s96, 0x80080
	s_mov_b32 m0, s33
	ds_read_b128 v[198:201], v137 offset:50176
	buffer_load_dwordx4 v135, s[40:43], s52 offen lds
	s_mov_b32 m0, s36
	ds_read_b128 v[202:205], v137 offset:51200
	buffer_load_dwordx4 v133, s[40:43], s96 offen lds
	s_mov_b32 m0, s37
	ds_read_b128 v[228:231], v137 offset:52224
	buffer_load_dwordx4 v135, s[40:43], s96 offen lds
	s_mov_b32 m0, s34
	ds_read_b128 v[232:235], v137 offset:53248
	buffer_load_dwordx4 v132, s[60:63], s95 offen lds
	s_mov_b32 m0, s35
	ds_read_b128 v[236:239], v137 offset:54272
	buffer_load_dwordx4 v134, s[60:63], s95 offen lds
	ds_read_b128 v[240:243], v137 offset:55296
	ds_read_b128 v[244:247], v137 offset:56320
	s_waitcnt vmcnt(8)
	s_waitcnt lgkmcnt(0)
	s_setprio 1
	s_barrier
	v_mfma_f32_16x16x32_bf16 v[62:65], v[140:143], v[194:197], v[62:65]
	v_mfma_f32_16x16x32_bf16 v[62:65], v[154:157], v[198:201], v[62:65]
	v_mfma_f32_16x16x32_bf16 v[46:49], v[140:143], v[202:205], v[46:49]
	v_mfma_f32_16x16x32_bf16 v[46:49], v[154:157], v[228:231], v[46:49]
	v_mfma_f32_16x16x32_bf16 v[30:33], v[140:143], v[232:235], v[30:33]
	v_mfma_f32_16x16x32_bf16 v[30:33], v[154:157], v[236:239], v[30:33]
	v_mfma_f32_16x16x32_bf16 v[14:17], v[140:143], v[240:243], v[14:17]
	v_mfma_f32_16x16x32_bf16 v[14:17], v[154:157], v[244:247], v[14:17]
	v_mfma_f32_16x16x32_bf16 v[6:9], v[170:173], v[240:243], v[6:9]
	v_mfma_f32_16x16x32_bf16 v[6:9], v[174:177], v[244:247], v[6:9]
	v_mfma_f32_16x16x32_bf16 v[22:25], v[170:173], v[232:235], v[22:25]
	v_mfma_f32_16x16x32_bf16 v[22:25], v[174:177], v[236:239], v[22:25]
	v_mfma_f32_16x16x32_bf16 v[38:41], v[170:173], v[202:205], v[38:41]
	v_mfma_f32_16x16x32_bf16 v[38:41], v[174:177], v[228:231], v[38:41]
	v_mfma_f32_16x16x32_bf16 v[54:57], v[170:173], v[194:197], v[54:57]
	v_mfma_f32_16x16x32_bf16 v[54:57], v[174:177], v[198:201], v[54:57]
	v_mfma_f32_16x16x32_bf16 v[50:53], v[186:189], v[194:197], v[50:53]
	v_mfma_f32_16x16x32_bf16 v[50:53], v[190:193], v[198:201], v[50:53]
	v_mfma_f32_16x16x32_bf16 v[34:37], v[186:189], v[202:205], v[34:37]
	v_mfma_f32_16x16x32_bf16 v[34:37], v[190:193], v[228:231], v[34:37]
	v_mfma_f32_16x16x32_bf16 v[18:21], v[186:189], v[232:235], v[18:21]
	v_mfma_f32_16x16x32_bf16 v[18:21], v[190:193], v[236:239], v[18:21]
	v_mfma_f32_16x16x32_bf16 v[2:5], v[186:189], v[240:243], v[2:5]
	v_mfma_f32_16x16x32_bf16 v[2:5], v[190:193], v[244:247], v[2:5]
	v_mfma_f32_16x16x32_bf16 v[10:13], v[178:181], v[240:243], v[10:13]
	v_mfma_f32_16x16x32_bf16 v[10:13], v[182:185], v[244:247], v[10:13]
	v_mfma_f32_16x16x32_bf16 v[26:29], v[178:181], v[232:235], v[26:29]
	v_mfma_f32_16x16x32_bf16 v[26:29], v[182:185], v[236:239], v[26:29]
	v_mfma_f32_16x16x32_bf16 v[42:45], v[178:181], v[202:205], v[42:45]
	v_mfma_f32_16x16x32_bf16 v[42:45], v[182:185], v[228:231], v[42:45]
	v_mfma_f32_16x16x32_bf16 v[58:61], v[178:181], v[194:197], v[58:61]
	v_mfma_f32_16x16x32_bf16 v[58:61], v[182:185], v[198:201], v[58:61]
	s_barrier
	s_setprio 0
	s_add_i32 s94, s94, 2
	s_addk_i32 vcc_lo, 0x100
	s_addk_i32 vcc_hi, 0x100
	s_cmp_gt_u32 s94, 29
	s_cbranch_scc0 .LBB0_1880
	s_and_b64 vcc, exec, s[64:65]
	s_cbranch_vccz .LBB0_1883
	s_barrier

.LBB0_2155:
	s_mul_i32 s49, s48, 0x2c0000
	s_and_b64 s[8:9], s[42:43], exec
	s_mul_i32 s23, s15, 0x2c0000
	s_cselect_b32 s8, s49, s21
	s_cselect_b32 s9, s23, s13
	s_addk_i32 s13, 0x100
	s_add_i32 s21, s21, 0xc000
	s_mov_b32 s22, -2
	s_waitcnt lgkmcnt(0)
	v_add_u32_e32 v170, 0x10000, v140
	v_add_u32_e32 v186, 0x14000, v140
	ds_read_b128 v[132:135], v170
	ds_read_b128 v[142:145], v170 offset:1024
	ds_read_b128 v[154:157], v170 offset:2048
	ds_read_b128 v[170:173], v170 offset:3072
	ds_read_b128 v[174:177], v186
	ds_read_b128 v[178:181], v186 offset:1024
	ds_read_b128 v[182:185], v186 offset:2048
	ds_read_b128 v[186:189], v186 offset:3072
	s_add_i32 s26, s21, 0x4000
	s_cmpk_eq_i32 s22, 0x54
	s_cselect_b32 s52, s8, s26
	s_cselect_b32 s27, s9, s13
	s_or_b32 s26, s52, 0x8000
	s_mov_b32 m0, s84
	ds_read_b128 v[190:193], v141
	ds_read_b128 v[194:197], v141 offset:1024
	ds_read_b128 v[198:201], v141 offset:2048
	ds_read_b128 v[202:205], v141 offset:3072
	ds_read_b128 v[228:231], v141 offset:4096
	ds_read_b128 v[232:235], v141 offset:5120
	ds_read_b128 v[236:239], v141 offset:6144
	ds_read_b128 v[240:243], v141 offset:7168
	buffer_load_dwordx4 v136, s[60:63], s21 offen lds
	s_mov_b32 m0, s16
	s_nop 0
	buffer_load_dwordx4 v138, s[60:63], s21 offen lds
	s_waitcnt vmcnt(8)
	s_waitcnt lgkmcnt(0)
	s_setprio 1
	s_barrier
	v_mfma_f32_16x16x32_bf16 v[126:129], v[132:135], v[190:193], 0
	v_mfma_f32_16x16x32_bf16 v[126:129], v[142:145], v[194:197], v[126:129]
	v_mfma_f32_16x16x32_bf16 v[118:121], v[132:135], v[198:201], 0
	v_mfma_f32_16x16x32_bf16 v[118:121], v[142:145], v[202:205], v[118:121]
	v_mfma_f32_16x16x32_bf16 v[94:97], v[132:135], v[228:231], 0
	v_mfma_f32_16x16x32_bf16 v[94:97], v[142:145], v[232:235], v[94:97]
	v_mfma_f32_16x16x32_bf16 v[78:81], v[132:135], v[236:239], 0
	v_mfma_f32_16x16x32_bf16 v[78:81], v[142:145], v[240:243], v[78:81]
	v_mfma_f32_16x16x32_bf16 v[74:77], v[154:157], v[236:239], 0
	v_mfma_f32_16x16x32_bf16 v[74:77], v[170:173], v[240:243], v[74:77]
	v_mfma_f32_16x16x32_bf16 v[90:93], v[154:157], v[228:231], 0
	v_mfma_f32_16x16x32_bf16 v[90:93], v[170:173], v[232:235], v[90:93]
	v_mfma_f32_16x16x32_bf16 v[114:117], v[154:157], v[198:201], 0
	v_mfma_f32_16x16x32_bf16 v[114:117], v[170:173], v[202:205], v[114:117]
	v_mfma_f32_16x16x32_bf16 v[106:109], v[154:157], v[190:193], 0
	v_mfma_f32_16x16x32_bf16 v[106:109], v[170:173], v[194:197], v[106:109]
	v_mfma_f32_16x16x32_bf16 v[110:113], v[182:185], v[190:193], 0
	v_mfma_f32_16x16x32_bf16 v[110:113], v[186:189], v[194:197], v[110:113]
	v_mfma_f32_16x16x32_bf16 v[98:101], v[182:185], v[198:201], 0
	v_mfma_f32_16x16x32_bf16 v[98:101], v[186:189], v[202:205], v[98:101]
	v_mfma_f32_16x16x32_bf16 v[82:85], v[182:185], v[228:231], 0
	v_mfma_f32_16x16x32_bf16 v[82:85], v[186:189], v[232:235], v[82:85]
	v_mfma_f32_16x16x32_bf16 v[66:69], v[182:185], v[236:239], 0
	v_mfma_f32_16x16x32_bf16 v[66:69], v[186:189], v[240:243], v[66:69]
	v_mfma_f32_16x16x32_bf16 v[70:73], v[174:177], v[236:239], 0
	v_mfma_f32_16x16x32_bf16 v[70:73], v[178:181], v[240:243], v[70:73]
	v_mfma_f32_16x16x32_bf16 v[86:89], v[174:177], v[228:231], 0
	v_mfma_f32_16x16x32_bf16 v[86:89], v[178:181], v[232:235], v[86:89]
	v_mfma_f32_16x16x32_bf16 v[102:105], v[174:177], v[198:201], 0
	v_mfma_f32_16x16x32_bf16 v[102:105], v[178:181], v[202:205], v[102:105]
	v_mfma_f32_16x16x32_bf16 v[122:125], v[174:177], v[190:193], 0
	v_mfma_f32_16x16x32_bf16 v[122:125], v[178:181], v[194:197], v[122:125]
	s_barrier
	s_setprio 0
	s_mov_b32 s46, s62
	s_mov_b32 s47, s63
	s_mov_b32 m0, s18
	ds_read_b128 v[190:193], v141 offset:16384
	buffer_load_dwordx4 v137, s[44:47], s27 offen lds
	s_add_i32 s53, s27, 0x160000
	s_mov_b32 m0, s19
	ds_read_b128 v[194:197], v141 offset:17408
	buffer_load_dwordx4 v139, s[44:47], s27 offen lds
	s_mov_b32 m0, s24
	ds_read_b128 v[198:201], v141 offset:18432
	buffer_load_dwordx4 v137, s[44:47], s53 offen lds
	s_mov_b32 m0, s25
	ds_read_b128 v[202:205], v141 offset:19456
	buffer_load_dwordx4 v139, s[44:47], s53 offen lds
	s_mov_b32 m0, s14
	ds_read_b128 v[228:231], v141 offset:20480
	buffer_load_dwordx4 v136, s[60:63], s52 offen lds
	s_mov_b32 m0, s30
	ds_read_b128 v[232:235], v141 offset:21504
	buffer_load_dwordx4 v138, s[60:63], s52 offen lds
	ds_read_b128 v[236:239], v141 offset:22528
	ds_read_b128 v[240:243], v141 offset:23552
	s_waitcnt vmcnt(8)
	s_waitcnt lgkmcnt(0)
	s_setprio 1
	s_barrier
	v_mfma_f32_16x16x32_bf16 v[62:65], v[132:135], v[190:193], 0
	v_mfma_f32_16x16x32_bf16 v[62:65], v[142:145], v[194:197], v[62:65]
	v_mfma_f32_16x16x32_bf16 v[46:49], v[132:135], v[198:201], 0
	v_mfma_f32_16x16x32_bf16 v[46:49], v[142:145], v[202:205], v[46:49]
	v_mfma_f32_16x16x32_bf16 v[30:33], v[132:135], v[228:231], 0
	v_mfma_f32_16x16x32_bf16 v[30:33], v[142:145], v[232:235], v[30:33]
	v_mfma_f32_16x16x32_bf16 v[14:17], v[132:135], v[236:239], 0
	v_mfma_f32_16x16x32_bf16 v[14:17], v[142:145], v[240:243], v[14:17]
	v_mfma_f32_16x16x32_bf16 v[10:13], v[154:157], v[236:239], 0
	v_mfma_f32_16x16x32_bf16 v[10:13], v[170:173], v[240:243], v[10:13]
	v_mfma_f32_16x16x32_bf16 v[26:29], v[154:157], v[228:231], 0
	v_mfma_f32_16x16x32_bf16 v[26:29], v[170:173], v[232:235], v[26:29]
	v_mfma_f32_16x16x32_bf16 v[42:45], v[154:157], v[198:201], 0
	v_mfma_f32_16x16x32_bf16 v[42:45], v[170:173], v[202:205], v[42:45]
	v_mfma_f32_16x16x32_bf16 v[58:61], v[154:157], v[190:193], 0
	v_mfma_f32_16x16x32_bf16 v[58:61], v[170:173], v[194:197], v[58:61]
	v_mfma_f32_16x16x32_bf16 v[50:53], v[182:185], v[190:193], 0
	v_mfma_f32_16x16x32_bf16 v[50:53], v[186:189], v[194:197], v[50:53]
	v_mfma_f32_16x16x32_bf16 v[34:37], v[182:185], v[198:201], 0
	v_mfma_f32_16x16x32_bf16 v[34:37], v[186:189], v[202:205], v[34:37]
	v_mfma_f32_16x16x32_bf16 v[18:21], v[182:185], v[228:231], 0
	v_mfma_f32_16x16x32_bf16 v[18:21], v[186:189], v[232:235], v[18:21]
	v_mfma_f32_16x16x32_bf16 v[2:5], v[182:185], v[236:239], 0
	v_mfma_f32_16x16x32_bf16 v[2:5], v[186:189], v[240:243], v[2:5]
	v_mfma_f32_16x16x32_bf16 v[6:9], v[174:177], v[236:239], 0
	v_mfma_f32_16x16x32_bf16 v[6:9], v[178:181], v[240:243], v[6:9]
	v_mfma_f32_16x16x32_bf16 v[22:25], v[174:177], v[228:231], 0
	v_mfma_f32_16x16x32_bf16 v[22:25], v[178:181], v[232:235], v[22:25]
	v_mfma_f32_16x16x32_bf16 v[38:41], v[174:177], v[198:201], 0
	v_mfma_f32_16x16x32_bf16 v[38:41], v[178:181], v[202:205], v[38:41]
	v_mfma_f32_16x16x32_bf16 v[54:57], v[174:177], v[190:193], 0
	v_mfma_f32_16x16x32_bf16 v[54:57], v[178:181], v[194:197], v[54:57]
	s_barrier
	s_setprio 0
	v_add_u32_e32 v170, 0x18000, v140
	v_add_u32_e32 v186, 0x1c000, v140
	ds_read_b128 v[132:135], v170
	ds_read_b128 v[142:145], v170 offset:1024
	ds_read_b128 v[154:157], v170 offset:2048
	ds_read_b128 v[170:173], v170 offset:3072
	ds_read_b128 v[174:177], v186
	ds_read_b128 v[178:181], v186 offset:1024
	ds_read_b128 v[182:185], v186 offset:2048
	ds_read_b128 v[186:189], v186 offset:3072
	s_bitset1_b32 s52, 14
	s_mov_b32 m0, s31
	ds_read_b128 v[190:193], v141 offset:32768
	ds_read_b128 v[194:197], v141 offset:33792
	ds_read_b128 v[198:201], v141 offset:34816
	ds_read_b128 v[202:205], v141 offset:35840
	ds_read_b128 v[228:231], v141 offset:36864
	ds_read_b128 v[232:235], v141 offset:37888
	ds_read_b128 v[236:239], v141 offset:38912
	ds_read_b128 v[240:243], v141 offset:39936
	buffer_load_dwordx4 v136, s[60:63], s52 offen lds
	s_mov_b32 m0, s33
	s_nop 0
	buffer_load_dwordx4 v138, s[60:63], s52 offen lds
	s_waitcnt vmcnt(8)
	s_waitcnt lgkmcnt(0)
	s_setprio 1
	s_barrier
	v_mfma_f32_16x16x32_bf16 v[126:129], v[132:135], v[190:193], v[126:129]
	v_mfma_f32_16x16x32_bf16 v[126:129], v[142:145], v[194:197], v[126:129]
	v_mfma_f32_16x16x32_bf16 v[118:121], v[132:135], v[198:201], v[118:121]
	v_mfma_f32_16x16x32_bf16 v[118:121], v[142:145], v[202:205], v[118:121]
	v_mfma_f32_16x16x32_bf16 v[94:97], v[132:135], v[228:231], v[94:97]
	v_mfma_f32_16x16x32_bf16 v[94:97], v[142:145], v[232:235], v[94:97]
	v_mfma_f32_16x16x32_bf16 v[78:81], v[132:135], v[236:239], v[78:81]
	v_mfma_f32_16x16x32_bf16 v[78:81], v[142:145], v[240:243], v[78:81]
	v_mfma_f32_16x16x32_bf16 v[74:77], v[154:157], v[236:239], v[74:77]
	v_mfma_f32_16x16x32_bf16 v[74:77], v[170:173], v[240:243], v[74:77]
	v_mfma_f32_16x16x32_bf16 v[90:93], v[154:157], v[228:231], v[90:93]
	v_mfma_f32_16x16x32_bf16 v[90:93], v[170:173], v[232:235], v[90:93]
	v_mfma_f32_16x16x32_bf16 v[114:117], v[154:157], v[198:201], v[114:117]
	v_mfma_f32_16x16x32_bf16 v[114:117], v[170:173], v[202:205], v[114:117]
	v_mfma_f32_16x16x32_bf16 v[106:109], v[154:157], v[190:193], v[106:109]
	v_mfma_f32_16x16x32_bf16 v[106:109], v[170:173], v[194:197], v[106:109]
	v_mfma_f32_16x16x32_bf16 v[110:113], v[182:185], v[190:193], v[110:113]
	v_mfma_f32_16x16x32_bf16 v[110:113], v[186:189], v[194:197], v[110:113]
	v_mfma_f32_16x16x32_bf16 v[98:101], v[182:185], v[198:201], v[98:101]
	v_mfma_f32_16x16x32_bf16 v[98:101], v[186:189], v[202:205], v[98:101]
	v_mfma_f32_16x16x32_bf16 v[82:85], v[182:185], v[228:231], v[82:85]
	v_mfma_f32_16x16x32_bf16 v[82:85], v[186:189], v[232:235], v[82:85]
	v_mfma_f32_16x16x32_bf16 v[66:69], v[182:185], v[236:239], v[66:69]
	v_mfma_f32_16x16x32_bf16 v[66:69], v[186:189], v[240:243], v[66:69]
	v_mfma_f32_16x16x32_bf16 v[70:73], v[174:177], v[236:239], v[70:73]
	v_mfma_f32_16x16x32_bf16 v[70:73], v[178:181], v[240:243], v[70:73]
	v_mfma_f32_16x16x32_bf16 v[86:89], v[174:177], v[228:231], v[86:89]
	v_mfma_f32_16x16x32_bf16 v[86:89], v[178:181], v[232:235], v[86:89]
	v_mfma_f32_16x16x32_bf16 v[102:105], v[174:177], v[198:201], v[102:105]
	v_mfma_f32_16x16x32_bf16 v[102:105], v[178:181], v[202:205], v[102:105]
	v_mfma_f32_16x16x32_bf16 v[122:125], v[174:177], v[190:193], v[122:125]
	v_mfma_f32_16x16x32_bf16 v[122:125], v[178:181], v[194:197], v[122:125]
	s_barrier
	s_setprio 0
	s_or_b32 s52, s27, 0x80
	s_mov_b32 m0, s68
	ds_read_b128 v[190:193], v141 offset:49152
	buffer_load_dwordx4 v137, s[44:47], s52 offen lds
	s_add_i32 s27, s27, 0x160080
	s_mov_b32 m0, s69
	ds_read_b128 v[194:197], v141 offset:50176
	buffer_load_dwordx4 v139, s[44:47], s52 offen lds
	s_mov_b32 m0, s72
	ds_read_b128 v[198:201], v141 offset:51200
	buffer_load_dwordx4 v137, s[44:47], s27 offen lds
	s_mov_b32 m0, s73
	ds_read_b128 v[202:205], v141 offset:52224
	buffer_load_dwordx4 v139, s[44:47], s27 offen lds
	s_mov_b32 m0, s70
	ds_read_b128 v[228:231], v141 offset:53248
	buffer_load_dwordx4 v136, s[60:63], s26 offen lds
	s_mov_b32 m0, s71
	ds_read_b128 v[232:235], v141 offset:54272
	buffer_load_dwordx4 v138, s[60:63], s26 offen lds
	ds_read_b128 v[236:239], v141 offset:55296
	ds_read_b128 v[240:243], v141 offset:56320
	s_waitcnt vmcnt(8)
	s_waitcnt lgkmcnt(0)
	s_setprio 1
	s_barrier
	v_mfma_f32_16x16x32_bf16 v[62:65], v[132:135], v[190:193], v[62:65]
	v_mfma_f32_16x16x32_bf16 v[62:65], v[142:145], v[194:197], v[62:65]
	v_mfma_f32_16x16x32_bf16 v[46:49], v[132:135], v[198:201], v[46:49]
	v_mfma_f32_16x16x32_bf16 v[46:49], v[142:145], v[202:205], v[46:49]
	v_mfma_f32_16x16x32_bf16 v[30:33], v[132:135], v[228:231], v[30:33]
	v_mfma_f32_16x16x32_bf16 v[30:33], v[142:145], v[232:235], v[30:33]
	v_mfma_f32_16x16x32_bf16 v[14:17], v[132:135], v[236:239], v[14:17]
	v_mfma_f32_16x16x32_bf16 v[14:17], v[142:145], v[240:243], v[14:17]
	v_mfma_f32_16x16x32_bf16 v[10:13], v[154:157], v[236:239], v[10:13]
	v_mfma_f32_16x16x32_bf16 v[10:13], v[170:173], v[240:243], v[10:13]
	v_mfma_f32_16x16x32_bf16 v[26:29], v[154:157], v[228:231], v[26:29]
	v_mfma_f32_16x16x32_bf16 v[26:29], v[170:173], v[232:235], v[26:29]
	v_mfma_f32_16x16x32_bf16 v[42:45], v[154:157], v[198:201], v[42:45]
	v_mfma_f32_16x16x32_bf16 v[42:45], v[170:173], v[202:205], v[42:45]
	v_mfma_f32_16x16x32_bf16 v[58:61], v[154:157], v[190:193], v[58:61]
	v_mfma_f32_16x16x32_bf16 v[58:61], v[170:173], v[194:197], v[58:61]
	v_mfma_f32_16x16x32_bf16 v[50:53], v[182:185], v[190:193], v[50:53]
	v_mfma_f32_16x16x32_bf16 v[50:53], v[186:189], v[194:197], v[50:53]
	v_mfma_f32_16x16x32_bf16 v[34:37], v[182:185], v[198:201], v[34:37]
	v_mfma_f32_16x16x32_bf16 v[34:37], v[186:189], v[202:205], v[34:37]
	v_mfma_f32_16x16x32_bf16 v[18:21], v[182:185], v[228:231], v[18:21]
	v_mfma_f32_16x16x32_bf16 v[18:21], v[186:189], v[232:235], v[18:21]
	v_mfma_f32_16x16x32_bf16 v[2:5], v[182:185], v[236:239], v[2:5]
	v_mfma_f32_16x16x32_bf16 v[2:5], v[186:189], v[240:243], v[2:5]
	v_mfma_f32_16x16x32_bf16 v[6:9], v[174:177], v[236:239], v[6:9]
	v_mfma_f32_16x16x32_bf16 v[6:9], v[178:181], v[240:243], v[6:9]
	v_mfma_f32_16x16x32_bf16 v[22:25], v[174:177], v[228:231], v[22:25]
	v_mfma_f32_16x16x32_bf16 v[22:25], v[178:181], v[232:235], v[22:25]
	v_mfma_f32_16x16x32_bf16 v[38:41], v[174:177], v[198:201], v[38:41]
	v_mfma_f32_16x16x32_bf16 v[38:41], v[178:181], v[202:205], v[38:41]
	v_mfma_f32_16x16x32_bf16 v[54:57], v[174:177], v[190:193], v[54:57]
	v_mfma_f32_16x16x32_bf16 v[54:57], v[178:181], v[194:197], v[54:57]
	s_barrier
	s_setprio 0
	s_addk_i32 s13, 0x100
	s_add_i32 s22, s22, 2
	s_add_i32 s21, s21, 0x10000
	s_cmpk_gt_u32 s22, 0x55
.LBB0_2156:
	v_add_u32_e32 v170, 0x10000, v140
	v_add_u32_e32 v186, 0x14000, v140
	ds_read_b128 v[132:135], v170
	ds_read_b128 v[142:145], v170 offset:1024
	ds_read_b128 v[154:157], v170 offset:2048
	ds_read_b128 v[170:173], v170 offset:3072
	ds_read_b128 v[174:177], v186
	ds_read_b128 v[178:181], v186 offset:1024
	ds_read_b128 v[182:185], v186 offset:2048
	ds_read_b128 v[186:189], v186 offset:3072
	s_add_i32 s26, s21, 0x4000
	s_cmpk_eq_i32 s22, 0x54
	s_cselect_b32 s52, s8, s26
	s_cselect_b32 s27, s9, s13
	s_or_b32 s26, s52, 0x8000
	s_mov_b32 m0, s84
	ds_read_b128 v[190:193], v141
	ds_read_b128 v[194:197], v141 offset:1024
	ds_read_b128 v[198:201], v141 offset:2048
	ds_read_b128 v[202:205], v141 offset:3072
	ds_read_b128 v[228:231], v141 offset:4096
	ds_read_b128 v[232:235], v141 offset:5120
	ds_read_b128 v[236:239], v141 offset:6144
	ds_read_b128 v[240:243], v141 offset:7168
	buffer_load_dwordx4 v136, s[60:63], s21 offen lds
	s_mov_b32 m0, s16
	s_nop 0
	buffer_load_dwordx4 v138, s[60:63], s21 offen lds
	s_waitcnt vmcnt(8)
	s_waitcnt lgkmcnt(0)
	s_setprio 1
	s_barrier
	v_mfma_f32_16x16x32_bf16 v[126:129], v[132:135], v[190:193], v[126:129]
	v_mfma_f32_16x16x32_bf16 v[126:129], v[142:145], v[194:197], v[126:129]
	v_mfma_f32_16x16x32_bf16 v[118:121], v[132:135], v[198:201], v[118:121]
	v_mfma_f32_16x16x32_bf16 v[118:121], v[142:145], v[202:205], v[118:121]
	v_mfma_f32_16x16x32_bf16 v[94:97], v[132:135], v[228:231], v[94:97]
	v_mfma_f32_16x16x32_bf16 v[94:97], v[142:145], v[232:235], v[94:97]
	v_mfma_f32_16x16x32_bf16 v[78:81], v[132:135], v[236:239], v[78:81]
	v_mfma_f32_16x16x32_bf16 v[78:81], v[142:145], v[240:243], v[78:81]
	v_mfma_f32_16x16x32_bf16 v[74:77], v[154:157], v[236:239], v[74:77]
	v_mfma_f32_16x16x32_bf16 v[74:77], v[170:173], v[240:243], v[74:77]
	v_mfma_f32_16x16x32_bf16 v[90:93], v[154:157], v[228:231], v[90:93]
	v_mfma_f32_16x16x32_bf16 v[90:93], v[170:173], v[232:235], v[90:93]
	v_mfma_f32_16x16x32_bf16 v[114:117], v[154:157], v[198:201], v[114:117]
	v_mfma_f32_16x16x32_bf16 v[114:117], v[170:173], v[202:205], v[114:117]
	v_mfma_f32_16x16x32_bf16 v[106:109], v[154:157], v[190:193], v[106:109]
	v_mfma_f32_16x16x32_bf16 v[106:109], v[170:173], v[194:197], v[106:109]
	v_mfma_f32_16x16x32_bf16 v[110:113], v[182:185], v[190:193], v[110:113]
	v_mfma_f32_16x16x32_bf16 v[110:113], v[186:189], v[194:197], v[110:113]
	v_mfma_f32_16x16x32_bf16 v[98:101], v[182:185], v[198:201], v[98:101]
	v_mfma_f32_16x16x32_bf16 v[98:101], v[186:189], v[202:205], v[98:101]
	v_mfma_f32_16x16x32_bf16 v[82:85], v[182:185], v[228:231], v[82:85]
	v_mfma_f32_16x16x32_bf16 v[82:85], v[186:189], v[232:235], v[82:85]
	v_mfma_f32_16x16x32_bf16 v[66:69], v[182:185], v[236:239], v[66:69]
	v_mfma_f32_16x16x32_bf16 v[66:69], v[186:189], v[240:243], v[66:69]
	v_mfma_f32_16x16x32_bf16 v[70:73], v[174:177], v[236:239], v[70:73]
	v_mfma_f32_16x16x32_bf16 v[70:73], v[178:181], v[240:243], v[70:73]
	v_mfma_f32_16x16x32_bf16 v[86:89], v[174:177], v[228:231], v[86:89]
	v_mfma_f32_16x16x32_bf16 v[86:89], v[178:181], v[232:235], v[86:89]
	v_mfma_f32_16x16x32_bf16 v[102:105], v[174:177], v[198:201], v[102:105]
	v_mfma_f32_16x16x32_bf16 v[102:105], v[178:181], v[202:205], v[102:105]
	v_mfma_f32_16x16x32_bf16 v[122:125], v[174:177], v[190:193], v[122:125]
	v_mfma_f32_16x16x32_bf16 v[122:125], v[178:181], v[194:197], v[122:125]
	s_barrier
	s_setprio 0
	s_mov_b32 s46, s62
	s_mov_b32 s47, s63
	s_mov_b32 m0, s18
	ds_read_b128 v[190:193], v141 offset:16384
	buffer_load_dwordx4 v137, s[44:47], s27 offen lds
	s_add_i32 s53, s27, 0x160000
	s_mov_b32 m0, s19
	ds_read_b128 v[194:197], v141 offset:17408
	buffer_load_dwordx4 v139, s[44:47], s27 offen lds
	s_mov_b32 m0, s24
	ds_read_b128 v[198:201], v141 offset:18432
	buffer_load_dwordx4 v137, s[44:47], s53 offen lds
	s_mov_b32 m0, s25
	ds_read_b128 v[202:205], v141 offset:19456
	buffer_load_dwordx4 v139, s[44:47], s53 offen lds
	s_mov_b32 m0, s14
	ds_read_b128 v[228:231], v141 offset:20480
	buffer_load_dwordx4 v136, s[60:63], s52 offen lds
	s_mov_b32 m0, s30
	ds_read_b128 v[232:235], v141 offset:21504
	buffer_load_dwordx4 v138, s[60:63], s52 offen lds
	ds_read_b128 v[236:239], v141 offset:22528
	ds_read_b128 v[240:243], v141 offset:23552
	s_waitcnt vmcnt(8)
	s_waitcnt lgkmcnt(0)
	s_setprio 1
	s_barrier
	v_mfma_f32_16x16x32_bf16 v[62:65], v[132:135], v[190:193], v[62:65]
	v_mfma_f32_16x16x32_bf16 v[62:65], v[142:145], v[194:197], v[62:65]
	v_mfma_f32_16x16x32_bf16 v[46:49], v[132:135], v[198:201], v[46:49]
	v_mfma_f32_16x16x32_bf16 v[46:49], v[142:145], v[202:205], v[46:49]
	v_mfma_f32_16x16x32_bf16 v[30:33], v[132:135], v[228:231], v[30:33]
	v_mfma_f32_16x16x32_bf16 v[30:33], v[142:145], v[232:235], v[30:33]
	v_mfma_f32_16x16x32_bf16 v[14:17], v[132:135], v[236:239], v[14:17]
	v_mfma_f32_16x16x32_bf16 v[14:17], v[142:145], v[240:243], v[14:17]
	v_mfma_f32_16x16x32_bf16 v[10:13], v[154:157], v[236:239], v[10:13]
	v_mfma_f32_16x16x32_bf16 v[10:13], v[170:173], v[240:243], v[10:13]
	v_mfma_f32_16x16x32_bf16 v[26:29], v[154:157], v[228:231], v[26:29]
	v_mfma_f32_16x16x32_bf16 v[26:29], v[170:173], v[232:235], v[26:29]
	v_mfma_f32_16x16x32_bf16 v[42:45], v[154:157], v[198:201], v[42:45]
	v_mfma_f32_16x16x32_bf16 v[42:45], v[170:173], v[202:205], v[42:45]
	v_mfma_f32_16x16x32_bf16 v[58:61], v[154:157], v[190:193], v[58:61]
	v_mfma_f32_16x16x32_bf16 v[58:61], v[170:173], v[194:197], v[58:61]
	v_mfma_f32_16x16x32_bf16 v[50:53], v[182:185], v[190:193], v[50:53]
	v_mfma_f32_16x16x32_bf16 v[50:53], v[186:189], v[194:197], v[50:53]
	v_mfma_f32_16x16x32_bf16 v[34:37], v[182:185], v[198:201], v[34:37]
	v_mfma_f32_16x16x32_bf16 v[34:37], v[186:189], v[202:205], v[34:37]
	v_mfma_f32_16x16x32_bf16 v[18:21], v[182:185], v[228:231], v[18:21]
	v_mfma_f32_16x16x32_bf16 v[18:21], v[186:189], v[232:235], v[18:21]
	v_mfma_f32_16x16x32_bf16 v[2:5], v[182:185], v[236:239], v[2:5]
	v_mfma_f32_16x16x32_bf16 v[2:5], v[186:189], v[240:243], v[2:5]
	v_mfma_f32_16x16x32_bf16 v[6:9], v[174:177], v[236:239], v[6:9]
	v_mfma_f32_16x16x32_bf16 v[6:9], v[178:181], v[240:243], v[6:9]
	v_mfma_f32_16x16x32_bf16 v[22:25], v[174:177], v[228:231], v[22:25]
	v_mfma_f32_16x16x32_bf16 v[22:25], v[178:181], v[232:235], v[22:25]
	v_mfma_f32_16x16x32_bf16 v[38:41], v[174:177], v[198:201], v[38:41]
	v_mfma_f32_16x16x32_bf16 v[38:41], v[178:181], v[202:205], v[38:41]
	v_mfma_f32_16x16x32_bf16 v[54:57], v[174:177], v[190:193], v[54:57]
	v_mfma_f32_16x16x32_bf16 v[54:57], v[178:181], v[194:197], v[54:57]
	s_barrier
	s_setprio 0
	v_add_u32_e32 v170, 0x18000, v140
	v_add_u32_e32 v186, 0x1c000, v140
	ds_read_b128 v[132:135], v170
	ds_read_b128 v[142:145], v170 offset:1024
	ds_read_b128 v[154:157], v170 offset:2048
	ds_read_b128 v[170:173], v170 offset:3072
	ds_read_b128 v[174:177], v186
	ds_read_b128 v[178:181], v186 offset:1024
	ds_read_b128 v[182:185], v186 offset:2048
	ds_read_b128 v[186:189], v186 offset:3072
	s_bitset1_b32 s52, 14
	s_mov_b32 m0, s31
	ds_read_b128 v[190:193], v141 offset:32768
	ds_read_b128 v[194:197], v141 offset:33792
	ds_read_b128 v[198:201], v141 offset:34816
	ds_read_b128 v[202:205], v141 offset:35840
	ds_read_b128 v[228:231], v141 offset:36864
	ds_read_b128 v[232:235], v141 offset:37888
	ds_read_b128 v[236:239], v141 offset:38912
	ds_read_b128 v[240:243], v141 offset:39936
	buffer_load_dwordx4 v136, s[60:63], s52 offen lds
	s_mov_b32 m0, s33
	s_nop 0
	buffer_load_dwordx4 v138, s[60:63], s52 offen lds
	s_waitcnt vmcnt(8)
	s_waitcnt lgkmcnt(0)
	s_setprio 1
	s_barrier
	v_mfma_f32_16x16x32_bf16 v[126:129], v[132:135], v[190:193], v[126:129]
	v_mfma_f32_16x16x32_bf16 v[126:129], v[142:145], v[194:197], v[126:129]
	v_mfma_f32_16x16x32_bf16 v[118:121], v[132:135], v[198:201], v[118:121]
	v_mfma_f32_16x16x32_bf16 v[118:121], v[142:145], v[202:205], v[118:121]
	v_mfma_f32_16x16x32_bf16 v[94:97], v[132:135], v[228:231], v[94:97]
	v_mfma_f32_16x16x32_bf16 v[94:97], v[142:145], v[232:235], v[94:97]
	v_mfma_f32_16x16x32_bf16 v[78:81], v[132:135], v[236:239], v[78:81]
	v_mfma_f32_16x16x32_bf16 v[78:81], v[142:145], v[240:243], v[78:81]
	v_mfma_f32_16x16x32_bf16 v[74:77], v[154:157], v[236:239], v[74:77]
	v_mfma_f32_16x16x32_bf16 v[74:77], v[170:173], v[240:243], v[74:77]
	v_mfma_f32_16x16x32_bf16 v[90:93], v[154:157], v[228:231], v[90:93]
	v_mfma_f32_16x16x32_bf16 v[90:93], v[170:173], v[232:235], v[90:93]
	v_mfma_f32_16x16x32_bf16 v[114:117], v[154:157], v[198:201], v[114:117]
	v_mfma_f32_16x16x32_bf16 v[114:117], v[170:173], v[202:205], v[114:117]
	v_mfma_f32_16x16x32_bf16 v[106:109], v[154:157], v[190:193], v[106:109]
	v_mfma_f32_16x16x32_bf16 v[106:109], v[170:173], v[194:197], v[106:109]
	v_mfma_f32_16x16x32_bf16 v[110:113], v[182:185], v[190:193], v[110:113]
	v_mfma_f32_16x16x32_bf16 v[110:113], v[186:189], v[194:197], v[110:113]
	v_mfma_f32_16x16x32_bf16 v[98:101], v[182:185], v[198:201], v[98:101]
	v_mfma_f32_16x16x32_bf16 v[98:101], v[186:189], v[202:205], v[98:101]
	v_mfma_f32_16x16x32_bf16 v[82:85], v[182:185], v[228:231], v[82:85]
	v_mfma_f32_16x16x32_bf16 v[82:85], v[186:189], v[232:235], v[82:85]
	v_mfma_f32_16x16x32_bf16 v[66:69], v[182:185], v[236:239], v[66:69]
	v_mfma_f32_16x16x32_bf16 v[66:69], v[186:189], v[240:243], v[66:69]
	v_mfma_f32_16x16x32_bf16 v[70:73], v[174:177], v[236:239], v[70:73]
	v_mfma_f32_16x16x32_bf16 v[70:73], v[178:181], v[240:243], v[70:73]
	v_mfma_f32_16x16x32_bf16 v[86:89], v[174:177], v[228:231], v[86:89]
	v_mfma_f32_16x16x32_bf16 v[86:89], v[178:181], v[232:235], v[86:89]
	v_mfma_f32_16x16x32_bf16 v[102:105], v[174:177], v[198:201], v[102:105]
	v_mfma_f32_16x16x32_bf16 v[102:105], v[178:181], v[202:205], v[102:105]
	v_mfma_f32_16x16x32_bf16 v[122:125], v[174:177], v[190:193], v[122:125]
	v_mfma_f32_16x16x32_bf16 v[122:125], v[178:181], v[194:197], v[122:125]
	s_barrier
	s_setprio 0
	s_or_b32 s52, s27, 0x80
	s_mov_b32 m0, s68
	ds_read_b128 v[190:193], v141 offset:49152
	buffer_load_dwordx4 v137, s[44:47], s52 offen lds
	s_add_i32 s27, s27, 0x160080
	s_mov_b32 m0, s69
	ds_read_b128 v[194:197], v141 offset:50176
	buffer_load_dwordx4 v139, s[44:47], s52 offen lds
	s_mov_b32 m0, s72
	ds_read_b128 v[198:201], v141 offset:51200
	buffer_load_dwordx4 v137, s[44:47], s27 offen lds
	s_mov_b32 m0, s73
	ds_read_b128 v[202:205], v141 offset:52224
	buffer_load_dwordx4 v139, s[44:47], s27 offen lds
	s_mov_b32 m0, s70
	ds_read_b128 v[228:231], v141 offset:53248
	buffer_load_dwordx4 v136, s[60:63], s26 offen lds
	s_mov_b32 m0, s71
	ds_read_b128 v[232:235], v141 offset:54272
	buffer_load_dwordx4 v138, s[60:63], s26 offen lds
	ds_read_b128 v[236:239], v141 offset:55296
	ds_read_b128 v[240:243], v141 offset:56320
	s_waitcnt vmcnt(8)
	s_waitcnt lgkmcnt(0)
	s_setprio 1
	s_barrier
	v_mfma_f32_16x16x32_bf16 v[62:65], v[132:135], v[190:193], v[62:65]
	v_mfma_f32_16x16x32_bf16 v[62:65], v[142:145], v[194:197], v[62:65]
	v_mfma_f32_16x16x32_bf16 v[46:49], v[132:135], v[198:201], v[46:49]
	v_mfma_f32_16x16x32_bf16 v[46:49], v[142:145], v[202:205], v[46:49]
	v_mfma_f32_16x16x32_bf16 v[30:33], v[132:135], v[228:231], v[30:33]
	v_mfma_f32_16x16x32_bf16 v[30:33], v[142:145], v[232:235], v[30:33]
	v_mfma_f32_16x16x32_bf16 v[14:17], v[132:135], v[236:239], v[14:17]
	v_mfma_f32_16x16x32_bf16 v[14:17], v[142:145], v[240:243], v[14:17]
	v_mfma_f32_16x16x32_bf16 v[10:13], v[154:157], v[236:239], v[10:13]
	v_mfma_f32_16x16x32_bf16 v[10:13], v[170:173], v[240:243], v[10:13]
	v_mfma_f32_16x16x32_bf16 v[26:29], v[154:157], v[228:231], v[26:29]
	v_mfma_f32_16x16x32_bf16 v[26:29], v[170:173], v[232:235], v[26:29]
	v_mfma_f32_16x16x32_bf16 v[42:45], v[154:157], v[198:201], v[42:45]
	v_mfma_f32_16x16x32_bf16 v[42:45], v[170:173], v[202:205], v[42:45]
	v_mfma_f32_16x16x32_bf16 v[58:61], v[154:157], v[190:193], v[58:61]
	v_mfma_f32_16x16x32_bf16 v[58:61], v[170:173], v[194:197], v[58:61]
	v_mfma_f32_16x16x32_bf16 v[50:53], v[182:185], v[190:193], v[50:53]
	v_mfma_f32_16x16x32_bf16 v[50:53], v[186:189], v[194:197], v[50:53]
	v_mfma_f32_16x16x32_bf16 v[34:37], v[182:185], v[198:201], v[34:37]
	v_mfma_f32_16x16x32_bf16 v[34:37], v[186:189], v[202:205], v[34:37]
	v_mfma_f32_16x16x32_bf16 v[18:21], v[182:185], v[228:231], v[18:21]
	v_mfma_f32_16x16x32_bf16 v[18:21], v[186:189], v[232:235], v[18:21]
	v_mfma_f32_16x16x32_bf16 v[2:5], v[182:185], v[236:239], v[2:5]
	v_mfma_f32_16x16x32_bf16 v[2:5], v[186:189], v[240:243], v[2:5]
	v_mfma_f32_16x16x32_bf16 v[6:9], v[174:177], v[236:239], v[6:9]
	v_mfma_f32_16x16x32_bf16 v[6:9], v[178:181], v[240:243], v[6:9]
	v_mfma_f32_16x16x32_bf16 v[22:25], v[174:177], v[228:231], v[22:25]
	v_mfma_f32_16x16x32_bf16 v[22:25], v[178:181], v[232:235], v[22:25]
	v_mfma_f32_16x16x32_bf16 v[38:41], v[174:177], v[198:201], v[38:41]
	v_mfma_f32_16x16x32_bf16 v[38:41], v[178:181], v[202:205], v[38:41]
	v_mfma_f32_16x16x32_bf16 v[54:57], v[174:177], v[190:193], v[54:57]
	v_mfma_f32_16x16x32_bf16 v[54:57], v[178:181], v[194:197], v[54:57]
	s_barrier
	s_setprio 0
	s_addk_i32 s13, 0x100
	s_add_i32 s22, s22, 2
	s_add_i32 s21, s21, 0x10000
	s_cmpk_gt_u32 s22, 0x55
	s_cbranch_scc0 .LBB0_2156
	s_and_b64 vcc, exec, s[66:67]
	s_cbranch_vccz .LBB0_2159
	s_barrier

.LBB0_2173:
	v_mov_b32_e32 v125, 0
	s_mul_i32 s69, s68, s12
	s_mul_i32 s70, s67, s12
	s_andn2_b64 vcc, exec, s[34:35]
	v_mov_b32_e32 v124, v125
	v_mov_b32_e32 v123, v125
	v_mov_b32_e32 v122, v125
	v_mov_b32_e32 v129, v125
	v_mov_b32_e32 v128, v125
	v_mov_b32_e32 v127, v125
	v_mov_b32_e32 v126, v125
	v_mov_b32_e32 v113, v125
	v_mov_b32_e32 v112, v125
	v_mov_b32_e32 v111, v125
	v_mov_b32_e32 v110, v125
	v_mov_b32_e32 v109, v125
	v_mov_b32_e32 v108, v125
	v_mov_b32_e32 v107, v125
	v_mov_b32_e32 v106, v125
	v_mov_b32_e32 v97, v125
	v_mov_b32_e32 v96, v125
	v_mov_b32_e32 v95, v125
	v_mov_b32_e32 v94, v125
	v_mov_b32_e32 v93, v125
	v_mov_b32_e32 v92, v125
	v_mov_b32_e32 v91, v125
	v_mov_b32_e32 v90, v125
	v_mov_b32_e32 v81, v125
	v_mov_b32_e32 v80, v125
	v_mov_b32_e32 v79, v125
	v_mov_b32_e32 v78, v125
	v_mov_b32_e32 v77, v125
	v_mov_b32_e32 v76, v125
	v_mov_b32_e32 v75, v125
	v_mov_b32_e32 v74, v125
	v_mov_b32_e32 v121, v125
	v_mov_b32_e32 v120, v125
	v_mov_b32_e32 v119, v125
	v_mov_b32_e32 v118, v125
	v_mov_b32_e32 v117, v125
	v_mov_b32_e32 v116, v125
	v_mov_b32_e32 v115, v125
	v_mov_b32_e32 v114, v125
	v_mov_b32_e32 v105, v125
	v_mov_b32_e32 v104, v125
	v_mov_b32_e32 v103, v125
	v_mov_b32_e32 v102, v125
	v_mov_b32_e32 v101, v125
	v_mov_b32_e32 v100, v125
	v_mov_b32_e32 v99, v125
	v_mov_b32_e32 v98, v125
	v_mov_b32_e32 v89, v125
	v_mov_b32_e32 v88, v125
	v_mov_b32_e32 v87, v125
	v_mov_b32_e32 v86, v125
	v_mov_b32_e32 v85, v125
	v_mov_b32_e32 v84, v125
	v_mov_b32_e32 v83, v125
	v_mov_b32_e32 v82, v125
	v_mov_b32_e32 v73, v125
	v_mov_b32_e32 v72, v125
	v_mov_b32_e32 v71, v125
	v_mov_b32_e32 v70, v125
	v_mov_b32_e32 v69, v125
	v_mov_b32_e32 v68, v125
	v_mov_b32_e32 v67, v125
	v_mov_b32_e32 v66, v125
	v_mov_b32_e32 v65, v125
	v_mov_b32_e32 v64, v125
	v_mov_b32_e32 v63, v125
	v_mov_b32_e32 v62, v125
	v_mov_b32_e32 v61, v125
	v_mov_b32_e32 v60, v125
	v_mov_b32_e32 v59, v125
	v_mov_b32_e32 v58, v125
	v_mov_b32_e32 v49, v125
	v_mov_b32_e32 v48, v125
	v_mov_b32_e32 v47, v125
	v_mov_b32_e32 v46, v125
	v_mov_b32_e32 v45, v125
	v_mov_b32_e32 v44, v125
	v_mov_b32_e32 v43, v125
	v_mov_b32_e32 v42, v125
	v_mov_b32_e32 v33, v125
	v_mov_b32_e32 v32, v125
	v_mov_b32_e32 v31, v125
	v_mov_b32_e32 v30, v125
	v_mov_b32_e32 v29, v125
	v_mov_b32_e32 v28, v125
	v_mov_b32_e32 v27, v125
	v_mov_b32_e32 v26, v125
	v_mov_b32_e32 v17, v125
	v_mov_b32_e32 v16, v125
	v_mov_b32_e32 v15, v125
	v_mov_b32_e32 v14, v125
	v_mov_b32_e32 v13, v125
	v_mov_b32_e32 v12, v125
	v_mov_b32_e32 v11, v125
	v_mov_b32_e32 v10, v125
	v_mov_b32_e32 v57, v125
	v_mov_b32_e32 v56, v125
	v_mov_b32_e32 v55, v125
	v_mov_b32_e32 v54, v125
	v_mov_b32_e32 v53, v125
	v_mov_b32_e32 v52, v125
	v_mov_b32_e32 v51, v125
	v_mov_b32_e32 v50, v125
	v_mov_b32_e32 v41, v125
	v_mov_b32_e32 v40, v125
	v_mov_b32_e32 v39, v125
	v_mov_b32_e32 v38, v125
	v_mov_b32_e32 v37, v125
	v_mov_b32_e32 v36, v125
	v_mov_b32_e32 v35, v125
	v_mov_b32_e32 v34, v125
	v_mov_b32_e32 v25, v125
	v_mov_b32_e32 v24, v125
	v_mov_b32_e32 v23, v125
	v_mov_b32_e32 v22, v125
	v_mov_b32_e32 v21, v125
	v_mov_b32_e32 v20, v125
	v_mov_b32_e32 v19, v125
	v_mov_b32_e32 v18, v125
	v_mov_b32_e32 v9, v125
	v_mov_b32_e32 v8, v125
	v_mov_b32_e32 v7, v125
	v_mov_b32_e32 v6, v125
	v_mov_b32_e32 v5, v125
	v_mov_b32_e32 v4, v125
	v_mov_b32_e32 v3, v125
	v_mov_b32_e32 v2, v125
	s_cbranch_vccnz .LBB0_2177
	s_and_b64 s[8:9], s[40:41], exec
	s_cselect_b32 s8, s69, s73
	s_cselect_b32 s9, s70, s82
	s_addk_i32 s73, 0x80
	s_addk_i32 s82, 0x100
	s_mov_b32 s83, 0
	v_add_u32_e32 v144, 0x10000, v134
	ds_read_b128 v[136:139], v144
	ds_read_b128 v[140:143], v144 offset:1024
	ds_read_b128 v[154:157], v144 offset:2048
	ds_read_b128 v[170:173], v144 offset:3072
	v_add_u32_e32 v144, 0x14000, v134
	ds_read_b128 v[174:177], v144
	ds_read_b128 v[178:181], v144 offset:1024
	ds_read_b128 v[182:185], v144 offset:2048
	ds_read_b128 v[186:189], v144 offset:3072
	s_add_i32 s46, s73, 0x80
	s_cmp_eq_u32 s49, s83
	s_cselect_b32 s52, s8, s46
	s_cselect_b32 s85, s9, s82
	s_add_i32 s84, s52, 0x80
	s_add_i32 s46, s2, s73
	s_mov_b32 m0, s64
	ds_read_b128 v[190:193], v135
	ds_read_b128 v[194:197], v135 offset:1024
	ds_read_b128 v[198:201], v135 offset:2048
	ds_read_b128 v[202:205], v135 offset:3072
	ds_read_b128 v[228:231], v135 offset:4096
	ds_read_b128 v[232:235], v135 offset:5120
	ds_read_b128 v[236:239], v135 offset:6144
	ds_read_b128 v[240:243], v135 offset:7168
	buffer_load_dwordx4 v130, s[60:63], s46 offen lds
	s_mov_b32 m0, s65
	s_nop 0
	buffer_load_dwordx4 v132, s[60:63], s46 offen lds
	s_waitcnt vmcnt(8)
	s_waitcnt lgkmcnt(0)
	s_setprio 1
	s_barrier
	v_mfma_f32_16x16x32_bf16 v[122:125], v[136:139], v[190:193], 0
	v_mfma_f32_16x16x32_bf16 v[122:125], v[140:143], v[194:197], v[122:125]
	v_mfma_f32_16x16x32_bf16 v[110:113], v[136:139], v[198:201], 0
	v_mfma_f32_16x16x32_bf16 v[110:113], v[140:143], v[202:205], v[110:113]
	v_mfma_f32_16x16x32_bf16 v[94:97], v[136:139], v[228:231], 0
	v_mfma_f32_16x16x32_bf16 v[94:97], v[140:143], v[232:235], v[94:97]
	v_mfma_f32_16x16x32_bf16 v[78:81], v[136:139], v[236:239], 0
	v_mfma_f32_16x16x32_bf16 v[78:81], v[140:143], v[240:243], v[78:81]
	v_mfma_f32_16x16x32_bf16 v[74:77], v[154:157], v[236:239], 0
	v_mfma_f32_16x16x32_bf16 v[74:77], v[170:173], v[240:243], v[74:77]
	v_mfma_f32_16x16x32_bf16 v[90:93], v[154:157], v[228:231], 0
	v_mfma_f32_16x16x32_bf16 v[90:93], v[170:173], v[232:235], v[90:93]
	v_mfma_f32_16x16x32_bf16 v[106:109], v[154:157], v[198:201], 0
	v_mfma_f32_16x16x32_bf16 v[106:109], v[170:173], v[202:205], v[106:109]
	v_mfma_f32_16x16x32_bf16 v[126:129], v[154:157], v[190:193], 0
	v_mfma_f32_16x16x32_bf16 v[126:129], v[170:173], v[194:197], v[126:129]
	v_mfma_f32_16x16x32_bf16 v[114:117], v[182:185], v[190:193], 0
	v_mfma_f32_16x16x32_bf16 v[114:117], v[186:189], v[194:197], v[114:117]
	v_mfma_f32_16x16x32_bf16 v[98:101], v[182:185], v[198:201], 0
	v_mfma_f32_16x16x32_bf16 v[98:101], v[186:189], v[202:205], v[98:101]
	v_mfma_f32_16x16x32_bf16 v[82:85], v[182:185], v[228:231], 0
	v_mfma_f32_16x16x32_bf16 v[82:85], v[186:189], v[232:235], v[82:85]
	v_mfma_f32_16x16x32_bf16 v[66:69], v[182:185], v[236:239], 0
	v_mfma_f32_16x16x32_bf16 v[66:69], v[186:189], v[240:243], v[66:69]
	v_mfma_f32_16x16x32_bf16 v[70:73], v[174:177], v[236:239], 0
	v_mfma_f32_16x16x32_bf16 v[70:73], v[178:181], v[240:243], v[70:73]
	v_mfma_f32_16x16x32_bf16 v[86:89], v[174:177], v[228:231], 0
	v_mfma_f32_16x16x32_bf16 v[86:89], v[178:181], v[232:235], v[86:89]
	v_mfma_f32_16x16x32_bf16 v[102:105], v[174:177], v[198:201], 0
	v_mfma_f32_16x16x32_bf16 v[102:105], v[178:181], v[202:205], v[102:105]
	v_mfma_f32_16x16x32_bf16 v[118:121], v[174:177], v[190:193], 0
	v_mfma_f32_16x16x32_bf16 v[118:121], v[178:181], v[194:197], v[118:121]
	s_barrier
	s_setprio 0
	s_mov_b32 s46, s62
	s_mov_b32 s47, s63
	s_mov_b32 m0, s14
	ds_read_b128 v[190:193], v135 offset:16384
	buffer_load_dwordx4 v131, s[44:47], s85 offen lds
	s_add_i32 s53, s85, s2
	s_mov_b32 m0, s15
	ds_read_b128 v[194:197], v135 offset:17408
	buffer_load_dwordx4 v133, s[44:47], s85 offen lds
	s_mov_b32 m0, s16
	ds_read_b128 v[198:201], v135 offset:18432
	buffer_load_dwordx4 v131, s[44:47], s53 offen lds
	s_mov_b32 m0, s18
	ds_read_b128 v[202:205], v135 offset:19456
	buffer_load_dwordx4 v133, s[44:47], s53 offen lds
	s_mov_b32 m0, s13
	ds_read_b128 v[228:231], v135 offset:20480
	buffer_load_dwordx4 v130, s[60:63], s52 offen lds
	s_mov_b32 m0, s19
	ds_read_b128 v[232:235], v135 offset:21504
	buffer_load_dwordx4 v132, s[60:63], s52 offen lds
	ds_read_b128 v[236:239], v135 offset:22528
	ds_read_b128 v[240:243], v135 offset:23552
	s_waitcnt vmcnt(8)
	s_waitcnt lgkmcnt(0)
	s_setprio 1
	s_barrier
	v_mfma_f32_16x16x32_bf16 v[62:65], v[136:139], v[190:193], 0
	v_mfma_f32_16x16x32_bf16 v[62:65], v[140:143], v[194:197], v[62:65]
	v_mfma_f32_16x16x32_bf16 v[46:49], v[136:139], v[198:201], 0
	v_mfma_f32_16x16x32_bf16 v[46:49], v[140:143], v[202:205], v[46:49]
	v_mfma_f32_16x16x32_bf16 v[30:33], v[136:139], v[228:231], 0
	v_mfma_f32_16x16x32_bf16 v[30:33], v[140:143], v[232:235], v[30:33]
	v_mfma_f32_16x16x32_bf16 v[14:17], v[136:139], v[236:239], 0
	v_mfma_f32_16x16x32_bf16 v[14:17], v[140:143], v[240:243], v[14:17]
	v_mfma_f32_16x16x32_bf16 v[10:13], v[154:157], v[236:239], 0
	v_mfma_f32_16x16x32_bf16 v[10:13], v[170:173], v[240:243], v[10:13]
	v_mfma_f32_16x16x32_bf16 v[26:29], v[154:157], v[228:231], 0
	v_mfma_f32_16x16x32_bf16 v[26:29], v[170:173], v[232:235], v[26:29]
	v_mfma_f32_16x16x32_bf16 v[42:45], v[154:157], v[198:201], 0
	v_mfma_f32_16x16x32_bf16 v[42:45], v[170:173], v[202:205], v[42:45]
	v_mfma_f32_16x16x32_bf16 v[58:61], v[154:157], v[190:193], 0
	v_mfma_f32_16x16x32_bf16 v[58:61], v[170:173], v[194:197], v[58:61]
	v_mfma_f32_16x16x32_bf16 v[50:53], v[182:185], v[190:193], 0
	v_mfma_f32_16x16x32_bf16 v[50:53], v[186:189], v[194:197], v[50:53]
	v_mfma_f32_16x16x32_bf16 v[34:37], v[182:185], v[198:201], 0
	v_mfma_f32_16x16x32_bf16 v[34:37], v[186:189], v[202:205], v[34:37]
	v_mfma_f32_16x16x32_bf16 v[18:21], v[182:185], v[228:231], 0
	v_mfma_f32_16x16x32_bf16 v[18:21], v[186:189], v[232:235], v[18:21]
	v_mfma_f32_16x16x32_bf16 v[2:5], v[182:185], v[236:239], 0
	v_mfma_f32_16x16x32_bf16 v[2:5], v[186:189], v[240:243], v[2:5]
	v_mfma_f32_16x16x32_bf16 v[6:9], v[174:177], v[236:239], 0
	v_mfma_f32_16x16x32_bf16 v[6:9], v[178:181], v[240:243], v[6:9]
	v_mfma_f32_16x16x32_bf16 v[22:25], v[174:177], v[228:231], 0
	v_mfma_f32_16x16x32_bf16 v[22:25], v[178:181], v[232:235], v[22:25]
	v_mfma_f32_16x16x32_bf16 v[38:41], v[174:177], v[198:201], 0
	v_mfma_f32_16x16x32_bf16 v[38:41], v[178:181], v[202:205], v[38:41]
	v_mfma_f32_16x16x32_bf16 v[54:57], v[174:177], v[190:193], 0
	v_mfma_f32_16x16x32_bf16 v[54:57], v[178:181], v[194:197], v[54:57]
	s_barrier
	s_setprio 0
	v_add_u32_e32 v144, 0x18000, v134
	ds_read_b128 v[136:139], v144
	ds_read_b128 v[140:143], v144 offset:1024
	ds_read_b128 v[154:157], v144 offset:2048
	ds_read_b128 v[170:173], v144 offset:3072
	v_add_u32_e32 v144, 0x1c000, v134
	ds_read_b128 v[174:177], v144
	ds_read_b128 v[178:181], v144 offset:1024
	ds_read_b128 v[182:185], v144 offset:2048
	ds_read_b128 v[186:189], v144 offset:3072
	s_add_i32 s52, s52, s2
	s_mov_b32 m0, s21
	ds_read_b128 v[190:193], v135 offset:32768
	ds_read_b128 v[194:197], v135 offset:33792
	ds_read_b128 v[198:201], v135 offset:34816
	ds_read_b128 v[202:205], v135 offset:35840
	ds_read_b128 v[228:231], v135 offset:36864
	ds_read_b128 v[232:235], v135 offset:37888
	ds_read_b128 v[236:239], v135 offset:38912
	ds_read_b128 v[240:243], v135 offset:39936
	buffer_load_dwordx4 v130, s[60:63], s52 offen lds
	s_mov_b32 m0, s22
	s_nop 0
	buffer_load_dwordx4 v132, s[60:63], s52 offen lds
	s_waitcnt vmcnt(8)
	s_waitcnt lgkmcnt(0)
	s_setprio 1
	s_barrier
	v_mfma_f32_16x16x32_bf16 v[122:125], v[136:139], v[190:193], v[122:125]
	v_mfma_f32_16x16x32_bf16 v[122:125], v[140:143], v[194:197], v[122:125]
	v_mfma_f32_16x16x32_bf16 v[110:113], v[136:139], v[198:201], v[110:113]
	v_mfma_f32_16x16x32_bf16 v[110:113], v[140:143], v[202:205], v[110:113]
	v_mfma_f32_16x16x32_bf16 v[94:97], v[136:139], v[228:231], v[94:97]
	v_mfma_f32_16x16x32_bf16 v[94:97], v[140:143], v[232:235], v[94:97]
	v_mfma_f32_16x16x32_bf16 v[78:81], v[136:139], v[236:239], v[78:81]
	v_mfma_f32_16x16x32_bf16 v[78:81], v[140:143], v[240:243], v[78:81]
	v_mfma_f32_16x16x32_bf16 v[74:77], v[154:157], v[236:239], v[74:77]
	v_mfma_f32_16x16x32_bf16 v[74:77], v[170:173], v[240:243], v[74:77]
	v_mfma_f32_16x16x32_bf16 v[90:93], v[154:157], v[228:231], v[90:93]
	v_mfma_f32_16x16x32_bf16 v[90:93], v[170:173], v[232:235], v[90:93]
	v_mfma_f32_16x16x32_bf16 v[106:109], v[154:157], v[198:201], v[106:109]
	v_mfma_f32_16x16x32_bf16 v[106:109], v[170:173], v[202:205], v[106:109]
	v_mfma_f32_16x16x32_bf16 v[126:129], v[154:157], v[190:193], v[126:129]
	v_mfma_f32_16x16x32_bf16 v[126:129], v[170:173], v[194:197], v[126:129]
	v_mfma_f32_16x16x32_bf16 v[114:117], v[182:185], v[190:193], v[114:117]
	v_mfma_f32_16x16x32_bf16 v[114:117], v[186:189], v[194:197], v[114:117]
	v_mfma_f32_16x16x32_bf16 v[98:101], v[182:185], v[198:201], v[98:101]
	v_mfma_f32_16x16x32_bf16 v[98:101], v[186:189], v[202:205], v[98:101]
	v_mfma_f32_16x16x32_bf16 v[82:85], v[182:185], v[228:231], v[82:85]
	v_mfma_f32_16x16x32_bf16 v[82:85], v[186:189], v[232:235], v[82:85]
	v_mfma_f32_16x16x32_bf16 v[66:69], v[182:185], v[236:239], v[66:69]
	v_mfma_f32_16x16x32_bf16 v[66:69], v[186:189], v[240:243], v[66:69]
	v_mfma_f32_16x16x32_bf16 v[70:73], v[174:177], v[236:239], v[70:73]
	v_mfma_f32_16x16x32_bf16 v[70:73], v[178:181], v[240:243], v[70:73]
	v_mfma_f32_16x16x32_bf16 v[86:89], v[174:177], v[228:231], v[86:89]
	v_mfma_f32_16x16x32_bf16 v[86:89], v[178:181], v[232:235], v[86:89]
	v_mfma_f32_16x16x32_bf16 v[102:105], v[174:177], v[198:201], v[102:105]
	v_mfma_f32_16x16x32_bf16 v[102:105], v[178:181], v[202:205], v[102:105]
	v_mfma_f32_16x16x32_bf16 v[118:121], v[174:177], v[190:193], v[118:121]
	v_mfma_f32_16x16x32_bf16 v[118:121], v[178:181], v[194:197], v[118:121]
	s_barrier
	s_setprio 0
	s_add_i32 s52, s85, 0x80
	s_mov_b32 m0, s33
	ds_read_b128 v[190:193], v135 offset:49152
	buffer_load_dwordx4 v131, s[44:47], s52 offen lds
	s_mov_b32 m0, s36
	ds_read_b128 v[194:197], v135 offset:50176
	buffer_load_dwordx4 v133, s[44:47], s52 offen lds
	s_add_i32 s52, s52, s2
	s_mov_b32 m0, s43
	ds_read_b128 v[198:201], v135 offset:51200
	buffer_load_dwordx4 v131, s[44:47], s52 offen lds
	s_mov_b32 m0, s48
	ds_read_b128 v[202:205], v135 offset:52224
	buffer_load_dwordx4 v133, s[44:47], s52 offen lds
	s_mov_b32 m0, s37
	ds_read_b128 v[228:231], v135 offset:53248
	buffer_load_dwordx4 v130, s[60:63], s84 offen lds
	s_mov_b32 m0, s42
	ds_read_b128 v[232:235], v135 offset:54272
	buffer_load_dwordx4 v132, s[60:63], s84 offen lds
	ds_read_b128 v[236:239], v135 offset:55296
	ds_read_b128 v[240:243], v135 offset:56320
	s_waitcnt vmcnt(8)
	s_waitcnt lgkmcnt(0)
	s_setprio 1
	s_barrier
	v_mfma_f32_16x16x32_bf16 v[62:65], v[136:139], v[190:193], v[62:65]
	v_mfma_f32_16x16x32_bf16 v[62:65], v[140:143], v[194:197], v[62:65]
	v_mfma_f32_16x16x32_bf16 v[46:49], v[136:139], v[198:201], v[46:49]
	v_mfma_f32_16x16x32_bf16 v[46:49], v[140:143], v[202:205], v[46:49]
	v_mfma_f32_16x16x32_bf16 v[30:33], v[136:139], v[228:231], v[30:33]
	v_mfma_f32_16x16x32_bf16 v[30:33], v[140:143], v[232:235], v[30:33]
	v_mfma_f32_16x16x32_bf16 v[14:17], v[136:139], v[236:239], v[14:17]
	v_mfma_f32_16x16x32_bf16 v[14:17], v[140:143], v[240:243], v[14:17]
	v_mfma_f32_16x16x32_bf16 v[10:13], v[154:157], v[236:239], v[10:13]
	v_mfma_f32_16x16x32_bf16 v[10:13], v[170:173], v[240:243], v[10:13]
	v_mfma_f32_16x16x32_bf16 v[26:29], v[154:157], v[228:231], v[26:29]
	v_mfma_f32_16x16x32_bf16 v[26:29], v[170:173], v[232:235], v[26:29]
	v_mfma_f32_16x16x32_bf16 v[42:45], v[154:157], v[198:201], v[42:45]
	v_mfma_f32_16x16x32_bf16 v[42:45], v[170:173], v[202:205], v[42:45]
	v_mfma_f32_16x16x32_bf16 v[58:61], v[154:157], v[190:193], v[58:61]
	v_mfma_f32_16x16x32_bf16 v[58:61], v[170:173], v[194:197], v[58:61]
	v_mfma_f32_16x16x32_bf16 v[50:53], v[182:185], v[190:193], v[50:53]
	v_mfma_f32_16x16x32_bf16 v[50:53], v[186:189], v[194:197], v[50:53]
	v_mfma_f32_16x16x32_bf16 v[34:37], v[182:185], v[198:201], v[34:37]
	v_mfma_f32_16x16x32_bf16 v[34:37], v[186:189], v[202:205], v[34:37]
	v_mfma_f32_16x16x32_bf16 v[18:21], v[182:185], v[228:231], v[18:21]
	v_mfma_f32_16x16x32_bf16 v[18:21], v[186:189], v[232:235], v[18:21]
	v_mfma_f32_16x16x32_bf16 v[2:5], v[182:185], v[236:239], v[2:5]
	v_mfma_f32_16x16x32_bf16 v[2:5], v[186:189], v[240:243], v[2:5]
	v_mfma_f32_16x16x32_bf16 v[6:9], v[174:177], v[236:239], v[6:9]
	v_mfma_f32_16x16x32_bf16 v[6:9], v[178:181], v[240:243], v[6:9]
	v_mfma_f32_16x16x32_bf16 v[22:25], v[174:177], v[228:231], v[22:25]
	v_mfma_f32_16x16x32_bf16 v[22:25], v[178:181], v[232:235], v[22:25]
	v_mfma_f32_16x16x32_bf16 v[38:41], v[174:177], v[198:201], v[38:41]
	v_mfma_f32_16x16x32_bf16 v[38:41], v[178:181], v[202:205], v[38:41]
	v_mfma_f32_16x16x32_bf16 v[54:57], v[174:177], v[190:193], v[54:57]
	v_mfma_f32_16x16x32_bf16 v[54:57], v[178:181], v[194:197], v[54:57]
	s_barrier
	s_setprio 0
	s_add_i32 s83, s83, 2
	s_addk_i32 s73, 0x100
	s_addk_i32 s82, 0x100
	s_cmp_ge_i32 s83, s23
.LBB0_2175:
	v_add_u32_e32 v144, 0x10000, v134
	ds_read_b128 v[136:139], v144
	ds_read_b128 v[140:143], v144 offset:1024
	ds_read_b128 v[154:157], v144 offset:2048
	ds_read_b128 v[170:173], v144 offset:3072
	v_add_u32_e32 v144, 0x14000, v134
	ds_read_b128 v[174:177], v144
	ds_read_b128 v[178:181], v144 offset:1024
	ds_read_b128 v[182:185], v144 offset:2048
	ds_read_b128 v[186:189], v144 offset:3072
	s_add_i32 s46, s73, 0x80
	s_cmp_eq_u32 s49, s83
	s_cselect_b32 s52, s8, s46
	s_cselect_b32 s85, s9, s82
	s_add_i32 s84, s52, 0x80
	s_add_i32 s46, s2, s73
	s_mov_b32 m0, s64
	ds_read_b128 v[190:193], v135
	ds_read_b128 v[194:197], v135 offset:1024
	ds_read_b128 v[198:201], v135 offset:2048
	ds_read_b128 v[202:205], v135 offset:3072
	ds_read_b128 v[228:231], v135 offset:4096
	ds_read_b128 v[232:235], v135 offset:5120
	ds_read_b128 v[236:239], v135 offset:6144
	ds_read_b128 v[240:243], v135 offset:7168
	buffer_load_dwordx4 v130, s[60:63], s46 offen lds
	s_mov_b32 m0, s65
	s_nop 0
	buffer_load_dwordx4 v132, s[60:63], s46 offen lds
	s_waitcnt vmcnt(8)
	s_waitcnt lgkmcnt(0)
	s_setprio 1
	s_barrier
	v_mfma_f32_16x16x32_bf16 v[122:125], v[136:139], v[190:193], v[122:125]
	v_mfma_f32_16x16x32_bf16 v[122:125], v[140:143], v[194:197], v[122:125]
	v_mfma_f32_16x16x32_bf16 v[110:113], v[136:139], v[198:201], v[110:113]
	v_mfma_f32_16x16x32_bf16 v[110:113], v[140:143], v[202:205], v[110:113]
	v_mfma_f32_16x16x32_bf16 v[94:97], v[136:139], v[228:231], v[94:97]
	v_mfma_f32_16x16x32_bf16 v[94:97], v[140:143], v[232:235], v[94:97]
	v_mfma_f32_16x16x32_bf16 v[78:81], v[136:139], v[236:239], v[78:81]
	v_mfma_f32_16x16x32_bf16 v[78:81], v[140:143], v[240:243], v[78:81]
	v_mfma_f32_16x16x32_bf16 v[74:77], v[154:157], v[236:239], v[74:77]
	v_mfma_f32_16x16x32_bf16 v[74:77], v[170:173], v[240:243], v[74:77]
	v_mfma_f32_16x16x32_bf16 v[90:93], v[154:157], v[228:231], v[90:93]
	v_mfma_f32_16x16x32_bf16 v[90:93], v[170:173], v[232:235], v[90:93]
	v_mfma_f32_16x16x32_bf16 v[106:109], v[154:157], v[198:201], v[106:109]
	v_mfma_f32_16x16x32_bf16 v[106:109], v[170:173], v[202:205], v[106:109]
	v_mfma_f32_16x16x32_bf16 v[126:129], v[154:157], v[190:193], v[126:129]
	v_mfma_f32_16x16x32_bf16 v[126:129], v[170:173], v[194:197], v[126:129]
	v_mfma_f32_16x16x32_bf16 v[114:117], v[182:185], v[190:193], v[114:117]
	v_mfma_f32_16x16x32_bf16 v[114:117], v[186:189], v[194:197], v[114:117]
	v_mfma_f32_16x16x32_bf16 v[98:101], v[182:185], v[198:201], v[98:101]
	v_mfma_f32_16x16x32_bf16 v[98:101], v[186:189], v[202:205], v[98:101]
	v_mfma_f32_16x16x32_bf16 v[82:85], v[182:185], v[228:231], v[82:85]
	v_mfma_f32_16x16x32_bf16 v[82:85], v[186:189], v[232:235], v[82:85]
	v_mfma_f32_16x16x32_bf16 v[66:69], v[182:185], v[236:239], v[66:69]
	v_mfma_f32_16x16x32_bf16 v[66:69], v[186:189], v[240:243], v[66:69]
	v_mfma_f32_16x16x32_bf16 v[70:73], v[174:177], v[236:239], v[70:73]
	v_mfma_f32_16x16x32_bf16 v[70:73], v[178:181], v[240:243], v[70:73]
	v_mfma_f32_16x16x32_bf16 v[86:89], v[174:177], v[228:231], v[86:89]
	v_mfma_f32_16x16x32_bf16 v[86:89], v[178:181], v[232:235], v[86:89]
	v_mfma_f32_16x16x32_bf16 v[102:105], v[174:177], v[198:201], v[102:105]
	v_mfma_f32_16x16x32_bf16 v[102:105], v[178:181], v[202:205], v[102:105]
	v_mfma_f32_16x16x32_bf16 v[118:121], v[174:177], v[190:193], v[118:121]
	v_mfma_f32_16x16x32_bf16 v[118:121], v[178:181], v[194:197], v[118:121]
	s_barrier
	s_setprio 0
	s_mov_b32 s46, s62
	s_mov_b32 s47, s63
	s_mov_b32 m0, s14
	ds_read_b128 v[190:193], v135 offset:16384
	buffer_load_dwordx4 v131, s[44:47], s85 offen lds
	s_add_i32 s53, s85, s2
	s_mov_b32 m0, s15
	ds_read_b128 v[194:197], v135 offset:17408
	buffer_load_dwordx4 v133, s[44:47], s85 offen lds
	s_mov_b32 m0, s16
	ds_read_b128 v[198:201], v135 offset:18432
	buffer_load_dwordx4 v131, s[44:47], s53 offen lds
	s_mov_b32 m0, s18
	ds_read_b128 v[202:205], v135 offset:19456
	buffer_load_dwordx4 v133, s[44:47], s53 offen lds
	s_mov_b32 m0, s13
	ds_read_b128 v[228:231], v135 offset:20480
	buffer_load_dwordx4 v130, s[60:63], s52 offen lds
	s_mov_b32 m0, s19
	ds_read_b128 v[232:235], v135 offset:21504
	buffer_load_dwordx4 v132, s[60:63], s52 offen lds
	ds_read_b128 v[236:239], v135 offset:22528
	ds_read_b128 v[240:243], v135 offset:23552
	s_waitcnt vmcnt(8)
	s_waitcnt lgkmcnt(0)
	s_setprio 1
	s_barrier
	v_mfma_f32_16x16x32_bf16 v[62:65], v[136:139], v[190:193], v[62:65]
	v_mfma_f32_16x16x32_bf16 v[62:65], v[140:143], v[194:197], v[62:65]
	v_mfma_f32_16x16x32_bf16 v[46:49], v[136:139], v[198:201], v[46:49]
	v_mfma_f32_16x16x32_bf16 v[46:49], v[140:143], v[202:205], v[46:49]
	v_mfma_f32_16x16x32_bf16 v[30:33], v[136:139], v[228:231], v[30:33]
	v_mfma_f32_16x16x32_bf16 v[30:33], v[140:143], v[232:235], v[30:33]
	v_mfma_f32_16x16x32_bf16 v[14:17], v[136:139], v[236:239], v[14:17]
	v_mfma_f32_16x16x32_bf16 v[14:17], v[140:143], v[240:243], v[14:17]
	v_mfma_f32_16x16x32_bf16 v[10:13], v[154:157], v[236:239], v[10:13]
	v_mfma_f32_16x16x32_bf16 v[10:13], v[170:173], v[240:243], v[10:13]
	v_mfma_f32_16x16x32_bf16 v[26:29], v[154:157], v[228:231], v[26:29]
	v_mfma_f32_16x16x32_bf16 v[26:29], v[170:173], v[232:235], v[26:29]
	v_mfma_f32_16x16x32_bf16 v[42:45], v[154:157], v[198:201], v[42:45]
	v_mfma_f32_16x16x32_bf16 v[42:45], v[170:173], v[202:205], v[42:45]
	v_mfma_f32_16x16x32_bf16 v[58:61], v[154:157], v[190:193], v[58:61]
	v_mfma_f32_16x16x32_bf16 v[58:61], v[170:173], v[194:197], v[58:61]
	v_mfma_f32_16x16x32_bf16 v[50:53], v[182:185], v[190:193], v[50:53]
	v_mfma_f32_16x16x32_bf16 v[50:53], v[186:189], v[194:197], v[50:53]
	v_mfma_f32_16x16x32_bf16 v[34:37], v[182:185], v[198:201], v[34:37]
	v_mfma_f32_16x16x32_bf16 v[34:37], v[186:189], v[202:205], v[34:37]
	v_mfma_f32_16x16x32_bf16 v[18:21], v[182:185], v[228:231], v[18:21]
	v_mfma_f32_16x16x32_bf16 v[18:21], v[186:189], v[232:235], v[18:21]
	v_mfma_f32_16x16x32_bf16 v[2:5], v[182:185], v[236:239], v[2:5]
	v_mfma_f32_16x16x32_bf16 v[2:5], v[186:189], v[240:243], v[2:5]
	v_mfma_f32_16x16x32_bf16 v[6:9], v[174:177], v[236:239], v[6:9]
	v_mfma_f32_16x16x32_bf16 v[6:9], v[178:181], v[240:243], v[6:9]
	v_mfma_f32_16x16x32_bf16 v[22:25], v[174:177], v[228:231], v[22:25]
	v_mfma_f32_16x16x32_bf16 v[22:25], v[178:181], v[232:235], v[22:25]
	v_mfma_f32_16x16x32_bf16 v[38:41], v[174:177], v[198:201], v[38:41]
	v_mfma_f32_16x16x32_bf16 v[38:41], v[178:181], v[202:205], v[38:41]
	v_mfma_f32_16x16x32_bf16 v[54:57], v[174:177], v[190:193], v[54:57]
	v_mfma_f32_16x16x32_bf16 v[54:57], v[178:181], v[194:197], v[54:57]
	s_barrier
	s_setprio 0
	v_add_u32_e32 v144, 0x18000, v134
	ds_read_b128 v[136:139], v144
	ds_read_b128 v[140:143], v144 offset:1024
	ds_read_b128 v[154:157], v144 offset:2048
	ds_read_b128 v[170:173], v144 offset:3072
	v_add_u32_e32 v144, 0x1c000, v134
	ds_read_b128 v[174:177], v144
	ds_read_b128 v[178:181], v144 offset:1024
	ds_read_b128 v[182:185], v144 offset:2048
	ds_read_b128 v[186:189], v144 offset:3072
	s_add_i32 s52, s52, s2
	s_mov_b32 m0, s21
	ds_read_b128 v[190:193], v135 offset:32768
	ds_read_b128 v[194:197], v135 offset:33792
	ds_read_b128 v[198:201], v135 offset:34816
	ds_read_b128 v[202:205], v135 offset:35840
	ds_read_b128 v[228:231], v135 offset:36864
	ds_read_b128 v[232:235], v135 offset:37888
	ds_read_b128 v[236:239], v135 offset:38912
	ds_read_b128 v[240:243], v135 offset:39936
	buffer_load_dwordx4 v130, s[60:63], s52 offen lds
	s_mov_b32 m0, s22
	s_nop 0
	buffer_load_dwordx4 v132, s[60:63], s52 offen lds
	s_waitcnt vmcnt(8)
	s_waitcnt lgkmcnt(0)
	s_setprio 1
	s_barrier
	v_mfma_f32_16x16x32_bf16 v[122:125], v[136:139], v[190:193], v[122:125]
	v_mfma_f32_16x16x32_bf16 v[122:125], v[140:143], v[194:197], v[122:125]
	v_mfma_f32_16x16x32_bf16 v[110:113], v[136:139], v[198:201], v[110:113]
	v_mfma_f32_16x16x32_bf16 v[110:113], v[140:143], v[202:205], v[110:113]
	v_mfma_f32_16x16x32_bf16 v[94:97], v[136:139], v[228:231], v[94:97]
	v_mfma_f32_16x16x32_bf16 v[94:97], v[140:143], v[232:235], v[94:97]
	v_mfma_f32_16x16x32_bf16 v[78:81], v[136:139], v[236:239], v[78:81]
	v_mfma_f32_16x16x32_bf16 v[78:81], v[140:143], v[240:243], v[78:81]
	v_mfma_f32_16x16x32_bf16 v[74:77], v[154:157], v[236:239], v[74:77]
	v_mfma_f32_16x16x32_bf16 v[74:77], v[170:173], v[240:243], v[74:77]
	v_mfma_f32_16x16x32_bf16 v[90:93], v[154:157], v[228:231], v[90:93]
	v_mfma_f32_16x16x32_bf16 v[90:93], v[170:173], v[232:235], v[90:93]
	v_mfma_f32_16x16x32_bf16 v[106:109], v[154:157], v[198:201], v[106:109]
	v_mfma_f32_16x16x32_bf16 v[106:109], v[170:173], v[202:205], v[106:109]
	v_mfma_f32_16x16x32_bf16 v[126:129], v[154:157], v[190:193], v[126:129]
	v_mfma_f32_16x16x32_bf16 v[126:129], v[170:173], v[194:197], v[126:129]
	v_mfma_f32_16x16x32_bf16 v[114:117], v[182:185], v[190:193], v[114:117]
	v_mfma_f32_16x16x32_bf16 v[114:117], v[186:189], v[194:197], v[114:117]
	v_mfma_f32_16x16x32_bf16 v[98:101], v[182:185], v[198:201], v[98:101]
	v_mfma_f32_16x16x32_bf16 v[98:101], v[186:189], v[202:205], v[98:101]
	v_mfma_f32_16x16x32_bf16 v[82:85], v[182:185], v[228:231], v[82:85]
	v_mfma_f32_16x16x32_bf16 v[82:85], v[186:189], v[232:235], v[82:85]
	v_mfma_f32_16x16x32_bf16 v[66:69], v[182:185], v[236:239], v[66:69]
	v_mfma_f32_16x16x32_bf16 v[66:69], v[186:189], v[240:243], v[66:69]
	v_mfma_f32_16x16x32_bf16 v[70:73], v[174:177], v[236:239], v[70:73]
	v_mfma_f32_16x16x32_bf16 v[70:73], v[178:181], v[240:243], v[70:73]
	v_mfma_f32_16x16x32_bf16 v[86:89], v[174:177], v[228:231], v[86:89]
	v_mfma_f32_16x16x32_bf16 v[86:89], v[178:181], v[232:235], v[86:89]
	v_mfma_f32_16x16x32_bf16 v[102:105], v[174:177], v[198:201], v[102:105]
	v_mfma_f32_16x16x32_bf16 v[102:105], v[178:181], v[202:205], v[102:105]
	v_mfma_f32_16x16x32_bf16 v[118:121], v[174:177], v[190:193], v[118:121]
	v_mfma_f32_16x16x32_bf16 v[118:121], v[178:181], v[194:197], v[118:121]
	s_barrier
	s_setprio 0
	s_add_i32 s52, s85, 0x80
	s_mov_b32 m0, s33
	ds_read_b128 v[190:193], v135 offset:49152
	buffer_load_dwordx4 v131, s[44:47], s52 offen lds
	s_mov_b32 m0, s36
	ds_read_b128 v[194:197], v135 offset:50176
	buffer_load_dwordx4 v133, s[44:47], s52 offen lds
	s_add_i32 s52, s52, s2
	s_mov_b32 m0, s43
	ds_read_b128 v[198:201], v135 offset:51200
	buffer_load_dwordx4 v131, s[44:47], s52 offen lds
	s_mov_b32 m0, s48
	ds_read_b128 v[202:205], v135 offset:52224
	buffer_load_dwordx4 v133, s[44:47], s52 offen lds
	s_mov_b32 m0, s37
	ds_read_b128 v[228:231], v135 offset:53248
	buffer_load_dwordx4 v130, s[60:63], s84 offen lds
	s_mov_b32 m0, s42
	ds_read_b128 v[232:235], v135 offset:54272
	buffer_load_dwordx4 v132, s[60:63], s84 offen lds
	ds_read_b128 v[236:239], v135 offset:55296
	ds_read_b128 v[240:243], v135 offset:56320
	s_waitcnt vmcnt(8)
	s_waitcnt lgkmcnt(0)
	s_setprio 1
	s_barrier
	v_mfma_f32_16x16x32_bf16 v[62:65], v[136:139], v[190:193], v[62:65]
	v_mfma_f32_16x16x32_bf16 v[62:65], v[140:143], v[194:197], v[62:65]
	v_mfma_f32_16x16x32_bf16 v[46:49], v[136:139], v[198:201], v[46:49]
	v_mfma_f32_16x16x32_bf16 v[46:49], v[140:143], v[202:205], v[46:49]
	v_mfma_f32_16x16x32_bf16 v[30:33], v[136:139], v[228:231], v[30:33]
	v_mfma_f32_16x16x32_bf16 v[30:33], v[140:143], v[232:235], v[30:33]
	v_mfma_f32_16x16x32_bf16 v[14:17], v[136:139], v[236:239], v[14:17]
	v_mfma_f32_16x16x32_bf16 v[14:17], v[140:143], v[240:243], v[14:17]
	v_mfma_f32_16x16x32_bf16 v[10:13], v[154:157], v[236:239], v[10:13]
	v_mfma_f32_16x16x32_bf16 v[10:13], v[170:173], v[240:243], v[10:13]
	v_mfma_f32_16x16x32_bf16 v[26:29], v[154:157], v[228:231], v[26:29]
	v_mfma_f32_16x16x32_bf16 v[26:29], v[170:173], v[232:235], v[26:29]
	v_mfma_f32_16x16x32_bf16 v[42:45], v[154:157], v[198:201], v[42:45]
	v_mfma_f32_16x16x32_bf16 v[42:45], v[170:173], v[202:205], v[42:45]
	v_mfma_f32_16x16x32_bf16 v[58:61], v[154:157], v[190:193], v[58:61]
	v_mfma_f32_16x16x32_bf16 v[58:61], v[170:173], v[194:197], v[58:61]
	v_mfma_f32_16x16x32_bf16 v[50:53], v[182:185], v[190:193], v[50:53]
	v_mfma_f32_16x16x32_bf16 v[50:53], v[186:189], v[194:197], v[50:53]
	v_mfma_f32_16x16x32_bf16 v[34:37], v[182:185], v[198:201], v[34:37]
	v_mfma_f32_16x16x32_bf16 v[34:37], v[186:189], v[202:205], v[34:37]
	v_mfma_f32_16x16x32_bf16 v[18:21], v[182:185], v[228:231], v[18:21]
	v_mfma_f32_16x16x32_bf16 v[18:21], v[186:189], v[232:235], v[18:21]
	v_mfma_f32_16x16x32_bf16 v[2:5], v[182:185], v[236:239], v[2:5]
	v_mfma_f32_16x16x32_bf16 v[2:5], v[186:189], v[240:243], v[2:5]
	v_mfma_f32_16x16x32_bf16 v[6:9], v[174:177], v[236:239], v[6:9]
	v_mfma_f32_16x16x32_bf16 v[6:9], v[178:181], v[240:243], v[6:9]
	v_mfma_f32_16x16x32_bf16 v[22:25], v[174:177], v[228:231], v[22:25]
	v_mfma_f32_16x16x32_bf16 v[22:25], v[178:181], v[232:235], v[22:25]
	v_mfma_f32_16x16x32_bf16 v[38:41], v[174:177], v[198:201], v[38:41]
	v_mfma_f32_16x16x32_bf16 v[38:41], v[178:181], v[202:205], v[38:41]
	v_mfma_f32_16x16x32_bf16 v[54:57], v[174:177], v[190:193], v[54:57]
	v_mfma_f32_16x16x32_bf16 v[54:57], v[178:181], v[194:197], v[54:57]
	s_barrier
	s_setprio 0
	s_add_i32 s83, s83, 2
	s_addk_i32 s73, 0x100
	s_addk_i32 s82, 0x100
	s_cmp_ge_i32 s83, s23
	s_cbranch_scc0 .LBB0_2175
	v_readlane_b32 s83, v252, 30

.LBB0_2449:
	s_lshl_b32 s73, s72, 20
	s_and_b64 s[8:9], s[40:41], exec
	s_cselect_b32 s8, s73, s13
	s_lshl_b32 s84, s71, 20
	s_and_b64 s[24:25], s[40:41], exec
	s_cselect_b32 s9, s84, s21
	s_add_i32 s13, s13, 0x80080
	s_addk_i32 s21, 0x100
	s_mov_b32 s22, -2
	s_waitcnt lgkmcnt(0)
	v_add_u32_e32 v142, 0x10000, v188
	v_add_u32_e32 v182, 0x14000, v188
	ds_read_b128 v[130:133], v142
	ds_read_b128 v[134:137], v142 offset:1024
	ds_read_b128 v[138:141], v142 offset:2048
	ds_read_b128 v[142:145], v142 offset:3072
	ds_read_b128 v[154:157], v182
	ds_read_b128 v[174:177], v182 offset:1024
	ds_read_b128 v[178:181], v182 offset:2048
	ds_read_b128 v[190:193], v182 offset:3072
	s_add_i32 s24, s13, 0xfff80080
	s_cmp_eq_u32 s22, 28
	s_cselect_b32 s52, s8, s24
	s_cselect_b32 s25, s9, s21
	s_or_b32 s24, s52, 0x80
	s_mov_b32 m0, s68
	ds_read_b128 v[194:197], v189
	ds_read_b128 v[198:201], v189 offset:1024
	ds_read_b128 v[202:205], v189 offset:2048
	ds_read_b128 v[228:231], v189 offset:3072
	ds_read_b128 v[232:235], v189 offset:4096
	ds_read_b128 v[236:239], v189 offset:5120
	ds_read_b128 v[240:243], v189 offset:6144
	ds_read_b128 v[244:247], v189 offset:7168
	buffer_load_dwordx4 v184, s[60:63], s13 offen lds
	s_mov_b32 m0, s70
	s_nop 0
	buffer_load_dwordx4 v186, s[60:63], s13 offen lds
	s_waitcnt vmcnt(8)
	s_waitcnt lgkmcnt(0)
	s_setprio 1
	s_barrier
	v_mfma_f32_16x16x32_bf16 v[126:129], v[130:133], v[194:197], 0
	v_mfma_f32_16x16x32_bf16 v[126:129], v[134:137], v[198:201], v[126:129]
	v_mfma_f32_16x16x32_bf16 v[110:113], v[130:133], v[202:205], 0
	v_mfma_f32_16x16x32_bf16 v[110:113], v[134:137], v[228:231], v[110:113]
	v_mfma_f32_16x16x32_bf16 v[94:97], v[130:133], v[232:235], 0
	v_mfma_f32_16x16x32_bf16 v[94:97], v[134:137], v[236:239], v[94:97]
	v_mfma_f32_16x16x32_bf16 v[78:81], v[130:133], v[240:243], 0
	v_mfma_f32_16x16x32_bf16 v[78:81], v[134:137], v[244:247], v[78:81]
	v_mfma_f32_16x16x32_bf16 v[74:77], v[138:141], v[240:243], 0
	v_mfma_f32_16x16x32_bf16 v[74:77], v[142:145], v[244:247], v[74:77]
	v_mfma_f32_16x16x32_bf16 v[90:93], v[138:141], v[232:235], 0
	v_mfma_f32_16x16x32_bf16 v[90:93], v[142:145], v[236:239], v[90:93]
	v_mfma_f32_16x16x32_bf16 v[106:109], v[138:141], v[202:205], 0
	v_mfma_f32_16x16x32_bf16 v[106:109], v[142:145], v[228:231], v[106:109]
	v_mfma_f32_16x16x32_bf16 v[122:125], v[138:141], v[194:197], 0
	v_mfma_f32_16x16x32_bf16 v[122:125], v[142:145], v[198:201], v[122:125]
	v_mfma_f32_16x16x32_bf16 v[114:117], v[178:181], v[194:197], 0
	v_mfma_f32_16x16x32_bf16 v[114:117], v[190:193], v[198:201], v[114:117]
	v_mfma_f32_16x16x32_bf16 v[98:101], v[178:181], v[202:205], 0
	v_mfma_f32_16x16x32_bf16 v[98:101], v[190:193], v[228:231], v[98:101]
	v_mfma_f32_16x16x32_bf16 v[82:85], v[178:181], v[232:235], 0
	v_mfma_f32_16x16x32_bf16 v[82:85], v[190:193], v[236:239], v[82:85]
	v_mfma_f32_16x16x32_bf16 v[66:69], v[178:181], v[240:243], 0
	v_mfma_f32_16x16x32_bf16 v[66:69], v[190:193], v[244:247], v[66:69]
	v_mfma_f32_16x16x32_bf16 v[70:73], v[154:157], v[240:243], 0
	v_mfma_f32_16x16x32_bf16 v[70:73], v[174:177], v[244:247], v[70:73]
	v_mfma_f32_16x16x32_bf16 v[86:89], v[154:157], v[232:235], 0
	v_mfma_f32_16x16x32_bf16 v[86:89], v[174:177], v[236:239], v[86:89]
	v_mfma_f32_16x16x32_bf16 v[102:105], v[154:157], v[202:205], 0
	v_mfma_f32_16x16x32_bf16 v[102:105], v[174:177], v[228:231], v[102:105]
	v_mfma_f32_16x16x32_bf16 v[118:121], v[154:157], v[194:197], 0
	v_mfma_f32_16x16x32_bf16 v[118:121], v[174:177], v[198:201], v[118:121]
	s_barrier
	s_setprio 0
	s_mov_b32 s46, s62
	s_mov_b32 s47, s63
	s_mov_b32 m0, s16
	ds_read_b128 v[194:197], v189 offset:16384
	buffer_load_dwordx4 v185, s[44:47], s25 offen lds
	s_add_i32 s53, s25, 0x80000
	s_mov_b32 m0, s18
	ds_read_b128 v[198:201], v189 offset:17408
	buffer_load_dwordx4 v187, s[44:47], s25 offen lds
	s_mov_b32 m0, s19
	ds_read_b128 v[202:205], v189 offset:18432
	buffer_load_dwordx4 v185, s[44:47], s53 offen lds
	s_mov_b32 m0, s23
	ds_read_b128 v[228:231], v189 offset:19456
	buffer_load_dwordx4 v187, s[44:47], s53 offen lds
	s_mov_b32 m0, s15
	ds_read_b128 v[232:235], v189 offset:20480
	buffer_load_dwordx4 v184, s[60:63], s52 offen lds
	s_mov_b32 m0, s26
	ds_read_b128 v[236:239], v189 offset:21504
	buffer_load_dwordx4 v186, s[60:63], s52 offen lds
	ds_read_b128 v[240:243], v189 offset:22528
	ds_read_b128 v[244:247], v189 offset:23552
	s_waitcnt vmcnt(8)
	s_waitcnt lgkmcnt(0)
	s_setprio 1
	s_barrier
	v_mfma_f32_16x16x32_bf16 v[62:65], v[130:133], v[194:197], 0
	v_mfma_f32_16x16x32_bf16 v[62:65], v[134:137], v[198:201], v[62:65]
	v_mfma_f32_16x16x32_bf16 v[46:49], v[130:133], v[202:205], 0
	v_mfma_f32_16x16x32_bf16 v[46:49], v[134:137], v[228:231], v[46:49]
	v_mfma_f32_16x16x32_bf16 v[30:33], v[130:133], v[232:235], 0
	v_mfma_f32_16x16x32_bf16 v[30:33], v[134:137], v[236:239], v[30:33]
	v_mfma_f32_16x16x32_bf16 v[14:17], v[130:133], v[240:243], 0
	v_mfma_f32_16x16x32_bf16 v[14:17], v[134:137], v[244:247], v[14:17]
	v_mfma_f32_16x16x32_bf16 v[10:13], v[138:141], v[240:243], 0
	v_mfma_f32_16x16x32_bf16 v[10:13], v[142:145], v[244:247], v[10:13]
	v_mfma_f32_16x16x32_bf16 v[26:29], v[138:141], v[232:235], 0
	v_mfma_f32_16x16x32_bf16 v[26:29], v[142:145], v[236:239], v[26:29]
	v_mfma_f32_16x16x32_bf16 v[42:45], v[138:141], v[202:205], 0
	v_mfma_f32_16x16x32_bf16 v[42:45], v[142:145], v[228:231], v[42:45]
	v_mfma_f32_16x16x32_bf16 v[58:61], v[138:141], v[194:197], 0
	v_mfma_f32_16x16x32_bf16 v[58:61], v[142:145], v[198:201], v[58:61]
	v_mfma_f32_16x16x32_bf16 v[50:53], v[178:181], v[194:197], 0
	v_mfma_f32_16x16x32_bf16 v[50:53], v[190:193], v[198:201], v[50:53]
	v_mfma_f32_16x16x32_bf16 v[34:37], v[178:181], v[202:205], 0
	v_mfma_f32_16x16x32_bf16 v[34:37], v[190:193], v[228:231], v[34:37]
	v_mfma_f32_16x16x32_bf16 v[18:21], v[178:181], v[232:235], 0
	v_mfma_f32_16x16x32_bf16 v[18:21], v[190:193], v[236:239], v[18:21]
	v_mfma_f32_16x16x32_bf16 v[2:5], v[178:181], v[240:243], 0
	v_mfma_f32_16x16x32_bf16 v[2:5], v[190:193], v[244:247], v[2:5]
	v_mfma_f32_16x16x32_bf16 v[6:9], v[154:157], v[240:243], 0
	v_mfma_f32_16x16x32_bf16 v[6:9], v[174:177], v[244:247], v[6:9]
	v_mfma_f32_16x16x32_bf16 v[22:25], v[154:157], v[232:235], 0
	v_mfma_f32_16x16x32_bf16 v[22:25], v[174:177], v[236:239], v[22:25]
	v_mfma_f32_16x16x32_bf16 v[38:41], v[154:157], v[202:205], 0
	v_mfma_f32_16x16x32_bf16 v[38:41], v[174:177], v[228:231], v[38:41]
	v_mfma_f32_16x16x32_bf16 v[54:57], v[154:157], v[194:197], 0
	v_mfma_f32_16x16x32_bf16 v[54:57], v[174:177], v[198:201], v[54:57]
	s_barrier
	s_setprio 0
	v_add_u32_e32 v142, 0x18000, v188
	v_add_u32_e32 v182, 0x1c000, v188
	ds_read_b128 v[130:133], v142
	ds_read_b128 v[134:137], v142 offset:1024
	ds_read_b128 v[138:141], v142 offset:2048
	ds_read_b128 v[142:145], v142 offset:3072
	ds_read_b128 v[154:157], v182
	ds_read_b128 v[174:177], v182 offset:1024
	ds_read_b128 v[178:181], v182 offset:2048
	ds_read_b128 v[190:193], v182 offset:3072
	s_add_i32 s52, s52, 0x80000
	s_mov_b32 m0, s27
	ds_read_b128 v[194:197], v189 offset:32768
	ds_read_b128 v[198:201], v189 offset:33792
	ds_read_b128 v[202:205], v189 offset:34816
	ds_read_b128 v[228:231], v189 offset:35840
	ds_read_b128 v[232:235], v189 offset:36864
	ds_read_b128 v[236:239], v189 offset:37888
	ds_read_b128 v[240:243], v189 offset:38912
	ds_read_b128 v[244:247], v189 offset:39936
	buffer_load_dwordx4 v184, s[60:63], s52 offen lds
	s_mov_b32 m0, s30
	s_nop 0
	buffer_load_dwordx4 v186, s[60:63], s52 offen lds
	s_waitcnt vmcnt(8)
	s_waitcnt lgkmcnt(0)
	s_setprio 1
	s_barrier
	v_mfma_f32_16x16x32_bf16 v[126:129], v[130:133], v[194:197], v[126:129]
	v_mfma_f32_16x16x32_bf16 v[126:129], v[134:137], v[198:201], v[126:129]
	v_mfma_f32_16x16x32_bf16 v[110:113], v[130:133], v[202:205], v[110:113]
	v_mfma_f32_16x16x32_bf16 v[110:113], v[134:137], v[228:231], v[110:113]
	v_mfma_f32_16x16x32_bf16 v[94:97], v[130:133], v[232:235], v[94:97]
	v_mfma_f32_16x16x32_bf16 v[94:97], v[134:137], v[236:239], v[94:97]
	v_mfma_f32_16x16x32_bf16 v[78:81], v[130:133], v[240:243], v[78:81]
	v_mfma_f32_16x16x32_bf16 v[78:81], v[134:137], v[244:247], v[78:81]
	v_mfma_f32_16x16x32_bf16 v[74:77], v[138:141], v[240:243], v[74:77]
	v_mfma_f32_16x16x32_bf16 v[74:77], v[142:145], v[244:247], v[74:77]
	v_mfma_f32_16x16x32_bf16 v[90:93], v[138:141], v[232:235], v[90:93]
	v_mfma_f32_16x16x32_bf16 v[90:93], v[142:145], v[236:239], v[90:93]
	v_mfma_f32_16x16x32_bf16 v[106:109], v[138:141], v[202:205], v[106:109]
	v_mfma_f32_16x16x32_bf16 v[106:109], v[142:145], v[228:231], v[106:109]
	v_mfma_f32_16x16x32_bf16 v[122:125], v[138:141], v[194:197], v[122:125]
	v_mfma_f32_16x16x32_bf16 v[122:125], v[142:145], v[198:201], v[122:125]
	v_mfma_f32_16x16x32_bf16 v[114:117], v[178:181], v[194:197], v[114:117]
	v_mfma_f32_16x16x32_bf16 v[114:117], v[190:193], v[198:201], v[114:117]
	v_mfma_f32_16x16x32_bf16 v[98:101], v[178:181], v[202:205], v[98:101]
	v_mfma_f32_16x16x32_bf16 v[98:101], v[190:193], v[228:231], v[98:101]
	v_mfma_f32_16x16x32_bf16 v[82:85], v[178:181], v[232:235], v[82:85]
	v_mfma_f32_16x16x32_bf16 v[82:85], v[190:193], v[236:239], v[82:85]
	v_mfma_f32_16x16x32_bf16 v[66:69], v[178:181], v[240:243], v[66:69]
	v_mfma_f32_16x16x32_bf16 v[66:69], v[190:193], v[244:247], v[66:69]
	v_mfma_f32_16x16x32_bf16 v[70:73], v[154:157], v[240:243], v[70:73]
	v_mfma_f32_16x16x32_bf16 v[70:73], v[174:177], v[244:247], v[70:73]
	v_mfma_f32_16x16x32_bf16 v[86:89], v[154:157], v[232:235], v[86:89]
	v_mfma_f32_16x16x32_bf16 v[86:89], v[174:177], v[236:239], v[86:89]
	v_mfma_f32_16x16x32_bf16 v[102:105], v[154:157], v[202:205], v[102:105]
	v_mfma_f32_16x16x32_bf16 v[102:105], v[174:177], v[228:231], v[102:105]
	v_mfma_f32_16x16x32_bf16 v[118:121], v[154:157], v[194:197], v[118:121]
	v_mfma_f32_16x16x32_bf16 v[118:121], v[174:177], v[198:201], v[118:121]
	s_barrier
	s_setprio 0
	s_or_b32 s52, s25, 0x80
	s_mov_b32 m0, s36
	ds_read_b128 v[194:197], v189 offset:49152
	buffer_load_dwordx4 v185, s[44:47], s52 offen lds
	s_add_i32 s25, s25, 0x80080
	s_mov_b32 m0, s37
	ds_read_b128 v[198:201], v189 offset:50176
	buffer_load_dwordx4 v187, s[44:47], s52 offen lds
	s_mov_b32 m0, s66
	ds_read_b128 v[202:205], v189 offset:51200
	buffer_load_dwordx4 v185, s[44:47], s25 offen lds
	s_mov_b32 m0, s67
	ds_read_b128 v[228:231], v189 offset:52224
	buffer_load_dwordx4 v187, s[44:47], s25 offen lds
	s_mov_b32 m0, s48
	ds_read_b128 v[232:235], v189 offset:53248
	buffer_load_dwordx4 v184, s[60:63], s24 offen lds
	s_mov_b32 m0, s49
	ds_read_b128 v[236:239], v189 offset:54272
	buffer_load_dwordx4 v186, s[60:63], s24 offen lds
	ds_read_b128 v[240:243], v189 offset:55296
	ds_read_b128 v[244:247], v189 offset:56320
	s_waitcnt vmcnt(8)
	s_waitcnt lgkmcnt(0)
	s_setprio 1
	s_barrier
	v_mfma_f32_16x16x32_bf16 v[62:65], v[130:133], v[194:197], v[62:65]
	v_mfma_f32_16x16x32_bf16 v[62:65], v[134:137], v[198:201], v[62:65]
	v_mfma_f32_16x16x32_bf16 v[46:49], v[130:133], v[202:205], v[46:49]
	v_mfma_f32_16x16x32_bf16 v[46:49], v[134:137], v[228:231], v[46:49]
	v_mfma_f32_16x16x32_bf16 v[30:33], v[130:133], v[232:235], v[30:33]
	v_mfma_f32_16x16x32_bf16 v[30:33], v[134:137], v[236:239], v[30:33]
	v_mfma_f32_16x16x32_bf16 v[14:17], v[130:133], v[240:243], v[14:17]
	v_mfma_f32_16x16x32_bf16 v[14:17], v[134:137], v[244:247], v[14:17]
	v_mfma_f32_16x16x32_bf16 v[10:13], v[138:141], v[240:243], v[10:13]
	v_mfma_f32_16x16x32_bf16 v[10:13], v[142:145], v[244:247], v[10:13]
	v_mfma_f32_16x16x32_bf16 v[26:29], v[138:141], v[232:235], v[26:29]
	v_mfma_f32_16x16x32_bf16 v[26:29], v[142:145], v[236:239], v[26:29]
	v_mfma_f32_16x16x32_bf16 v[42:45], v[138:141], v[202:205], v[42:45]
	v_mfma_f32_16x16x32_bf16 v[42:45], v[142:145], v[228:231], v[42:45]
	v_mfma_f32_16x16x32_bf16 v[58:61], v[138:141], v[194:197], v[58:61]
	v_mfma_f32_16x16x32_bf16 v[58:61], v[142:145], v[198:201], v[58:61]
	v_mfma_f32_16x16x32_bf16 v[50:53], v[178:181], v[194:197], v[50:53]
	v_mfma_f32_16x16x32_bf16 v[50:53], v[190:193], v[198:201], v[50:53]
	v_mfma_f32_16x16x32_bf16 v[34:37], v[178:181], v[202:205], v[34:37]
	v_mfma_f32_16x16x32_bf16 v[34:37], v[190:193], v[228:231], v[34:37]
	v_mfma_f32_16x16x32_bf16 v[18:21], v[178:181], v[232:235], v[18:21]
	v_mfma_f32_16x16x32_bf16 v[18:21], v[190:193], v[236:239], v[18:21]
	v_mfma_f32_16x16x32_bf16 v[2:5], v[178:181], v[240:243], v[2:5]
	v_mfma_f32_16x16x32_bf16 v[2:5], v[190:193], v[244:247], v[2:5]
	v_mfma_f32_16x16x32_bf16 v[6:9], v[154:157], v[240:243], v[6:9]
	v_mfma_f32_16x16x32_bf16 v[6:9], v[174:177], v[244:247], v[6:9]
	v_mfma_f32_16x16x32_bf16 v[22:25], v[154:157], v[232:235], v[22:25]
	v_mfma_f32_16x16x32_bf16 v[22:25], v[174:177], v[236:239], v[22:25]
	v_mfma_f32_16x16x32_bf16 v[38:41], v[154:157], v[202:205], v[38:41]
	v_mfma_f32_16x16x32_bf16 v[38:41], v[174:177], v[228:231], v[38:41]
	v_mfma_f32_16x16x32_bf16 v[54:57], v[154:157], v[194:197], v[54:57]
	v_mfma_f32_16x16x32_bf16 v[54:57], v[174:177], v[198:201], v[54:57]
	s_barrier
	s_setprio 0
	s_add_i32 s22, s22, 2
	s_addk_i32 s13, 0x100
	s_addk_i32 s21, 0x100
	s_cmp_gt_u32 s22, 29
.LBB0_2450:
	v_add_u32_e32 v142, 0x10000, v188
	v_add_u32_e32 v182, 0x14000, v188
	ds_read_b128 v[130:133], v142
	ds_read_b128 v[134:137], v142 offset:1024
	ds_read_b128 v[138:141], v142 offset:2048
	ds_read_b128 v[142:145], v142 offset:3072
	ds_read_b128 v[154:157], v182
	ds_read_b128 v[174:177], v182 offset:1024
	ds_read_b128 v[178:181], v182 offset:2048
	ds_read_b128 v[190:193], v182 offset:3072
	s_add_i32 s24, s13, 0xfff80080
	s_cmp_eq_u32 s22, 28
	s_cselect_b32 s52, s8, s24
	s_cselect_b32 s25, s9, s21
	s_or_b32 s24, s52, 0x80
	s_mov_b32 m0, s68
	ds_read_b128 v[194:197], v189
	ds_read_b128 v[198:201], v189 offset:1024
	ds_read_b128 v[202:205], v189 offset:2048
	ds_read_b128 v[228:231], v189 offset:3072
	ds_read_b128 v[232:235], v189 offset:4096
	ds_read_b128 v[236:239], v189 offset:5120
	ds_read_b128 v[240:243], v189 offset:6144
	ds_read_b128 v[244:247], v189 offset:7168
	buffer_load_dwordx4 v184, s[60:63], s13 offen lds
	s_mov_b32 m0, s70
	s_nop 0
	buffer_load_dwordx4 v186, s[60:63], s13 offen lds
	s_waitcnt vmcnt(8)
	s_waitcnt lgkmcnt(0)
	s_setprio 1
	s_barrier
	v_mfma_f32_16x16x32_bf16 v[126:129], v[130:133], v[194:197], v[126:129]
	v_mfma_f32_16x16x32_bf16 v[126:129], v[134:137], v[198:201], v[126:129]
	v_mfma_f32_16x16x32_bf16 v[110:113], v[130:133], v[202:205], v[110:113]
	v_mfma_f32_16x16x32_bf16 v[110:113], v[134:137], v[228:231], v[110:113]
	v_mfma_f32_16x16x32_bf16 v[94:97], v[130:133], v[232:235], v[94:97]
	v_mfma_f32_16x16x32_bf16 v[94:97], v[134:137], v[236:239], v[94:97]
	v_mfma_f32_16x16x32_bf16 v[78:81], v[130:133], v[240:243], v[78:81]
	v_mfma_f32_16x16x32_bf16 v[78:81], v[134:137], v[244:247], v[78:81]
	v_mfma_f32_16x16x32_bf16 v[74:77], v[138:141], v[240:243], v[74:77]
	v_mfma_f32_16x16x32_bf16 v[74:77], v[142:145], v[244:247], v[74:77]
	v_mfma_f32_16x16x32_bf16 v[90:93], v[138:141], v[232:235], v[90:93]
	v_mfma_f32_16x16x32_bf16 v[90:93], v[142:145], v[236:239], v[90:93]
	v_mfma_f32_16x16x32_bf16 v[106:109], v[138:141], v[202:205], v[106:109]
	v_mfma_f32_16x16x32_bf16 v[106:109], v[142:145], v[228:231], v[106:109]
	v_mfma_f32_16x16x32_bf16 v[122:125], v[138:141], v[194:197], v[122:125]
	v_mfma_f32_16x16x32_bf16 v[122:125], v[142:145], v[198:201], v[122:125]
	v_mfma_f32_16x16x32_bf16 v[114:117], v[178:181], v[194:197], v[114:117]
	v_mfma_f32_16x16x32_bf16 v[114:117], v[190:193], v[198:201], v[114:117]
	v_mfma_f32_16x16x32_bf16 v[98:101], v[178:181], v[202:205], v[98:101]
	v_mfma_f32_16x16x32_bf16 v[98:101], v[190:193], v[228:231], v[98:101]
	v_mfma_f32_16x16x32_bf16 v[82:85], v[178:181], v[232:235], v[82:85]
	v_mfma_f32_16x16x32_bf16 v[82:85], v[190:193], v[236:239], v[82:85]
	v_mfma_f32_16x16x32_bf16 v[66:69], v[178:181], v[240:243], v[66:69]
	v_mfma_f32_16x16x32_bf16 v[66:69], v[190:193], v[244:247], v[66:69]
	v_mfma_f32_16x16x32_bf16 v[70:73], v[154:157], v[240:243], v[70:73]
	v_mfma_f32_16x16x32_bf16 v[70:73], v[174:177], v[244:247], v[70:73]
	v_mfma_f32_16x16x32_bf16 v[86:89], v[154:157], v[232:235], v[86:89]
	v_mfma_f32_16x16x32_bf16 v[86:89], v[174:177], v[236:239], v[86:89]
	v_mfma_f32_16x16x32_bf16 v[102:105], v[154:157], v[202:205], v[102:105]
	v_mfma_f32_16x16x32_bf16 v[102:105], v[174:177], v[228:231], v[102:105]
	v_mfma_f32_16x16x32_bf16 v[118:121], v[154:157], v[194:197], v[118:121]
	v_mfma_f32_16x16x32_bf16 v[118:121], v[174:177], v[198:201], v[118:121]
	s_barrier
	s_setprio 0
	s_mov_b32 s46, s62
	s_mov_b32 s47, s63
	s_mov_b32 m0, s16
	ds_read_b128 v[194:197], v189 offset:16384
	buffer_load_dwordx4 v185, s[44:47], s25 offen lds
	s_add_i32 s53, s25, 0x80000
	s_mov_b32 m0, s18
	ds_read_b128 v[198:201], v189 offset:17408
	buffer_load_dwordx4 v187, s[44:47], s25 offen lds
	s_mov_b32 m0, s19
	ds_read_b128 v[202:205], v189 offset:18432
	buffer_load_dwordx4 v185, s[44:47], s53 offen lds
	s_mov_b32 m0, s23
	ds_read_b128 v[228:231], v189 offset:19456
	buffer_load_dwordx4 v187, s[44:47], s53 offen lds
	s_mov_b32 m0, s15
	ds_read_b128 v[232:235], v189 offset:20480
	buffer_load_dwordx4 v184, s[60:63], s52 offen lds
	s_mov_b32 m0, s26
	ds_read_b128 v[236:239], v189 offset:21504
	buffer_load_dwordx4 v186, s[60:63], s52 offen lds
	ds_read_b128 v[240:243], v189 offset:22528
	ds_read_b128 v[244:247], v189 offset:23552
	s_waitcnt vmcnt(8)
	s_waitcnt lgkmcnt(0)
	s_setprio 1
	s_barrier
	v_mfma_f32_16x16x32_bf16 v[62:65], v[130:133], v[194:197], v[62:65]
	v_mfma_f32_16x16x32_bf16 v[62:65], v[134:137], v[198:201], v[62:65]
	v_mfma_f32_16x16x32_bf16 v[46:49], v[130:133], v[202:205], v[46:49]
	v_mfma_f32_16x16x32_bf16 v[46:49], v[134:137], v[228:231], v[46:49]
	v_mfma_f32_16x16x32_bf16 v[30:33], v[130:133], v[232:235], v[30:33]
	v_mfma_f32_16x16x32_bf16 v[30:33], v[134:137], v[236:239], v[30:33]
	v_mfma_f32_16x16x32_bf16 v[14:17], v[130:133], v[240:243], v[14:17]
	v_mfma_f32_16x16x32_bf16 v[14:17], v[134:137], v[244:247], v[14:17]
	v_mfma_f32_16x16x32_bf16 v[10:13], v[138:141], v[240:243], v[10:13]
	v_mfma_f32_16x16x32_bf16 v[10:13], v[142:145], v[244:247], v[10:13]
	v_mfma_f32_16x16x32_bf16 v[26:29], v[138:141], v[232:235], v[26:29]
	v_mfma_f32_16x16x32_bf16 v[26:29], v[142:145], v[236:239], v[26:29]
	v_mfma_f32_16x16x32_bf16 v[42:45], v[138:141], v[202:205], v[42:45]
	v_mfma_f32_16x16x32_bf16 v[42:45], v[142:145], v[228:231], v[42:45]
	v_mfma_f32_16x16x32_bf16 v[58:61], v[138:141], v[194:197], v[58:61]
	v_mfma_f32_16x16x32_bf16 v[58:61], v[142:145], v[198:201], v[58:61]
	v_mfma_f32_16x16x32_bf16 v[50:53], v[178:181], v[194:197], v[50:53]
	v_mfma_f32_16x16x32_bf16 v[50:53], v[190:193], v[198:201], v[50:53]
	v_mfma_f32_16x16x32_bf16 v[34:37], v[178:181], v[202:205], v[34:37]
	v_mfma_f32_16x16x32_bf16 v[34:37], v[190:193], v[228:231], v[34:37]
	v_mfma_f32_16x16x32_bf16 v[18:21], v[178:181], v[232:235], v[18:21]
	v_mfma_f32_16x16x32_bf16 v[18:21], v[190:193], v[236:239], v[18:21]
	v_mfma_f32_16x16x32_bf16 v[2:5], v[178:181], v[240:243], v[2:5]
	v_mfma_f32_16x16x32_bf16 v[2:5], v[190:193], v[244:247], v[2:5]
	v_mfma_f32_16x16x32_bf16 v[6:9], v[154:157], v[240:243], v[6:9]
	v_mfma_f32_16x16x32_bf16 v[6:9], v[174:177], v[244:247], v[6:9]
	v_mfma_f32_16x16x32_bf16 v[22:25], v[154:157], v[232:235], v[22:25]
	v_mfma_f32_16x16x32_bf16 v[22:25], v[174:177], v[236:239], v[22:25]
	v_mfma_f32_16x16x32_bf16 v[38:41], v[154:157], v[202:205], v[38:41]
	v_mfma_f32_16x16x32_bf16 v[38:41], v[174:177], v[228:231], v[38:41]
	v_mfma_f32_16x16x32_bf16 v[54:57], v[154:157], v[194:197], v[54:57]
	v_mfma_f32_16x16x32_bf16 v[54:57], v[174:177], v[198:201], v[54:57]
	s_barrier
	s_setprio 0
	v_add_u32_e32 v142, 0x18000, v188
	v_add_u32_e32 v182, 0x1c000, v188
	ds_read_b128 v[130:133], v142
	ds_read_b128 v[134:137], v142 offset:1024
	ds_read_b128 v[138:141], v142 offset:2048
	ds_read_b128 v[142:145], v142 offset:3072
	ds_read_b128 v[154:157], v182
	ds_read_b128 v[174:177], v182 offset:1024
	ds_read_b128 v[178:181], v182 offset:2048
	ds_read_b128 v[190:193], v182 offset:3072
	s_add_i32 s52, s52, 0x80000
	s_mov_b32 m0, s27
	ds_read_b128 v[194:197], v189 offset:32768
	ds_read_b128 v[198:201], v189 offset:33792
	ds_read_b128 v[202:205], v189 offset:34816
	ds_read_b128 v[228:231], v189 offset:35840
	ds_read_b128 v[232:235], v189 offset:36864
	ds_read_b128 v[236:239], v189 offset:37888
	ds_read_b128 v[240:243], v189 offset:38912
	ds_read_b128 v[244:247], v189 offset:39936
	buffer_load_dwordx4 v184, s[60:63], s52 offen lds
	s_mov_b32 m0, s30
	s_nop 0
	buffer_load_dwordx4 v186, s[60:63], s52 offen lds
	s_waitcnt vmcnt(8)
	s_waitcnt lgkmcnt(0)
	s_setprio 1
	s_barrier
	v_mfma_f32_16x16x32_bf16 v[126:129], v[130:133], v[194:197], v[126:129]
	v_mfma_f32_16x16x32_bf16 v[126:129], v[134:137], v[198:201], v[126:129]
	v_mfma_f32_16x16x32_bf16 v[110:113], v[130:133], v[202:205], v[110:113]
	v_mfma_f32_16x16x32_bf16 v[110:113], v[134:137], v[228:231], v[110:113]
	v_mfma_f32_16x16x32_bf16 v[94:97], v[130:133], v[232:235], v[94:97]
	v_mfma_f32_16x16x32_bf16 v[94:97], v[134:137], v[236:239], v[94:97]
	v_mfma_f32_16x16x32_bf16 v[78:81], v[130:133], v[240:243], v[78:81]
	v_mfma_f32_16x16x32_bf16 v[78:81], v[134:137], v[244:247], v[78:81]
	v_mfma_f32_16x16x32_bf16 v[74:77], v[138:141], v[240:243], v[74:77]
	v_mfma_f32_16x16x32_bf16 v[74:77], v[142:145], v[244:247], v[74:77]
	v_mfma_f32_16x16x32_bf16 v[90:93], v[138:141], v[232:235], v[90:93]
	v_mfma_f32_16x16x32_bf16 v[90:93], v[142:145], v[236:239], v[90:93]
	v_mfma_f32_16x16x32_bf16 v[106:109], v[138:141], v[202:205], v[106:109]
	v_mfma_f32_16x16x32_bf16 v[106:109], v[142:145], v[228:231], v[106:109]
	v_mfma_f32_16x16x32_bf16 v[122:125], v[138:141], v[194:197], v[122:125]
	v_mfma_f32_16x16x32_bf16 v[122:125], v[142:145], v[198:201], v[122:125]
	v_mfma_f32_16x16x32_bf16 v[114:117], v[178:181], v[194:197], v[114:117]
	v_mfma_f32_16x16x32_bf16 v[114:117], v[190:193], v[198:201], v[114:117]
	v_mfma_f32_16x16x32_bf16 v[98:101], v[178:181], v[202:205], v[98:101]
	v_mfma_f32_16x16x32_bf16 v[98:101], v[190:193], v[228:231], v[98:101]
	v_mfma_f32_16x16x32_bf16 v[82:85], v[178:181], v[232:235], v[82:85]
	v_mfma_f32_16x16x32_bf16 v[82:85], v[190:193], v[236:239], v[82:85]
	v_mfma_f32_16x16x32_bf16 v[66:69], v[178:181], v[240:243], v[66:69]
	v_mfma_f32_16x16x32_bf16 v[66:69], v[190:193], v[244:247], v[66:69]
	v_mfma_f32_16x16x32_bf16 v[70:73], v[154:157], v[240:243], v[70:73]
	v_mfma_f32_16x16x32_bf16 v[70:73], v[174:177], v[244:247], v[70:73]
	v_mfma_f32_16x16x32_bf16 v[86:89], v[154:157], v[232:235], v[86:89]
	v_mfma_f32_16x16x32_bf16 v[86:89], v[174:177], v[236:239], v[86:89]
	v_mfma_f32_16x16x32_bf16 v[102:105], v[154:157], v[202:205], v[102:105]
	v_mfma_f32_16x16x32_bf16 v[102:105], v[174:177], v[228:231], v[102:105]
	v_mfma_f32_16x16x32_bf16 v[118:121], v[154:157], v[194:197], v[118:121]
	v_mfma_f32_16x16x32_bf16 v[118:121], v[174:177], v[198:201], v[118:121]
	s_barrier
	s_setprio 0
	s_or_b32 s52, s25, 0x80
	s_mov_b32 m0, s36
	ds_read_b128 v[194:197], v189 offset:49152
	buffer_load_dwordx4 v185, s[44:47], s52 offen lds
	s_add_i32 s25, s25, 0x80080
	s_mov_b32 m0, s37
	ds_read_b128 v[198:201], v189 offset:50176
	buffer_load_dwordx4 v187, s[44:47], s52 offen lds
	s_mov_b32 m0, s66
	ds_read_b128 v[202:205], v189 offset:51200
	buffer_load_dwordx4 v185, s[44:47], s25 offen lds
	s_mov_b32 m0, s67
	ds_read_b128 v[228:231], v189 offset:52224
	buffer_load_dwordx4 v187, s[44:47], s25 offen lds
	s_mov_b32 m0, s48
	ds_read_b128 v[232:235], v189 offset:53248
	buffer_load_dwordx4 v184, s[60:63], s24 offen lds
	s_mov_b32 m0, s49
	ds_read_b128 v[236:239], v189 offset:54272
	buffer_load_dwordx4 v186, s[60:63], s24 offen lds
	ds_read_b128 v[240:243], v189 offset:55296
	ds_read_b128 v[244:247], v189 offset:56320
	s_waitcnt vmcnt(8)
	s_waitcnt lgkmcnt(0)
	s_setprio 1
	s_barrier
	v_mfma_f32_16x16x32_bf16 v[62:65], v[130:133], v[194:197], v[62:65]
	v_mfma_f32_16x16x32_bf16 v[62:65], v[134:137], v[198:201], v[62:65]
	v_mfma_f32_16x16x32_bf16 v[46:49], v[130:133], v[202:205], v[46:49]
	v_mfma_f32_16x16x32_bf16 v[46:49], v[134:137], v[228:231], v[46:49]
	v_mfma_f32_16x16x32_bf16 v[30:33], v[130:133], v[232:235], v[30:33]
	v_mfma_f32_16x16x32_bf16 v[30:33], v[134:137], v[236:239], v[30:33]
	v_mfma_f32_16x16x32_bf16 v[14:17], v[130:133], v[240:243], v[14:17]
	v_mfma_f32_16x16x32_bf16 v[14:17], v[134:137], v[244:247], v[14:17]
	v_mfma_f32_16x16x32_bf16 v[10:13], v[138:141], v[240:243], v[10:13]
	v_mfma_f32_16x16x32_bf16 v[10:13], v[142:145], v[244:247], v[10:13]
	v_mfma_f32_16x16x32_bf16 v[26:29], v[138:141], v[232:235], v[26:29]
	v_mfma_f32_16x16x32_bf16 v[26:29], v[142:145], v[236:239], v[26:29]
	v_mfma_f32_16x16x32_bf16 v[42:45], v[138:141], v[202:205], v[42:45]
	v_mfma_f32_16x16x32_bf16 v[42:45], v[142:145], v[228:231], v[42:45]
	v_mfma_f32_16x16x32_bf16 v[58:61], v[138:141], v[194:197], v[58:61]
	v_mfma_f32_16x16x32_bf16 v[58:61], v[142:145], v[198:201], v[58:61]
	v_mfma_f32_16x16x32_bf16 v[50:53], v[178:181], v[194:197], v[50:53]
	v_mfma_f32_16x16x32_bf16 v[50:53], v[190:193], v[198:201], v[50:53]
	v_mfma_f32_16x16x32_bf16 v[34:37], v[178:181], v[202:205], v[34:37]
	v_mfma_f32_16x16x32_bf16 v[34:37], v[190:193], v[228:231], v[34:37]
	v_mfma_f32_16x16x32_bf16 v[18:21], v[178:181], v[232:235], v[18:21]
	v_mfma_f32_16x16x32_bf16 v[18:21], v[190:193], v[236:239], v[18:21]
	v_mfma_f32_16x16x32_bf16 v[2:5], v[178:181], v[240:243], v[2:5]
	v_mfma_f32_16x16x32_bf16 v[2:5], v[190:193], v[244:247], v[2:5]
	v_mfma_f32_16x16x32_bf16 v[6:9], v[154:157], v[240:243], v[6:9]
	v_mfma_f32_16x16x32_bf16 v[6:9], v[174:177], v[244:247], v[6:9]
	v_mfma_f32_16x16x32_bf16 v[22:25], v[154:157], v[232:235], v[22:25]
	v_mfma_f32_16x16x32_bf16 v[22:25], v[174:177], v[236:239], v[22:25]
	v_mfma_f32_16x16x32_bf16 v[38:41], v[154:157], v[202:205], v[38:41]
	v_mfma_f32_16x16x32_bf16 v[38:41], v[174:177], v[228:231], v[38:41]
	v_mfma_f32_16x16x32_bf16 v[54:57], v[154:157], v[194:197], v[54:57]
	v_mfma_f32_16x16x32_bf16 v[54:57], v[174:177], v[198:201], v[54:57]
	s_barrier
	s_setprio 0
	s_add_i32 s22, s22, 2
	s_addk_i32 s13, 0x100
	s_addk_i32 s21, 0x100
	s_cmp_gt_u32 s22, 29
	s_cbranch_scc0 .LBB0_2450
	s_and_b64 vcc, exec, s[64:65]
	s_cbranch_vccz .LBB0_2453
	s_barrier
